# hoist1
# speedup vs baseline: 1.0110x; 1.0110x over previous
; #define STAGE(P, BASE, LD, br, kt) do { const char* _g = (const char*)((BASE) + (size_t)(br) * (LD) + (size_t)(kt) * 64); \
;     for (int _i = 0; _i < 2; ++_i) { int _b = tidx * 16 + _i * 8192; int _r, _c; stage_rc(_b, _r, _c); \
;       __builtin_amdgcn_global_load_lds((const unsigned*)(_g + (unsigned)((_r * (LD) + _c) * 2)), (unsigned*)((char*)(P) + _b), 16, 0, 0); } } while (0)
; #define LDA(dst, b, h) for (int m = 0; m < 4; ++m) for (int k = 0; k < 2; ++k) \
;     dst[m][k] = *reinterpret_cast<const bf16x8*>((char*)SA(b, h) + lds_byte(wr * 64 + m * 16 + fr, k * 32 + fq * 8))
; #define LDB(dst, b, h) for (int n = 0; n < 2; ++n) for (int k = 0; k < 2; ++k) \
;     dst[n][k] = *reinterpret_cast<const bf16x8*>((char*)SB(b, h) + lds_byte(wc * 32 + n * 16 + fr, k * 32 + fq * 8))
; #define MMA(ai, bj, At_, Bt_) do { __builtin_amdgcn_s_setprio(1); \
;     for (int k = 0; k < 2; ++k) for (int m = 0; m < 4; ++m) for (int n = 0; n < 2; ++n) \
;       acc[ai][bj][m][n] = __builtin_amdgcn_mfma_f32_16x16x32_bf16(At_[m][k], Bt_[n][k], acc[ai][bj][m][n], 0, 0, 0); \
;     __builtin_amdgcn_s_setprio(0); } while (0)
; #define WAIT_L(n) asm volatile("s_waitcnt lgkmcnt(" #n ")" ::: "memory")
; #define BAR __builtin_amdgcn_s_barrier()
; #define SCHED __builtin_amdgcn_sched_barrier(0)
; template <int EPI, int lda, int ldb, int N, int K>
; __device__ __forceinline__ void gemm_phase(const u16* __restrict__ A, const u16* __restrict__ Bt, const GemmEpi ep, int wv) {
;     ...
;       LDB(B0, 0, 0); SCHED; LDA(At, 0, 0); STAGE(SA(1, 1), Ab, lda, brow + HALF, t + 1);
;       WAIT_L(8); BAR; WAIT_L(0); MMA(0, 0, At, B0); BAR; SCHED;
;       LDB(B1, 0, 1); STAGE(SB(0, 0), Bt, ldb, bcol, t + 2);
;       BAR; WAIT_L(0); MMA(0, 1, At, B1); BAR;
;       LDA(At, 0, 1); STAGE(SA(0, 0), Ab, lda, brow, t + 2);
;       BAR; WAIT_L(0); MMA(1, 0, At, B0); BAR; SCHED;
.LBB0_53:
	ds_read_b128 v[172:175], v161
	ds_read_b128 v[176:179], v161 offset:1024
	ds_read_b128 v[180:183], v161 offset:2048
	ds_read_b128 v[184:187], v161 offset:3072
	v_add_u32_e32 v169, 0xc000, v148
	v_lshl_add_u64 v[236:237], v[136:137], 0, s[42:43]
	v_readfirstlane_b32 s45, v169
	v_add_u32_e32 v170, 0xe000, v148
	v_lshl_add_u64 v[162:163], v[236:237], 0, s[14:15]
	s_mov_b32 m0, s45
	v_lshl_add_u64 v[238:239], v[134:135], 0, s[42:43]
	v_readfirstlane_b32 s45, v170
	ds_read_b128 v[164:167], v152
	ds_read_b128 v[188:191], v152 offset:1024
	ds_read_b128 v[192:195], v151
	ds_read_b128 v[196:199], v151 offset:1024
	ds_read_b128 v[200:203], v150
	ds_read_b128 v[204:207], v150 offset:1024
	ds_read_b128 v[208:211], v149
	ds_read_b128 v[212:215], v149 offset:1024
	global_load_lds_dwordx4 v[162:163], off
	v_lshl_add_u64 v[162:163], v[238:239], 0, s[14:15]
	s_mov_b32 m0, s45
	s_nop 0
	global_load_lds_dwordx4 v[162:163], off
	s_waitcnt lgkmcnt(8)
	s_barrier
	s_waitcnt lgkmcnt(0)
	s_waitcnt lgkmcnt(0)
	v_mfma_f32_16x16x32_bf16 v[124:127], v[172:175], v[164:167], v[124:127]
	ds_read_b128 v[216:219], v160
	v_mfma_f32_16x16x32_bf16 v[120:123], v[180:183], v[164:167], v[120:123]
	v_mfma_f32_16x16x32_bf16 v[116:119], v[172:175], v[192:195], v[116:119]
	ds_read_b128 v[220:223], v160 offset:1024
	v_mfma_f32_16x16x32_bf16 v[112:115], v[180:183], v[192:195], v[112:115]
	v_mfma_f32_16x16x32_bf16 v[108:111], v[172:175], v[200:203], v[108:111]
	ds_read_b128 v[224:227], v160 offset:2048
	v_mfma_f32_16x16x32_bf16 v[104:107], v[180:183], v[200:203], v[104:107]
	v_mfma_f32_16x16x32_bf16 v[100:103], v[172:175], v[208:211], v[100:103]
	ds_read_b128 v[228:231], v160 offset:3072
	v_mfma_f32_16x16x32_bf16 v[96:99], v[180:183], v[208:211], v[96:99]
	v_mfma_f32_16x16x32_bf16 v[124:127], v[176:179], v[188:191], v[124:127]
	v_mfma_f32_16x16x32_bf16 v[120:123], v[184:187], v[188:191], v[120:123]
	v_mfma_f32_16x16x32_bf16 v[116:119], v[176:179], v[196:199], v[116:119]
	v_mfma_f32_16x16x32_bf16 v[112:115], v[184:187], v[196:199], v[112:115]
	v_mfma_f32_16x16x32_bf16 v[108:111], v[176:179], v[204:207], v[108:111]
	v_mfma_f32_16x16x32_bf16 v[104:107], v[184:187], v[204:207], v[104:107]
	v_mfma_f32_16x16x32_bf16 v[100:103], v[176:179], v[212:215], v[100:103]
	v_mfma_f32_16x16x32_bf16 v[96:99], v[184:187], v[212:215], v[96:99]
	s_barrier
	v_add_u32_e32 v162, s54, v153
	v_lshl_add_u64 v[240:241], v[140:141], 0, s[42:43]
	v_readfirstlane_b32 s45, v162
	v_add_u32_e32 v163, 0x2000, v162
	v_lshl_add_u64 v[232:233], v[240:241], 0, s[16:17]
	s_mov_b32 m0, s45
	v_lshl_add_u64 v[242:243], v[138:139], 0, s[42:43]
	v_readfirstlane_b32 s45, v163
	global_load_lds_dwordx4 v[232:233], off
	v_lshl_add_u64 v[232:233], v[242:243], 0, s[16:17]
	s_mov_b32 m0, s45
	s_nop 0
	global_load_lds_dwordx4 v[232:233], off
	s_barrier
	s_waitcnt lgkmcnt(0)
	s_waitcnt lgkmcnt(0)
	v_mfma_f32_16x16x32_bf16 v[92:95], v[216:219], v[164:167], v[92:95]
	v_mfma_f32_16x16x32_bf16 v[88:91], v[224:227], v[164:167], v[88:91]
	v_mfma_f32_16x16x32_bf16 v[84:87], v[216:219], v[192:195], v[84:87]
	v_mfma_f32_16x16x32_bf16 v[80:83], v[224:227], v[192:195], v[80:83]
	v_mfma_f32_16x16x32_bf16 v[76:79], v[216:219], v[200:203], v[76:79]
	v_mfma_f32_16x16x32_bf16 v[72:75], v[224:227], v[200:203], v[72:75]
	v_mfma_f32_16x16x32_bf16 v[68:71], v[216:219], v[208:211], v[68:71]
	v_mfma_f32_16x16x32_bf16 v[64:67], v[224:227], v[208:211], v[64:67]
	v_mfma_f32_16x16x32_bf16 v[92:95], v[220:223], v[188:191], v[92:95]
	v_mfma_f32_16x16x32_bf16 v[88:91], v[228:231], v[188:191], v[88:91]
	v_mfma_f32_16x16x32_bf16 v[84:87], v[220:223], v[196:199], v[84:87]
	v_mfma_f32_16x16x32_bf16 v[80:83], v[228:231], v[196:199], v[80:83]
	v_mfma_f32_16x16x32_bf16 v[76:79], v[220:223], v[204:207], v[76:79]
	v_mfma_f32_16x16x32_bf16 v[72:75], v[228:231], v[204:207], v[72:75]
	v_mfma_f32_16x16x32_bf16 v[68:71], v[220:223], v[212:215], v[68:71]
	v_mfma_f32_16x16x32_bf16 v[64:67], v[228:231], v[212:215], v[64:67]
	v_readfirstlane_b32 s45, v148
	v_lshl_add_u64 v[164:165], v[236:237], 0, s[18:19]
	s_mov_b32 m0, s45
	s_barrier
	ds_read_b128 v[188:191], v152 offset:16384
	ds_read_b128 v[192:195], v152 offset:17408
	ds_read_b128 v[196:199], v151 offset:16384
	ds_read_b128 v[200:203], v151 offset:17408
	ds_read_b128 v[204:207], v150 offset:16384
	ds_read_b128 v[208:211], v150 offset:17408
	ds_read_b128 v[212:215], v149 offset:16384
	ds_read_b128 v[232:235], v149 offset:17408
	global_load_lds_dwordx4 v[164:165], off
	v_add_u32_e32 v164, 0x2000, v148
	v_lshl_add_u64 v[166:167], v[238:239], 0, s[18:19]
	v_readfirstlane_b32 s45, v164
	s_mov_b32 m0, s45
	s_nop 0
	global_load_lds_dwordx4 v[166:167], off
	s_barrier
	s_waitcnt lgkmcnt(0)
	s_waitcnt lgkmcnt(0)
	v_mfma_f32_16x16x32_bf16 v[60:63], v[172:175], v[188:191], v[60:63]
	v_mfma_f32_16x16x32_bf16 v[56:59], v[180:183], v[188:191], v[56:59]
	v_mfma_f32_16x16x32_bf16 v[52:55], v[172:175], v[196:199], v[52:55]
	v_mfma_f32_16x16x32_bf16 v[48:51], v[180:183], v[196:199], v[48:51]
	v_mfma_f32_16x16x32_bf16 v[44:47], v[172:175], v[204:207], v[44:47]
	v_mfma_f32_16x16x32_bf16 v[40:43], v[180:183], v[204:207], v[40:43]
	v_mfma_f32_16x16x32_bf16 v[36:39], v[172:175], v[212:215], v[36:39]
	v_mfma_f32_16x16x32_bf16 v[32:35], v[180:183], v[212:215], v[32:35]
	v_mfma_f32_16x16x32_bf16 v[60:63], v[176:179], v[192:195], v[60:63]
	v_mfma_f32_16x16x32_bf16 v[56:59], v[184:187], v[192:195], v[56:59]
	v_mfma_f32_16x16x32_bf16 v[52:55], v[176:179], v[200:203], v[52:55]
	v_mfma_f32_16x16x32_bf16 v[48:51], v[184:187], v[200:203], v[48:51]
	v_mfma_f32_16x16x32_bf16 v[44:47], v[176:179], v[208:211], v[44:47]
	v_mfma_f32_16x16x32_bf16 v[40:43], v[184:187], v[208:211], v[40:43]
	v_mfma_f32_16x16x32_bf16 v[36:39], v[176:179], v[232:235], v[36:39]
	v_mfma_f32_16x16x32_bf16 v[32:35], v[184:187], v[232:235], v[32:35]
	s_barrier
; #define STAGE(P, BASE, LD, br, kt) do { const char* _g = (const char*)((BASE) + (size_t)(br) * (LD) + (size_t)(kt) * 64); \
;     for (int _i = 0; _i < 2; ++_i) { int _b = tidx * 16 + _i * 8192; int _r, _c; stage_rc(_b, _r, _c); \
;       __builtin_amdgcn_global_load_lds((const unsigned*)(_g + (unsigned)((_r * (LD) + _c) * 2)), (unsigned*)((char*)(P) + _b), 16, 0, 0); } } while (0)
; #define LDA(dst, b, h) for (int m = 0; m < 4; ++m) for (int k = 0; k < 2; ++k) \
;     dst[m][k] = *reinterpret_cast<const bf16x8*>((char*)SA(b, h) + lds_byte(wr * 64 + m * 16 + fr, k * 32 + fq * 8))
; #define LDB(dst, b, h) for (int n = 0; n < 2; ++n) for (int k = 0; k < 2; ++k) \
;     dst[n][k] = *reinterpret_cast<const bf16x8*>((char*)SB(b, h) + lds_byte(wc * 32 + n * 16 + fr, k * 32 + fq * 8))
; #define MMA(ai, bj, At_, Bt_) do { __builtin_amdgcn_s_setprio(1); \
;     for (int k = 0; k < 2; ++k) for (int m = 0; m < 4; ++m) for (int n = 0; n < 2; ++n) \
;       acc[ai][bj][m][n] = __builtin_amdgcn_mfma_f32_16x16x32_bf16(At_[m][k], Bt_[n][k], acc[ai][bj][m][n], 0, 0, 0); \
;     __builtin_amdgcn_s_setprio(0); } while (0)
; #define WAIT_V(n) asm volatile("s_waitcnt vmcnt(" #n ")" ::: "memory")
; #define WAIT_L(n) asm volatile("s_waitcnt lgkmcnt(" #n ")" ::: "memory")
; #define BAR __builtin_amdgcn_s_barrier()
; #define SCHED __builtin_amdgcn_sched_barrier(0)
; template <int EPI, int lda, int ldb, int N, int K>
; __device__ __forceinline__ void gemm_phase(const u16* __restrict__ A, const u16* __restrict__ Bt, const GemmEpi ep, int wv) {
;     ...
;       STAGE(SB(0, 1), Bt, ldb, bcol + HALF, t + 2);
;       WAIT_V(6); BAR; MMA(1, 1, At, B1); BAR;
;       LDB(B0, 1, 0); SCHED; LDA(At, 1, 0); STAGE(SA(0, 1), Ab, lda, brow + HALF, t + 2);
;       WAIT_L(8); BAR; WAIT_L(0); MMA(0, 0, At, B0); BAR; SCHED;
;       LDB(B1, 1, 1); STAGE(SB(1, 0), Bt, ldb, bcol, t + 3);
;       BAR; WAIT_L(0); MMA(0, 1, At, B1); BAR;
	v_add_u32_e32 v165, s55, v153
	v_lshl_add_u64 v[166:167], v[240:241], 0, s[20:21]
	v_readfirstlane_b32 s45, v165
	s_mov_b32 m0, s45
	v_lshl_add_u64 v[172:173], v[242:243], 0, s[20:21]
	global_load_lds_dwordx4 v[166:167], off
	v_add_u32_e32 v166, 0x2000, v165
	s_nop 0
	v_readfirstlane_b32 s45, v166
	s_mov_b32 m0, s45
	s_nop 0
	global_load_lds_dwordx4 v[172:173], off
	s_waitcnt vmcnt(6)
	s_barrier
	v_mfma_f32_16x16x32_bf16 v[28:31], v[216:219], v[188:191], v[28:31]
	ds_read_b128 v[172:175], v156
	v_mfma_f32_16x16x32_bf16 v[24:27], v[224:227], v[188:191], v[24:27]
	v_mfma_f32_16x16x32_bf16 v[20:23], v[216:219], v[196:199], v[20:23]
	ds_read_b128 v[176:179], v156 offset:1024
	v_mfma_f32_16x16x32_bf16 v[16:19], v[224:227], v[196:199], v[16:19]
	v_mfma_f32_16x16x32_bf16 v[12:15], v[216:219], v[204:207], v[12:15]
	ds_read_b128 v[180:183], v156 offset:2048
	v_mfma_f32_16x16x32_bf16 v[8:11], v[224:227], v[204:207], v[8:11]
	v_mfma_f32_16x16x32_bf16 v[4:7], v[216:219], v[212:215], v[4:7]
	ds_read_b128 v[184:187], v156 offset:3072
	v_mfma_f32_16x16x32_bf16 v[0:3], v[224:227], v[212:215], v[0:3]
	v_mfma_f32_16x16x32_bf16 v[28:31], v[220:223], v[192:195], v[28:31]
	v_mfma_f32_16x16x32_bf16 v[24:27], v[228:231], v[192:195], v[24:27]
	v_mfma_f32_16x16x32_bf16 v[20:23], v[220:223], v[200:203], v[20:23]
	v_mfma_f32_16x16x32_bf16 v[16:19], v[228:231], v[200:203], v[16:19]
	v_mfma_f32_16x16x32_bf16 v[12:15], v[220:223], v[208:211], v[12:15]
	v_mfma_f32_16x16x32_bf16 v[8:11], v[228:231], v[208:211], v[8:11]
	v_mfma_f32_16x16x32_bf16 v[4:7], v[220:223], v[232:235], v[4:7]
	v_mfma_f32_16x16x32_bf16 v[0:3], v[228:231], v[232:235], v[0:3]
	s_barrier
	v_add_u32_e32 v167, 0x4000, v148
	v_add_u32_e32 v168, 0x6000, v148
	v_readfirstlane_b32 s45, v167
	v_lshl_add_u64 v[220:221], v[236:237], 0, s[22:23]
	s_mov_b32 m0, s45
	v_readfirstlane_b32 s45, v168
	ds_read_b128 v[188:191], v152 offset:32768
	ds_read_b128 v[192:195], v152 offset:33792
	ds_read_b128 v[196:199], v151 offset:32768
	ds_read_b128 v[200:203], v151 offset:33792
	ds_read_b128 v[204:207], v150 offset:32768
	ds_read_b128 v[208:211], v150 offset:33792
	ds_read_b128 v[212:215], v149 offset:32768
	ds_read_b128 v[216:219], v149 offset:33792
	global_load_lds_dwordx4 v[220:221], off
	v_lshl_add_u64 v[220:221], v[238:239], 0, s[22:23]
	s_mov_b32 m0, s45
	s_nop 0
	global_load_lds_dwordx4 v[220:221], off
	s_waitcnt lgkmcnt(8)
	s_barrier
	s_waitcnt lgkmcnt(0)
	s_waitcnt lgkmcnt(0)
	v_mfma_f32_16x16x32_bf16 v[124:127], v[172:175], v[188:191], v[124:127]
	ds_read_b128 v[220:223], v154
	v_mfma_f32_16x16x32_bf16 v[120:123], v[180:183], v[188:191], v[120:123]
	v_mfma_f32_16x16x32_bf16 v[116:119], v[172:175], v[196:199], v[116:119]
	ds_read_b128 v[224:227], v154 offset:1024
	v_mfma_f32_16x16x32_bf16 v[112:115], v[180:183], v[196:199], v[112:115]
	v_mfma_f32_16x16x32_bf16 v[108:111], v[172:175], v[204:207], v[108:111]
	ds_read_b128 v[228:231], v154 offset:2048
	v_mfma_f32_16x16x32_bf16 v[104:107], v[180:183], v[204:207], v[104:107]
	v_mfma_f32_16x16x32_bf16 v[100:103], v[172:175], v[212:215], v[100:103]
	ds_read_b128 v[232:235], v154 offset:3072
	v_mfma_f32_16x16x32_bf16 v[96:99], v[180:183], v[212:215], v[96:99]
	v_mfma_f32_16x16x32_bf16 v[124:127], v[176:179], v[192:195], v[124:127]
	v_mfma_f32_16x16x32_bf16 v[120:123], v[184:187], v[192:195], v[120:123]
	v_mfma_f32_16x16x32_bf16 v[116:119], v[176:179], v[200:203], v[116:119]
	v_mfma_f32_16x16x32_bf16 v[112:115], v[184:187], v[200:203], v[112:115]
	v_mfma_f32_16x16x32_bf16 v[108:111], v[176:179], v[208:211], v[108:111]
	v_mfma_f32_16x16x32_bf16 v[104:107], v[184:187], v[208:211], v[104:107]
	v_mfma_f32_16x16x32_bf16 v[100:103], v[176:179], v[216:219], v[100:103]
	v_mfma_f32_16x16x32_bf16 v[96:99], v[184:187], v[216:219], v[96:99]
	s_barrier
	v_readfirstlane_b32 s45, v155
	v_add_u32_e32 v171, 0x2000, v155
	v_lshl_add_u64 v[244:245], v[240:241], 0, s[24:25]
	s_mov_b32 m0, s45
	v_readfirstlane_b32 s45, v171
	global_load_lds_dwordx4 v[244:245], off
	v_lshl_add_u64 v[244:245], v[242:243], 0, s[24:25]
	s_mov_b32 m0, s45
	s_nop 0
	global_load_lds_dwordx4 v[244:245], off
	s_barrier
	s_waitcnt lgkmcnt(0)
	s_waitcnt lgkmcnt(0)
	v_mfma_f32_16x16x32_bf16 v[92:95], v[220:223], v[188:191], v[92:95]
	v_mfma_f32_16x16x32_bf16 v[88:91], v[228:231], v[188:191], v[88:91]
	v_mfma_f32_16x16x32_bf16 v[84:87], v[220:223], v[196:199], v[84:87]
	v_mfma_f32_16x16x32_bf16 v[80:83], v[228:231], v[196:199], v[80:83]
	v_mfma_f32_16x16x32_bf16 v[76:79], v[220:223], v[204:207], v[76:79]
	v_mfma_f32_16x16x32_bf16 v[72:75], v[228:231], v[204:207], v[72:75]
	v_mfma_f32_16x16x32_bf16 v[68:71], v[220:223], v[212:215], v[68:71]
	v_mfma_f32_16x16x32_bf16 v[64:67], v[228:231], v[212:215], v[64:67]
	v_mfma_f32_16x16x32_bf16 v[92:95], v[224:227], v[192:195], v[92:95]
	v_mfma_f32_16x16x32_bf16 v[88:91], v[232:235], v[192:195], v[88:91]
	v_mfma_f32_16x16x32_bf16 v[84:87], v[224:227], v[200:203], v[84:87]
	v_mfma_f32_16x16x32_bf16 v[80:83], v[232:235], v[200:203], v[80:83]
	v_mfma_f32_16x16x32_bf16 v[76:79], v[224:227], v[208:211], v[76:79]
	v_mfma_f32_16x16x32_bf16 v[72:75], v[232:235], v[208:211], v[72:75]
	v_mfma_f32_16x16x32_bf16 v[68:71], v[224:227], v[216:219], v[68:71]
	v_mfma_f32_16x16x32_bf16 v[64:67], v[232:235], v[216:219], v[64:67]
	v_readfirstlane_b32 s45, v157
	v_lshl_add_u64 v[236:237], v[236:237], 0, s[26:27]
	s_mov_b32 m0, s45
	v_readfirstlane_b32 s45, v158
	s_barrier
; #define STAGE(P, BASE, LD, br, kt) do { const char* _g = (const char*)((BASE) + (size_t)(br) * (LD) + (size_t)(kt) * 64); \
;     for (int _i = 0; _i < 2; ++_i) { int _b = tidx * 16 + _i * 8192; int _r, _c; stage_rc(_b, _r, _c); \
;       __builtin_amdgcn_global_load_lds((const unsigned*)(_g + (unsigned)((_r * (LD) + _c) * 2)), (unsigned*)((char*)(P) + _b), 16, 0, 0); } } while (0)
; #define LDA(dst, b, h) for (int m = 0; m < 4; ++m) for (int k = 0; k < 2; ++k) \
;     dst[m][k] = *reinterpret_cast<const bf16x8*>((char*)SA(b, h) + lds_byte(wr * 64 + m * 16 + fr, k * 32 + fq * 8))
; #define LDB(dst, b, h) for (int n = 0; n < 2; ++n) for (int k = 0; k < 2; ++k) \
;     dst[n][k] = *reinterpret_cast<const bf16x8*>((char*)SB(b, h) + lds_byte(wc * 32 + n * 16 + fr, k * 32 + fq * 8))
; #define MMA(ai, bj, At_, Bt_) do { __builtin_amdgcn_s_setprio(1); \
;     for (int k = 0; k < 2; ++k) for (int m = 0; m < 4; ++m) for (int n = 0; n < 2; ++n) \
;       acc[ai][bj][m][n] = __builtin_amdgcn_mfma_f32_16x16x32_bf16(At_[m][k], Bt_[n][k], acc[ai][bj][m][n], 0, 0, 0); \
;     __builtin_amdgcn_s_setprio(0); } while (0)
; #define WAIT_V(n) asm volatile("s_waitcnt vmcnt(" #n ")" ::: "memory")
; #define WAIT_L(n) asm volatile("s_waitcnt lgkmcnt(" #n ")" ::: "memory")
; #define BAR __builtin_amdgcn_s_barrier()
; #define SCHED __builtin_amdgcn_sched_barrier(0)
; template <int EPI, int lda, int ldb, int N, int K>
; __device__ __forceinline__ void gemm_phase(const u16* __restrict__ A, const u16* __restrict__ Bt, const GemmEpi ep, int wv) {
;     ...
;       LDA(At, 1, 1); STAGE(SA(1, 0), Ab, lda, brow, t + 3);
;       BAR; WAIT_L(0); MMA(1, 0, At, B0); BAR; SCHED;
;       STAGE(SB(1, 1), Bt, ldb, bcol + HALF, t + 3);
;       WAIT_V(6); BAR; MMA(1, 1, At, B1); BAR;
;     }
;     { LDB(B0, 0, 0); LDA(At, 0, 0); STAGE(SA(1, 1), Ab, lda, brow + HALF, nt - 1);
;       BAR; WAIT_L(0); MMA(0, 0, At, B0); BAR;
;       LDB(B1, 0, 1); BAR; WAIT_L(0); MMA(0, 1, At, B1); BAR;
	ds_read_b128 v[188:191], v152 offset:49152
	ds_read_b128 v[192:195], v152 offset:50176
	ds_read_b128 v[196:199], v151 offset:49152
	ds_read_b128 v[200:203], v151 offset:50176
	ds_read_b128 v[204:207], v150 offset:49152
	ds_read_b128 v[208:211], v150 offset:50176
	ds_read_b128 v[212:215], v149 offset:49152
	ds_read_b128 v[216:219], v149 offset:50176
	global_load_lds_dwordx4 v[236:237], off
	v_lshl_add_u64 v[236:237], v[238:239], 0, s[26:27]
	s_mov_b32 m0, s45
	s_nop 0
	global_load_lds_dwordx4 v[236:237], off
	s_barrier
	s_waitcnt lgkmcnt(0)
	s_waitcnt lgkmcnt(0)
	v_mfma_f32_16x16x32_bf16 v[60:63], v[172:175], v[188:191], v[60:63]
	v_mfma_f32_16x16x32_bf16 v[56:59], v[180:183], v[188:191], v[56:59]
	v_mfma_f32_16x16x32_bf16 v[52:55], v[172:175], v[196:199], v[52:55]
	v_mfma_f32_16x16x32_bf16 v[48:51], v[180:183], v[196:199], v[48:51]
	v_mfma_f32_16x16x32_bf16 v[44:47], v[172:175], v[204:207], v[44:47]
	v_mfma_f32_16x16x32_bf16 v[40:43], v[180:183], v[204:207], v[40:43]
	v_mfma_f32_16x16x32_bf16 v[36:39], v[172:175], v[212:215], v[36:39]
	v_mfma_f32_16x16x32_bf16 v[32:35], v[180:183], v[212:215], v[32:35]
	v_mfma_f32_16x16x32_bf16 v[60:63], v[176:179], v[192:195], v[60:63]
	v_mfma_f32_16x16x32_bf16 v[56:59], v[184:187], v[192:195], v[56:59]
	v_mfma_f32_16x16x32_bf16 v[52:55], v[176:179], v[200:203], v[52:55]
	v_mfma_f32_16x16x32_bf16 v[48:51], v[184:187], v[200:203], v[48:51]
	v_mfma_f32_16x16x32_bf16 v[44:47], v[176:179], v[208:211], v[44:47]
	v_mfma_f32_16x16x32_bf16 v[40:43], v[184:187], v[208:211], v[40:43]
	v_mfma_f32_16x16x32_bf16 v[36:39], v[176:179], v[216:219], v[36:39]
	v_mfma_f32_16x16x32_bf16 v[32:35], v[184:187], v[216:219], v[32:35]
	s_barrier
	v_readfirstlane_b32 s45, v159
	v_add_u32_e32 v171, 0x2000, v159
	v_lshl_add_u64 v[172:173], v[240:241], 0, s[34:35]
	s_mov_b32 m0, s45
	v_readfirstlane_b32 s45, v171
	global_load_lds_dwordx4 v[172:173], off
	v_lshl_add_u64 v[172:173], v[242:243], 0, s[34:35]
	s_mov_b32 m0, s45
	s_nop 0
	global_load_lds_dwordx4 v[172:173], off
	s_waitcnt vmcnt(6)
	s_barrier
	v_mfma_f32_16x16x32_bf16 v[28:31], v[220:223], v[188:191], v[28:31]
	v_mfma_f32_16x16x32_bf16 v[24:27], v[228:231], v[188:191], v[24:27]
	v_mfma_f32_16x16x32_bf16 v[20:23], v[220:223], v[196:199], v[20:23]
	v_mfma_f32_16x16x32_bf16 v[16:19], v[228:231], v[196:199], v[16:19]
	v_mfma_f32_16x16x32_bf16 v[12:15], v[220:223], v[204:207], v[12:15]
	v_mfma_f32_16x16x32_bf16 v[8:11], v[228:231], v[204:207], v[8:11]
	v_mfma_f32_16x16x32_bf16 v[4:7], v[220:223], v[212:215], v[4:7]
	v_mfma_f32_16x16x32_bf16 v[0:3], v[228:231], v[212:215], v[0:3]
	v_mfma_f32_16x16x32_bf16 v[28:31], v[224:227], v[192:195], v[28:31]
	v_mfma_f32_16x16x32_bf16 v[24:27], v[232:235], v[192:195], v[24:27]
	v_mfma_f32_16x16x32_bf16 v[20:23], v[224:227], v[200:203], v[20:23]
	v_mfma_f32_16x16x32_bf16 v[16:19], v[232:235], v[200:203], v[16:19]
	v_mfma_f32_16x16x32_bf16 v[12:15], v[224:227], v[208:211], v[12:15]
	v_mfma_f32_16x16x32_bf16 v[8:11], v[232:235], v[208:211], v[8:11]
	v_mfma_f32_16x16x32_bf16 v[4:7], v[224:227], v[216:219], v[4:7]
	v_mfma_f32_16x16x32_bf16 v[0:3], v[232:235], v[216:219], v[0:3]
	s_add_i32 s44, s44, 2
	s_add_u32 s42, s42, 0x100
	s_addc_u32 s43, s43, 0
	s_cmp_gt_u32 s44, 27
	s_barrier
	s_cbranch_scc0 .LBB0_53
	s_add_i32 s42, s38, 0x80
	s_mul_hi_i32 s43, s42, 0x1080
	s_mulk_i32 s42, 0x1080
	s_add_u32 s42, s51, s42
	s_addc_u32 s43, s52, s43
	v_lshl_add_u64 v[158:159], s[42:43], 0, v[128:129]
	v_readfirstlane_b32 s44, v169
	v_lshl_add_u64 v[158:159], v[158:159], 0, s[36:37]
	s_mov_b32 m0, s44
	ds_read_b128 v[134:137], v161
	ds_read_b128 v[138:141], v161 offset:1024
	ds_read_b128 v[172:175], v161 offset:2048
	ds_read_b128 v[176:179], v161 offset:3072
	ds_read_b128 v[180:183], v152
	ds_read_b128 v[184:187], v152 offset:1024
	ds_read_b128 v[188:191], v151
	ds_read_b128 v[192:195], v151 offset:1024
	ds_read_b128 v[196:199], v150
	ds_read_b128 v[200:203], v150 offset:1024
	ds_read_b128 v[204:207], v149
	ds_read_b128 v[208:211], v149 offset:1024
	global_load_lds_dwordx4 v[158:159], off
	v_lshl_add_u64 v[158:159], s[42:43], 0, v[132:133]
	v_readfirstlane_b32 s42, v170
	v_lshl_add_u64 v[158:159], v[158:159], 0, s[36:37]
	s_mov_b32 m0, s42
	s_nop 0
	global_load_lds_dwordx4 v[158:159], off
	s_barrier
	s_waitcnt lgkmcnt(0)
	s_waitcnt lgkmcnt(0)
	v_mfma_f32_16x16x32_bf16 v[124:127], v[134:137], v[180:183], v[124:127]
	v_mfma_f32_16x16x32_bf16 v[120:123], v[172:175], v[180:183], v[120:123]
	v_mfma_f32_16x16x32_bf16 v[116:119], v[134:137], v[188:191], v[116:119]
	v_mfma_f32_16x16x32_bf16 v[112:115], v[172:175], v[188:191], v[112:115]
	v_mfma_f32_16x16x32_bf16 v[108:111], v[134:137], v[196:199], v[108:111]
	v_mfma_f32_16x16x32_bf16 v[104:107], v[172:175], v[196:199], v[104:107]
	v_mfma_f32_16x16x32_bf16 v[100:103], v[134:137], v[204:207], v[100:103]
	v_mfma_f32_16x16x32_bf16 v[96:99], v[172:175], v[204:207], v[96:99]
	v_mfma_f32_16x16x32_bf16 v[124:127], v[138:141], v[184:187], v[124:127]
	v_mfma_f32_16x16x32_bf16 v[120:123], v[176:179], v[184:187], v[120:123]
	v_mfma_f32_16x16x32_bf16 v[116:119], v[138:141], v[192:195], v[116:119]
	v_mfma_f32_16x16x32_bf16 v[112:115], v[176:179], v[192:195], v[112:115]
	v_mfma_f32_16x16x32_bf16 v[108:111], v[138:141], v[200:203], v[108:111]
	v_mfma_f32_16x16x32_bf16 v[104:107], v[176:179], v[200:203], v[104:107]
	v_mfma_f32_16x16x32_bf16 v[100:103], v[138:141], v[208:211], v[100:103]
	v_mfma_f32_16x16x32_bf16 v[96:99], v[176:179], v[208:211], v[96:99]
	s_barrier
	ds_read_b128 v[212:215], v160
	ds_read_b128 v[216:219], v160 offset:1024
	ds_read_b128 v[220:223], v160 offset:2048
	ds_read_b128 v[158:161], v160 offset:3072
	s_barrier
; #define LDA(dst, b, h) for (int m = 0; m < 4; ++m) for (int k = 0; k < 2; ++k) \
;     dst[m][k] = *reinterpret_cast<const bf16x8*>((char*)SA(b, h) + lds_byte(wr * 64 + m * 16 + fr, k * 32 + fq * 8))
; #define LDB(dst, b, h) for (int n = 0; n < 2; ++n) for (int k = 0; k < 2; ++k) \
;     dst[n][k] = *reinterpret_cast<const bf16x8*>((char*)SB(b, h) + lds_byte(wc * 32 + n * 16 + fr, k * 32 + fq * 8))
; #define MMA(ai, bj, At_, Bt_) do { __builtin_amdgcn_s_setprio(1); \
;     for (int k = 0; k < 2; ++k) for (int m = 0; m < 4; ++m) for (int n = 0; n < 2; ++n) \
;       acc[ai][bj][m][n] = __builtin_amdgcn_mfma_f32_16x16x32_bf16(At_[m][k], Bt_[n][k], acc[ai][bj][m][n], 0, 0, 0); \
;     __builtin_amdgcn_s_setprio(0); } while (0)
; #define WAIT_V(n) asm volatile("s_waitcnt vmcnt(" #n ")" ::: "memory")
; #define WAIT_L(n) asm volatile("s_waitcnt lgkmcnt(" #n ")" ::: "memory")
; #define BAR __builtin_amdgcn_s_barrier()
; template <int EPI, int lda, int ldb, int N, int K>
; __device__ __forceinline__ void gemm_phase(const u16* __restrict__ A, const u16* __restrict__ Bt, const GemmEpi ep, int wv) {
;     ...
;       LDB(B1, 0, 1); BAR; WAIT_L(0); MMA(0, 1, At, B1); BAR;
;       LDA(At, 0, 1); WAIT_V(4); BAR; WAIT_L(0); MMA(1, 0, At, B0); MMA(1, 1, At, B1); BAR; }
;     { LDB(B0, 1, 0); LDA(At, 1, 0); WAIT_V(2); BAR; WAIT_L(0); MMA(0, 0, At, B0); BAR;
	s_waitcnt lgkmcnt(0)
	s_waitcnt lgkmcnt(0)
	v_mfma_f32_16x16x32_bf16 v[92:95], v[212:215], v[180:183], v[92:95]
	v_mfma_f32_16x16x32_bf16 v[88:91], v[220:223], v[180:183], v[88:91]
	v_mfma_f32_16x16x32_bf16 v[76:79], v[212:215], v[196:199], v[76:79]
	v_mfma_f32_16x16x32_bf16 v[72:75], v[220:223], v[196:199], v[72:75]
	v_mfma_f32_16x16x32_bf16 v[84:87], v[212:215], v[188:191], v[84:87]
	v_mfma_f32_16x16x32_bf16 v[80:83], v[220:223], v[188:191], v[80:83]
	v_mfma_f32_16x16x32_bf16 v[68:71], v[212:215], v[204:207], v[68:71]
	v_mfma_f32_16x16x32_bf16 v[64:67], v[220:223], v[204:207], v[64:67]
	v_mfma_f32_16x16x32_bf16 v[92:95], v[216:219], v[184:187], v[92:95]
	v_mfma_f32_16x16x32_bf16 v[88:91], v[158:161], v[184:187], v[88:91]
	v_mfma_f32_16x16x32_bf16 v[76:79], v[216:219], v[200:203], v[76:79]
	v_mfma_f32_16x16x32_bf16 v[72:75], v[158:161], v[200:203], v[72:75]
	v_mfma_f32_16x16x32_bf16 v[180:183], v[216:219], v[192:195], v[84:87]
	v_mfma_f32_16x16x32_bf16 v[184:187], v[158:161], v[192:195], v[80:83]
	v_mfma_f32_16x16x32_bf16 v[188:191], v[216:219], v[208:211], v[68:71]
	v_mfma_f32_16x16x32_bf16 v[192:195], v[158:161], v[208:211], v[64:67]
	s_barrier
	s_nop 0
	ds_read_b128 v[64:67], v152 offset:16384
	ds_read_b128 v[68:71], v152 offset:17408
	ds_read_b128 v[80:83], v151 offset:16384
	ds_read_b128 v[84:87], v151 offset:17408
	ds_read_b128 v[196:199], v150 offset:16384
	ds_read_b128 v[200:203], v150 offset:17408
	ds_read_b128 v[204:207], v149 offset:16384
	ds_read_b128 v[208:211], v149 offset:17408
	s_waitcnt vmcnt(4)
	s_barrier
	s_waitcnt lgkmcnt(0)
	s_waitcnt lgkmcnt(0)
	v_mfma_f32_16x16x32_bf16 v[60:63], v[134:137], v[64:67], v[60:63]
	v_mfma_f32_16x16x32_bf16 v[56:59], v[172:175], v[64:67], v[56:59]
	v_mfma_f32_16x16x32_bf16 v[52:55], v[134:137], v[80:83], v[52:55]
	v_mfma_f32_16x16x32_bf16 v[48:51], v[172:175], v[80:83], v[48:51]
	v_mfma_f32_16x16x32_bf16 v[44:47], v[134:137], v[196:199], v[44:47]
	v_mfma_f32_16x16x32_bf16 v[40:43], v[172:175], v[196:199], v[40:43]
	v_mfma_f32_16x16x32_bf16 v[36:39], v[134:137], v[204:207], v[36:39]
	v_mfma_f32_16x16x32_bf16 v[32:35], v[172:175], v[204:207], v[32:35]
	v_mfma_f32_16x16x32_bf16 v[60:63], v[138:141], v[68:71], v[60:63]
	v_mfma_f32_16x16x32_bf16 v[56:59], v[176:179], v[68:71], v[56:59]
	v_mfma_f32_16x16x32_bf16 v[52:55], v[138:141], v[84:87], v[52:55]
	v_mfma_f32_16x16x32_bf16 v[48:51], v[176:179], v[84:87], v[48:51]
	v_mfma_f32_16x16x32_bf16 v[44:47], v[138:141], v[200:203], v[44:47]
	v_mfma_f32_16x16x32_bf16 v[40:43], v[176:179], v[200:203], v[40:43]
	v_mfma_f32_16x16x32_bf16 v[36:39], v[138:141], v[208:211], v[36:39]
	v_mfma_f32_16x16x32_bf16 v[32:35], v[176:179], v[208:211], v[32:35]
	v_mfma_f32_16x16x32_bf16 v[28:31], v[212:215], v[64:67], v[28:31]
	v_mfma_f32_16x16x32_bf16 v[24:27], v[220:223], v[64:67], v[24:27]
	v_mfma_f32_16x16x32_bf16 v[12:15], v[212:215], v[196:199], v[12:15]
	v_mfma_f32_16x16x32_bf16 v[8:11], v[220:223], v[196:199], v[8:11]
	v_mfma_f32_16x16x32_bf16 v[20:23], v[212:215], v[80:83], v[20:23]
	v_mfma_f32_16x16x32_bf16 v[16:19], v[220:223], v[80:83], v[16:19]
	v_mfma_f32_16x16x32_bf16 v[4:7], v[212:215], v[204:207], v[4:7]
	v_mfma_f32_16x16x32_bf16 v[0:3], v[220:223], v[204:207], v[0:3]
	v_mfma_f32_16x16x32_bf16 v[28:31], v[216:219], v[68:71], v[28:31]
	v_mfma_f32_16x16x32_bf16 v[24:27], v[158:161], v[68:71], v[24:27]
	v_mfma_f32_16x16x32_bf16 v[12:15], v[216:219], v[200:203], v[12:15]
	v_mfma_f32_16x16x32_bf16 v[8:11], v[158:161], v[200:203], v[8:11]
	v_mfma_f32_16x16x32_bf16 v[134:137], v[216:219], v[84:87], v[20:23]
	v_mfma_f32_16x16x32_bf16 v[138:141], v[158:161], v[84:87], v[16:19]
	v_mfma_f32_16x16x32_bf16 v[170:173], v[216:219], v[208:211], v[4:7]
	v_mfma_f32_16x16x32_bf16 v[158:161], v[158:161], v[208:211], v[0:3]
	s_barrier
	s_nop 0
	ds_read_b128 v[0:3], v156
	ds_read_b128 v[4:7], v156 offset:1024
	ds_read_b128 v[16:19], v156 offset:2048
	ds_read_b128 v[174:177], v156 offset:3072
	ds_read_b128 v[20:23], v152 offset:32768
	ds_read_b128 v[196:199], v152 offset:33792
	ds_read_b128 v[200:203], v151 offset:32768
	ds_read_b128 v[204:207], v151 offset:33792
	ds_read_b128 v[208:211], v150 offset:32768
	ds_read_b128 v[212:215], v150 offset:33792
	ds_read_b128 v[216:219], v149 offset:32768
	ds_read_b128 v[220:223], v149 offset:33792
	s_waitcnt vmcnt(2)
	s_barrier
; #define UNR _Pragma("unroll")
; #define LDA(dst, b, h) for (int m = 0; m < 4; ++m) for (int k = 0; k < 2; ++k) \
;     dst[m][k] = *reinterpret_cast<const bf16x8*>((char*)SA(b, h) + lds_byte(wr * 64 + m * 16 + fr, k * 32 + fq * 8))
; #define LDB(dst, b, h) for (int n = 0; n < 2; ++n) for (int k = 0; k < 2; ++k) \
;     dst[n][k] = *reinterpret_cast<const bf16x8*>((char*)SB(b, h) + lds_byte(wc * 32 + n * 16 + fr, k * 32 + fq * 8))
; #define MMA(ai, bj, At_, Bt_) do { __builtin_amdgcn_s_setprio(1); \
;     for (int k = 0; k < 2; ++k) for (int m = 0; m < 4; ++m) for (int n = 0; n < 2; ++n) \
;       acc[ai][bj][m][n] = __builtin_amdgcn_mfma_f32_16x16x32_bf16(At_[m][k], Bt_[n][k], acc[ai][bj][m][n], 0, 0, 0); \
;     __builtin_amdgcn_s_setprio(0); } while (0)
; #define WAIT_V(n) asm volatile("s_waitcnt vmcnt(" #n ")" ::: "memory")
; #define WAIT_L(n) asm volatile("s_waitcnt lgkmcnt(" #n ")" ::: "memory")
; #define BAR __builtin_amdgcn_s_barrier()
; #define STAGE4(BROW, BCOL, PN) do { const u16* Ab_ = A + (EPI == EPI_RG ? ((PN) >> 1) * 256 : 0); \
;     STAGE(SB(0, 0), Bt, ldb, (BCOL), 0); STAGE(SA(0, 0), Ab_, lda, (BROW), 0); \
;     STAGE(SB(0, 1), Bt, ldb, (BCOL) + HALF, 0); STAGE(SA(0, 1), Ab_, lda, (BROW) + HALF, 0); } while (0)
; template <int EPI, int lda, int ldb, int N, int K>
; __device__ __forceinline__ void gemm_phase(const u16* __restrict__ A, const u16* __restrict__ Bt, const GemmEpi ep, int wv) {
;     ...
;     { LDB(B0, 1, 0); LDA(At, 1, 0); WAIT_V(2); BAR; WAIT_L(0); MMA(0, 0, At, B0); BAR;
;       LDB(B1, 1, 1); WAIT_V(0); BAR; WAIT_L(0); MMA(0, 1, At, B1); BAR;
;       LDA(At, 1, 1); BAR; WAIT_L(0); MMA(1, 0, At, B0); MMA(1, 1, At, B1); BAR; }
;     if (wr == 0) BAR;
;     int ntile = 0, nbrow = 0, nbcol = 0, npn = 0; bool more = false;
;     if constexpr (PF) { ntile = tile + gridDim.x; more = ntile < nwg; if (more) { TILE_COORDS(ntile, nbrow, nbcol, npn); STAGE4(nbrow, nbcol, npn); } }
;     float nss[8];
;     if constexpr (CONS) { UNR for (int pp = 0; pp < 8; ++pp) nss[pp] = 0.f;
;       if (more && tidx < 256) { UNR for (int pp = 0; pp < 8; ++pp) nss[pp] = ep.ss_in[(size_t)pp * T + nbrow + tidx]; } }
	s_waitcnt lgkmcnt(0)
	s_waitcnt lgkmcnt(0)
	v_mfma_f32_16x16x32_bf16 v[64:67], v[0:3], v[20:23], v[124:127]
	v_mfma_f32_16x16x32_bf16 v[68:71], v[16:19], v[20:23], v[120:123]
	v_mfma_f32_16x16x32_bf16 v[80:83], v[0:3], v[200:203], v[116:119]
	v_mfma_f32_16x16x32_bf16 v[84:87], v[16:19], v[200:203], v[112:115]
	v_mfma_f32_16x16x32_bf16 v[108:111], v[0:3], v[208:211], v[108:111]
	v_mfma_f32_16x16x32_bf16 v[104:107], v[16:19], v[208:211], v[104:107]
	v_mfma_f32_16x16x32_bf16 v[120:123], v[0:3], v[216:219], v[100:103]
	v_mfma_f32_16x16x32_bf16 v[124:127], v[16:19], v[216:219], v[96:99]
	v_mfma_f32_16x16x32_bf16 v[116:119], v[4:7], v[196:199], v[64:67]
	v_mfma_f32_16x16x32_bf16 v[112:115], v[174:177], v[196:199], v[68:71]
	v_mfma_f32_16x16x32_bf16 v[100:103], v[4:7], v[204:207], v[80:83]
	v_mfma_f32_16x16x32_bf16 v[96:99], v[174:177], v[204:207], v[84:87]
	v_mfma_f32_16x16x32_bf16 v[84:87], v[4:7], v[212:215], v[108:111]
	v_mfma_f32_16x16x32_bf16 v[80:83], v[174:177], v[212:215], v[104:107]
	v_mfma_f32_16x16x32_bf16 v[68:71], v[4:7], v[220:223], v[120:123]
	v_mfma_f32_16x16x32_bf16 v[64:67], v[174:177], v[220:223], v[124:127]
	s_barrier
	ds_read_b128 v[224:227], v154
	ds_read_b128 v[228:231], v154 offset:1024
	ds_read_b128 v[232:235], v154 offset:2048
	ds_read_b128 v[154:157], v154 offset:3072
	s_waitcnt vmcnt(0)
	s_barrier
	s_waitcnt lgkmcnt(0)
	s_waitcnt lgkmcnt(0)
	v_mfma_f32_16x16x32_bf16 v[92:95], v[224:227], v[20:23], v[92:95]
	v_mfma_f32_16x16x32_bf16 v[20:23], v[232:235], v[20:23], v[88:91]
	v_mfma_f32_16x16x32_bf16 v[88:91], v[224:227], v[200:203], v[180:183]
	v_mfma_f32_16x16x32_bf16 v[104:107], v[232:235], v[200:203], v[184:187]
	v_mfma_f32_16x16x32_bf16 v[76:79], v[224:227], v[208:211], v[76:79]
	v_mfma_f32_16x16x32_bf16 v[72:75], v[232:235], v[208:211], v[72:75]
	v_mfma_f32_16x16x32_bf16 v[178:181], v[224:227], v[216:219], v[188:191]
	v_mfma_f32_16x16x32_bf16 v[182:185], v[232:235], v[216:219], v[192:195]
	v_mfma_f32_16x16x32_bf16 v[124:127], v[228:231], v[196:199], v[92:95]
	v_mfma_f32_16x16x32_bf16 v[120:123], v[154:157], v[196:199], v[20:23]
	v_mfma_f32_16x16x32_bf16 v[108:111], v[228:231], v[204:207], v[88:91]
	v_mfma_f32_16x16x32_bf16 v[104:107], v[154:157], v[204:207], v[104:107]
	v_mfma_f32_16x16x32_bf16 v[92:95], v[228:231], v[212:215], v[76:79]
	v_mfma_f32_16x16x32_bf16 v[88:91], v[154:157], v[212:215], v[72:75]
	v_mfma_f32_16x16x32_bf16 v[76:79], v[228:231], v[220:223], v[178:181]
	v_mfma_f32_16x16x32_bf16 v[72:75], v[154:157], v[220:223], v[182:185]
	s_barrier
	ds_read_b128 v[178:181], v152 offset:49152
	ds_read_b128 v[182:185], v152 offset:50176
	ds_read_b128 v[186:189], v151 offset:49152
	ds_read_b128 v[190:193], v151 offset:50176
	ds_read_b128 v[194:197], v150 offset:49152
	ds_read_b128 v[150:153], v150 offset:50176
	ds_read_b128 v[198:201], v149 offset:49152
	ds_read_b128 v[202:205], v149 offset:50176
	s_barrier
	s_waitcnt lgkmcnt(0)
	s_waitcnt lgkmcnt(0)
	v_mfma_f32_16x16x32_bf16 v[20:23], v[0:3], v[178:181], v[60:63]
	v_mfma_f32_16x16x32_bf16 v[56:59], v[16:19], v[178:181], v[56:59]
	v_mfma_f32_16x16x32_bf16 v[60:63], v[0:3], v[186:189], v[52:55]
	v_mfma_f32_16x16x32_bf16 v[206:209], v[16:19], v[186:189], v[48:51]
	v_mfma_f32_16x16x32_bf16 v[44:47], v[0:3], v[194:197], v[44:47]
	v_mfma_f32_16x16x32_bf16 v[40:43], v[16:19], v[194:197], v[40:43]
	v_mfma_f32_16x16x32_bf16 v[0:3], v[0:3], v[198:201], v[36:39]
	v_mfma_f32_16x16x32_bf16 v[210:213], v[16:19], v[198:201], v[32:35]
	v_mfma_f32_16x16x32_bf16 v[52:55], v[4:7], v[182:185], v[20:23]
	v_mfma_f32_16x16x32_bf16 v[48:51], v[174:177], v[182:185], v[56:59]
	v_mfma_f32_16x16x32_bf16 v[36:39], v[4:7], v[190:193], v[60:63]
	v_mfma_f32_16x16x32_bf16 v[32:35], v[174:177], v[190:193], v[206:209]
	v_mfma_f32_16x16x32_bf16 v[20:23], v[4:7], v[150:153], v[44:47]
	v_mfma_f32_16x16x32_bf16 v[16:19], v[174:177], v[150:153], v[40:43]
	v_mfma_f32_16x16x32_bf16 v[4:7], v[4:7], v[202:205], v[0:3]
	v_mfma_f32_16x16x32_bf16 v[0:3], v[174:177], v[202:205], v[210:213]
	v_mfma_f32_16x16x32_bf16 v[28:31], v[224:227], v[178:181], v[28:31]
	v_mfma_f32_16x16x32_bf16 v[24:27], v[232:235], v[178:181], v[24:27]
	v_mfma_f32_16x16x32_bf16 v[40:43], v[224:227], v[186:189], v[134:137]
	v_mfma_f32_16x16x32_bf16 v[134:137], v[232:235], v[186:189], v[138:141]
	v_mfma_f32_16x16x32_bf16 v[12:15], v[224:227], v[194:197], v[12:15]
	v_mfma_f32_16x16x32_bf16 v[8:11], v[232:235], v[194:197], v[8:11]
	v_mfma_f32_16x16x32_bf16 v[138:141], v[224:227], v[198:201], v[170:173]
	v_mfma_f32_16x16x32_bf16 v[158:161], v[232:235], v[198:201], v[158:161]
	v_mfma_f32_16x16x32_bf16 v[60:63], v[228:231], v[182:185], v[28:31]
	v_mfma_f32_16x16x32_bf16 v[56:59], v[154:157], v[182:185], v[24:27]
	v_mfma_f32_16x16x32_bf16 v[44:47], v[228:231], v[190:193], v[40:43]
	v_mfma_f32_16x16x32_bf16 v[40:43], v[154:157], v[190:193], v[134:137]
	v_mfma_f32_16x16x32_bf16 v[28:31], v[228:231], v[150:153], v[12:15]
	v_mfma_f32_16x16x32_bf16 v[24:27], v[154:157], v[150:153], v[8:11]
	v_mfma_f32_16x16x32_bf16 v[12:15], v[228:231], v[202:205], v[138:141]
	v_mfma_f32_16x16x32_bf16 v[8:11], v[154:157], v[202:205], v[158:161]
	v_cmp_gt_u32_e32 vcc, s56, v130
	s_barrier
	s_and_saveexec_b64 s[42:43], vcc
	s_cbranch_execz .LBB0_56
	s_barrier

; #define STAGE(P, BASE, LD, br, kt) do { const char* _g = (const char*)((BASE) + (size_t)(br) * (LD) + (size_t)(kt) * 64); \
;     for (int _i = 0; _i < 2; ++_i) { int _b = tidx * 16 + _i * 8192; int _r, _c; stage_rc(_b, _r, _c); \
;       __builtin_amdgcn_global_load_lds((const unsigned*)(_g + (unsigned)((_r * (LD) + _c) * 2)), (unsigned*)((char*)(P) + _b), 16, 0, 0); } } while (0)
; #define LDA(dst, b, h) for (int m = 0; m < 4; ++m) for (int k = 0; k < 2; ++k) \
;     dst[m][k] = *reinterpret_cast<const bf16x8*>((char*)SA(b, h) + lds_byte(wr * 64 + m * 16 + fr, k * 32 + fq * 8))
; #define LDB(dst, b, h) for (int n = 0; n < 2; ++n) for (int k = 0; k < 2; ++k) \
;     dst[n][k] = *reinterpret_cast<const bf16x8*>((char*)SB(b, h) + lds_byte(wc * 32 + n * 16 + fr, k * 32 + fq * 8))
; #define MMA(ai, bj, At_, Bt_) do { __builtin_amdgcn_s_setprio(1); \
;     for (int k = 0; k < 2; ++k) for (int m = 0; m < 4; ++m) for (int n = 0; n < 2; ++n) \
;       acc[ai][bj][m][n] = __builtin_amdgcn_mfma_f32_16x16x32_bf16(At_[m][k], Bt_[n][k], acc[ai][bj][m][n], 0, 0, 0); \
;     __builtin_amdgcn_s_setprio(0); } while (0)
; #define WAIT_L(n) asm volatile("s_waitcnt lgkmcnt(" #n ")" ::: "memory")
; #define BAR __builtin_amdgcn_s_barrier()
; #define SCHED __builtin_amdgcn_sched_barrier(0)
; template <int EPI, int lda, int ldb, int N, int K>
; __device__ __forceinline__ void gemm_phase(const u16* __restrict__ A, const u16* __restrict__ Bt, const GemmEpi ep, int wv) {
;     ...
;       LDB(B0, 0, 0); SCHED; LDA(At, 0, 0); STAGE(SA(1, 1), Ab, lda, brow + HALF, t + 1);
;       WAIT_L(8); BAR; WAIT_L(0); MMA(0, 0, At, B0); BAR; SCHED;
;       LDB(B1, 0, 1); STAGE(SB(0, 0), Bt, ldb, bcol, t + 2);
;       BAR; WAIT_L(0); MMA(0, 1, At, B1); BAR;
;       LDA(At, 0, 1); STAGE(SA(0, 0), Ab, lda, brow, t + 2);
;       BAR; WAIT_L(0); MMA(1, 0, At, B0); BAR; SCHED;
.LBB0_224:
	ds_read_b128 v[168:171], v164
	ds_read_b128 v[174:177], v164 offset:1024
	ds_read_b128 v[178:181], v164 offset:2048
	ds_read_b128 v[182:185], v164 offset:3072
	v_add_u32_e32 v172, 0xc000, v147
	v_lshl_add_u64 v[238:239], v[136:137], 0, s[44:45]
	v_readfirstlane_b32 s66, v172
	v_add_u32_e32 v173, 0xe000, v147
	v_lshl_add_u64 v[166:167], v[238:239], 0, s[18:19]
	s_mov_b32 m0, s66
	v_lshl_add_u64 v[240:241], v[134:135], 0, s[44:45]
	v_readfirstlane_b32 s66, v173
	ds_read_b128 v[186:189], v155
	ds_read_b128 v[190:193], v155 offset:1024
	ds_read_b128 v[194:197], v154
	ds_read_b128 v[198:201], v154 offset:1024
	ds_read_b128 v[202:205], v153
	ds_read_b128 v[206:209], v153 offset:1024
	ds_read_b128 v[210:213], v152
	ds_read_b128 v[214:217], v152 offset:1024
	global_load_lds_dwordx4 v[166:167], off
	v_lshl_add_u64 v[166:167], v[240:241], 0, s[18:19]
	s_mov_b32 m0, s66
	s_nop 0
	global_load_lds_dwordx4 v[166:167], off
	s_waitcnt lgkmcnt(8)
	s_barrier
	s_waitcnt lgkmcnt(0)
	s_waitcnt lgkmcnt(0)
	v_mfma_f32_16x16x32_bf16 v[124:127], v[168:171], v[186:189], v[124:127]
	ds_read_b128 v[218:221], v163
	v_mfma_f32_16x16x32_bf16 v[120:123], v[178:181], v[186:189], v[120:123]
	v_mfma_f32_16x16x32_bf16 v[116:119], v[168:171], v[194:197], v[116:119]
	ds_read_b128 v[222:225], v163 offset:1024
	v_mfma_f32_16x16x32_bf16 v[112:115], v[178:181], v[194:197], v[112:115]
	v_mfma_f32_16x16x32_bf16 v[108:111], v[168:171], v[202:205], v[108:111]
	ds_read_b128 v[226:229], v163 offset:2048
	v_mfma_f32_16x16x32_bf16 v[104:107], v[178:181], v[202:205], v[104:107]
	v_mfma_f32_16x16x32_bf16 v[100:103], v[168:171], v[210:213], v[100:103]
	ds_read_b128 v[230:233], v163 offset:3072
	v_mfma_f32_16x16x32_bf16 v[96:99], v[178:181], v[210:213], v[96:99]
	v_mfma_f32_16x16x32_bf16 v[124:127], v[174:177], v[190:193], v[124:127]
	v_mfma_f32_16x16x32_bf16 v[120:123], v[182:185], v[190:193], v[120:123]
	v_mfma_f32_16x16x32_bf16 v[116:119], v[174:177], v[198:201], v[116:119]
	v_mfma_f32_16x16x32_bf16 v[112:115], v[182:185], v[198:201], v[112:115]
	v_mfma_f32_16x16x32_bf16 v[108:111], v[174:177], v[206:209], v[108:111]
	v_mfma_f32_16x16x32_bf16 v[104:107], v[182:185], v[206:209], v[104:107]
	v_mfma_f32_16x16x32_bf16 v[100:103], v[174:177], v[214:217], v[100:103]
	v_mfma_f32_16x16x32_bf16 v[96:99], v[182:185], v[214:217], v[96:99]
	s_barrier
	v_add_u32_e32 v165, s55, v156
	v_lshl_add_u64 v[242:243], v[144:145], 0, s[44:45]
	v_readfirstlane_b32 s66, v165
	v_lshl_add_u64 v[166:167], v[242:243], 0, s[20:21]
	s_mov_b32 m0, s66
	global_load_lds_dwordx4 v[166:167], off
	v_add_u32_e32 v166, 0x2000, v165
	v_lshl_add_u64 v[244:245], v[142:143], 0, s[44:45]
	v_readfirstlane_b32 s66, v166
	v_lshl_add_u64 v[234:235], v[244:245], 0, s[20:21]
	s_mov_b32 m0, s66
	s_nop 0
	global_load_lds_dwordx4 v[234:235], off
	s_barrier
	s_waitcnt lgkmcnt(0)
	s_waitcnt lgkmcnt(0)
	v_mfma_f32_16x16x32_bf16 v[92:95], v[218:221], v[186:189], v[92:95]
	v_mfma_f32_16x16x32_bf16 v[88:91], v[226:229], v[186:189], v[88:91]
	v_mfma_f32_16x16x32_bf16 v[84:87], v[218:221], v[194:197], v[84:87]
	v_mfma_f32_16x16x32_bf16 v[80:83], v[226:229], v[194:197], v[80:83]
	v_mfma_f32_16x16x32_bf16 v[76:79], v[218:221], v[202:205], v[76:79]
	v_mfma_f32_16x16x32_bf16 v[72:75], v[226:229], v[202:205], v[72:75]
	v_mfma_f32_16x16x32_bf16 v[68:71], v[218:221], v[210:213], v[68:71]
	v_mfma_f32_16x16x32_bf16 v[64:67], v[226:229], v[210:213], v[64:67]
	v_mfma_f32_16x16x32_bf16 v[92:95], v[222:225], v[190:193], v[92:95]
	v_mfma_f32_16x16x32_bf16 v[88:91], v[230:233], v[190:193], v[88:91]
	v_mfma_f32_16x16x32_bf16 v[84:87], v[222:225], v[198:201], v[84:87]
	v_mfma_f32_16x16x32_bf16 v[80:83], v[230:233], v[198:201], v[80:83]
	v_mfma_f32_16x16x32_bf16 v[76:79], v[222:225], v[206:209], v[76:79]
	v_mfma_f32_16x16x32_bf16 v[72:75], v[230:233], v[206:209], v[72:75]
	v_mfma_f32_16x16x32_bf16 v[68:71], v[222:225], v[214:217], v[68:71]
	v_mfma_f32_16x16x32_bf16 v[64:67], v[230:233], v[214:217], v[64:67]
	v_readfirstlane_b32 s66, v147
	v_add_u32_e32 v167, 0x2000, v147
	v_lshl_add_u64 v[234:235], v[238:239], 0, s[22:23]
	s_mov_b32 m0, s66
	v_readfirstlane_b32 s66, v167
	s_barrier
	ds_read_b128 v[186:189], v155 offset:16384
	ds_read_b128 v[190:193], v155 offset:17408
	ds_read_b128 v[194:197], v154 offset:16384
	ds_read_b128 v[198:201], v154 offset:17408
	ds_read_b128 v[202:205], v153 offset:16384
	ds_read_b128 v[206:209], v153 offset:17408
	ds_read_b128 v[210:213], v152 offset:16384
	ds_read_b128 v[214:217], v152 offset:17408
	global_load_lds_dwordx4 v[234:235], off
	v_lshl_add_u64 v[234:235], v[240:241], 0, s[22:23]
	s_mov_b32 m0, s66
	s_nop 0
	global_load_lds_dwordx4 v[234:235], off
	s_barrier
	s_waitcnt lgkmcnt(0)
	s_waitcnt lgkmcnt(0)
	v_mfma_f32_16x16x32_bf16 v[60:63], v[168:171], v[186:189], v[60:63]
	v_mfma_f32_16x16x32_bf16 v[56:59], v[178:181], v[186:189], v[56:59]
	v_mfma_f32_16x16x32_bf16 v[52:55], v[168:171], v[194:197], v[52:55]
	v_mfma_f32_16x16x32_bf16 v[48:51], v[178:181], v[194:197], v[48:51]
	v_mfma_f32_16x16x32_bf16 v[44:47], v[168:171], v[202:205], v[44:47]
	v_mfma_f32_16x16x32_bf16 v[40:43], v[178:181], v[202:205], v[40:43]
	v_mfma_f32_16x16x32_bf16 v[36:39], v[168:171], v[210:213], v[36:39]
	v_mfma_f32_16x16x32_bf16 v[32:35], v[178:181], v[210:213], v[32:35]
	v_mfma_f32_16x16x32_bf16 v[60:63], v[174:177], v[190:193], v[60:63]
	v_mfma_f32_16x16x32_bf16 v[56:59], v[182:185], v[190:193], v[56:59]
	v_mfma_f32_16x16x32_bf16 v[52:55], v[174:177], v[198:201], v[52:55]
	v_mfma_f32_16x16x32_bf16 v[48:51], v[182:185], v[198:201], v[48:51]
	v_mfma_f32_16x16x32_bf16 v[44:47], v[174:177], v[206:209], v[44:47]
	v_mfma_f32_16x16x32_bf16 v[40:43], v[182:185], v[206:209], v[40:43]
	v_mfma_f32_16x16x32_bf16 v[36:39], v[174:177], v[214:217], v[36:39]
	v_mfma_f32_16x16x32_bf16 v[32:35], v[182:185], v[214:217], v[32:35]
	s_barrier
; #define STAGE(P, BASE, LD, br, kt) do { const char* _g = (const char*)((BASE) + (size_t)(br) * (LD) + (size_t)(kt) * 64); \
;     for (int _i = 0; _i < 2; ++_i) { int _b = tidx * 16 + _i * 8192; int _r, _c; stage_rc(_b, _r, _c); \
;       __builtin_amdgcn_global_load_lds((const unsigned*)(_g + (unsigned)((_r * (LD) + _c) * 2)), (unsigned*)((char*)(P) + _b), 16, 0, 0); } } while (0)
; #define LDA(dst, b, h) for (int m = 0; m < 4; ++m) for (int k = 0; k < 2; ++k) \
;     dst[m][k] = *reinterpret_cast<const bf16x8*>((char*)SA(b, h) + lds_byte(wr * 64 + m * 16 + fr, k * 32 + fq * 8))
; #define LDB(dst, b, h) for (int n = 0; n < 2; ++n) for (int k = 0; k < 2; ++k) \
;     dst[n][k] = *reinterpret_cast<const bf16x8*>((char*)SB(b, h) + lds_byte(wc * 32 + n * 16 + fr, k * 32 + fq * 8))
; #define MMA(ai, bj, At_, Bt_) do { __builtin_amdgcn_s_setprio(1); \
;     for (int k = 0; k < 2; ++k) for (int m = 0; m < 4; ++m) for (int n = 0; n < 2; ++n) \
;       acc[ai][bj][m][n] = __builtin_amdgcn_mfma_f32_16x16x32_bf16(At_[m][k], Bt_[n][k], acc[ai][bj][m][n], 0, 0, 0); \
;     __builtin_amdgcn_s_setprio(0); } while (0)
; #define WAIT_V(n) asm volatile("s_waitcnt vmcnt(" #n ")" ::: "memory")
; #define WAIT_L(n) asm volatile("s_waitcnt lgkmcnt(" #n ")" ::: "memory")
; #define BAR __builtin_amdgcn_s_barrier()
; #define SCHED __builtin_amdgcn_sched_barrier(0)
; template <int EPI, int lda, int ldb, int N, int K>
; __device__ __forceinline__ void gemm_phase(const u16* __restrict__ A, const u16* __restrict__ Bt, const GemmEpi ep, int wv) {
;     ...
;       STAGE(SB(0, 1), Bt, ldb, bcol + HALF, t + 2);
;       WAIT_V(6); BAR; MMA(1, 1, At, B1); BAR;
;       LDB(B0, 1, 0); SCHED; LDA(At, 1, 0); STAGE(SA(0, 1), Ab, lda, brow + HALF, t + 2);
;       WAIT_L(8); BAR; WAIT_L(0); MMA(0, 0, At, B0); BAR; SCHED;
;       LDB(B1, 1, 1); STAGE(SB(1, 0), Bt, ldb, bcol, t + 3);
;       BAR; WAIT_L(0); MMA(0, 1, At, B1); BAR;
	v_add_u32_e32 v168, s56, v156
	v_lshl_add_u64 v[246:247], v[140:141], 0, s[44:45]
	v_readfirstlane_b32 s66, v168
	v_add_u32_e32 v169, 0x2000, v168
	v_lshl_add_u64 v[170:171], v[246:247], 0, s[24:25]
	s_mov_b32 m0, s66
	v_lshl_add_u64 v[248:249], v[138:139], 0, s[44:45]
	v_readfirstlane_b32 s66, v169
	global_load_lds_dwordx4 v[170:171], off
	v_lshl_add_u64 v[170:171], v[248:249], 0, s[24:25]
	s_mov_b32 m0, s66
	s_nop 0
	global_load_lds_dwordx4 v[170:171], off
	s_waitcnt vmcnt(6)
	s_barrier
	v_mfma_f32_16x16x32_bf16 v[28:31], v[218:221], v[186:189], v[28:31]
	v_mfma_f32_16x16x32_bf16 v[24:27], v[226:229], v[186:189], v[24:27]
	ds_read_b128 v[174:177], v159
	v_mfma_f32_16x16x32_bf16 v[20:23], v[218:221], v[194:197], v[20:23]
	v_mfma_f32_16x16x32_bf16 v[16:19], v[226:229], v[194:197], v[16:19]
	ds_read_b128 v[178:181], v159 offset:1024
	v_mfma_f32_16x16x32_bf16 v[12:15], v[218:221], v[202:205], v[12:15]
	v_mfma_f32_16x16x32_bf16 v[8:11], v[226:229], v[202:205], v[8:11]
	ds_read_b128 v[182:185], v159 offset:2048
	v_mfma_f32_16x16x32_bf16 v[4:7], v[218:221], v[210:213], v[4:7]
	v_mfma_f32_16x16x32_bf16 v[0:3], v[226:229], v[210:213], v[0:3]
	ds_read_b128 v[186:189], v159 offset:3072
	v_mfma_f32_16x16x32_bf16 v[28:31], v[222:225], v[190:193], v[28:31]
	v_mfma_f32_16x16x32_bf16 v[24:27], v[230:233], v[190:193], v[24:27]
	v_mfma_f32_16x16x32_bf16 v[20:23], v[222:225], v[198:201], v[20:23]
	v_mfma_f32_16x16x32_bf16 v[16:19], v[230:233], v[198:201], v[16:19]
	v_mfma_f32_16x16x32_bf16 v[12:15], v[222:225], v[206:209], v[12:15]
	v_mfma_f32_16x16x32_bf16 v[8:11], v[230:233], v[206:209], v[8:11]
	v_mfma_f32_16x16x32_bf16 v[4:7], v[222:225], v[214:217], v[4:7]
	v_mfma_f32_16x16x32_bf16 v[0:3], v[230:233], v[214:217], v[0:3]
	s_barrier
	v_add_u32_e32 v170, 0x4000, v147
	v_add_u32_e32 v171, 0x6000, v147
	v_readfirstlane_b32 s66, v170
	v_lshl_add_u64 v[222:223], v[238:239], 0, s[26:27]
	s_mov_b32 m0, s66
	v_readfirstlane_b32 s66, v171
	ds_read_b128 v[190:193], v155 offset:32768
	ds_read_b128 v[194:197], v155 offset:33792
	ds_read_b128 v[198:201], v154 offset:32768
	ds_read_b128 v[202:205], v154 offset:33792
	ds_read_b128 v[206:209], v153 offset:32768
	ds_read_b128 v[210:213], v153 offset:33792
	ds_read_b128 v[214:217], v152 offset:32768
	ds_read_b128 v[218:221], v152 offset:33792
	global_load_lds_dwordx4 v[222:223], off
	v_lshl_add_u64 v[222:223], v[240:241], 0, s[26:27]
	s_mov_b32 m0, s66
	s_nop 0
	global_load_lds_dwordx4 v[222:223], off
	s_waitcnt lgkmcnt(8)
	s_barrier
	s_waitcnt lgkmcnt(0)
	s_waitcnt lgkmcnt(0)
	v_mfma_f32_16x16x32_bf16 v[124:127], v[174:177], v[190:193], v[124:127]
	ds_read_b128 v[222:225], v157
	v_mfma_f32_16x16x32_bf16 v[120:123], v[182:185], v[190:193], v[120:123]
	v_mfma_f32_16x16x32_bf16 v[116:119], v[174:177], v[198:201], v[116:119]
	ds_read_b128 v[226:229], v157 offset:1024
	v_mfma_f32_16x16x32_bf16 v[112:115], v[182:185], v[198:201], v[112:115]
	v_mfma_f32_16x16x32_bf16 v[108:111], v[174:177], v[206:209], v[108:111]
	ds_read_b128 v[230:233], v157 offset:2048
	v_mfma_f32_16x16x32_bf16 v[104:107], v[182:185], v[206:209], v[104:107]
	v_mfma_f32_16x16x32_bf16 v[100:103], v[174:177], v[214:217], v[100:103]
	ds_read_b128 v[234:237], v157 offset:3072
	v_mfma_f32_16x16x32_bf16 v[96:99], v[182:185], v[214:217], v[96:99]
	v_mfma_f32_16x16x32_bf16 v[124:127], v[178:181], v[194:197], v[124:127]
	v_mfma_f32_16x16x32_bf16 v[120:123], v[186:189], v[194:197], v[120:123]
	v_mfma_f32_16x16x32_bf16 v[116:119], v[178:181], v[202:205], v[116:119]
	v_mfma_f32_16x16x32_bf16 v[112:115], v[186:189], v[202:205], v[112:115]
	v_mfma_f32_16x16x32_bf16 v[108:111], v[178:181], v[210:213], v[108:111]
	v_mfma_f32_16x16x32_bf16 v[104:107], v[186:189], v[210:213], v[104:107]
	v_mfma_f32_16x16x32_bf16 v[100:103], v[178:181], v[218:221], v[100:103]
	v_mfma_f32_16x16x32_bf16 v[96:99], v[186:189], v[218:221], v[96:99]
	s_barrier
	v_readfirstlane_b32 s66, v158
	v_lshl_add_u64 v[242:243], v[242:243], 0, s[36:37]
	s_mov_b32 m0, s66
	global_load_lds_dwordx4 v[242:243], off
	v_lshl_add_u64 v[242:243], v[244:245], 0, s[36:37]
	v_add_u32_e32 v244, 0x2000, v158
	s_nop 0
	v_readfirstlane_b32 s66, v244
	s_mov_b32 m0, s66
	s_nop 0
	global_load_lds_dwordx4 v[242:243], off
	s_barrier
	s_waitcnt lgkmcnt(0)
	s_waitcnt lgkmcnt(0)
	v_mfma_f32_16x16x32_bf16 v[92:95], v[222:225], v[190:193], v[92:95]
	v_mfma_f32_16x16x32_bf16 v[88:91], v[230:233], v[190:193], v[88:91]
	v_mfma_f32_16x16x32_bf16 v[84:87], v[222:225], v[198:201], v[84:87]
	v_mfma_f32_16x16x32_bf16 v[80:83], v[230:233], v[198:201], v[80:83]
	v_mfma_f32_16x16x32_bf16 v[76:79], v[222:225], v[206:209], v[76:79]
	v_mfma_f32_16x16x32_bf16 v[72:75], v[230:233], v[206:209], v[72:75]
	v_mfma_f32_16x16x32_bf16 v[68:71], v[222:225], v[214:217], v[68:71]
	v_mfma_f32_16x16x32_bf16 v[64:67], v[230:233], v[214:217], v[64:67]
	v_mfma_f32_16x16x32_bf16 v[92:95], v[226:229], v[194:197], v[92:95]
	v_mfma_f32_16x16x32_bf16 v[88:91], v[234:237], v[194:197], v[88:91]
	v_mfma_f32_16x16x32_bf16 v[84:87], v[226:229], v[202:205], v[84:87]
	v_mfma_f32_16x16x32_bf16 v[80:83], v[234:237], v[202:205], v[80:83]
	v_mfma_f32_16x16x32_bf16 v[76:79], v[226:229], v[210:213], v[76:79]
	v_mfma_f32_16x16x32_bf16 v[72:75], v[234:237], v[210:213], v[72:75]
	v_mfma_f32_16x16x32_bf16 v[68:71], v[226:229], v[218:221], v[68:71]
	v_mfma_f32_16x16x32_bf16 v[64:67], v[234:237], v[218:221], v[64:67]
	v_readfirstlane_b32 s66, v160
	v_lshl_add_u64 v[238:239], v[238:239], 0, s[38:39]
	s_mov_b32 m0, s66
	v_readfirstlane_b32 s66, v161
	s_barrier
; #define STAGE(P, BASE, LD, br, kt) do { const char* _g = (const char*)((BASE) + (size_t)(br) * (LD) + (size_t)(kt) * 64); \
;     for (int _i = 0; _i < 2; ++_i) { int _b = tidx * 16 + _i * 8192; int _r, _c; stage_rc(_b, _r, _c); \
;       __builtin_amdgcn_global_load_lds((const unsigned*)(_g + (unsigned)((_r * (LD) + _c) * 2)), (unsigned*)((char*)(P) + _b), 16, 0, 0); } } while (0)
; #define LDA(dst, b, h) for (int m = 0; m < 4; ++m) for (int k = 0; k < 2; ++k) \
;     dst[m][k] = *reinterpret_cast<const bf16x8*>((char*)SA(b, h) + lds_byte(wr * 64 + m * 16 + fr, k * 32 + fq * 8))
; #define LDB(dst, b, h) for (int n = 0; n < 2; ++n) for (int k = 0; k < 2; ++k) \
;     dst[n][k] = *reinterpret_cast<const bf16x8*>((char*)SB(b, h) + lds_byte(wc * 32 + n * 16 + fr, k * 32 + fq * 8))
; #define MMA(ai, bj, At_, Bt_) do { __builtin_amdgcn_s_setprio(1); \
;     for (int k = 0; k < 2; ++k) for (int m = 0; m < 4; ++m) for (int n = 0; n < 2; ++n) \
;       acc[ai][bj][m][n] = __builtin_amdgcn_mfma_f32_16x16x32_bf16(At_[m][k], Bt_[n][k], acc[ai][bj][m][n], 0, 0, 0); \
;     __builtin_amdgcn_s_setprio(0); } while (0)
; #define WAIT_V(n) asm volatile("s_waitcnt vmcnt(" #n ")" ::: "memory")
; #define WAIT_L(n) asm volatile("s_waitcnt lgkmcnt(" #n ")" ::: "memory")
; #define BAR __builtin_amdgcn_s_barrier()
; #define SCHED __builtin_amdgcn_sched_barrier(0)
; template <int EPI, int lda, int ldb, int N, int K>
; __device__ __forceinline__ void gemm_phase(const u16* __restrict__ A, const u16* __restrict__ Bt, const GemmEpi ep, int wv) {
;     ...
;       LDA(At, 1, 1); STAGE(SA(1, 0), Ab, lda, brow, t + 3);
;       BAR; WAIT_L(0); MMA(1, 0, At, B0); BAR; SCHED;
;       STAGE(SB(1, 1), Bt, ldb, bcol + HALF, t + 3);
;       WAIT_V(6); BAR; MMA(1, 1, At, B1); BAR;
;     }
;     { LDB(B0, 0, 0); LDA(At, 0, 0); STAGE(SA(1, 1), Ab, lda, brow + HALF, nt - 1);
;       BAR; WAIT_L(0); MMA(0, 0, At, B0); BAR;
;       LDB(B1, 0, 1); BAR; WAIT_L(0); MMA(0, 1, At, B1); BAR;
	ds_read_b128 v[190:193], v155 offset:49152
	ds_read_b128 v[194:197], v155 offset:50176
	ds_read_b128 v[198:201], v154 offset:49152
	ds_read_b128 v[202:205], v154 offset:50176
	ds_read_b128 v[206:209], v153 offset:49152
	ds_read_b128 v[210:213], v153 offset:50176
	ds_read_b128 v[214:217], v152 offset:49152
	ds_read_b128 v[218:221], v152 offset:50176
	global_load_lds_dwordx4 v[238:239], off
	v_lshl_add_u64 v[238:239], v[240:241], 0, s[38:39]
	s_mov_b32 m0, s66
	s_nop 0
	global_load_lds_dwordx4 v[238:239], off
	s_barrier
	s_waitcnt lgkmcnt(0)
	s_waitcnt lgkmcnt(0)
	v_mfma_f32_16x16x32_bf16 v[60:63], v[174:177], v[190:193], v[60:63]
	v_mfma_f32_16x16x32_bf16 v[56:59], v[182:185], v[190:193], v[56:59]
	v_mfma_f32_16x16x32_bf16 v[52:55], v[174:177], v[198:201], v[52:55]
	v_mfma_f32_16x16x32_bf16 v[48:51], v[182:185], v[198:201], v[48:51]
	v_mfma_f32_16x16x32_bf16 v[44:47], v[174:177], v[206:209], v[44:47]
	v_mfma_f32_16x16x32_bf16 v[40:43], v[182:185], v[206:209], v[40:43]
	v_mfma_f32_16x16x32_bf16 v[36:39], v[174:177], v[214:217], v[36:39]
	v_mfma_f32_16x16x32_bf16 v[32:35], v[182:185], v[214:217], v[32:35]
	v_mfma_f32_16x16x32_bf16 v[60:63], v[178:181], v[194:197], v[60:63]
	v_mfma_f32_16x16x32_bf16 v[56:59], v[186:189], v[194:197], v[56:59]
	v_mfma_f32_16x16x32_bf16 v[52:55], v[178:181], v[202:205], v[52:55]
	v_mfma_f32_16x16x32_bf16 v[48:51], v[186:189], v[202:205], v[48:51]
	v_mfma_f32_16x16x32_bf16 v[44:47], v[178:181], v[210:213], v[44:47]
	v_mfma_f32_16x16x32_bf16 v[40:43], v[186:189], v[210:213], v[40:43]
	v_mfma_f32_16x16x32_bf16 v[36:39], v[178:181], v[218:221], v[36:39]
	v_mfma_f32_16x16x32_bf16 v[32:35], v[186:189], v[218:221], v[32:35]
	s_barrier
	v_readfirstlane_b32 s66, v162
	v_add_u32_e32 v176, 0x2000, v162
	v_lshl_add_u64 v[174:175], v[246:247], 0, s[42:43]
	s_mov_b32 m0, s66
	v_readfirstlane_b32 s66, v176
	global_load_lds_dwordx4 v[174:175], off
	v_lshl_add_u64 v[174:175], v[248:249], 0, s[42:43]
	s_mov_b32 m0, s66
	s_nop 0
	global_load_lds_dwordx4 v[174:175], off
	s_waitcnt vmcnt(6)
	s_barrier
	v_mfma_f32_16x16x32_bf16 v[28:31], v[222:225], v[190:193], v[28:31]
	v_mfma_f32_16x16x32_bf16 v[24:27], v[230:233], v[190:193], v[24:27]
	v_mfma_f32_16x16x32_bf16 v[20:23], v[222:225], v[198:201], v[20:23]
	v_mfma_f32_16x16x32_bf16 v[16:19], v[230:233], v[198:201], v[16:19]
	v_mfma_f32_16x16x32_bf16 v[12:15], v[222:225], v[206:209], v[12:15]
	v_mfma_f32_16x16x32_bf16 v[8:11], v[230:233], v[206:209], v[8:11]
	v_mfma_f32_16x16x32_bf16 v[4:7], v[222:225], v[214:217], v[4:7]
	v_mfma_f32_16x16x32_bf16 v[0:3], v[230:233], v[214:217], v[0:3]
	v_mfma_f32_16x16x32_bf16 v[28:31], v[226:229], v[194:197], v[28:31]
	v_mfma_f32_16x16x32_bf16 v[24:27], v[234:237], v[194:197], v[24:27]
	v_mfma_f32_16x16x32_bf16 v[20:23], v[226:229], v[202:205], v[20:23]
	v_mfma_f32_16x16x32_bf16 v[16:19], v[234:237], v[202:205], v[16:19]
	v_mfma_f32_16x16x32_bf16 v[12:15], v[226:229], v[210:213], v[12:15]
	v_mfma_f32_16x16x32_bf16 v[8:11], v[234:237], v[210:213], v[8:11]
	v_mfma_f32_16x16x32_bf16 v[4:7], v[226:229], v[218:221], v[4:7]
	v_mfma_f32_16x16x32_bf16 v[0:3], v[234:237], v[218:221], v[0:3]
	s_add_i32 s65, s65, 2
	s_add_u32 s44, s44, 0x100
	s_addc_u32 s45, s45, 0
	s_cmpk_gt_u32 s65, 0x51
	s_barrier
	s_cbranch_scc0 .LBB0_224
	s_add_i32 s44, s14, 0x80
	s_mul_hi_i32 s45, s44, 0x2b00
	s_mulk_i32 s44, 0x2b00
	s_add_u32 s44, s48, s44
	s_addc_u32 s45, s49, s45
	s_add_u32 s44, s44, 0x2a80
	s_addc_u32 s45, s45, 0
	v_readfirstlane_b32 s65, v172
	v_lshl_add_u64 v[160:161], s[44:45], 0, v[128:129]
	s_mov_b32 m0, s65
	ds_read_b128 v[134:137], v164
	ds_read_b128 v[138:141], v164 offset:1024
	ds_read_b128 v[142:145], v164 offset:2048
	ds_read_b128 v[174:177], v164 offset:3072
	ds_read_b128 v[178:181], v155
	ds_read_b128 v[182:185], v155 offset:1024
	ds_read_b128 v[186:189], v154
	ds_read_b128 v[190:193], v154 offset:1024
	ds_read_b128 v[194:197], v153
	ds_read_b128 v[198:201], v153 offset:1024
	ds_read_b128 v[202:205], v152
	ds_read_b128 v[206:209], v152 offset:1024
	global_load_lds_dwordx4 v[160:161], off
	v_lshl_add_u64 v[160:161], s[44:45], 0, v[132:133]
	v_readfirstlane_b32 s44, v173
	s_mov_b32 m0, s44
	s_nop 0
	global_load_lds_dwordx4 v[160:161], off
	s_barrier
	s_waitcnt lgkmcnt(0)
	s_waitcnt lgkmcnt(0)
	v_mfma_f32_16x16x32_bf16 v[124:127], v[134:137], v[178:181], v[124:127]
	v_mfma_f32_16x16x32_bf16 v[120:123], v[142:145], v[178:181], v[120:123]
	v_mfma_f32_16x16x32_bf16 v[116:119], v[134:137], v[186:189], v[116:119]
	v_mfma_f32_16x16x32_bf16 v[112:115], v[142:145], v[186:189], v[112:115]
	v_mfma_f32_16x16x32_bf16 v[108:111], v[134:137], v[194:197], v[108:111]
	v_mfma_f32_16x16x32_bf16 v[104:107], v[142:145], v[194:197], v[104:107]
	v_mfma_f32_16x16x32_bf16 v[100:103], v[134:137], v[202:205], v[100:103]
	v_mfma_f32_16x16x32_bf16 v[96:99], v[142:145], v[202:205], v[96:99]
	v_mfma_f32_16x16x32_bf16 v[124:127], v[138:141], v[182:185], v[124:127]
	v_mfma_f32_16x16x32_bf16 v[120:123], v[174:177], v[182:185], v[120:123]
	v_mfma_f32_16x16x32_bf16 v[116:119], v[138:141], v[190:193], v[116:119]
	v_mfma_f32_16x16x32_bf16 v[112:115], v[174:177], v[190:193], v[112:115]
	v_mfma_f32_16x16x32_bf16 v[108:111], v[138:141], v[198:201], v[108:111]
	v_mfma_f32_16x16x32_bf16 v[104:107], v[174:177], v[198:201], v[104:107]
	v_mfma_f32_16x16x32_bf16 v[100:103], v[138:141], v[206:209], v[100:103]
	v_mfma_f32_16x16x32_bf16 v[96:99], v[174:177], v[206:209], v[96:99]
	s_barrier
	ds_read_b128 v[210:213], v163
	ds_read_b128 v[214:217], v163 offset:1024
	ds_read_b128 v[218:221], v163 offset:2048
	ds_read_b128 v[160:163], v163 offset:3072
	s_barrier
; #define LDA(dst, b, h) for (int m = 0; m < 4; ++m) for (int k = 0; k < 2; ++k) \
;     dst[m][k] = *reinterpret_cast<const bf16x8*>((char*)SA(b, h) + lds_byte(wr * 64 + m * 16 + fr, k * 32 + fq * 8))
; #define LDB(dst, b, h) for (int n = 0; n < 2; ++n) for (int k = 0; k < 2; ++k) \
;     dst[n][k] = *reinterpret_cast<const bf16x8*>((char*)SB(b, h) + lds_byte(wc * 32 + n * 16 + fr, k * 32 + fq * 8))
; #define MMA(ai, bj, At_, Bt_) do { __builtin_amdgcn_s_setprio(1); \
;     for (int k = 0; k < 2; ++k) for (int m = 0; m < 4; ++m) for (int n = 0; n < 2; ++n) \
;       acc[ai][bj][m][n] = __builtin_amdgcn_mfma_f32_16x16x32_bf16(At_[m][k], Bt_[n][k], acc[ai][bj][m][n], 0, 0, 0); \
;     __builtin_amdgcn_s_setprio(0); } while (0)
; #define WAIT_V(n) asm volatile("s_waitcnt vmcnt(" #n ")" ::: "memory")
; #define WAIT_L(n) asm volatile("s_waitcnt lgkmcnt(" #n ")" ::: "memory")
; #define BAR __builtin_amdgcn_s_barrier()
; template <int EPI, int lda, int ldb, int N, int K>
; __device__ __forceinline__ void gemm_phase(const u16* __restrict__ A, const u16* __restrict__ Bt, const GemmEpi ep, int wv) {
;     ...
;       LDB(B1, 0, 1); BAR; WAIT_L(0); MMA(0, 1, At, B1); BAR;
;       LDA(At, 0, 1); WAIT_V(4); BAR; WAIT_L(0); MMA(1, 0, At, B0); MMA(1, 1, At, B1); BAR; }
;     { LDB(B0, 1, 0); LDA(At, 1, 0); WAIT_V(2); BAR; WAIT_L(0); MMA(0, 0, At, B0); BAR;
	s_waitcnt lgkmcnt(0)
	s_waitcnt lgkmcnt(0)
	v_mfma_f32_16x16x32_bf16 v[92:95], v[210:213], v[178:181], v[92:95]
	v_mfma_f32_16x16x32_bf16 v[88:91], v[218:221], v[178:181], v[88:91]
	v_mfma_f32_16x16x32_bf16 v[76:79], v[210:213], v[194:197], v[76:79]
	v_mfma_f32_16x16x32_bf16 v[72:75], v[218:221], v[194:197], v[72:75]
	v_mfma_f32_16x16x32_bf16 v[84:87], v[210:213], v[186:189], v[84:87]
	v_mfma_f32_16x16x32_bf16 v[80:83], v[218:221], v[186:189], v[80:83]
	v_mfma_f32_16x16x32_bf16 v[68:71], v[210:213], v[202:205], v[68:71]
	v_mfma_f32_16x16x32_bf16 v[64:67], v[218:221], v[202:205], v[64:67]
	v_mfma_f32_16x16x32_bf16 v[92:95], v[214:217], v[182:185], v[92:95]
	v_mfma_f32_16x16x32_bf16 v[88:91], v[160:163], v[182:185], v[88:91]
	v_mfma_f32_16x16x32_bf16 v[76:79], v[214:217], v[198:201], v[76:79]
	v_mfma_f32_16x16x32_bf16 v[72:75], v[160:163], v[198:201], v[72:75]
	v_mfma_f32_16x16x32_bf16 v[178:181], v[214:217], v[190:193], v[84:87]
	v_mfma_f32_16x16x32_bf16 v[182:185], v[160:163], v[190:193], v[80:83]
	v_mfma_f32_16x16x32_bf16 v[186:189], v[214:217], v[206:209], v[68:71]
	v_mfma_f32_16x16x32_bf16 v[190:193], v[160:163], v[206:209], v[64:67]
	s_barrier
	s_nop 0
	ds_read_b128 v[64:67], v155 offset:16384
	ds_read_b128 v[68:71], v155 offset:17408
	ds_read_b128 v[80:83], v154 offset:16384
	ds_read_b128 v[84:87], v154 offset:17408
	ds_read_b128 v[194:197], v153 offset:16384
	ds_read_b128 v[198:201], v153 offset:17408
	ds_read_b128 v[202:205], v152 offset:16384
	ds_read_b128 v[206:209], v152 offset:17408
	s_waitcnt vmcnt(4)
	s_barrier
	s_waitcnt lgkmcnt(0)
	s_waitcnt lgkmcnt(0)
	v_mfma_f32_16x16x32_bf16 v[60:63], v[134:137], v[64:67], v[60:63]
	v_mfma_f32_16x16x32_bf16 v[56:59], v[142:145], v[64:67], v[56:59]
	v_mfma_f32_16x16x32_bf16 v[52:55], v[134:137], v[80:83], v[52:55]
	v_mfma_f32_16x16x32_bf16 v[48:51], v[142:145], v[80:83], v[48:51]
	v_mfma_f32_16x16x32_bf16 v[44:47], v[134:137], v[194:197], v[44:47]
	v_mfma_f32_16x16x32_bf16 v[40:43], v[142:145], v[194:197], v[40:43]
	v_mfma_f32_16x16x32_bf16 v[36:39], v[134:137], v[202:205], v[36:39]
	v_mfma_f32_16x16x32_bf16 v[32:35], v[142:145], v[202:205], v[32:35]
	v_mfma_f32_16x16x32_bf16 v[60:63], v[138:141], v[68:71], v[60:63]
	v_mfma_f32_16x16x32_bf16 v[56:59], v[174:177], v[68:71], v[56:59]
	v_mfma_f32_16x16x32_bf16 v[52:55], v[138:141], v[84:87], v[52:55]
	v_mfma_f32_16x16x32_bf16 v[48:51], v[174:177], v[84:87], v[48:51]
	v_mfma_f32_16x16x32_bf16 v[44:47], v[138:141], v[198:201], v[44:47]
	v_mfma_f32_16x16x32_bf16 v[40:43], v[174:177], v[198:201], v[40:43]
	v_mfma_f32_16x16x32_bf16 v[36:39], v[138:141], v[206:209], v[36:39]
	v_mfma_f32_16x16x32_bf16 v[32:35], v[174:177], v[206:209], v[32:35]
	v_mfma_f32_16x16x32_bf16 v[28:31], v[210:213], v[64:67], v[28:31]
	v_mfma_f32_16x16x32_bf16 v[16:19], v[218:221], v[80:83], v[16:19]
	v_mfma_f32_16x16x32_bf16 v[12:15], v[210:213], v[194:197], v[12:15]
	v_mfma_f32_16x16x32_bf16 v[0:3], v[218:221], v[202:205], v[0:3]
	v_mfma_f32_16x16x32_bf16 v[24:27], v[218:221], v[64:67], v[24:27]
	v_mfma_f32_16x16x32_bf16 v[20:23], v[210:213], v[80:83], v[20:23]
	v_mfma_f32_16x16x32_bf16 v[8:11], v[218:221], v[194:197], v[8:11]
	v_mfma_f32_16x16x32_bf16 v[4:7], v[210:213], v[202:205], v[4:7]
	v_mfma_f32_16x16x32_bf16 v[28:31], v[214:217], v[68:71], v[28:31]
	v_mfma_f32_16x16x32_bf16 v[16:19], v[160:163], v[84:87], v[16:19]
	v_mfma_f32_16x16x32_bf16 v[12:15], v[214:217], v[198:201], v[12:15]
	v_mfma_f32_16x16x32_bf16 v[0:3], v[160:163], v[206:209], v[0:3]
	v_mfma_f32_16x16x32_bf16 v[134:137], v[160:163], v[68:71], v[24:27]
	v_mfma_f32_16x16x32_bf16 v[138:141], v[214:217], v[84:87], v[20:23]
	v_mfma_f32_16x16x32_bf16 v[142:145], v[160:163], v[198:201], v[8:11]
	v_mfma_f32_16x16x32_bf16 v[172:175], v[214:217], v[206:209], v[4:7]
	s_barrier
	s_nop 0
	ds_read_b128 v[4:7], v159
	ds_read_b128 v[8:11], v159 offset:1024
	ds_read_b128 v[20:23], v159 offset:2048
	ds_read_b128 v[158:161], v159 offset:3072
	ds_read_b128 v[24:27], v155 offset:32768
	ds_read_b128 v[194:197], v155 offset:33792
	ds_read_b128 v[198:201], v154 offset:32768
	ds_read_b128 v[202:205], v154 offset:33792
	ds_read_b128 v[206:209], v153 offset:32768
	ds_read_b128 v[210:213], v153 offset:33792
	ds_read_b128 v[214:217], v152 offset:32768
	ds_read_b128 v[218:221], v152 offset:33792
	s_waitcnt vmcnt(2)
	s_barrier
; #define UNR _Pragma("unroll")
; #define LDA(dst, b, h) for (int m = 0; m < 4; ++m) for (int k = 0; k < 2; ++k) \
;     dst[m][k] = *reinterpret_cast<const bf16x8*>((char*)SA(b, h) + lds_byte(wr * 64 + m * 16 + fr, k * 32 + fq * 8))
; #define LDB(dst, b, h) for (int n = 0; n < 2; ++n) for (int k = 0; k < 2; ++k) \
;     dst[n][k] = *reinterpret_cast<const bf16x8*>((char*)SB(b, h) + lds_byte(wc * 32 + n * 16 + fr, k * 32 + fq * 8))
; #define MMA(ai, bj, At_, Bt_) do { __builtin_amdgcn_s_setprio(1); \
;     for (int k = 0; k < 2; ++k) for (int m = 0; m < 4; ++m) for (int n = 0; n < 2; ++n) \
;       acc[ai][bj][m][n] = __builtin_amdgcn_mfma_f32_16x16x32_bf16(At_[m][k], Bt_[n][k], acc[ai][bj][m][n], 0, 0, 0); \
;     __builtin_amdgcn_s_setprio(0); } while (0)
; #define WAIT_V(n) asm volatile("s_waitcnt vmcnt(" #n ")" ::: "memory")
; #define WAIT_L(n) asm volatile("s_waitcnt lgkmcnt(" #n ")" ::: "memory")
; #define BAR __builtin_amdgcn_s_barrier()
; #define STAGE4(BROW, BCOL, PN) do { const u16* Ab_ = A + (EPI == EPI_RG ? ((PN) >> 1) * 256 : 0); \
;     STAGE(SB(0, 0), Bt, ldb, (BCOL), 0); STAGE(SA(0, 0), Ab_, lda, (BROW), 0); \
;     STAGE(SB(0, 1), Bt, ldb, (BCOL) + HALF, 0); STAGE(SA(0, 1), Ab_, lda, (BROW) + HALF, 0); } while (0)
; template <int EPI, int lda, int ldb, int N, int K>
; __device__ __forceinline__ void gemm_phase(const u16* __restrict__ A, const u16* __restrict__ Bt, const GemmEpi ep, int wv) {
;     ...
;     { LDB(B0, 1, 0); LDA(At, 1, 0); WAIT_V(2); BAR; WAIT_L(0); MMA(0, 0, At, B0); BAR;
;       LDB(B1, 1, 1); WAIT_V(0); BAR; WAIT_L(0); MMA(0, 1, At, B1); BAR;
;       LDA(At, 1, 1); BAR; WAIT_L(0); MMA(1, 0, At, B0); MMA(1, 1, At, B1); BAR; }
;     if (wr == 0) BAR;
;     int ntile = 0, nbrow = 0, nbcol = 0, npn = 0; bool more = false;
;     if constexpr (PF) { ntile = tile + gridDim.x; more = ntile < nwg; if (more) { TILE_COORDS(ntile, nbrow, nbcol, npn); STAGE4(nbrow, nbcol, npn); } }
;     float nss[8];
;     if constexpr (CONS) { UNR for (int pp = 0; pp < 8; ++pp) nss[pp] = 0.f;
;       if (more && tidx < 256) { UNR for (int pp = 0; pp < 8; ++pp) nss[pp] = ep.ss_in[(size_t)pp * T + nbrow + tidx]; } }
	s_waitcnt lgkmcnt(0)
	s_waitcnt lgkmcnt(0)
	v_mfma_f32_16x16x32_bf16 v[64:67], v[4:7], v[24:27], v[124:127]
	v_mfma_f32_16x16x32_bf16 v[68:71], v[20:23], v[24:27], v[120:123]
	v_mfma_f32_16x16x32_bf16 v[80:83], v[4:7], v[198:201], v[116:119]
	v_mfma_f32_16x16x32_bf16 v[84:87], v[20:23], v[198:201], v[112:115]
	v_mfma_f32_16x16x32_bf16 v[108:111], v[4:7], v[206:209], v[108:111]
	v_mfma_f32_16x16x32_bf16 v[104:107], v[20:23], v[206:209], v[104:107]
	v_mfma_f32_16x16x32_bf16 v[120:123], v[4:7], v[214:217], v[100:103]
	v_mfma_f32_16x16x32_bf16 v[124:127], v[20:23], v[214:217], v[96:99]
	v_mfma_f32_16x16x32_bf16 v[116:119], v[8:11], v[194:197], v[64:67]
	v_mfma_f32_16x16x32_bf16 v[112:115], v[158:161], v[194:197], v[68:71]
	v_mfma_f32_16x16x32_bf16 v[100:103], v[8:11], v[202:205], v[80:83]
	v_mfma_f32_16x16x32_bf16 v[96:99], v[158:161], v[202:205], v[84:87]
	v_mfma_f32_16x16x32_bf16 v[84:87], v[8:11], v[210:213], v[108:111]
	v_mfma_f32_16x16x32_bf16 v[80:83], v[158:161], v[210:213], v[104:107]
	v_mfma_f32_16x16x32_bf16 v[68:71], v[8:11], v[218:221], v[120:123]
	v_mfma_f32_16x16x32_bf16 v[64:67], v[158:161], v[218:221], v[124:127]
	s_barrier
	ds_read_b128 v[222:225], v157
	ds_read_b128 v[226:229], v157 offset:1024
	ds_read_b128 v[230:233], v157 offset:2048
	ds_read_b128 v[234:237], v157 offset:3072
	s_waitcnt vmcnt(0)
	s_barrier
	s_waitcnt lgkmcnt(0)
	s_waitcnt lgkmcnt(0)
	v_mfma_f32_16x16x32_bf16 v[92:95], v[222:225], v[24:27], v[92:95]
	v_mfma_f32_16x16x32_bf16 v[24:27], v[230:233], v[24:27], v[88:91]
	v_mfma_f32_16x16x32_bf16 v[88:91], v[222:225], v[198:201], v[178:181]
	v_mfma_f32_16x16x32_bf16 v[104:107], v[230:233], v[198:201], v[182:185]
	v_mfma_f32_16x16x32_bf16 v[76:79], v[222:225], v[206:209], v[76:79]
	v_mfma_f32_16x16x32_bf16 v[72:75], v[230:233], v[206:209], v[72:75]
	v_mfma_f32_16x16x32_bf16 v[176:179], v[222:225], v[214:217], v[186:189]
	v_mfma_f32_16x16x32_bf16 v[180:183], v[230:233], v[214:217], v[190:193]
	v_mfma_f32_16x16x32_bf16 v[124:127], v[226:229], v[194:197], v[92:95]
	v_mfma_f32_16x16x32_bf16 v[120:123], v[234:237], v[194:197], v[24:27]
	v_mfma_f32_16x16x32_bf16 v[108:111], v[226:229], v[202:205], v[88:91]
	v_mfma_f32_16x16x32_bf16 v[104:107], v[234:237], v[202:205], v[104:107]
	v_mfma_f32_16x16x32_bf16 v[92:95], v[226:229], v[210:213], v[76:79]
	v_mfma_f32_16x16x32_bf16 v[88:91], v[234:237], v[210:213], v[72:75]
	v_mfma_f32_16x16x32_bf16 v[76:79], v[226:229], v[218:221], v[176:179]
	v_mfma_f32_16x16x32_bf16 v[72:75], v[234:237], v[218:221], v[180:183]
	s_barrier
	ds_read_b128 v[176:179], v155 offset:49152
	ds_read_b128 v[180:183], v155 offset:50176
	ds_read_b128 v[184:187], v154 offset:49152
	ds_read_b128 v[154:157], v154 offset:50176
	ds_read_b128 v[188:191], v153 offset:49152
	ds_read_b128 v[192:195], v153 offset:50176
	ds_read_b128 v[196:199], v152 offset:49152
	ds_read_b128 v[200:203], v152 offset:50176
	s_barrier
	s_waitcnt lgkmcnt(0)
	s_waitcnt lgkmcnt(0)
	v_mfma_f32_16x16x32_bf16 v[24:27], v[4:7], v[176:179], v[60:63]
	v_mfma_f32_16x16x32_bf16 v[60:63], v[20:23], v[176:179], v[56:59]
	v_mfma_f32_16x16x32_bf16 v[204:207], v[4:7], v[184:187], v[52:55]
	v_mfma_f32_16x16x32_bf16 v[48:51], v[20:23], v[184:187], v[48:51]
	v_mfma_f32_16x16x32_bf16 v[44:47], v[4:7], v[188:191], v[44:47]
	v_mfma_f32_16x16x32_bf16 v[208:211], v[20:23], v[188:191], v[40:43]
	v_mfma_f32_16x16x32_bf16 v[4:7], v[4:7], v[196:199], v[36:39]
	v_mfma_f32_16x16x32_bf16 v[32:35], v[20:23], v[196:199], v[32:35]
	v_mfma_f32_16x16x32_bf16 v[56:59], v[8:11], v[180:183], v[24:27]
	v_mfma_f32_16x16x32_bf16 v[52:55], v[158:161], v[180:183], v[60:63]
	v_mfma_f32_16x16x32_bf16 v[40:43], v[8:11], v[154:157], v[204:207]
	v_mfma_f32_16x16x32_bf16 v[36:39], v[158:161], v[154:157], v[48:51]
	v_mfma_f32_16x16x32_bf16 v[24:27], v[8:11], v[192:195], v[44:47]
	v_mfma_f32_16x16x32_bf16 v[20:23], v[158:161], v[192:195], v[208:211]
	v_mfma_f32_16x16x32_bf16 v[8:11], v[8:11], v[200:203], v[4:7]
	v_mfma_f32_16x16x32_bf16 v[4:7], v[158:161], v[200:203], v[32:35]
	v_mfma_f32_16x16x32_bf16 v[28:31], v[222:225], v[176:179], v[28:31]
	v_mfma_f32_16x16x32_bf16 v[32:35], v[230:233], v[176:179], v[134:137]
	v_mfma_f32_16x16x32_bf16 v[44:47], v[222:225], v[184:187], v[138:141]
	v_mfma_f32_16x16x32_bf16 v[16:19], v[230:233], v[184:187], v[16:19]
	v_mfma_f32_16x16x32_bf16 v[12:15], v[222:225], v[188:191], v[12:15]
	v_mfma_f32_16x16x32_bf16 v[134:137], v[230:233], v[188:191], v[142:145]
	v_mfma_f32_16x16x32_bf16 v[138:141], v[222:225], v[196:199], v[172:175]
	v_mfma_f32_16x16x32_bf16 v[0:3], v[230:233], v[196:199], v[0:3]
	v_mfma_f32_16x16x32_bf16 v[60:63], v[226:229], v[180:183], v[28:31]
	v_mfma_f32_16x16x32_bf16 v[48:51], v[234:237], v[180:183], v[32:35]
	v_mfma_f32_16x16x32_bf16 v[44:47], v[226:229], v[154:157], v[44:47]
	v_mfma_f32_16x16x32_bf16 v[32:35], v[234:237], v[154:157], v[16:19]
	v_mfma_f32_16x16x32_bf16 v[28:31], v[226:229], v[192:195], v[12:15]
	v_mfma_f32_16x16x32_bf16 v[16:19], v[234:237], v[192:195], v[134:137]
	v_mfma_f32_16x16x32_bf16 v[12:15], v[226:229], v[200:203], v[138:141]
	v_mfma_f32_16x16x32_bf16 v[0:3], v[234:237], v[200:203], v[0:3]
	v_cmp_gt_u32_e32 vcc, s62, v130
	s_barrier
	s_and_saveexec_b64 s[44:45], vcc
	s_cbranch_execz .LBB0_227
	s_barrier

; #define STAGE(P, BASE, LD, br, kt) do { const char* _g = (const char*)((BASE) + (size_t)(br) * (LD) + (size_t)(kt) * 64); \
;     for (int _i = 0; _i < 2; ++_i) { int _b = tidx * 16 + _i * 8192; int _r, _c; stage_rc(_b, _r, _c); \
;       __builtin_amdgcn_global_load_lds((const unsigned*)(_g + (unsigned)((_r * (LD) + _c) * 2)), (unsigned*)((char*)(P) + _b), 16, 0, 0); } } while (0)
; #define LDA(dst, b, h) for (int m = 0; m < 4; ++m) for (int k = 0; k < 2; ++k) \
;     dst[m][k] = *reinterpret_cast<const bf16x8*>((char*)SA(b, h) + lds_byte(wr * 64 + m * 16 + fr, k * 32 + fq * 8))
; #define LDB(dst, b, h) for (int n = 0; n < 2; ++n) for (int k = 0; k < 2; ++k) \
;     dst[n][k] = *reinterpret_cast<const bf16x8*>((char*)SB(b, h) + lds_byte(wc * 32 + n * 16 + fr, k * 32 + fq * 8))
; #define MMA(ai, bj, At_, Bt_) do { __builtin_amdgcn_s_setprio(1); \
;     for (int k = 0; k < 2; ++k) for (int m = 0; m < 4; ++m) for (int n = 0; n < 2; ++n) \
;       acc[ai][bj][m][n] = __builtin_amdgcn_mfma_f32_16x16x32_bf16(At_[m][k], Bt_[n][k], acc[ai][bj][m][n], 0, 0, 0); \
;     __builtin_amdgcn_s_setprio(0); } while (0)
; #define WAIT_L(n) asm volatile("s_waitcnt lgkmcnt(" #n ")" ::: "memory")
; #define BAR __builtin_amdgcn_s_barrier()
; #define SCHED __builtin_amdgcn_sched_barrier(0)
; template <int EPI, int lda, int ldb, int N, int K>
; __device__ __forceinline__ void gemm_phase(const u16* __restrict__ A, const u16* __restrict__ Bt, const GemmEpi ep, int wv) {
;     ...
;       LDB(B0, 0, 0); SCHED; LDA(At, 0, 0); STAGE(SA(1, 1), Ab, lda, brow + HALF, t + 1);
;       WAIT_L(8); BAR; WAIT_L(0); MMA(0, 0, At, B0); BAR; SCHED;
;       LDB(B1, 0, 1); STAGE(SB(0, 0), Bt, ldb, bcol, t + 2);
;       BAR; WAIT_L(0); MMA(0, 1, At, B1); BAR;
;       LDA(At, 0, 1); STAGE(SA(0, 0), Ab, lda, brow, t + 2);
;       BAR; WAIT_L(0); MMA(1, 0, At, B0); BAR; SCHED;
.LBB0_340:
	ds_read_b128 v[166:169], v162
	ds_read_b128 v[172:175], v162 offset:1024
	ds_read_b128 v[176:179], v162 offset:2048
	ds_read_b128 v[180:183], v162 offset:3072
	v_add_u32_e32 v170, 0xc000, v149
	v_lshl_add_u64 v[236:237], v[138:139], 0, s[48:49]
	v_readfirstlane_b32 s51, v170
	v_add_u32_e32 v171, 0xe000, v149
	v_lshl_add_u64 v[164:165], v[236:237], 0, s[18:19]
	s_mov_b32 m0, s51
	v_lshl_add_u64 v[238:239], v[140:141], 0, s[48:49]
	v_readfirstlane_b32 s51, v171
	ds_read_b128 v[184:187], v153
	ds_read_b128 v[188:191], v153 offset:1024
	ds_read_b128 v[192:195], v152
	ds_read_b128 v[196:199], v152 offset:1024
	ds_read_b128 v[200:203], v151
	ds_read_b128 v[204:207], v151 offset:1024
	ds_read_b128 v[208:211], v150
	ds_read_b128 v[212:215], v150 offset:1024
	global_load_lds_dwordx4 v[164:165], off
	v_lshl_add_u64 v[164:165], v[238:239], 0, s[18:19]
	s_mov_b32 m0, s51
	s_nop 0
	global_load_lds_dwordx4 v[164:165], off
	s_waitcnt lgkmcnt(8)
	s_barrier
	s_waitcnt lgkmcnt(0)
	s_waitcnt lgkmcnt(0)
	v_mfma_f32_16x16x32_bf16 v[124:127], v[184:187], v[166:169], v[124:127]
	ds_read_b128 v[216:219], v161
	v_mfma_f32_16x16x32_bf16 v[120:123], v[184:187], v[176:179], v[120:123]
	v_mfma_f32_16x16x32_bf16 v[116:119], v[192:195], v[166:169], v[116:119]
	ds_read_b128 v[220:223], v161 offset:1024
	v_mfma_f32_16x16x32_bf16 v[112:115], v[192:195], v[176:179], v[112:115]
	v_mfma_f32_16x16x32_bf16 v[108:111], v[200:203], v[166:169], v[108:111]
	ds_read_b128 v[224:227], v161 offset:2048
	v_mfma_f32_16x16x32_bf16 v[104:107], v[200:203], v[176:179], v[104:107]
	v_mfma_f32_16x16x32_bf16 v[100:103], v[208:211], v[166:169], v[100:103]
	ds_read_b128 v[228:231], v161 offset:3072
	v_mfma_f32_16x16x32_bf16 v[96:99], v[208:211], v[176:179], v[96:99]
	v_mfma_f32_16x16x32_bf16 v[124:127], v[188:191], v[172:175], v[124:127]
	v_mfma_f32_16x16x32_bf16 v[120:123], v[188:191], v[180:183], v[120:123]
	v_mfma_f32_16x16x32_bf16 v[116:119], v[196:199], v[172:175], v[116:119]
	v_mfma_f32_16x16x32_bf16 v[112:115], v[196:199], v[180:183], v[112:115]
	v_mfma_f32_16x16x32_bf16 v[108:111], v[204:207], v[172:175], v[108:111]
	v_mfma_f32_16x16x32_bf16 v[104:107], v[204:207], v[180:183], v[104:107]
	v_mfma_f32_16x16x32_bf16 v[100:103], v[212:215], v[172:175], v[100:103]
	v_mfma_f32_16x16x32_bf16 v[96:99], v[212:215], v[180:183], v[96:99]
	s_barrier
	v_add_u32_e32 v163, s62, v155
	v_lshl_add_u64 v[240:241], v[134:135], 0, s[48:49]
	v_readfirstlane_b32 s51, v163
	v_lshl_add_u64 v[164:165], v[240:241], 0, s[20:21]
	s_mov_b32 m0, s51
	global_load_lds_dwordx4 v[164:165], off
	v_add_u32_e32 v164, 0x2000, v163
	v_lshl_add_u64 v[242:243], v[136:137], 0, s[48:49]
	v_readfirstlane_b32 s51, v164
	v_lshl_add_u64 v[232:233], v[242:243], 0, s[20:21]
	s_mov_b32 m0, s51
	s_nop 0
	global_load_lds_dwordx4 v[232:233], off
	s_barrier
	s_waitcnt lgkmcnt(0)
	s_waitcnt lgkmcnt(0)
	v_mfma_f32_16x16x32_bf16 v[92:95], v[184:187], v[216:219], v[92:95]
	v_mfma_f32_16x16x32_bf16 v[88:91], v[184:187], v[224:227], v[88:91]
	v_mfma_f32_16x16x32_bf16 v[84:87], v[192:195], v[216:219], v[84:87]
	v_mfma_f32_16x16x32_bf16 v[80:83], v[192:195], v[224:227], v[80:83]
	v_mfma_f32_16x16x32_bf16 v[76:79], v[200:203], v[216:219], v[76:79]
	v_mfma_f32_16x16x32_bf16 v[72:75], v[200:203], v[224:227], v[72:75]
	v_mfma_f32_16x16x32_bf16 v[68:71], v[208:211], v[216:219], v[68:71]
	v_mfma_f32_16x16x32_bf16 v[64:67], v[208:211], v[224:227], v[64:67]
	v_mfma_f32_16x16x32_bf16 v[92:95], v[188:191], v[220:223], v[92:95]
	v_mfma_f32_16x16x32_bf16 v[88:91], v[188:191], v[228:231], v[88:91]
	v_mfma_f32_16x16x32_bf16 v[84:87], v[196:199], v[220:223], v[84:87]
	v_mfma_f32_16x16x32_bf16 v[80:83], v[196:199], v[228:231], v[80:83]
	v_mfma_f32_16x16x32_bf16 v[76:79], v[204:207], v[220:223], v[76:79]
	v_mfma_f32_16x16x32_bf16 v[72:75], v[204:207], v[228:231], v[72:75]
	v_mfma_f32_16x16x32_bf16 v[68:71], v[212:215], v[220:223], v[68:71]
	v_mfma_f32_16x16x32_bf16 v[64:67], v[212:215], v[228:231], v[64:67]
	v_readfirstlane_b32 s51, v149
	v_add_u32_e32 v165, 0x2000, v149
	v_lshl_add_u64 v[232:233], v[236:237], 0, s[22:23]
	s_mov_b32 m0, s51
	v_readfirstlane_b32 s51, v165
	s_barrier
	ds_read_b128 v[184:187], v153 offset:16384
	ds_read_b128 v[188:191], v153 offset:17408
	ds_read_b128 v[192:195], v152 offset:16384
	ds_read_b128 v[196:199], v152 offset:17408
	ds_read_b128 v[200:203], v151 offset:16384
	ds_read_b128 v[204:207], v151 offset:17408
	ds_read_b128 v[208:211], v150 offset:16384
	ds_read_b128 v[212:215], v150 offset:17408
	global_load_lds_dwordx4 v[232:233], off
	v_lshl_add_u64 v[232:233], v[238:239], 0, s[22:23]
	s_mov_b32 m0, s51
	s_nop 0
	global_load_lds_dwordx4 v[232:233], off
	s_barrier
	s_waitcnt lgkmcnt(0)
	s_waitcnt lgkmcnt(0)
	v_mfma_f32_16x16x32_bf16 v[60:63], v[184:187], v[166:169], v[60:63]
	v_mfma_f32_16x16x32_bf16 v[56:59], v[184:187], v[176:179], v[56:59]
	v_mfma_f32_16x16x32_bf16 v[52:55], v[192:195], v[166:169], v[52:55]
	v_mfma_f32_16x16x32_bf16 v[48:51], v[192:195], v[176:179], v[48:51]
	v_mfma_f32_16x16x32_bf16 v[44:47], v[200:203], v[166:169], v[44:47]
	v_mfma_f32_16x16x32_bf16 v[40:43], v[200:203], v[176:179], v[40:43]
	v_mfma_f32_16x16x32_bf16 v[36:39], v[208:211], v[166:169], v[36:39]
	v_mfma_f32_16x16x32_bf16 v[32:35], v[208:211], v[176:179], v[32:35]
	v_mfma_f32_16x16x32_bf16 v[60:63], v[188:191], v[172:175], v[60:63]
	v_mfma_f32_16x16x32_bf16 v[56:59], v[188:191], v[180:183], v[56:59]
	v_mfma_f32_16x16x32_bf16 v[52:55], v[196:199], v[172:175], v[52:55]
	v_mfma_f32_16x16x32_bf16 v[48:51], v[196:199], v[180:183], v[48:51]
	v_mfma_f32_16x16x32_bf16 v[44:47], v[204:207], v[172:175], v[44:47]
	v_mfma_f32_16x16x32_bf16 v[40:43], v[204:207], v[180:183], v[40:43]
	v_mfma_f32_16x16x32_bf16 v[36:39], v[212:215], v[172:175], v[36:39]
	v_mfma_f32_16x16x32_bf16 v[32:35], v[212:215], v[180:183], v[32:35]
	s_barrier
; #define STAGE(P, BASE, LD, br, kt) do { const char* _g = (const char*)((BASE) + (size_t)(br) * (LD) + (size_t)(kt) * 64); \
;     for (int _i = 0; _i < 2; ++_i) { int _b = tidx * 16 + _i * 8192; int _r, _c; stage_rc(_b, _r, _c); \
;       __builtin_amdgcn_global_load_lds((const unsigned*)(_g + (unsigned)((_r * (LD) + _c) * 2)), (unsigned*)((char*)(P) + _b), 16, 0, 0); } } while (0)
; #define LDA(dst, b, h) for (int m = 0; m < 4; ++m) for (int k = 0; k < 2; ++k) \
;     dst[m][k] = *reinterpret_cast<const bf16x8*>((char*)SA(b, h) + lds_byte(wr * 64 + m * 16 + fr, k * 32 + fq * 8))
; #define LDB(dst, b, h) for (int n = 0; n < 2; ++n) for (int k = 0; k < 2; ++k) \
;     dst[n][k] = *reinterpret_cast<const bf16x8*>((char*)SB(b, h) + lds_byte(wc * 32 + n * 16 + fr, k * 32 + fq * 8))
; #define MMA(ai, bj, At_, Bt_) do { __builtin_amdgcn_s_setprio(1); \
;     for (int k = 0; k < 2; ++k) for (int m = 0; m < 4; ++m) for (int n = 0; n < 2; ++n) \
;       acc[ai][bj][m][n] = __builtin_amdgcn_mfma_f32_16x16x32_bf16(At_[m][k], Bt_[n][k], acc[ai][bj][m][n], 0, 0, 0); \
;     __builtin_amdgcn_s_setprio(0); } while (0)
; #define WAIT_V(n) asm volatile("s_waitcnt vmcnt(" #n ")" ::: "memory")
; #define WAIT_L(n) asm volatile("s_waitcnt lgkmcnt(" #n ")" ::: "memory")
; #define BAR __builtin_amdgcn_s_barrier()
; #define SCHED __builtin_amdgcn_sched_barrier(0)
; template <int EPI, int lda, int ldb, int N, int K>
; __device__ __forceinline__ void gemm_phase(const u16* __restrict__ A, const u16* __restrict__ Bt, const GemmEpi ep, int wv) {
;     ...
;       STAGE(SB(0, 1), Bt, ldb, bcol + HALF, t + 2);
;       WAIT_V(6); BAR; MMA(1, 1, At, B1); BAR;
;       LDB(B0, 1, 0); SCHED; LDA(At, 1, 0); STAGE(SA(0, 1), Ab, lda, brow + HALF, t + 2);
;       WAIT_L(8); BAR; WAIT_L(0); MMA(0, 0, At, B0); BAR; SCHED;
;       LDB(B1, 1, 1); STAGE(SB(1, 0), Bt, ldb, bcol, t + 3);
;       BAR; WAIT_L(0); MMA(0, 1, At, B1); BAR;
	v_add_u32_e32 v166, s63, v155
	v_add_u32_e32 v167, 0x2000, v166
	v_readfirstlane_b32 s51, v166
	v_lshl_add_u64 v[168:169], v[240:241], 0, s[24:25]
	s_mov_b32 m0, s51
	v_readfirstlane_b32 s51, v167
	global_load_lds_dwordx4 v[168:169], off
	v_lshl_add_u64 v[168:169], v[242:243], 0, s[24:25]
	s_mov_b32 m0, s51
	s_nop 0
	global_load_lds_dwordx4 v[168:169], off
	s_waitcnt vmcnt(6)
	s_barrier
	v_mfma_f32_16x16x32_bf16 v[28:31], v[184:187], v[216:219], v[28:31]
	v_mfma_f32_16x16x32_bf16 v[24:27], v[184:187], v[224:227], v[24:27]
	ds_read_b128 v[172:175], v156
	v_mfma_f32_16x16x32_bf16 v[20:23], v[192:195], v[216:219], v[20:23]
	v_mfma_f32_16x16x32_bf16 v[16:19], v[192:195], v[224:227], v[16:19]
	ds_read_b128 v[176:179], v156 offset:1024
	v_mfma_f32_16x16x32_bf16 v[12:15], v[200:203], v[216:219], v[12:15]
	v_mfma_f32_16x16x32_bf16 v[8:11], v[200:203], v[224:227], v[8:11]
	ds_read_b128 v[180:183], v156 offset:2048
	v_mfma_f32_16x16x32_bf16 v[4:7], v[208:211], v[216:219], v[4:7]
	v_mfma_f32_16x16x32_bf16 v[0:3], v[208:211], v[224:227], v[0:3]
	ds_read_b128 v[184:187], v156 offset:3072
	v_mfma_f32_16x16x32_bf16 v[28:31], v[188:191], v[220:223], v[28:31]
	v_mfma_f32_16x16x32_bf16 v[24:27], v[188:191], v[228:231], v[24:27]
	v_mfma_f32_16x16x32_bf16 v[20:23], v[196:199], v[220:223], v[20:23]
	v_mfma_f32_16x16x32_bf16 v[16:19], v[196:199], v[228:231], v[16:19]
	v_mfma_f32_16x16x32_bf16 v[12:15], v[204:207], v[220:223], v[12:15]
	v_mfma_f32_16x16x32_bf16 v[8:11], v[204:207], v[228:231], v[8:11]
	v_mfma_f32_16x16x32_bf16 v[4:7], v[212:215], v[220:223], v[4:7]
	v_mfma_f32_16x16x32_bf16 v[0:3], v[212:215], v[228:231], v[0:3]
	s_barrier
	v_add_u32_e32 v168, 0x4000, v149
	v_add_u32_e32 v169, 0x6000, v149
	v_readfirstlane_b32 s51, v168
	v_lshl_add_u64 v[220:221], v[236:237], 0, s[26:27]
	s_mov_b32 m0, s51
	v_readfirstlane_b32 s51, v169
	ds_read_b128 v[188:191], v153 offset:32768
	ds_read_b128 v[192:195], v153 offset:33792
	ds_read_b128 v[196:199], v152 offset:32768
	ds_read_b128 v[200:203], v152 offset:33792
	ds_read_b128 v[204:207], v151 offset:32768
	ds_read_b128 v[208:211], v151 offset:33792
	ds_read_b128 v[212:215], v150 offset:32768
	ds_read_b128 v[216:219], v150 offset:33792
	global_load_lds_dwordx4 v[220:221], off
	v_lshl_add_u64 v[220:221], v[238:239], 0, s[26:27]
	s_mov_b32 m0, s51
	s_nop 0
	global_load_lds_dwordx4 v[220:221], off
	s_waitcnt lgkmcnt(8)
	s_barrier
	s_waitcnt lgkmcnt(0)
	s_waitcnt lgkmcnt(0)
	v_mfma_f32_16x16x32_bf16 v[124:127], v[188:191], v[172:175], v[124:127]
	ds_read_b128 v[220:223], v154
	v_mfma_f32_16x16x32_bf16 v[120:123], v[188:191], v[180:183], v[120:123]
	v_mfma_f32_16x16x32_bf16 v[116:119], v[196:199], v[172:175], v[116:119]
	ds_read_b128 v[224:227], v154 offset:1024
	v_mfma_f32_16x16x32_bf16 v[112:115], v[196:199], v[180:183], v[112:115]
	v_mfma_f32_16x16x32_bf16 v[108:111], v[204:207], v[172:175], v[108:111]
	ds_read_b128 v[228:231], v154 offset:2048
	v_mfma_f32_16x16x32_bf16 v[104:107], v[204:207], v[180:183], v[104:107]
	v_mfma_f32_16x16x32_bf16 v[100:103], v[212:215], v[172:175], v[100:103]
	ds_read_b128 v[232:235], v154 offset:3072
	v_mfma_f32_16x16x32_bf16 v[96:99], v[212:215], v[180:183], v[96:99]
	v_mfma_f32_16x16x32_bf16 v[124:127], v[192:195], v[176:179], v[124:127]
	v_mfma_f32_16x16x32_bf16 v[120:123], v[192:195], v[184:187], v[120:123]
	v_mfma_f32_16x16x32_bf16 v[116:119], v[200:203], v[176:179], v[116:119]
	v_mfma_f32_16x16x32_bf16 v[112:115], v[200:203], v[184:187], v[112:115]
	v_mfma_f32_16x16x32_bf16 v[108:111], v[208:211], v[176:179], v[108:111]
	v_mfma_f32_16x16x32_bf16 v[104:107], v[208:211], v[184:187], v[104:107]
	v_mfma_f32_16x16x32_bf16 v[100:103], v[216:219], v[176:179], v[100:103]
	v_mfma_f32_16x16x32_bf16 v[96:99], v[216:219], v[184:187], v[96:99]
	s_barrier
	v_readfirstlane_b32 s51, v157
	v_add_u32_e32 v246, 0x2000, v157
	v_lshl_add_u64 v[244:245], v[240:241], 0, s[36:37]
	s_mov_b32 m0, s51
	v_readfirstlane_b32 s51, v246
	global_load_lds_dwordx4 v[244:245], off
	v_lshl_add_u64 v[244:245], v[242:243], 0, s[36:37]
	s_mov_b32 m0, s51
	s_nop 0
	global_load_lds_dwordx4 v[244:245], off
	s_barrier
	s_waitcnt lgkmcnt(0)
	s_waitcnt lgkmcnt(0)
	v_mfma_f32_16x16x32_bf16 v[92:95], v[188:191], v[220:223], v[92:95]
	v_mfma_f32_16x16x32_bf16 v[88:91], v[188:191], v[228:231], v[88:91]
	v_mfma_f32_16x16x32_bf16 v[84:87], v[196:199], v[220:223], v[84:87]
	v_mfma_f32_16x16x32_bf16 v[80:83], v[196:199], v[228:231], v[80:83]
	v_mfma_f32_16x16x32_bf16 v[76:79], v[204:207], v[220:223], v[76:79]
	v_mfma_f32_16x16x32_bf16 v[72:75], v[204:207], v[228:231], v[72:75]
	v_mfma_f32_16x16x32_bf16 v[68:71], v[212:215], v[220:223], v[68:71]
	v_mfma_f32_16x16x32_bf16 v[64:67], v[212:215], v[228:231], v[64:67]
	v_mfma_f32_16x16x32_bf16 v[92:95], v[192:195], v[224:227], v[92:95]
	v_mfma_f32_16x16x32_bf16 v[88:91], v[192:195], v[232:235], v[88:91]
	v_mfma_f32_16x16x32_bf16 v[84:87], v[200:203], v[224:227], v[84:87]
	v_mfma_f32_16x16x32_bf16 v[80:83], v[200:203], v[232:235], v[80:83]
	v_mfma_f32_16x16x32_bf16 v[76:79], v[208:211], v[224:227], v[76:79]
	v_mfma_f32_16x16x32_bf16 v[72:75], v[208:211], v[232:235], v[72:75]
	v_mfma_f32_16x16x32_bf16 v[68:71], v[216:219], v[224:227], v[68:71]
	v_mfma_f32_16x16x32_bf16 v[64:67], v[216:219], v[232:235], v[64:67]
	v_readfirstlane_b32 s51, v158
	v_lshl_add_u64 v[236:237], v[236:237], 0, s[38:39]
	s_mov_b32 m0, s51
	v_readfirstlane_b32 s51, v159
	s_barrier
; #define STAGE(P, BASE, LD, br, kt) do { const char* _g = (const char*)((BASE) + (size_t)(br) * (LD) + (size_t)(kt) * 64); \
;     for (int _i = 0; _i < 2; ++_i) { int _b = tidx * 16 + _i * 8192; int _r, _c; stage_rc(_b, _r, _c); \
;       __builtin_amdgcn_global_load_lds((const unsigned*)(_g + (unsigned)((_r * (LD) + _c) * 2)), (unsigned*)((char*)(P) + _b), 16, 0, 0); } } while (0)
; #define LDA(dst, b, h) for (int m = 0; m < 4; ++m) for (int k = 0; k < 2; ++k) \
;     dst[m][k] = *reinterpret_cast<const bf16x8*>((char*)SA(b, h) + lds_byte(wr * 64 + m * 16 + fr, k * 32 + fq * 8))
; #define LDB(dst, b, h) for (int n = 0; n < 2; ++n) for (int k = 0; k < 2; ++k) \
;     dst[n][k] = *reinterpret_cast<const bf16x8*>((char*)SB(b, h) + lds_byte(wc * 32 + n * 16 + fr, k * 32 + fq * 8))
; #define MMA(ai, bj, At_, Bt_) do { __builtin_amdgcn_s_setprio(1); \
;     for (int k = 0; k < 2; ++k) for (int m = 0; m < 4; ++m) for (int n = 0; n < 2; ++n) \
;       acc[ai][bj][m][n] = __builtin_amdgcn_mfma_f32_16x16x32_bf16(At_[m][k], Bt_[n][k], acc[ai][bj][m][n], 0, 0, 0); \
;     __builtin_amdgcn_s_setprio(0); } while (0)
; #define WAIT_V(n) asm volatile("s_waitcnt vmcnt(" #n ")" ::: "memory")
; #define WAIT_L(n) asm volatile("s_waitcnt lgkmcnt(" #n ")" ::: "memory")
; #define BAR __builtin_amdgcn_s_barrier()
; #define SCHED __builtin_amdgcn_sched_barrier(0)
; template <int EPI, int lda, int ldb, int N, int K>
; __device__ __forceinline__ void gemm_phase(const u16* __restrict__ A, const u16* __restrict__ Bt, const GemmEpi ep, int wv) {
;     ...
;       LDA(At, 1, 1); STAGE(SA(1, 0), Ab, lda, brow, t + 3);
;       BAR; WAIT_L(0); MMA(1, 0, At, B0); BAR; SCHED;
;       STAGE(SB(1, 1), Bt, ldb, bcol + HALF, t + 3);
;       WAIT_V(6); BAR; MMA(1, 1, At, B1); BAR;
;     }
;     { LDB(B0, 0, 0); LDA(At, 0, 0); STAGE(SA(1, 1), Ab, lda, brow + HALF, nt - 1);
;       BAR; WAIT_L(0); MMA(0, 0, At, B0); BAR;
;       LDB(B1, 0, 1); BAR; WAIT_L(0); MMA(0, 1, At, B1); BAR;
	ds_read_b128 v[188:191], v153 offset:49152
	ds_read_b128 v[192:195], v153 offset:50176
	ds_read_b128 v[196:199], v152 offset:49152
	ds_read_b128 v[200:203], v152 offset:50176
	ds_read_b128 v[204:207], v151 offset:49152
	ds_read_b128 v[208:211], v151 offset:50176
	ds_read_b128 v[212:215], v150 offset:49152
	ds_read_b128 v[216:219], v150 offset:50176
	global_load_lds_dwordx4 v[236:237], off
	v_lshl_add_u64 v[236:237], v[238:239], 0, s[38:39]
	s_mov_b32 m0, s51
	s_nop 0
	global_load_lds_dwordx4 v[236:237], off
	s_barrier
	s_waitcnt lgkmcnt(0)
	s_waitcnt lgkmcnt(0)
	v_mfma_f32_16x16x32_bf16 v[60:63], v[188:191], v[172:175], v[60:63]
	v_mfma_f32_16x16x32_bf16 v[56:59], v[188:191], v[180:183], v[56:59]
	v_mfma_f32_16x16x32_bf16 v[52:55], v[196:199], v[172:175], v[52:55]
	v_mfma_f32_16x16x32_bf16 v[48:51], v[196:199], v[180:183], v[48:51]
	v_mfma_f32_16x16x32_bf16 v[44:47], v[204:207], v[172:175], v[44:47]
	v_mfma_f32_16x16x32_bf16 v[40:43], v[204:207], v[180:183], v[40:43]
	v_mfma_f32_16x16x32_bf16 v[36:39], v[212:215], v[172:175], v[36:39]
	v_mfma_f32_16x16x32_bf16 v[32:35], v[212:215], v[180:183], v[32:35]
	v_mfma_f32_16x16x32_bf16 v[60:63], v[192:195], v[176:179], v[60:63]
	v_mfma_f32_16x16x32_bf16 v[56:59], v[192:195], v[184:187], v[56:59]
	v_mfma_f32_16x16x32_bf16 v[52:55], v[200:203], v[176:179], v[52:55]
	v_mfma_f32_16x16x32_bf16 v[48:51], v[200:203], v[184:187], v[48:51]
	v_mfma_f32_16x16x32_bf16 v[44:47], v[208:211], v[176:179], v[44:47]
	v_mfma_f32_16x16x32_bf16 v[40:43], v[208:211], v[184:187], v[40:43]
	v_mfma_f32_16x16x32_bf16 v[36:39], v[216:219], v[176:179], v[36:39]
	v_mfma_f32_16x16x32_bf16 v[32:35], v[216:219], v[184:187], v[32:35]
	s_barrier
	v_readfirstlane_b32 s51, v160
	v_add_u32_e32 v174, 0x2000, v160
	v_lshl_add_u64 v[172:173], v[240:241], 0, s[42:43]
	s_mov_b32 m0, s51
	v_readfirstlane_b32 s51, v174
	global_load_lds_dwordx4 v[172:173], off
	v_lshl_add_u64 v[172:173], v[242:243], 0, s[42:43]
	s_mov_b32 m0, s51
	s_nop 0
	global_load_lds_dwordx4 v[172:173], off
	s_waitcnt vmcnt(6)
	s_barrier
	v_mfma_f32_16x16x32_bf16 v[28:31], v[188:191], v[220:223], v[28:31]
	v_mfma_f32_16x16x32_bf16 v[24:27], v[188:191], v[228:231], v[24:27]
	v_mfma_f32_16x16x32_bf16 v[20:23], v[196:199], v[220:223], v[20:23]
	v_mfma_f32_16x16x32_bf16 v[16:19], v[196:199], v[228:231], v[16:19]
	v_mfma_f32_16x16x32_bf16 v[12:15], v[204:207], v[220:223], v[12:15]
	v_mfma_f32_16x16x32_bf16 v[8:11], v[204:207], v[228:231], v[8:11]
	v_mfma_f32_16x16x32_bf16 v[4:7], v[212:215], v[220:223], v[4:7]
	v_mfma_f32_16x16x32_bf16 v[0:3], v[212:215], v[228:231], v[0:3]
	v_mfma_f32_16x16x32_bf16 v[28:31], v[192:195], v[224:227], v[28:31]
	v_mfma_f32_16x16x32_bf16 v[24:27], v[192:195], v[232:235], v[24:27]
	v_mfma_f32_16x16x32_bf16 v[20:23], v[200:203], v[224:227], v[20:23]
	v_mfma_f32_16x16x32_bf16 v[16:19], v[200:203], v[232:235], v[16:19]
	v_mfma_f32_16x16x32_bf16 v[12:15], v[208:211], v[224:227], v[12:15]
	v_mfma_f32_16x16x32_bf16 v[8:11], v[208:211], v[232:235], v[8:11]
	v_mfma_f32_16x16x32_bf16 v[4:7], v[216:219], v[224:227], v[4:7]
	v_mfma_f32_16x16x32_bf16 v[0:3], v[216:219], v[232:235], v[0:3]
	s_add_i32 s50, s50, 2
	s_add_u32 s48, s48, 0x100
	s_addc_u32 s49, s49, 0
	s_cmp_gt_u32 s50, 27
	s_barrier
	s_cbranch_scc0 .LBB0_340
	s_add_i32 s48, s46, 0x80
	s_mul_hi_i32 s49, s48, 0x1080
	s_mulk_i32 s48, 0x1080
	s_add_u32 s48, s31, s48
	s_addc_u32 s49, s56, s49
	v_lshl_add_u64 v[158:159], s[48:49], 0, v[128:129]
	v_readfirstlane_b32 s50, v170
	v_lshl_add_u64 v[158:159], v[158:159], 0, s[44:45]
	s_mov_b32 m0, s50
	ds_read_b128 v[134:137], v162
	ds_read_b128 v[138:141], v162 offset:1024
	ds_read_b128 v[172:175], v162 offset:2048
	ds_read_b128 v[176:179], v162 offset:3072
	ds_read_b128 v[180:183], v153
	ds_read_b128 v[184:187], v153 offset:1024
	ds_read_b128 v[188:191], v152
	ds_read_b128 v[192:195], v152 offset:1024
	ds_read_b128 v[196:199], v151
	ds_read_b128 v[200:203], v151 offset:1024
	ds_read_b128 v[204:207], v150
	ds_read_b128 v[208:211], v150 offset:1024
	global_load_lds_dwordx4 v[158:159], off
	v_lshl_add_u64 v[158:159], s[48:49], 0, v[132:133]
	v_readfirstlane_b32 s48, v171
	v_lshl_add_u64 v[158:159], v[158:159], 0, s[44:45]
	s_mov_b32 m0, s48
	s_nop 0
	global_load_lds_dwordx4 v[158:159], off
	s_barrier
	s_waitcnt lgkmcnt(0)
	s_waitcnt lgkmcnt(0)
	v_mfma_f32_16x16x32_bf16 v[124:127], v[180:183], v[134:137], v[124:127]
	v_mfma_f32_16x16x32_bf16 v[120:123], v[180:183], v[172:175], v[120:123]
	v_mfma_f32_16x16x32_bf16 v[116:119], v[188:191], v[134:137], v[116:119]
	v_mfma_f32_16x16x32_bf16 v[112:115], v[188:191], v[172:175], v[112:115]
	v_mfma_f32_16x16x32_bf16 v[108:111], v[196:199], v[134:137], v[108:111]
	v_mfma_f32_16x16x32_bf16 v[104:107], v[196:199], v[172:175], v[104:107]
	v_mfma_f32_16x16x32_bf16 v[100:103], v[204:207], v[134:137], v[100:103]
	v_mfma_f32_16x16x32_bf16 v[96:99], v[204:207], v[172:175], v[96:99]
	v_mfma_f32_16x16x32_bf16 v[124:127], v[184:187], v[138:141], v[124:127]
	v_mfma_f32_16x16x32_bf16 v[120:123], v[184:187], v[176:179], v[120:123]
	v_mfma_f32_16x16x32_bf16 v[116:119], v[192:195], v[138:141], v[116:119]
	v_mfma_f32_16x16x32_bf16 v[112:115], v[192:195], v[176:179], v[112:115]
	v_mfma_f32_16x16x32_bf16 v[108:111], v[200:203], v[138:141], v[108:111]
	v_mfma_f32_16x16x32_bf16 v[104:107], v[200:203], v[176:179], v[104:107]
	v_mfma_f32_16x16x32_bf16 v[100:103], v[208:211], v[138:141], v[100:103]
	v_mfma_f32_16x16x32_bf16 v[96:99], v[208:211], v[176:179], v[96:99]
	s_barrier
	ds_read_b128 v[212:215], v161
	ds_read_b128 v[216:219], v161 offset:1024
	ds_read_b128 v[220:223], v161 offset:2048
	ds_read_b128 v[158:161], v161 offset:3072
	s_barrier
; #define LDA(dst, b, h) for (int m = 0; m < 4; ++m) for (int k = 0; k < 2; ++k) \
;     dst[m][k] = *reinterpret_cast<const bf16x8*>((char*)SA(b, h) + lds_byte(wr * 64 + m * 16 + fr, k * 32 + fq * 8))
; #define LDB(dst, b, h) for (int n = 0; n < 2; ++n) for (int k = 0; k < 2; ++k) \
;     dst[n][k] = *reinterpret_cast<const bf16x8*>((char*)SB(b, h) + lds_byte(wc * 32 + n * 16 + fr, k * 32 + fq * 8))
; #define MMA(ai, bj, At_, Bt_) do { __builtin_amdgcn_s_setprio(1); \
;     for (int k = 0; k < 2; ++k) for (int m = 0; m < 4; ++m) for (int n = 0; n < 2; ++n) \
;       acc[ai][bj][m][n] = __builtin_amdgcn_mfma_f32_16x16x32_bf16(At_[m][k], Bt_[n][k], acc[ai][bj][m][n], 0, 0, 0); \
;     __builtin_amdgcn_s_setprio(0); } while (0)
; #define WAIT_V(n) asm volatile("s_waitcnt vmcnt(" #n ")" ::: "memory")
; #define WAIT_L(n) asm volatile("s_waitcnt lgkmcnt(" #n ")" ::: "memory")
; #define BAR __builtin_amdgcn_s_barrier()
; template <int EPI, int lda, int ldb, int N, int K>
; __device__ __forceinline__ void gemm_phase(const u16* __restrict__ A, const u16* __restrict__ Bt, const GemmEpi ep, int wv) {
;     ...
;       LDB(B1, 0, 1); BAR; WAIT_L(0); MMA(0, 1, At, B1); BAR;
;       LDA(At, 0, 1); WAIT_V(4); BAR; WAIT_L(0); MMA(1, 0, At, B0); MMA(1, 1, At, B1); BAR; }
;     { LDB(B0, 1, 0); LDA(At, 1, 0); WAIT_V(2); BAR; WAIT_L(0); MMA(0, 0, At, B0); BAR;
	s_waitcnt lgkmcnt(0)
	s_waitcnt lgkmcnt(0)
	v_mfma_f32_16x16x32_bf16 v[92:95], v[180:183], v[212:215], v[92:95]
	v_mfma_f32_16x16x32_bf16 v[88:91], v[180:183], v[220:223], v[88:91]
	v_mfma_f32_16x16x32_bf16 v[76:79], v[196:199], v[212:215], v[76:79]
	v_mfma_f32_16x16x32_bf16 v[72:75], v[196:199], v[220:223], v[72:75]
	v_mfma_f32_16x16x32_bf16 v[68:71], v[204:207], v[212:215], v[68:71]
	v_mfma_f32_16x16x32_bf16 v[64:67], v[204:207], v[220:223], v[64:67]
	v_mfma_f32_16x16x32_bf16 v[84:87], v[188:191], v[212:215], v[84:87]
	v_mfma_f32_16x16x32_bf16 v[80:83], v[188:191], v[220:223], v[80:83]
	v_mfma_f32_16x16x32_bf16 v[92:95], v[184:187], v[216:219], v[92:95]
	v_mfma_f32_16x16x32_bf16 v[88:91], v[184:187], v[158:161], v[88:91]
	v_mfma_f32_16x16x32_bf16 v[76:79], v[200:203], v[216:219], v[76:79]
	v_mfma_f32_16x16x32_bf16 v[72:75], v[200:203], v[158:161], v[72:75]
	v_mfma_f32_16x16x32_bf16 v[68:71], v[208:211], v[216:219], v[68:71]
	v_mfma_f32_16x16x32_bf16 v[64:67], v[208:211], v[158:161], v[64:67]
	v_mfma_f32_16x16x32_bf16 v[180:183], v[192:195], v[216:219], v[84:87]
	v_mfma_f32_16x16x32_bf16 v[184:187], v[192:195], v[158:161], v[80:83]
	s_barrier
	s_nop 0
	ds_read_b128 v[80:83], v153 offset:16384
	ds_read_b128 v[84:87], v153 offset:17408
	ds_read_b128 v[188:191], v152 offset:16384
	ds_read_b128 v[192:195], v152 offset:17408
	ds_read_b128 v[196:199], v151 offset:16384
	ds_read_b128 v[200:203], v151 offset:17408
	ds_read_b128 v[204:207], v150 offset:16384
	ds_read_b128 v[208:211], v150 offset:17408
	s_waitcnt vmcnt(4)
	s_barrier
	s_waitcnt lgkmcnt(0)
	s_waitcnt lgkmcnt(0)
	v_mfma_f32_16x16x32_bf16 v[60:63], v[80:83], v[134:137], v[60:63]
	v_mfma_f32_16x16x32_bf16 v[44:47], v[196:199], v[134:137], v[44:47]
	v_mfma_f32_16x16x32_bf16 v[40:43], v[196:199], v[172:175], v[40:43]
	v_mfma_f32_16x16x32_bf16 v[36:39], v[204:207], v[134:137], v[36:39]
	v_mfma_f32_16x16x32_bf16 v[32:35], v[204:207], v[172:175], v[32:35]
	v_mfma_f32_16x16x32_bf16 v[56:59], v[80:83], v[172:175], v[56:59]
	v_mfma_f32_16x16x32_bf16 v[52:55], v[188:191], v[134:137], v[52:55]
	v_mfma_f32_16x16x32_bf16 v[48:51], v[188:191], v[172:175], v[48:51]
	v_mfma_f32_16x16x32_bf16 v[60:63], v[84:87], v[138:141], v[60:63]
	v_mfma_f32_16x16x32_bf16 v[44:47], v[200:203], v[138:141], v[44:47]
	v_mfma_f32_16x16x32_bf16 v[40:43], v[200:203], v[176:179], v[40:43]
	v_mfma_f32_16x16x32_bf16 v[36:39], v[208:211], v[138:141], v[36:39]
	v_mfma_f32_16x16x32_bf16 v[32:35], v[208:211], v[176:179], v[32:35]
	v_mfma_f32_16x16x32_bf16 v[134:137], v[84:87], v[176:179], v[56:59]
	v_mfma_f32_16x16x32_bf16 v[170:173], v[192:195], v[138:141], v[52:55]
	v_mfma_f32_16x16x32_bf16 v[224:227], v[192:195], v[176:179], v[48:51]
	v_mfma_f32_16x16x32_bf16 v[28:31], v[80:83], v[212:215], v[28:31]
	v_mfma_f32_16x16x32_bf16 v[20:23], v[188:191], v[212:215], v[20:23]
	v_mfma_f32_16x16x32_bf16 v[12:15], v[196:199], v[212:215], v[12:15]
	v_mfma_f32_16x16x32_bf16 v[4:7], v[204:207], v[212:215], v[4:7]
	v_mfma_f32_16x16x32_bf16 v[24:27], v[80:83], v[220:223], v[24:27]
	v_mfma_f32_16x16x32_bf16 v[16:19], v[188:191], v[220:223], v[16:19]
	v_mfma_f32_16x16x32_bf16 v[8:11], v[196:199], v[220:223], v[8:11]
	v_mfma_f32_16x16x32_bf16 v[0:3], v[204:207], v[220:223], v[0:3]
	v_mfma_f32_16x16x32_bf16 v[28:31], v[84:87], v[216:219], v[28:31]
	v_mfma_f32_16x16x32_bf16 v[20:23], v[192:195], v[216:219], v[20:23]
	v_mfma_f32_16x16x32_bf16 v[12:15], v[200:203], v[216:219], v[12:15]
	v_mfma_f32_16x16x32_bf16 v[4:7], v[208:211], v[216:219], v[4:7]
	v_mfma_f32_16x16x32_bf16 v[138:141], v[84:87], v[158:161], v[24:27]
	v_mfma_f32_16x16x32_bf16 v[174:177], v[192:195], v[158:161], v[16:19]
	v_mfma_f32_16x16x32_bf16 v[188:191], v[200:203], v[158:161], v[8:11]
	v_mfma_f32_16x16x32_bf16 v[158:161], v[208:211], v[158:161], v[0:3]
	s_barrier
	s_nop 0
	ds_read_b128 v[0:3], v156
	ds_read_b128 v[8:11], v156 offset:1024
	ds_read_b128 v[16:19], v156 offset:2048
	ds_read_b128 v[192:195], v156 offset:3072
	ds_read_b128 v[24:27], v153 offset:32768
	ds_read_b128 v[56:59], v153 offset:33792
	ds_read_b128 v[196:199], v152 offset:32768
	ds_read_b128 v[200:203], v152 offset:33792
	ds_read_b128 v[204:207], v151 offset:32768
	ds_read_b128 v[208:211], v151 offset:33792
	ds_read_b128 v[212:215], v150 offset:32768
	ds_read_b128 v[216:219], v150 offset:33792
	s_waitcnt vmcnt(2)
	s_barrier
; #define LDA(dst, b, h) for (int m = 0; m < 4; ++m) for (int k = 0; k < 2; ++k) \
;     dst[m][k] = *reinterpret_cast<const bf16x8*>((char*)SA(b, h) + lds_byte(wr * 64 + m * 16 + fr, k * 32 + fq * 8))
; #define LDB(dst, b, h) for (int n = 0; n < 2; ++n) for (int k = 0; k < 2; ++k) \
;     dst[n][k] = *reinterpret_cast<const bf16x8*>((char*)SB(b, h) + lds_byte(wc * 32 + n * 16 + fr, k * 32 + fq * 8))
; #define MMA(ai, bj, At_, Bt_) do { __builtin_amdgcn_s_setprio(1); \
;     for (int k = 0; k < 2; ++k) for (int m = 0; m < 4; ++m) for (int n = 0; n < 2; ++n) \
;       acc[ai][bj][m][n] = __builtin_amdgcn_mfma_f32_16x16x32_bf16(At_[m][k], Bt_[n][k], acc[ai][bj][m][n], 0, 0, 0); \
;     __builtin_amdgcn_s_setprio(0); } while (0)
; #define WAIT_V(n) asm volatile("s_waitcnt vmcnt(" #n ")" ::: "memory")
; #define WAIT_L(n) asm volatile("s_waitcnt lgkmcnt(" #n ")" ::: "memory")
; #define BAR __builtin_amdgcn_s_barrier()
; template <int EPI, int lda, int ldb, int N, int K>
; __device__ __forceinline__ void gemm_phase(const u16* __restrict__ A, const u16* __restrict__ Bt, const GemmEpi ep, int wv) {
;     ...
;     { LDB(B0, 1, 0); LDA(At, 1, 0); WAIT_V(2); BAR; WAIT_L(0); MMA(0, 0, At, B0); BAR;
;       LDB(B1, 1, 1); WAIT_V(0); BAR; WAIT_L(0); MMA(0, 1, At, B1); BAR;
;       LDA(At, 1, 1); BAR; WAIT_L(0); MMA(1, 0, At, B0); MMA(1, 1, At, B1); BAR; }
;     if (wr == 0) BAR;
	s_waitcnt lgkmcnt(0)
	s_waitcnt lgkmcnt(0)
	v_mfma_f32_16x16x32_bf16 v[48:51], v[24:27], v[0:3], v[124:127]
	v_mfma_f32_16x16x32_bf16 v[52:55], v[24:27], v[16:19], v[120:123]
	v_mfma_f32_16x16x32_bf16 v[80:83], v[196:199], v[0:3], v[116:119]
	v_mfma_f32_16x16x32_bf16 v[84:87], v[196:199], v[16:19], v[112:115]
	v_mfma_f32_16x16x32_bf16 v[108:111], v[204:207], v[0:3], v[108:111]
	v_mfma_f32_16x16x32_bf16 v[104:107], v[204:207], v[16:19], v[104:107]
	v_mfma_f32_16x16x32_bf16 v[112:115], v[212:215], v[0:3], v[100:103]
	v_mfma_f32_16x16x32_bf16 v[120:123], v[212:215], v[16:19], v[96:99]
	v_mfma_f32_16x16x32_bf16 v[124:127], v[56:59], v[8:11], v[48:51]
	v_mfma_f32_16x16x32_bf16 v[116:119], v[56:59], v[192:195], v[52:55]
	v_mfma_f32_16x16x32_bf16 v[100:103], v[200:203], v[8:11], v[80:83]
	v_mfma_f32_16x16x32_bf16 v[96:99], v[200:203], v[192:195], v[84:87]
	v_mfma_f32_16x16x32_bf16 v[84:87], v[208:211], v[8:11], v[108:111]
	v_mfma_f32_16x16x32_bf16 v[80:83], v[208:211], v[192:195], v[104:107]
	v_mfma_f32_16x16x32_bf16 v[52:55], v[216:219], v[8:11], v[112:115]
	v_mfma_f32_16x16x32_bf16 v[48:51], v[216:219], v[192:195], v[120:123]
	s_barrier
	ds_read_b128 v[220:223], v154
	ds_read_b128 v[228:231], v154 offset:1024
	ds_read_b128 v[232:235], v154 offset:2048
	ds_read_b128 v[154:157], v154 offset:3072
	s_waitcnt vmcnt(0)
	s_barrier
	s_waitcnt lgkmcnt(0)
	s_waitcnt lgkmcnt(0)
	v_mfma_f32_16x16x32_bf16 v[92:95], v[24:27], v[220:223], v[92:95]
	v_mfma_f32_16x16x32_bf16 v[24:27], v[24:27], v[232:235], v[88:91]
	v_mfma_f32_16x16x32_bf16 v[88:91], v[196:199], v[220:223], v[180:183]
	v_mfma_f32_16x16x32_bf16 v[104:107], v[196:199], v[232:235], v[184:187]
	v_mfma_f32_16x16x32_bf16 v[76:79], v[204:207], v[220:223], v[76:79]
	v_mfma_f32_16x16x32_bf16 v[72:75], v[204:207], v[232:235], v[72:75]
	v_mfma_f32_16x16x32_bf16 v[68:71], v[212:215], v[220:223], v[68:71]
	v_mfma_f32_16x16x32_bf16 v[64:67], v[212:215], v[232:235], v[64:67]
	v_mfma_f32_16x16x32_bf16 v[120:123], v[56:59], v[228:231], v[92:95]
	v_mfma_f32_16x16x32_bf16 v[112:115], v[56:59], v[154:157], v[24:27]
	v_mfma_f32_16x16x32_bf16 v[108:111], v[200:203], v[228:231], v[88:91]
	v_mfma_f32_16x16x32_bf16 v[104:107], v[200:203], v[154:157], v[104:107]
	v_mfma_f32_16x16x32_bf16 v[92:95], v[208:211], v[228:231], v[76:79]
	v_mfma_f32_16x16x32_bf16 v[88:91], v[208:211], v[154:157], v[72:75]
	v_mfma_f32_16x16x32_bf16 v[68:71], v[216:219], v[228:231], v[68:71]
	v_mfma_f32_16x16x32_bf16 v[56:59], v[216:219], v[154:157], v[64:67]
	s_barrier
	s_nop 0
	ds_read_b128 v[64:67], v153 offset:49152
	ds_read_b128 v[178:181], v153 offset:50176
	ds_read_b128 v[76:79], v152 offset:49152
	ds_read_b128 v[182:185], v152 offset:50176
	ds_read_b128 v[196:199], v151 offset:49152
	ds_read_b128 v[200:203], v151 offset:50176
	ds_read_b128 v[204:207], v150 offset:49152
	ds_read_b128 v[150:153], v150 offset:50176
	s_barrier
	s_waitcnt lgkmcnt(0)
	s_waitcnt lgkmcnt(0)
	v_mfma_f32_16x16x32_bf16 v[24:27], v[64:67], v[0:3], v[60:63]
	v_mfma_f32_16x16x32_bf16 v[60:63], v[64:67], v[16:19], v[134:137]
	v_mfma_f32_16x16x32_bf16 v[134:137], v[76:79], v[0:3], v[170:173]
	v_mfma_f32_16x16x32_bf16 v[170:173], v[76:79], v[16:19], v[224:227]
	v_mfma_f32_16x16x32_bf16 v[44:47], v[196:199], v[0:3], v[44:47]
	v_mfma_f32_16x16x32_bf16 v[208:211], v[196:199], v[16:19], v[40:43]
	v_mfma_f32_16x16x32_bf16 v[0:3], v[204:207], v[0:3], v[36:39]
	v_mfma_f32_16x16x32_bf16 v[36:39], v[204:207], v[16:19], v[32:35]
	v_mfma_f32_16x16x32_bf16 v[72:75], v[178:181], v[8:11], v[24:27]
	v_mfma_f32_16x16x32_bf16 v[60:63], v[178:181], v[192:195], v[60:63]
	v_mfma_f32_16x16x32_bf16 v[40:43], v[182:185], v[8:11], v[134:137]
	v_mfma_f32_16x16x32_bf16 v[32:35], v[182:185], v[192:195], v[170:173]
	v_mfma_f32_16x16x32_bf16 v[24:27], v[200:203], v[8:11], v[44:47]
	v_mfma_f32_16x16x32_bf16 v[16:19], v[200:203], v[192:195], v[208:211]
	v_mfma_f32_16x16x32_bf16 v[8:11], v[150:153], v[8:11], v[0:3]
	v_mfma_f32_16x16x32_bf16 v[0:3], v[150:153], v[192:195], v[36:39]
	v_mfma_f32_16x16x32_bf16 v[28:31], v[64:67], v[220:223], v[28:31]
	v_mfma_f32_16x16x32_bf16 v[36:39], v[64:67], v[232:235], v[138:141]
	v_mfma_f32_16x16x32_bf16 v[20:23], v[76:79], v[220:223], v[20:23]
	v_mfma_f32_16x16x32_bf16 v[134:137], v[76:79], v[232:235], v[174:177]
	v_mfma_f32_16x16x32_bf16 v[12:15], v[196:199], v[220:223], v[12:15]
	v_mfma_f32_16x16x32_bf16 v[138:141], v[196:199], v[232:235], v[188:191]
	v_mfma_f32_16x16x32_bf16 v[4:7], v[204:207], v[220:223], v[4:7]
	v_mfma_f32_16x16x32_bf16 v[158:161], v[204:207], v[232:235], v[158:161]
	v_mfma_f32_16x16x32_bf16 v[76:79], v[178:181], v[228:231], v[28:31]
	v_mfma_f32_16x16x32_bf16 v[64:67], v[178:181], v[154:157], v[36:39]
	v_mfma_f32_16x16x32_bf16 v[44:47], v[182:185], v[228:231], v[20:23]
	v_mfma_f32_16x16x32_bf16 v[36:39], v[182:185], v[154:157], v[134:137]
	v_mfma_f32_16x16x32_bf16 v[28:31], v[200:203], v[228:231], v[12:15]
	v_mfma_f32_16x16x32_bf16 v[20:23], v[200:203], v[154:157], v[138:141]
	v_mfma_f32_16x16x32_bf16 v[12:15], v[150:153], v[228:231], v[4:7]
	v_mfma_f32_16x16x32_bf16 v[4:7], v[150:153], v[154:157], v[158:161]
	v_cmp_gt_u32_e32 vcc, s64, v130
	s_barrier
	s_and_saveexec_b64 s[48:49], vcc
	s_cbranch_execz .LBB0_343
	s_barrier

; #define STAGE(P, BASE, LD, br, kt) do { const char* _g = (const char*)((BASE) + (size_t)(br) * (LD) + (size_t)(kt) * 64); \
;     for (int _i = 0; _i < 2; ++_i) { int _b = tidx * 16 + _i * 8192; int _r, _c; stage_rc(_b, _r, _c); \
;       __builtin_amdgcn_global_load_lds((const unsigned*)(_g + (unsigned)((_r * (LD) + _c) * 2)), (unsigned*)((char*)(P) + _b), 16, 0, 0); } } while (0)
; #define LDA(dst, b, h) for (int m = 0; m < 4; ++m) for (int k = 0; k < 2; ++k) \
;     dst[m][k] = *reinterpret_cast<const bf16x8*>((char*)SA(b, h) + lds_byte(wr * 64 + m * 16 + fr, k * 32 + fq * 8))
; #define LDB(dst, b, h) for (int n = 0; n < 2; ++n) for (int k = 0; k < 2; ++k) \
;     dst[n][k] = *reinterpret_cast<const bf16x8*>((char*)SB(b, h) + lds_byte(wc * 32 + n * 16 + fr, k * 32 + fq * 8))
; #define MMA(ai, bj, At_, Bt_) do { __builtin_amdgcn_s_setprio(1); \
;     for (int k = 0; k < 2; ++k) for (int m = 0; m < 4; ++m) for (int n = 0; n < 2; ++n) \
;       acc[ai][bj][m][n] = __builtin_amdgcn_mfma_f32_16x16x32_bf16(At_[m][k], Bt_[n][k], acc[ai][bj][m][n], 0, 0, 0); \
;     __builtin_amdgcn_s_setprio(0); } while (0)
; #define WAIT_V(n) asm volatile("s_waitcnt vmcnt(" #n ")" ::: "memory")
; #define WAIT_L(n) asm volatile("s_waitcnt lgkmcnt(" #n ")" ::: "memory")
; #define BAR __builtin_amdgcn_s_barrier()
; #define SCHED __builtin_amdgcn_sched_barrier(0)
; template <int EPI, int lda, int ldb, int N, int K>
; __device__ __forceinline__ void gemm_phase(const u16* __restrict__ A, const u16* __restrict__ Bt, const GemmEpi ep, int wv) {
;     ...
;     for (int t = 0; t < nt - 2; t += 2) {
;       LDB(B0, 0, 0); SCHED; LDA(At, 0, 0); STAGE(SA(1, 1), Ab, lda, brow + HALF, t + 1);
;       WAIT_L(8); BAR; WAIT_L(0); MMA(0, 0, At, B0); BAR; SCHED;
;       LDB(B1, 0, 1); STAGE(SB(0, 0), Bt, ldb, bcol, t + 2);
;       BAR; WAIT_L(0); MMA(0, 1, At, B1); BAR;
;       LDA(At, 0, 1); STAGE(SA(0, 0), Ab, lda, brow, t + 2);
;       BAR; WAIT_L(0); MMA(1, 0, At, B0); BAR; SCHED;
;       STAGE(SB(0, 1), Bt, ldb, bcol + HALF, t + 2);
;       WAIT_V(6); BAR; MMA(1, 1, At, B1); BAR;
.LBB0_654:
	ds_read_b128 v[164:167], v160
	ds_read_b128 v[170:173], v160 offset:1024
	ds_read_b128 v[174:177], v160 offset:2048
	ds_read_b128 v[178:181], v160 offset:3072
	v_add_u32_e32 v168, 0xc000, v143
	v_lshl_add_u64 v[234:235], v[138:139], 0, s[52:53]
	v_readfirstlane_b32 s55, v168
	v_add_u32_e32 v169, 0xe000, v143
	v_lshl_add_u64 v[162:163], v[234:235], 0, s[20:21]
	s_mov_b32 m0, s55
	v_lshl_add_u64 v[236:237], v[140:141], 0, s[52:53]
	v_readfirstlane_b32 s55, v169
	ds_read_b128 v[182:185], v151
	ds_read_b128 v[186:189], v151 offset:1024
	ds_read_b128 v[190:193], v150
	ds_read_b128 v[194:197], v150 offset:1024
	ds_read_b128 v[198:201], v149
	ds_read_b128 v[202:205], v149 offset:1024
	ds_read_b128 v[206:209], v148
	ds_read_b128 v[210:213], v148 offset:1024
	global_load_lds_dwordx4 v[162:163], off
	v_lshl_add_u64 v[162:163], v[236:237], 0, s[20:21]
	s_mov_b32 m0, s55
	s_nop 0
	global_load_lds_dwordx4 v[162:163], off
	s_waitcnt lgkmcnt(8)
	s_barrier
	s_waitcnt lgkmcnt(0)
	s_waitcnt lgkmcnt(0)
	v_mfma_f32_16x16x32_bf16 v[124:127], v[164:167], v[182:185], v[124:127]
	ds_read_b128 v[214:217], v159
	v_mfma_f32_16x16x32_bf16 v[120:123], v[174:177], v[182:185], v[120:123]
	v_mfma_f32_16x16x32_bf16 v[116:119], v[164:167], v[190:193], v[116:119]
	ds_read_b128 v[218:221], v159 offset:1024
	v_mfma_f32_16x16x32_bf16 v[112:115], v[174:177], v[190:193], v[112:115]
	v_mfma_f32_16x16x32_bf16 v[108:111], v[164:167], v[198:201], v[108:111]
	ds_read_b128 v[222:225], v159 offset:2048
	v_mfma_f32_16x16x32_bf16 v[104:107], v[174:177], v[198:201], v[104:107]
	v_mfma_f32_16x16x32_bf16 v[100:103], v[164:167], v[206:209], v[100:103]
	ds_read_b128 v[226:229], v159 offset:3072
	v_mfma_f32_16x16x32_bf16 v[96:99], v[174:177], v[206:209], v[96:99]
	v_mfma_f32_16x16x32_bf16 v[124:127], v[170:173], v[186:189], v[124:127]
	v_mfma_f32_16x16x32_bf16 v[120:123], v[178:181], v[186:189], v[120:123]
	v_mfma_f32_16x16x32_bf16 v[116:119], v[170:173], v[194:197], v[116:119]
	v_mfma_f32_16x16x32_bf16 v[112:115], v[178:181], v[194:197], v[112:115]
	v_mfma_f32_16x16x32_bf16 v[108:111], v[170:173], v[202:205], v[108:111]
	v_mfma_f32_16x16x32_bf16 v[104:107], v[178:181], v[202:205], v[104:107]
	v_mfma_f32_16x16x32_bf16 v[100:103], v[170:173], v[210:213], v[100:103]
	v_mfma_f32_16x16x32_bf16 v[96:99], v[178:181], v[210:213], v[96:99]
	s_barrier
	v_add_u32_e32 v161, s65, v153
	v_lshl_add_u64 v[238:239], v[134:135], 0, s[52:53]
	v_readfirstlane_b32 s55, v161
	v_lshl_add_u64 v[162:163], v[238:239], 0, s[22:23]
	s_mov_b32 m0, s55
	global_load_lds_dwordx4 v[162:163], off
	v_add_u32_e32 v162, 0x2000, v161
	v_lshl_add_u64 v[240:241], v[136:137], 0, s[52:53]
	v_readfirstlane_b32 s55, v162
	v_lshl_add_u64 v[230:231], v[240:241], 0, s[22:23]
	s_mov_b32 m0, s55
	s_nop 0
	global_load_lds_dwordx4 v[230:231], off
	s_barrier
	s_waitcnt lgkmcnt(0)
	s_waitcnt lgkmcnt(0)
	v_mfma_f32_16x16x32_bf16 v[92:95], v[214:217], v[182:185], v[92:95]
	v_mfma_f32_16x16x32_bf16 v[88:91], v[222:225], v[182:185], v[88:91]
	v_mfma_f32_16x16x32_bf16 v[84:87], v[214:217], v[190:193], v[84:87]
	v_mfma_f32_16x16x32_bf16 v[80:83], v[222:225], v[190:193], v[80:83]
	v_mfma_f32_16x16x32_bf16 v[76:79], v[214:217], v[198:201], v[76:79]
	v_mfma_f32_16x16x32_bf16 v[72:75], v[222:225], v[198:201], v[72:75]
	v_mfma_f32_16x16x32_bf16 v[68:71], v[214:217], v[206:209], v[68:71]
	v_mfma_f32_16x16x32_bf16 v[64:67], v[222:225], v[206:209], v[64:67]
	v_mfma_f32_16x16x32_bf16 v[92:95], v[218:221], v[186:189], v[92:95]
	v_mfma_f32_16x16x32_bf16 v[88:91], v[226:229], v[186:189], v[88:91]
	v_mfma_f32_16x16x32_bf16 v[84:87], v[218:221], v[194:197], v[84:87]
	v_mfma_f32_16x16x32_bf16 v[80:83], v[226:229], v[194:197], v[80:83]
	v_mfma_f32_16x16x32_bf16 v[76:79], v[218:221], v[202:205], v[76:79]
	v_mfma_f32_16x16x32_bf16 v[72:75], v[226:229], v[202:205], v[72:75]
	v_mfma_f32_16x16x32_bf16 v[68:71], v[218:221], v[210:213], v[68:71]
	v_mfma_f32_16x16x32_bf16 v[64:67], v[226:229], v[210:213], v[64:67]
	v_readfirstlane_b32 s55, v143
	v_add_u32_e32 v163, 0x2000, v143
	v_lshl_add_u64 v[230:231], v[234:235], 0, s[24:25]
	s_mov_b32 m0, s55
	v_readfirstlane_b32 s55, v163
	s_barrier
	ds_read_b128 v[182:185], v151 offset:16384
	ds_read_b128 v[186:189], v151 offset:17408
	ds_read_b128 v[190:193], v150 offset:16384
	ds_read_b128 v[194:197], v150 offset:17408
	ds_read_b128 v[198:201], v149 offset:16384
	ds_read_b128 v[202:205], v149 offset:17408
	ds_read_b128 v[206:209], v148 offset:16384
	ds_read_b128 v[210:213], v148 offset:17408
	global_load_lds_dwordx4 v[230:231], off
	v_lshl_add_u64 v[230:231], v[236:237], 0, s[24:25]
	s_mov_b32 m0, s55
	s_nop 0
	global_load_lds_dwordx4 v[230:231], off
	s_barrier
	s_waitcnt lgkmcnt(0)
	s_waitcnt lgkmcnt(0)
	v_mfma_f32_16x16x32_bf16 v[60:63], v[164:167], v[182:185], v[60:63]
	v_mfma_f32_16x16x32_bf16 v[56:59], v[174:177], v[182:185], v[56:59]
	v_mfma_f32_16x16x32_bf16 v[52:55], v[164:167], v[190:193], v[52:55]
	v_mfma_f32_16x16x32_bf16 v[48:51], v[174:177], v[190:193], v[48:51]
	v_mfma_f32_16x16x32_bf16 v[44:47], v[164:167], v[198:201], v[44:47]
	v_mfma_f32_16x16x32_bf16 v[40:43], v[174:177], v[198:201], v[40:43]
	v_mfma_f32_16x16x32_bf16 v[36:39], v[164:167], v[206:209], v[36:39]
	v_mfma_f32_16x16x32_bf16 v[32:35], v[174:177], v[206:209], v[32:35]
	v_mfma_f32_16x16x32_bf16 v[60:63], v[170:173], v[186:189], v[60:63]
	v_mfma_f32_16x16x32_bf16 v[56:59], v[178:181], v[186:189], v[56:59]
	v_mfma_f32_16x16x32_bf16 v[52:55], v[170:173], v[194:197], v[52:55]
	v_mfma_f32_16x16x32_bf16 v[48:51], v[178:181], v[194:197], v[48:51]
	v_mfma_f32_16x16x32_bf16 v[44:47], v[170:173], v[202:205], v[44:47]
	v_mfma_f32_16x16x32_bf16 v[40:43], v[178:181], v[202:205], v[40:43]
	v_mfma_f32_16x16x32_bf16 v[36:39], v[170:173], v[210:213], v[36:39]
	v_mfma_f32_16x16x32_bf16 v[32:35], v[178:181], v[210:213], v[32:35]
	s_barrier
; #define STAGE(P, BASE, LD, br, kt) do { const char* _g = (const char*)((BASE) + (size_t)(br) * (LD) + (size_t)(kt) * 64); \
;     for (int _i = 0; _i < 2; ++_i) { int _b = tidx * 16 + _i * 8192; int _r, _c; stage_rc(_b, _r, _c); \
;       __builtin_amdgcn_global_load_lds((const unsigned*)(_g + (unsigned)((_r * (LD) + _c) * 2)), (unsigned*)((char*)(P) + _b), 16, 0, 0); } } while (0)
; #define LDA(dst, b, h) for (int m = 0; m < 4; ++m) for (int k = 0; k < 2; ++k) \
;     dst[m][k] = *reinterpret_cast<const bf16x8*>((char*)SA(b, h) + lds_byte(wr * 64 + m * 16 + fr, k * 32 + fq * 8))
; #define LDB(dst, b, h) for (int n = 0; n < 2; ++n) for (int k = 0; k < 2; ++k) \
;     dst[n][k] = *reinterpret_cast<const bf16x8*>((char*)SB(b, h) + lds_byte(wc * 32 + n * 16 + fr, k * 32 + fq * 8))
; #define MMA(ai, bj, At_, Bt_) do { __builtin_amdgcn_s_setprio(1); \
;     for (int k = 0; k < 2; ++k) for (int m = 0; m < 4; ++m) for (int n = 0; n < 2; ++n) \
;       acc[ai][bj][m][n] = __builtin_amdgcn_mfma_f32_16x16x32_bf16(At_[m][k], Bt_[n][k], acc[ai][bj][m][n], 0, 0, 0); \
;     __builtin_amdgcn_s_setprio(0); } while (0)
; #define WAIT_V(n) asm volatile("s_waitcnt vmcnt(" #n ")" ::: "memory")
; #define WAIT_L(n) asm volatile("s_waitcnt lgkmcnt(" #n ")" ::: "memory")
; #define BAR __builtin_amdgcn_s_barrier()
; #define SCHED __builtin_amdgcn_sched_barrier(0)
; template <int EPI, int lda, int ldb, int N, int K>
; __device__ __forceinline__ void gemm_phase(const u16* __restrict__ A, const u16* __restrict__ Bt, const GemmEpi ep, int wv) {
;     ...
;       WAIT_V(6); BAR; MMA(1, 1, At, B1); BAR;
;       LDB(B0, 1, 0); SCHED; LDA(At, 1, 0); STAGE(SA(0, 1), Ab, lda, brow + HALF, t + 2);
;       WAIT_L(8); BAR; WAIT_L(0); MMA(0, 0, At, B0); BAR; SCHED;
;       LDB(B1, 1, 1); STAGE(SB(1, 0), Bt, ldb, bcol, t + 3);
;       BAR; WAIT_L(0); MMA(0, 1, At, B1); BAR;
;       LDA(At, 1, 1); STAGE(SA(1, 0), Ab, lda, brow, t + 3);
;       BAR; WAIT_L(0); MMA(1, 0, At, B0); BAR; SCHED;
	v_add_u32_e32 v164, s66, v153
	v_add_u32_e32 v165, 0x2000, v164
	v_readfirstlane_b32 s55, v164
	v_lshl_add_u64 v[166:167], v[238:239], 0, s[26:27]
	s_mov_b32 m0, s55
	v_readfirstlane_b32 s55, v165
	global_load_lds_dwordx4 v[166:167], off
	v_lshl_add_u64 v[166:167], v[240:241], 0, s[26:27]
	s_mov_b32 m0, s55
	s_nop 0
	global_load_lds_dwordx4 v[166:167], off
	s_waitcnt vmcnt(6)
	s_barrier
	v_mfma_f32_16x16x32_bf16 v[28:31], v[214:217], v[182:185], v[28:31]
	v_mfma_f32_16x16x32_bf16 v[24:27], v[222:225], v[182:185], v[24:27]
	ds_read_b128 v[170:173], v154
	v_mfma_f32_16x16x32_bf16 v[20:23], v[214:217], v[190:193], v[20:23]
	v_mfma_f32_16x16x32_bf16 v[16:19], v[222:225], v[190:193], v[16:19]
	ds_read_b128 v[174:177], v154 offset:1024
	v_mfma_f32_16x16x32_bf16 v[12:15], v[214:217], v[198:201], v[12:15]
	v_mfma_f32_16x16x32_bf16 v[8:11], v[222:225], v[198:201], v[8:11]
	ds_read_b128 v[178:181], v154 offset:2048
	v_mfma_f32_16x16x32_bf16 v[4:7], v[214:217], v[206:209], v[4:7]
	v_mfma_f32_16x16x32_bf16 v[0:3], v[222:225], v[206:209], v[0:3]
	ds_read_b128 v[182:185], v154 offset:3072
	v_mfma_f32_16x16x32_bf16 v[28:31], v[218:221], v[186:189], v[28:31]
	v_mfma_f32_16x16x32_bf16 v[24:27], v[226:229], v[186:189], v[24:27]
	v_mfma_f32_16x16x32_bf16 v[20:23], v[218:221], v[194:197], v[20:23]
	v_mfma_f32_16x16x32_bf16 v[16:19], v[226:229], v[194:197], v[16:19]
	v_mfma_f32_16x16x32_bf16 v[12:15], v[218:221], v[202:205], v[12:15]
	v_mfma_f32_16x16x32_bf16 v[8:11], v[226:229], v[202:205], v[8:11]
	v_mfma_f32_16x16x32_bf16 v[4:7], v[218:221], v[210:213], v[4:7]
	v_mfma_f32_16x16x32_bf16 v[0:3], v[226:229], v[210:213], v[0:3]
	s_barrier
	v_add_u32_e32 v166, 0x4000, v143
	v_add_u32_e32 v167, 0x6000, v143
	v_readfirstlane_b32 s55, v166
	v_lshl_add_u64 v[218:219], v[234:235], 0, s[42:43]
	s_mov_b32 m0, s55
	v_readfirstlane_b32 s55, v167
	ds_read_b128 v[186:189], v151 offset:32768
	ds_read_b128 v[190:193], v151 offset:33792
	ds_read_b128 v[194:197], v150 offset:32768
	ds_read_b128 v[198:201], v150 offset:33792
	ds_read_b128 v[202:205], v149 offset:32768
	ds_read_b128 v[206:209], v149 offset:33792
	ds_read_b128 v[210:213], v148 offset:32768
	ds_read_b128 v[214:217], v148 offset:33792
	global_load_lds_dwordx4 v[218:219], off
	v_lshl_add_u64 v[218:219], v[236:237], 0, s[42:43]
	s_mov_b32 m0, s55
	s_nop 0
	global_load_lds_dwordx4 v[218:219], off
	s_waitcnt lgkmcnt(8)
	s_barrier
	s_waitcnt lgkmcnt(0)
	s_waitcnt lgkmcnt(0)
	v_mfma_f32_16x16x32_bf16 v[124:127], v[170:173], v[186:189], v[124:127]
	ds_read_b128 v[218:221], v152
	v_mfma_f32_16x16x32_bf16 v[120:123], v[178:181], v[186:189], v[120:123]
	v_mfma_f32_16x16x32_bf16 v[116:119], v[170:173], v[194:197], v[116:119]
	ds_read_b128 v[222:225], v152 offset:1024
	v_mfma_f32_16x16x32_bf16 v[112:115], v[178:181], v[194:197], v[112:115]
	v_mfma_f32_16x16x32_bf16 v[108:111], v[170:173], v[202:205], v[108:111]
	ds_read_b128 v[226:229], v152 offset:2048
	v_mfma_f32_16x16x32_bf16 v[104:107], v[178:181], v[202:205], v[104:107]
	v_mfma_f32_16x16x32_bf16 v[100:103], v[170:173], v[210:213], v[100:103]
	ds_read_b128 v[230:233], v152 offset:3072
	v_mfma_f32_16x16x32_bf16 v[96:99], v[178:181], v[210:213], v[96:99]
	v_mfma_f32_16x16x32_bf16 v[124:127], v[174:177], v[190:193], v[124:127]
	v_mfma_f32_16x16x32_bf16 v[120:123], v[182:185], v[190:193], v[120:123]
	v_mfma_f32_16x16x32_bf16 v[116:119], v[174:177], v[198:201], v[116:119]
	v_mfma_f32_16x16x32_bf16 v[112:115], v[182:185], v[198:201], v[112:115]
	v_mfma_f32_16x16x32_bf16 v[108:111], v[174:177], v[206:209], v[108:111]
	v_mfma_f32_16x16x32_bf16 v[104:107], v[182:185], v[206:209], v[104:107]
	v_mfma_f32_16x16x32_bf16 v[100:103], v[174:177], v[214:217], v[100:103]
	v_mfma_f32_16x16x32_bf16 v[96:99], v[182:185], v[214:217], v[96:99]
	s_barrier
	v_readfirstlane_b32 s55, v155
	v_add_u32_e32 v244, 0x2000, v155
	v_lshl_add_u64 v[242:243], v[238:239], 0, s[44:45]
	s_mov_b32 m0, s55
	v_readfirstlane_b32 s55, v244
	global_load_lds_dwordx4 v[242:243], off
	v_lshl_add_u64 v[242:243], v[240:241], 0, s[44:45]
	s_mov_b32 m0, s55
	s_nop 0
	global_load_lds_dwordx4 v[242:243], off
	s_barrier
	s_waitcnt lgkmcnt(0)
	s_waitcnt lgkmcnt(0)
	v_mfma_f32_16x16x32_bf16 v[92:95], v[218:221], v[186:189], v[92:95]
	v_mfma_f32_16x16x32_bf16 v[88:91], v[226:229], v[186:189], v[88:91]
	v_mfma_f32_16x16x32_bf16 v[84:87], v[218:221], v[194:197], v[84:87]
	v_mfma_f32_16x16x32_bf16 v[80:83], v[226:229], v[194:197], v[80:83]
	v_mfma_f32_16x16x32_bf16 v[76:79], v[218:221], v[202:205], v[76:79]
	v_mfma_f32_16x16x32_bf16 v[72:75], v[226:229], v[202:205], v[72:75]
	v_mfma_f32_16x16x32_bf16 v[68:71], v[218:221], v[210:213], v[68:71]
	v_mfma_f32_16x16x32_bf16 v[64:67], v[226:229], v[210:213], v[64:67]
	v_mfma_f32_16x16x32_bf16 v[92:95], v[222:225], v[190:193], v[92:95]
	v_mfma_f32_16x16x32_bf16 v[88:91], v[230:233], v[190:193], v[88:91]
	v_mfma_f32_16x16x32_bf16 v[84:87], v[222:225], v[198:201], v[84:87]
	v_mfma_f32_16x16x32_bf16 v[80:83], v[230:233], v[198:201], v[80:83]
	v_mfma_f32_16x16x32_bf16 v[76:79], v[222:225], v[206:209], v[76:79]
	v_mfma_f32_16x16x32_bf16 v[72:75], v[230:233], v[206:209], v[72:75]
	v_mfma_f32_16x16x32_bf16 v[68:71], v[222:225], v[214:217], v[68:71]
	v_mfma_f32_16x16x32_bf16 v[64:67], v[230:233], v[214:217], v[64:67]
	v_readfirstlane_b32 s55, v156
	v_lshl_add_u64 v[234:235], v[234:235], 0, s[46:47]
	s_mov_b32 m0, s55
	v_readfirstlane_b32 s55, v157
	s_barrier
; #define STAGE(P, BASE, LD, br, kt) do { const char* _g = (const char*)((BASE) + (size_t)(br) * (LD) + (size_t)(kt) * 64); \
;     for (int _i = 0; _i < 2; ++_i) { int _b = tidx * 16 + _i * 8192; int _r, _c; stage_rc(_b, _r, _c); \
;       __builtin_amdgcn_global_load_lds((const unsigned*)(_g + (unsigned)((_r * (LD) + _c) * 2)), (unsigned*)((char*)(P) + _b), 16, 0, 0); } } while (0)
; #define LDA(dst, b, h) for (int m = 0; m < 4; ++m) for (int k = 0; k < 2; ++k) \
;     dst[m][k] = *reinterpret_cast<const bf16x8*>((char*)SA(b, h) + lds_byte(wr * 64 + m * 16 + fr, k * 32 + fq * 8))
; #define LDB(dst, b, h) for (int n = 0; n < 2; ++n) for (int k = 0; k < 2; ++k) \
;     dst[n][k] = *reinterpret_cast<const bf16x8*>((char*)SB(b, h) + lds_byte(wc * 32 + n * 16 + fr, k * 32 + fq * 8))
; #define MMA(ai, bj, At_, Bt_) do { __builtin_amdgcn_s_setprio(1); \
;     for (int k = 0; k < 2; ++k) for (int m = 0; m < 4; ++m) for (int n = 0; n < 2; ++n) \
;       acc[ai][bj][m][n] = __builtin_amdgcn_mfma_f32_16x16x32_bf16(At_[m][k], Bt_[n][k], acc[ai][bj][m][n], 0, 0, 0); \
;     __builtin_amdgcn_s_setprio(0); } while (0)
; #define WAIT_V(n) asm volatile("s_waitcnt vmcnt(" #n ")" ::: "memory")
; #define WAIT_L(n) asm volatile("s_waitcnt lgkmcnt(" #n ")" ::: "memory")
; #define BAR __builtin_amdgcn_s_barrier()
; #define SCHED __builtin_amdgcn_sched_barrier(0)
; template <int EPI, int lda, int ldb, int N, int K>
; __device__ __forceinline__ void gemm_phase(const u16* __restrict__ A, const u16* __restrict__ Bt, const GemmEpi ep, int wv) {
;     ...
;       LDA(At, 1, 1); STAGE(SA(1, 0), Ab, lda, brow, t + 3);
;       BAR; WAIT_L(0); MMA(1, 0, At, B0); BAR; SCHED;
;       STAGE(SB(1, 1), Bt, ldb, bcol + HALF, t + 3);
;       WAIT_V(6); BAR; MMA(1, 1, At, B1); BAR;
;     }
;     { LDB(B0, 0, 0); LDA(At, 0, 0); STAGE(SA(1, 1), Ab, lda, brow + HALF, nt - 1);
;       BAR; WAIT_L(0); MMA(0, 0, At, B0); BAR;
	ds_read_b128 v[186:189], v151 offset:49152
	ds_read_b128 v[190:193], v151 offset:50176
	ds_read_b128 v[194:197], v150 offset:49152
	ds_read_b128 v[198:201], v150 offset:50176
	ds_read_b128 v[202:205], v149 offset:49152
	ds_read_b128 v[206:209], v149 offset:50176
	ds_read_b128 v[210:213], v148 offset:49152
	ds_read_b128 v[214:217], v148 offset:50176
	global_load_lds_dwordx4 v[234:235], off
	v_lshl_add_u64 v[234:235], v[236:237], 0, s[46:47]
	s_mov_b32 m0, s55
	s_nop 0
	global_load_lds_dwordx4 v[234:235], off
	s_barrier
	s_waitcnt lgkmcnt(0)
	s_waitcnt lgkmcnt(0)
	v_mfma_f32_16x16x32_bf16 v[60:63], v[170:173], v[186:189], v[60:63]
	v_mfma_f32_16x16x32_bf16 v[56:59], v[178:181], v[186:189], v[56:59]
	v_mfma_f32_16x16x32_bf16 v[52:55], v[170:173], v[194:197], v[52:55]
	v_mfma_f32_16x16x32_bf16 v[48:51], v[178:181], v[194:197], v[48:51]
	v_mfma_f32_16x16x32_bf16 v[44:47], v[170:173], v[202:205], v[44:47]
	v_mfma_f32_16x16x32_bf16 v[40:43], v[178:181], v[202:205], v[40:43]
	v_mfma_f32_16x16x32_bf16 v[36:39], v[170:173], v[210:213], v[36:39]
	v_mfma_f32_16x16x32_bf16 v[32:35], v[178:181], v[210:213], v[32:35]
	v_mfma_f32_16x16x32_bf16 v[60:63], v[174:177], v[190:193], v[60:63]
	v_mfma_f32_16x16x32_bf16 v[56:59], v[182:185], v[190:193], v[56:59]
	v_mfma_f32_16x16x32_bf16 v[52:55], v[174:177], v[198:201], v[52:55]
	v_mfma_f32_16x16x32_bf16 v[48:51], v[182:185], v[198:201], v[48:51]
	v_mfma_f32_16x16x32_bf16 v[44:47], v[174:177], v[206:209], v[44:47]
	v_mfma_f32_16x16x32_bf16 v[40:43], v[182:185], v[206:209], v[40:43]
	v_mfma_f32_16x16x32_bf16 v[36:39], v[174:177], v[214:217], v[36:39]
	v_mfma_f32_16x16x32_bf16 v[32:35], v[182:185], v[214:217], v[32:35]
	s_barrier
	v_readfirstlane_b32 s55, v158
	v_add_u32_e32 v172, 0x2000, v158
	v_lshl_add_u64 v[170:171], v[238:239], 0, s[48:49]
	s_mov_b32 m0, s55
	v_readfirstlane_b32 s55, v172
	global_load_lds_dwordx4 v[170:171], off
	v_lshl_add_u64 v[170:171], v[240:241], 0, s[48:49]
	s_mov_b32 m0, s55
	s_nop 0
	global_load_lds_dwordx4 v[170:171], off
	s_waitcnt vmcnt(6)
	s_barrier
	v_mfma_f32_16x16x32_bf16 v[28:31], v[218:221], v[186:189], v[28:31]
	v_mfma_f32_16x16x32_bf16 v[24:27], v[226:229], v[186:189], v[24:27]
	v_mfma_f32_16x16x32_bf16 v[20:23], v[218:221], v[194:197], v[20:23]
	v_mfma_f32_16x16x32_bf16 v[16:19], v[226:229], v[194:197], v[16:19]
	v_mfma_f32_16x16x32_bf16 v[12:15], v[218:221], v[202:205], v[12:15]
	v_mfma_f32_16x16x32_bf16 v[8:11], v[226:229], v[202:205], v[8:11]
	v_mfma_f32_16x16x32_bf16 v[4:7], v[218:221], v[210:213], v[4:7]
	v_mfma_f32_16x16x32_bf16 v[0:3], v[226:229], v[210:213], v[0:3]
	v_mfma_f32_16x16x32_bf16 v[28:31], v[222:225], v[190:193], v[28:31]
	v_mfma_f32_16x16x32_bf16 v[24:27], v[230:233], v[190:193], v[24:27]
	v_mfma_f32_16x16x32_bf16 v[20:23], v[222:225], v[198:201], v[20:23]
	v_mfma_f32_16x16x32_bf16 v[16:19], v[230:233], v[198:201], v[16:19]
	v_mfma_f32_16x16x32_bf16 v[12:15], v[222:225], v[206:209], v[12:15]
	v_mfma_f32_16x16x32_bf16 v[8:11], v[230:233], v[206:209], v[8:11]
	v_mfma_f32_16x16x32_bf16 v[4:7], v[222:225], v[214:217], v[4:7]
	v_mfma_f32_16x16x32_bf16 v[0:3], v[230:233], v[214:217], v[0:3]
	s_add_i32 s54, s54, 2
	s_add_u32 s52, s52, 0x100
	s_addc_u32 s53, s53, 0
	s_cmp_gt_u32 s54, 27
	s_barrier
	s_cbranch_scc0 .LBB0_654
	s_lshl_b64 s[52:53], s[16:17], 12
	s_add_u32 s52, s14, s52
	s_addc_u32 s53, s15, s53
	s_add_u32 s52, s52, 0x80000
	s_addc_u32 s53, s53, 0
	v_lshl_add_u64 v[156:157], s[52:53], 0, v[128:129]
	v_readfirstlane_b32 s54, v168
	v_lshl_add_u64 v[156:157], v[156:157], 0, s[50:51]
	s_mov_b32 m0, s54
	ds_read_b128 v[134:137], v160
	ds_read_b128 v[138:141], v160 offset:1024
	ds_read_b128 v[170:173], v160 offset:2048
	ds_read_b128 v[174:177], v160 offset:3072
	ds_read_b128 v[178:181], v151
	ds_read_b128 v[182:185], v151 offset:1024
	ds_read_b128 v[186:189], v150
	ds_read_b128 v[190:193], v150 offset:1024
	ds_read_b128 v[194:197], v149
	ds_read_b128 v[198:201], v149 offset:1024
	ds_read_b128 v[202:205], v148
	ds_read_b128 v[206:209], v148 offset:1024
	global_load_lds_dwordx4 v[156:157], off
	v_lshl_add_u64 v[156:157], s[52:53], 0, v[132:133]
	v_readfirstlane_b32 s52, v169
	v_lshl_add_u64 v[156:157], v[156:157], 0, s[50:51]
	s_mov_b32 m0, s52
	s_nop 0
	global_load_lds_dwordx4 v[156:157], off
	s_barrier
	s_waitcnt lgkmcnt(0)
	s_waitcnt lgkmcnt(0)
	v_mfma_f32_16x16x32_bf16 v[124:127], v[134:137], v[178:181], v[124:127]
	v_mfma_f32_16x16x32_bf16 v[120:123], v[170:173], v[178:181], v[120:123]
	v_mfma_f32_16x16x32_bf16 v[116:119], v[134:137], v[186:189], v[116:119]
	v_mfma_f32_16x16x32_bf16 v[112:115], v[170:173], v[186:189], v[112:115]
	v_mfma_f32_16x16x32_bf16 v[108:111], v[134:137], v[194:197], v[108:111]
	v_mfma_f32_16x16x32_bf16 v[104:107], v[170:173], v[194:197], v[104:107]
	v_mfma_f32_16x16x32_bf16 v[100:103], v[134:137], v[202:205], v[100:103]
	v_mfma_f32_16x16x32_bf16 v[96:99], v[170:173], v[202:205], v[96:99]
	v_mfma_f32_16x16x32_bf16 v[124:127], v[138:141], v[182:185], v[124:127]
	v_mfma_f32_16x16x32_bf16 v[120:123], v[174:177], v[182:185], v[120:123]
	v_mfma_f32_16x16x32_bf16 v[116:119], v[138:141], v[190:193], v[116:119]
	v_mfma_f32_16x16x32_bf16 v[112:115], v[174:177], v[190:193], v[112:115]
	v_mfma_f32_16x16x32_bf16 v[108:111], v[138:141], v[198:201], v[108:111]
	v_mfma_f32_16x16x32_bf16 v[104:107], v[174:177], v[198:201], v[104:107]
	v_mfma_f32_16x16x32_bf16 v[100:103], v[138:141], v[206:209], v[100:103]
	v_mfma_f32_16x16x32_bf16 v[96:99], v[174:177], v[206:209], v[96:99]
	s_barrier
	ds_read_b128 v[210:213], v159
	ds_read_b128 v[214:217], v159 offset:1024
	ds_read_b128 v[218:221], v159 offset:2048
	ds_read_b128 v[156:159], v159 offset:3072
	s_barrier
; #define LDA(dst, b, h) for (int m = 0; m < 4; ++m) for (int k = 0; k < 2; ++k) \
;     dst[m][k] = *reinterpret_cast<const bf16x8*>((char*)SA(b, h) + lds_byte(wr * 64 + m * 16 + fr, k * 32 + fq * 8))
; #define LDB(dst, b, h) for (int n = 0; n < 2; ++n) for (int k = 0; k < 2; ++k) \
;     dst[n][k] = *reinterpret_cast<const bf16x8*>((char*)SB(b, h) + lds_byte(wc * 32 + n * 16 + fr, k * 32 + fq * 8))
; #define MMA(ai, bj, At_, Bt_) do { __builtin_amdgcn_s_setprio(1); \
;     for (int k = 0; k < 2; ++k) for (int m = 0; m < 4; ++m) for (int n = 0; n < 2; ++n) \
;       acc[ai][bj][m][n] = __builtin_amdgcn_mfma_f32_16x16x32_bf16(At_[m][k], Bt_[n][k], acc[ai][bj][m][n], 0, 0, 0); \
;     __builtin_amdgcn_s_setprio(0); } while (0)
; #define WAIT_V(n) asm volatile("s_waitcnt vmcnt(" #n ")" ::: "memory")
; #define WAIT_L(n) asm volatile("s_waitcnt lgkmcnt(" #n ")" ::: "memory")
; #define BAR __builtin_amdgcn_s_barrier()
; template <int EPI, int lda, int ldb, int N, int K>
; __device__ __forceinline__ void gemm_phase(const u16* __restrict__ A, const u16* __restrict__ Bt, const GemmEpi ep, int wv) {
;     ...
;       LDB(B1, 0, 1); BAR; WAIT_L(0); MMA(0, 1, At, B1); BAR;
;       LDA(At, 0, 1); WAIT_V(4); BAR; WAIT_L(0); MMA(1, 0, At, B0); MMA(1, 1, At, B1); BAR; }
;     { LDB(B0, 1, 0); LDA(At, 1, 0); WAIT_V(2); BAR; WAIT_L(0); MMA(0, 0, At, B0); BAR;
	s_waitcnt lgkmcnt(0)
	s_waitcnt lgkmcnt(0)
	v_mfma_f32_16x16x32_bf16 v[92:95], v[210:213], v[178:181], v[92:95]
	v_mfma_f32_16x16x32_bf16 v[88:91], v[218:221], v[178:181], v[88:91]
	v_mfma_f32_16x16x32_bf16 v[76:79], v[210:213], v[194:197], v[76:79]
	v_mfma_f32_16x16x32_bf16 v[72:75], v[218:221], v[194:197], v[72:75]
	v_mfma_f32_16x16x32_bf16 v[84:87], v[210:213], v[186:189], v[84:87]
	v_mfma_f32_16x16x32_bf16 v[80:83], v[218:221], v[186:189], v[80:83]
	v_mfma_f32_16x16x32_bf16 v[68:71], v[210:213], v[202:205], v[68:71]
	v_mfma_f32_16x16x32_bf16 v[64:67], v[218:221], v[202:205], v[64:67]
	v_mfma_f32_16x16x32_bf16 v[92:95], v[214:217], v[182:185], v[92:95]
	v_mfma_f32_16x16x32_bf16 v[88:91], v[156:159], v[182:185], v[88:91]
	v_mfma_f32_16x16x32_bf16 v[76:79], v[214:217], v[198:201], v[76:79]
	v_mfma_f32_16x16x32_bf16 v[72:75], v[156:159], v[198:201], v[72:75]
	v_mfma_f32_16x16x32_bf16 v[178:181], v[214:217], v[190:193], v[84:87]
	v_mfma_f32_16x16x32_bf16 v[182:185], v[156:159], v[190:193], v[80:83]
	v_mfma_f32_16x16x32_bf16 v[186:189], v[214:217], v[206:209], v[68:71]
	v_mfma_f32_16x16x32_bf16 v[190:193], v[156:159], v[206:209], v[64:67]
	s_barrier
	s_nop 0
	ds_read_b128 v[64:67], v151 offset:16384
	ds_read_b128 v[68:71], v151 offset:17408
	ds_read_b128 v[80:83], v150 offset:16384
	ds_read_b128 v[84:87], v150 offset:17408
	ds_read_b128 v[194:197], v149 offset:16384
	ds_read_b128 v[198:201], v149 offset:17408
	ds_read_b128 v[202:205], v148 offset:16384
	ds_read_b128 v[206:209], v148 offset:17408
	s_waitcnt vmcnt(4)
	s_barrier
	s_waitcnt lgkmcnt(0)
	s_waitcnt lgkmcnt(0)
	v_mfma_f32_16x16x32_bf16 v[60:63], v[134:137], v[64:67], v[60:63]
	v_mfma_f32_16x16x32_bf16 v[56:59], v[170:173], v[64:67], v[56:59]
	v_mfma_f32_16x16x32_bf16 v[52:55], v[134:137], v[80:83], v[52:55]
	v_mfma_f32_16x16x32_bf16 v[48:51], v[170:173], v[80:83], v[48:51]
	v_mfma_f32_16x16x32_bf16 v[44:47], v[134:137], v[194:197], v[44:47]
	v_mfma_f32_16x16x32_bf16 v[40:43], v[170:173], v[194:197], v[40:43]
	v_mfma_f32_16x16x32_bf16 v[36:39], v[134:137], v[202:205], v[36:39]
	v_mfma_f32_16x16x32_bf16 v[32:35], v[170:173], v[202:205], v[32:35]
	v_mfma_f32_16x16x32_bf16 v[60:63], v[138:141], v[68:71], v[60:63]
	v_mfma_f32_16x16x32_bf16 v[56:59], v[174:177], v[68:71], v[56:59]
	v_mfma_f32_16x16x32_bf16 v[52:55], v[138:141], v[84:87], v[52:55]
	v_mfma_f32_16x16x32_bf16 v[48:51], v[174:177], v[84:87], v[48:51]
	v_mfma_f32_16x16x32_bf16 v[44:47], v[138:141], v[198:201], v[44:47]
	v_mfma_f32_16x16x32_bf16 v[40:43], v[174:177], v[198:201], v[40:43]
	v_mfma_f32_16x16x32_bf16 v[36:39], v[138:141], v[206:209], v[36:39]
	v_mfma_f32_16x16x32_bf16 v[32:35], v[174:177], v[206:209], v[32:35]
	v_mfma_f32_16x16x32_bf16 v[28:31], v[210:213], v[64:67], v[28:31]
	v_mfma_f32_16x16x32_bf16 v[20:23], v[210:213], v[80:83], v[20:23]
	v_mfma_f32_16x16x32_bf16 v[12:15], v[210:213], v[194:197], v[12:15]
	v_mfma_f32_16x16x32_bf16 v[4:7], v[210:213], v[202:205], v[4:7]
	v_mfma_f32_16x16x32_bf16 v[24:27], v[218:221], v[64:67], v[24:27]
	v_mfma_f32_16x16x32_bf16 v[16:19], v[218:221], v[80:83], v[16:19]
	v_mfma_f32_16x16x32_bf16 v[8:11], v[218:221], v[194:197], v[8:11]
	v_mfma_f32_16x16x32_bf16 v[0:3], v[218:221], v[202:205], v[0:3]
	v_mfma_f32_16x16x32_bf16 v[28:31], v[214:217], v[68:71], v[28:31]
	v_mfma_f32_16x16x32_bf16 v[20:23], v[214:217], v[84:87], v[20:23]
	v_mfma_f32_16x16x32_bf16 v[12:15], v[214:217], v[198:201], v[12:15]
	v_mfma_f32_16x16x32_bf16 v[4:7], v[214:217], v[206:209], v[4:7]
	v_mfma_f32_16x16x32_bf16 v[134:137], v[156:159], v[68:71], v[24:27]
	v_mfma_f32_16x16x32_bf16 v[138:141], v[156:159], v[84:87], v[16:19]
	v_mfma_f32_16x16x32_bf16 v[168:171], v[156:159], v[198:201], v[8:11]
	v_mfma_f32_16x16x32_bf16 v[156:159], v[156:159], v[206:209], v[0:3]
	s_barrier
	s_nop 0
	ds_read_b128 v[0:3], v154
	ds_read_b128 v[8:11], v154 offset:1024
	ds_read_b128 v[16:19], v154 offset:2048
	ds_read_b128 v[172:175], v154 offset:3072
	ds_read_b128 v[24:27], v151 offset:32768
	ds_read_b128 v[194:197], v151 offset:33792
	ds_read_b128 v[198:201], v150 offset:32768
	ds_read_b128 v[202:205], v150 offset:33792
	ds_read_b128 v[206:209], v149 offset:32768
	ds_read_b128 v[210:213], v149 offset:33792
	ds_read_b128 v[214:217], v148 offset:32768
	ds_read_b128 v[218:221], v148 offset:33792
	s_waitcnt vmcnt(2)
	s_barrier
; #define LDA(dst, b, h) for (int m = 0; m < 4; ++m) for (int k = 0; k < 2; ++k) \
;     dst[m][k] = *reinterpret_cast<const bf16x8*>((char*)SA(b, h) + lds_byte(wr * 64 + m * 16 + fr, k * 32 + fq * 8))
; #define LDB(dst, b, h) for (int n = 0; n < 2; ++n) for (int k = 0; k < 2; ++k) \
;     dst[n][k] = *reinterpret_cast<const bf16x8*>((char*)SB(b, h) + lds_byte(wc * 32 + n * 16 + fr, k * 32 + fq * 8))
; #define MMA(ai, bj, At_, Bt_) do { __builtin_amdgcn_s_setprio(1); \
;     for (int k = 0; k < 2; ++k) for (int m = 0; m < 4; ++m) for (int n = 0; n < 2; ++n) \
;       acc[ai][bj][m][n] = __builtin_amdgcn_mfma_f32_16x16x32_bf16(At_[m][k], Bt_[n][k], acc[ai][bj][m][n], 0, 0, 0); \
;     __builtin_amdgcn_s_setprio(0); } while (0)
; #define WAIT_V(n) asm volatile("s_waitcnt vmcnt(" #n ")" ::: "memory")
; #define WAIT_L(n) asm volatile("s_waitcnt lgkmcnt(" #n ")" ::: "memory")
; #define BAR __builtin_amdgcn_s_barrier()
; template <int EPI, int lda, int ldb, int N, int K>
; __device__ __forceinline__ void gemm_phase(const u16* __restrict__ A, const u16* __restrict__ Bt, const GemmEpi ep, int wv) {
;     ...
;     { LDB(B0, 1, 0); LDA(At, 1, 0); WAIT_V(2); BAR; WAIT_L(0); MMA(0, 0, At, B0); BAR;
;       LDB(B1, 1, 1); WAIT_V(0); BAR; WAIT_L(0); MMA(0, 1, At, B1); BAR;
;       LDA(At, 1, 1); BAR; WAIT_L(0); MMA(1, 0, At, B0); MMA(1, 1, At, B1); BAR; }
;     if (wr == 0) BAR;
	s_waitcnt lgkmcnt(0)
	s_waitcnt lgkmcnt(0)
	v_mfma_f32_16x16x32_bf16 v[64:67], v[0:3], v[24:27], v[124:127]
	v_mfma_f32_16x16x32_bf16 v[68:71], v[16:19], v[24:27], v[120:123]
	v_mfma_f32_16x16x32_bf16 v[80:83], v[0:3], v[198:201], v[116:119]
	v_mfma_f32_16x16x32_bf16 v[84:87], v[16:19], v[198:201], v[112:115]
	v_mfma_f32_16x16x32_bf16 v[108:111], v[0:3], v[206:209], v[108:111]
	v_mfma_f32_16x16x32_bf16 v[104:107], v[16:19], v[206:209], v[104:107]
	v_mfma_f32_16x16x32_bf16 v[120:123], v[0:3], v[214:217], v[100:103]
	v_mfma_f32_16x16x32_bf16 v[124:127], v[16:19], v[214:217], v[96:99]
	v_mfma_f32_16x16x32_bf16 v[116:119], v[8:11], v[194:197], v[64:67]
	v_mfma_f32_16x16x32_bf16 v[112:115], v[172:175], v[194:197], v[68:71]
	v_mfma_f32_16x16x32_bf16 v[100:103], v[8:11], v[202:205], v[80:83]
	v_mfma_f32_16x16x32_bf16 v[96:99], v[172:175], v[202:205], v[84:87]
	v_mfma_f32_16x16x32_bf16 v[84:87], v[8:11], v[210:213], v[108:111]
	v_mfma_f32_16x16x32_bf16 v[80:83], v[172:175], v[210:213], v[104:107]
	v_mfma_f32_16x16x32_bf16 v[68:71], v[8:11], v[218:221], v[120:123]
	v_mfma_f32_16x16x32_bf16 v[64:67], v[172:175], v[218:221], v[124:127]
	s_barrier
	ds_read_b128 v[222:225], v152
	ds_read_b128 v[226:229], v152 offset:1024
	ds_read_b128 v[230:233], v152 offset:2048
	ds_read_b128 v[152:155], v152 offset:3072
	s_waitcnt vmcnt(0)
	s_barrier
	s_waitcnt lgkmcnt(0)
	s_waitcnt lgkmcnt(0)
	v_mfma_f32_16x16x32_bf16 v[92:95], v[222:225], v[24:27], v[92:95]
	v_mfma_f32_16x16x32_bf16 v[24:27], v[230:233], v[24:27], v[88:91]
	v_mfma_f32_16x16x32_bf16 v[88:91], v[222:225], v[198:201], v[178:181]
	v_mfma_f32_16x16x32_bf16 v[104:107], v[230:233], v[198:201], v[182:185]
	v_mfma_f32_16x16x32_bf16 v[76:79], v[222:225], v[206:209], v[76:79]
	v_mfma_f32_16x16x32_bf16 v[72:75], v[230:233], v[206:209], v[72:75]
	v_mfma_f32_16x16x32_bf16 v[176:179], v[222:225], v[214:217], v[186:189]
	v_mfma_f32_16x16x32_bf16 v[180:183], v[230:233], v[214:217], v[190:193]
	v_mfma_f32_16x16x32_bf16 v[124:127], v[226:229], v[194:197], v[92:95]
	v_mfma_f32_16x16x32_bf16 v[120:123], v[152:155], v[194:197], v[24:27]
	v_mfma_f32_16x16x32_bf16 v[108:111], v[226:229], v[202:205], v[88:91]
	v_mfma_f32_16x16x32_bf16 v[104:107], v[152:155], v[202:205], v[104:107]
	v_mfma_f32_16x16x32_bf16 v[92:95], v[226:229], v[210:213], v[76:79]
	v_mfma_f32_16x16x32_bf16 v[88:91], v[152:155], v[210:213], v[72:75]
	v_mfma_f32_16x16x32_bf16 v[76:79], v[226:229], v[218:221], v[176:179]
	v_mfma_f32_16x16x32_bf16 v[72:75], v[152:155], v[218:221], v[180:183]
	s_barrier
	ds_read_b128 v[176:179], v151 offset:49152
	ds_read_b128 v[180:183], v151 offset:50176
	ds_read_b128 v[184:187], v150 offset:49152
	ds_read_b128 v[188:191], v150 offset:50176
	ds_read_b128 v[192:195], v149 offset:49152
	ds_read_b128 v[196:199], v149 offset:50176
	ds_read_b128 v[200:203], v148 offset:49152
	ds_read_b128 v[148:151], v148 offset:50176
	s_barrier
	s_waitcnt lgkmcnt(0)
	s_waitcnt lgkmcnt(0)
	v_mfma_f32_16x16x32_bf16 v[24:27], v[0:3], v[176:179], v[60:63]
	v_mfma_f32_16x16x32_bf16 v[60:63], v[16:19], v[176:179], v[56:59]
	v_mfma_f32_16x16x32_bf16 v[52:55], v[0:3], v[184:187], v[52:55]
	v_mfma_f32_16x16x32_bf16 v[204:207], v[16:19], v[184:187], v[48:51]
	v_mfma_f32_16x16x32_bf16 v[44:47], v[0:3], v[192:195], v[44:47]
	v_mfma_f32_16x16x32_bf16 v[208:211], v[16:19], v[192:195], v[40:43]
	v_mfma_f32_16x16x32_bf16 v[0:3], v[0:3], v[200:203], v[36:39]
	v_mfma_f32_16x16x32_bf16 v[36:39], v[16:19], v[200:203], v[32:35]
	v_mfma_f32_16x16x32_bf16 v[56:59], v[8:11], v[180:183], v[24:27]
	v_mfma_f32_16x16x32_bf16 v[48:51], v[172:175], v[180:183], v[60:63]
	v_mfma_f32_16x16x32_bf16 v[40:43], v[8:11], v[188:191], v[52:55]
	v_mfma_f32_16x16x32_bf16 v[32:35], v[172:175], v[188:191], v[204:207]
	v_mfma_f32_16x16x32_bf16 v[24:27], v[8:11], v[196:199], v[44:47]
	v_mfma_f32_16x16x32_bf16 v[16:19], v[172:175], v[196:199], v[208:211]
	v_mfma_f32_16x16x32_bf16 v[8:11], v[8:11], v[148:151], v[0:3]
	v_mfma_f32_16x16x32_bf16 v[0:3], v[172:175], v[148:151], v[36:39]
	v_mfma_f32_16x16x32_bf16 v[28:31], v[222:225], v[176:179], v[28:31]
	v_mfma_f32_16x16x32_bf16 v[36:39], v[230:233], v[176:179], v[134:137]
	v_mfma_f32_16x16x32_bf16 v[20:23], v[222:225], v[184:187], v[20:23]
	v_mfma_f32_16x16x32_bf16 v[134:137], v[230:233], v[184:187], v[138:141]
	v_mfma_f32_16x16x32_bf16 v[12:15], v[222:225], v[192:195], v[12:15]
	v_mfma_f32_16x16x32_bf16 v[138:141], v[230:233], v[192:195], v[168:171]
	v_mfma_f32_16x16x32_bf16 v[4:7], v[222:225], v[200:203], v[4:7]
	v_mfma_f32_16x16x32_bf16 v[156:159], v[230:233], v[200:203], v[156:159]
	v_mfma_f32_16x16x32_bf16 v[60:63], v[226:229], v[180:183], v[28:31]
	v_mfma_f32_16x16x32_bf16 v[52:55], v[152:155], v[180:183], v[36:39]
	v_mfma_f32_16x16x32_bf16 v[44:47], v[226:229], v[188:191], v[20:23]
	v_mfma_f32_16x16x32_bf16 v[36:39], v[152:155], v[188:191], v[134:137]
	v_mfma_f32_16x16x32_bf16 v[28:31], v[226:229], v[196:199], v[12:15]
	v_mfma_f32_16x16x32_bf16 v[20:23], v[152:155], v[196:199], v[138:141]
	v_mfma_f32_16x16x32_bf16 v[12:15], v[226:229], v[148:151], v[4:7]
	v_mfma_f32_16x16x32_bf16 v[4:7], v[152:155], v[148:151], v[156:159]
	v_cmp_gt_u32_e32 vcc, s70, v130
	s_barrier
	s_and_saveexec_b64 s[52:53], vcc
	s_cbranch_execz .LBB0_657
	s_barrier

; #define STAGE(P, BASE, LD, br, kt) do { const char* _g = (const char*)((BASE) + (size_t)(br) * (LD) + (size_t)(kt) * 64); \
;     for (int _i = 0; _i < 2; ++_i) { int _b = tidx * 16 + _i * 8192; int _r, _c; stage_rc(_b, _r, _c); \
;       __builtin_amdgcn_global_load_lds((const unsigned*)(_g + (unsigned)((_r * (LD) + _c) * 2)), (unsigned*)((char*)(P) + _b), 16, 0, 0); } } while (0)
; #define LDA(dst, b, h) for (int m = 0; m < 4; ++m) for (int k = 0; k < 2; ++k) \
;     dst[m][k] = *reinterpret_cast<const bf16x8*>((char*)SA(b, h) + lds_byte(wr * 64 + m * 16 + fr, k * 32 + fq * 8))
; #define LDB(dst, b, h) for (int n = 0; n < 2; ++n) for (int k = 0; k < 2; ++k) \
;     dst[n][k] = *reinterpret_cast<const bf16x8*>((char*)SB(b, h) + lds_byte(wc * 32 + n * 16 + fr, k * 32 + fq * 8))
; #define MMA(ai, bj, At_, Bt_) do { __builtin_amdgcn_s_setprio(1); \
;     for (int k = 0; k < 2; ++k) for (int m = 0; m < 4; ++m) for (int n = 0; n < 2; ++n) \
;       acc[ai][bj][m][n] = __builtin_amdgcn_mfma_f32_16x16x32_bf16(At_[m][k], Bt_[n][k], acc[ai][bj][m][n], 0, 0, 0); \
;     __builtin_amdgcn_s_setprio(0); } while (0)
; #define WAIT_V(n) asm volatile("s_waitcnt vmcnt(" #n ")" ::: "memory")
; #define WAIT_L(n) asm volatile("s_waitcnt lgkmcnt(" #n ")" ::: "memory")
; #define BAR __builtin_amdgcn_s_barrier()
; #define SCHED __builtin_amdgcn_sched_barrier(0)
; template <int EPI, int lda, int ldb, int N, int K>
; __device__ __forceinline__ void gemm_phase(const u16* __restrict__ A, const u16* __restrict__ Bt, const GemmEpi ep, int wv) {
;     ...
;     for (int t = 0; t < nt - 2; t += 2) {
;       LDB(B0, 0, 0); SCHED; LDA(At, 0, 0); STAGE(SA(1, 1), Ab, lda, brow + HALF, t + 1);
;       WAIT_L(8); BAR; WAIT_L(0); MMA(0, 0, At, B0); BAR; SCHED;
;       LDB(B1, 0, 1); STAGE(SB(0, 0), Bt, ldb, bcol, t + 2);
;       BAR; WAIT_L(0); MMA(0, 1, At, B1); BAR;
;       LDA(At, 0, 1); STAGE(SA(0, 0), Ab, lda, brow, t + 2);
;       BAR; WAIT_L(0); MMA(1, 0, At, B0); BAR; SCHED;
;       STAGE(SB(0, 1), Bt, ldb, bcol + HALF, t + 2);
;       WAIT_V(6); BAR; MMA(1, 1, At, B1); BAR;
.LBB0_770:
	ds_read_b128 v[172:175], v161
	ds_read_b128 v[176:179], v161 offset:1024
	ds_read_b128 v[180:183], v161 offset:2048
	ds_read_b128 v[184:187], v161 offset:3072
	v_add_u32_e32 v169, 0xc000, v148
	v_lshl_add_u64 v[236:237], v[136:137], 0, s[50:51]
	v_readfirstlane_b32 s53, v169
	v_add_u32_e32 v170, 0xe000, v148
	v_lshl_add_u64 v[162:163], v[236:237], 0, s[18:19]
	s_mov_b32 m0, s53
	v_lshl_add_u64 v[238:239], v[134:135], 0, s[50:51]
	v_readfirstlane_b32 s53, v170
	ds_read_b128 v[164:167], v152
	ds_read_b128 v[188:191], v152 offset:1024
	ds_read_b128 v[192:195], v151
	ds_read_b128 v[196:199], v151 offset:1024
	ds_read_b128 v[200:203], v150
	ds_read_b128 v[204:207], v150 offset:1024
	ds_read_b128 v[208:211], v149
	ds_read_b128 v[212:215], v149 offset:1024
	global_load_lds_dwordx4 v[162:163], off
	v_lshl_add_u64 v[162:163], v[238:239], 0, s[18:19]
	s_mov_b32 m0, s53
	s_nop 0
	global_load_lds_dwordx4 v[162:163], off
	s_waitcnt lgkmcnt(8)
	s_barrier
	s_waitcnt lgkmcnt(0)
	s_waitcnt lgkmcnt(0)
	v_mfma_f32_16x16x32_bf16 v[124:127], v[172:175], v[164:167], v[124:127]
	ds_read_b128 v[216:219], v160
	v_mfma_f32_16x16x32_bf16 v[120:123], v[180:183], v[164:167], v[120:123]
	v_mfma_f32_16x16x32_bf16 v[116:119], v[172:175], v[192:195], v[116:119]
	ds_read_b128 v[220:223], v160 offset:1024
	v_mfma_f32_16x16x32_bf16 v[112:115], v[180:183], v[192:195], v[112:115]
	v_mfma_f32_16x16x32_bf16 v[108:111], v[172:175], v[200:203], v[108:111]
	ds_read_b128 v[224:227], v160 offset:2048
	v_mfma_f32_16x16x32_bf16 v[104:107], v[180:183], v[200:203], v[104:107]
	v_mfma_f32_16x16x32_bf16 v[100:103], v[172:175], v[208:211], v[100:103]
	ds_read_b128 v[228:231], v160 offset:3072
	v_mfma_f32_16x16x32_bf16 v[96:99], v[180:183], v[208:211], v[96:99]
	v_mfma_f32_16x16x32_bf16 v[124:127], v[176:179], v[188:191], v[124:127]
	v_mfma_f32_16x16x32_bf16 v[120:123], v[184:187], v[188:191], v[120:123]
	v_mfma_f32_16x16x32_bf16 v[116:119], v[176:179], v[196:199], v[116:119]
	v_mfma_f32_16x16x32_bf16 v[112:115], v[184:187], v[196:199], v[112:115]
	v_mfma_f32_16x16x32_bf16 v[108:111], v[176:179], v[204:207], v[108:111]
	v_mfma_f32_16x16x32_bf16 v[104:107], v[184:187], v[204:207], v[104:107]
	v_mfma_f32_16x16x32_bf16 v[100:103], v[176:179], v[212:215], v[100:103]
	v_mfma_f32_16x16x32_bf16 v[96:99], v[184:187], v[212:215], v[96:99]
	s_barrier
	v_add_u32_e32 v162, s64, v153
	v_lshl_add_u64 v[240:241], v[140:141], 0, s[50:51]
	v_readfirstlane_b32 s53, v162
	v_add_u32_e32 v163, 0x2000, v162
	v_lshl_add_u64 v[232:233], v[240:241], 0, s[20:21]
	s_mov_b32 m0, s53
	v_lshl_add_u64 v[242:243], v[138:139], 0, s[50:51]
	v_readfirstlane_b32 s53, v163
	global_load_lds_dwordx4 v[232:233], off
	v_lshl_add_u64 v[232:233], v[242:243], 0, s[20:21]
	s_mov_b32 m0, s53
	s_nop 0
	global_load_lds_dwordx4 v[232:233], off
	s_barrier
	s_waitcnt lgkmcnt(0)
	s_waitcnt lgkmcnt(0)
	v_mfma_f32_16x16x32_bf16 v[92:95], v[216:219], v[164:167], v[92:95]
	v_mfma_f32_16x16x32_bf16 v[88:91], v[224:227], v[164:167], v[88:91]
	v_mfma_f32_16x16x32_bf16 v[84:87], v[216:219], v[192:195], v[84:87]
	v_mfma_f32_16x16x32_bf16 v[80:83], v[224:227], v[192:195], v[80:83]
	v_mfma_f32_16x16x32_bf16 v[76:79], v[216:219], v[200:203], v[76:79]
	v_mfma_f32_16x16x32_bf16 v[72:75], v[224:227], v[200:203], v[72:75]
	v_mfma_f32_16x16x32_bf16 v[68:71], v[216:219], v[208:211], v[68:71]
	v_mfma_f32_16x16x32_bf16 v[64:67], v[224:227], v[208:211], v[64:67]
	v_mfma_f32_16x16x32_bf16 v[92:95], v[220:223], v[188:191], v[92:95]
	v_mfma_f32_16x16x32_bf16 v[88:91], v[228:231], v[188:191], v[88:91]
	v_mfma_f32_16x16x32_bf16 v[84:87], v[220:223], v[196:199], v[84:87]
	v_mfma_f32_16x16x32_bf16 v[80:83], v[228:231], v[196:199], v[80:83]
	v_mfma_f32_16x16x32_bf16 v[76:79], v[220:223], v[204:207], v[76:79]
	v_mfma_f32_16x16x32_bf16 v[72:75], v[228:231], v[204:207], v[72:75]
	v_mfma_f32_16x16x32_bf16 v[68:71], v[220:223], v[212:215], v[68:71]
	v_mfma_f32_16x16x32_bf16 v[64:67], v[228:231], v[212:215], v[64:67]
	v_readfirstlane_b32 s53, v148
	v_lshl_add_u64 v[164:165], v[236:237], 0, s[22:23]
	s_mov_b32 m0, s53
	s_barrier
	ds_read_b128 v[188:191], v152 offset:16384
	ds_read_b128 v[192:195], v152 offset:17408
	ds_read_b128 v[196:199], v151 offset:16384
	ds_read_b128 v[200:203], v151 offset:17408
	ds_read_b128 v[204:207], v150 offset:16384
	ds_read_b128 v[208:211], v150 offset:17408
	ds_read_b128 v[212:215], v149 offset:16384
	ds_read_b128 v[232:235], v149 offset:17408
	global_load_lds_dwordx4 v[164:165], off
	v_add_u32_e32 v164, 0x2000, v148
	v_lshl_add_u64 v[166:167], v[238:239], 0, s[22:23]
	v_readfirstlane_b32 s53, v164
	s_mov_b32 m0, s53
	s_nop 0
	global_load_lds_dwordx4 v[166:167], off
	s_barrier
	s_waitcnt lgkmcnt(0)
	s_waitcnt lgkmcnt(0)
	v_mfma_f32_16x16x32_bf16 v[60:63], v[172:175], v[188:191], v[60:63]
	v_mfma_f32_16x16x32_bf16 v[56:59], v[180:183], v[188:191], v[56:59]
	v_mfma_f32_16x16x32_bf16 v[52:55], v[172:175], v[196:199], v[52:55]
	v_mfma_f32_16x16x32_bf16 v[48:51], v[180:183], v[196:199], v[48:51]
	v_mfma_f32_16x16x32_bf16 v[44:47], v[172:175], v[204:207], v[44:47]
	v_mfma_f32_16x16x32_bf16 v[40:43], v[180:183], v[204:207], v[40:43]
	v_mfma_f32_16x16x32_bf16 v[36:39], v[172:175], v[212:215], v[36:39]
	v_mfma_f32_16x16x32_bf16 v[32:35], v[180:183], v[212:215], v[32:35]
	v_mfma_f32_16x16x32_bf16 v[60:63], v[176:179], v[192:195], v[60:63]
	v_mfma_f32_16x16x32_bf16 v[56:59], v[184:187], v[192:195], v[56:59]
	v_mfma_f32_16x16x32_bf16 v[52:55], v[176:179], v[200:203], v[52:55]
	v_mfma_f32_16x16x32_bf16 v[48:51], v[184:187], v[200:203], v[48:51]
	v_mfma_f32_16x16x32_bf16 v[44:47], v[176:179], v[208:211], v[44:47]
	v_mfma_f32_16x16x32_bf16 v[40:43], v[184:187], v[208:211], v[40:43]
	v_mfma_f32_16x16x32_bf16 v[36:39], v[176:179], v[232:235], v[36:39]
	v_mfma_f32_16x16x32_bf16 v[32:35], v[184:187], v[232:235], v[32:35]
	s_barrier
; #define STAGE(P, BASE, LD, br, kt) do { const char* _g = (const char*)((BASE) + (size_t)(br) * (LD) + (size_t)(kt) * 64); \
;     for (int _i = 0; _i < 2; ++_i) { int _b = tidx * 16 + _i * 8192; int _r, _c; stage_rc(_b, _r, _c); \
;       __builtin_amdgcn_global_load_lds((const unsigned*)(_g + (unsigned)((_r * (LD) + _c) * 2)), (unsigned*)((char*)(P) + _b), 16, 0, 0); } } while (0)
; #define LDA(dst, b, h) for (int m = 0; m < 4; ++m) for (int k = 0; k < 2; ++k) \
;     dst[m][k] = *reinterpret_cast<const bf16x8*>((char*)SA(b, h) + lds_byte(wr * 64 + m * 16 + fr, k * 32 + fq * 8))
; #define LDB(dst, b, h) for (int n = 0; n < 2; ++n) for (int k = 0; k < 2; ++k) \
;     dst[n][k] = *reinterpret_cast<const bf16x8*>((char*)SB(b, h) + lds_byte(wc * 32 + n * 16 + fr, k * 32 + fq * 8))
; #define MMA(ai, bj, At_, Bt_) do { __builtin_amdgcn_s_setprio(1); \
;     for (int k = 0; k < 2; ++k) for (int m = 0; m < 4; ++m) for (int n = 0; n < 2; ++n) \
;       acc[ai][bj][m][n] = __builtin_amdgcn_mfma_f32_16x16x32_bf16(At_[m][k], Bt_[n][k], acc[ai][bj][m][n], 0, 0, 0); \
;     __builtin_amdgcn_s_setprio(0); } while (0)
; #define WAIT_V(n) asm volatile("s_waitcnt vmcnt(" #n ")" ::: "memory")
; #define WAIT_L(n) asm volatile("s_waitcnt lgkmcnt(" #n ")" ::: "memory")
; #define BAR __builtin_amdgcn_s_barrier()
; #define SCHED __builtin_amdgcn_sched_barrier(0)
; template <int EPI, int lda, int ldb, int N, int K>
; __device__ __forceinline__ void gemm_phase(const u16* __restrict__ A, const u16* __restrict__ Bt, const GemmEpi ep, int wv) {
;     ...
;       WAIT_V(6); BAR; MMA(1, 1, At, B1); BAR;
;       LDB(B0, 1, 0); SCHED; LDA(At, 1, 0); STAGE(SA(0, 1), Ab, lda, brow + HALF, t + 2);
;       WAIT_L(8); BAR; WAIT_L(0); MMA(0, 0, At, B0); BAR; SCHED;
;       LDB(B1, 1, 1); STAGE(SB(1, 0), Bt, ldb, bcol, t + 3);
;       BAR; WAIT_L(0); MMA(0, 1, At, B1); BAR;
;       LDA(At, 1, 1); STAGE(SA(1, 0), Ab, lda, brow, t + 3);
;       BAR; WAIT_L(0); MMA(1, 0, At, B0); BAR; SCHED;
	v_add_u32_e32 v165, s65, v153
	v_lshl_add_u64 v[166:167], v[240:241], 0, s[24:25]
	v_readfirstlane_b32 s53, v165
	s_mov_b32 m0, s53
	v_lshl_add_u64 v[172:173], v[242:243], 0, s[24:25]
	global_load_lds_dwordx4 v[166:167], off
	v_add_u32_e32 v166, 0x2000, v165
	s_nop 0
	v_readfirstlane_b32 s53, v166
	s_mov_b32 m0, s53
	s_nop 0
	global_load_lds_dwordx4 v[172:173], off
	s_waitcnt vmcnt(6)
	s_barrier
	v_mfma_f32_16x16x32_bf16 v[28:31], v[216:219], v[188:191], v[28:31]
	ds_read_b128 v[172:175], v156
	v_mfma_f32_16x16x32_bf16 v[24:27], v[224:227], v[188:191], v[24:27]
	v_mfma_f32_16x16x32_bf16 v[20:23], v[216:219], v[196:199], v[20:23]
	ds_read_b128 v[176:179], v156 offset:1024
	v_mfma_f32_16x16x32_bf16 v[16:19], v[224:227], v[196:199], v[16:19]
	v_mfma_f32_16x16x32_bf16 v[12:15], v[216:219], v[204:207], v[12:15]
	ds_read_b128 v[180:183], v156 offset:2048
	v_mfma_f32_16x16x32_bf16 v[8:11], v[224:227], v[204:207], v[8:11]
	v_mfma_f32_16x16x32_bf16 v[4:7], v[216:219], v[212:215], v[4:7]
	ds_read_b128 v[184:187], v156 offset:3072
	v_mfma_f32_16x16x32_bf16 v[0:3], v[224:227], v[212:215], v[0:3]
	v_mfma_f32_16x16x32_bf16 v[28:31], v[220:223], v[192:195], v[28:31]
	v_mfma_f32_16x16x32_bf16 v[24:27], v[228:231], v[192:195], v[24:27]
	v_mfma_f32_16x16x32_bf16 v[20:23], v[220:223], v[200:203], v[20:23]
	v_mfma_f32_16x16x32_bf16 v[16:19], v[228:231], v[200:203], v[16:19]
	v_mfma_f32_16x16x32_bf16 v[12:15], v[220:223], v[208:211], v[12:15]
	v_mfma_f32_16x16x32_bf16 v[8:11], v[228:231], v[208:211], v[8:11]
	v_mfma_f32_16x16x32_bf16 v[4:7], v[220:223], v[232:235], v[4:7]
	v_mfma_f32_16x16x32_bf16 v[0:3], v[228:231], v[232:235], v[0:3]
	s_barrier
	v_add_u32_e32 v167, 0x4000, v148
	v_add_u32_e32 v168, 0x6000, v148
	v_readfirstlane_b32 s53, v167
	v_lshl_add_u64 v[220:221], v[236:237], 0, s[26:27]
	s_mov_b32 m0, s53
	v_readfirstlane_b32 s53, v168
	ds_read_b128 v[188:191], v152 offset:32768
	ds_read_b128 v[192:195], v152 offset:33792
	ds_read_b128 v[196:199], v151 offset:32768
	ds_read_b128 v[200:203], v151 offset:33792
	ds_read_b128 v[204:207], v150 offset:32768
	ds_read_b128 v[208:211], v150 offset:33792
	ds_read_b128 v[212:215], v149 offset:32768
	ds_read_b128 v[216:219], v149 offset:33792
	global_load_lds_dwordx4 v[220:221], off
	v_lshl_add_u64 v[220:221], v[238:239], 0, s[26:27]
	s_mov_b32 m0, s53
	s_nop 0
	global_load_lds_dwordx4 v[220:221], off
	s_waitcnt lgkmcnt(8)
	s_barrier
	s_waitcnt lgkmcnt(0)
	s_waitcnt lgkmcnt(0)
	v_mfma_f32_16x16x32_bf16 v[124:127], v[172:175], v[188:191], v[124:127]
	ds_read_b128 v[220:223], v154
	v_mfma_f32_16x16x32_bf16 v[120:123], v[180:183], v[188:191], v[120:123]
	v_mfma_f32_16x16x32_bf16 v[116:119], v[172:175], v[196:199], v[116:119]
	ds_read_b128 v[224:227], v154 offset:1024
	v_mfma_f32_16x16x32_bf16 v[112:115], v[180:183], v[196:199], v[112:115]
	v_mfma_f32_16x16x32_bf16 v[108:111], v[172:175], v[204:207], v[108:111]
	ds_read_b128 v[228:231], v154 offset:2048
	v_mfma_f32_16x16x32_bf16 v[104:107], v[180:183], v[204:207], v[104:107]
	v_mfma_f32_16x16x32_bf16 v[100:103], v[172:175], v[212:215], v[100:103]
	ds_read_b128 v[232:235], v154 offset:3072
	v_mfma_f32_16x16x32_bf16 v[96:99], v[180:183], v[212:215], v[96:99]
	v_mfma_f32_16x16x32_bf16 v[124:127], v[176:179], v[192:195], v[124:127]
	v_mfma_f32_16x16x32_bf16 v[120:123], v[184:187], v[192:195], v[120:123]
	v_mfma_f32_16x16x32_bf16 v[116:119], v[176:179], v[200:203], v[116:119]
	v_mfma_f32_16x16x32_bf16 v[112:115], v[184:187], v[200:203], v[112:115]
	v_mfma_f32_16x16x32_bf16 v[108:111], v[176:179], v[208:211], v[108:111]
	v_mfma_f32_16x16x32_bf16 v[104:107], v[184:187], v[208:211], v[104:107]
	v_mfma_f32_16x16x32_bf16 v[100:103], v[176:179], v[216:219], v[100:103]
	v_mfma_f32_16x16x32_bf16 v[96:99], v[184:187], v[216:219], v[96:99]
	s_barrier
	v_readfirstlane_b32 s53, v155
	v_add_u32_e32 v171, 0x2000, v155
	v_lshl_add_u64 v[244:245], v[240:241], 0, s[40:41]
	s_mov_b32 m0, s53
	v_readfirstlane_b32 s53, v171
	global_load_lds_dwordx4 v[244:245], off
	v_lshl_add_u64 v[244:245], v[242:243], 0, s[40:41]
	s_mov_b32 m0, s53
	s_nop 0
	global_load_lds_dwordx4 v[244:245], off
	s_barrier
	s_waitcnt lgkmcnt(0)
	s_waitcnt lgkmcnt(0)
	v_mfma_f32_16x16x32_bf16 v[92:95], v[220:223], v[188:191], v[92:95]
	v_mfma_f32_16x16x32_bf16 v[88:91], v[228:231], v[188:191], v[88:91]
	v_mfma_f32_16x16x32_bf16 v[84:87], v[220:223], v[196:199], v[84:87]
	v_mfma_f32_16x16x32_bf16 v[80:83], v[228:231], v[196:199], v[80:83]
	v_mfma_f32_16x16x32_bf16 v[76:79], v[220:223], v[204:207], v[76:79]
	v_mfma_f32_16x16x32_bf16 v[72:75], v[228:231], v[204:207], v[72:75]
	v_mfma_f32_16x16x32_bf16 v[68:71], v[220:223], v[212:215], v[68:71]
	v_mfma_f32_16x16x32_bf16 v[64:67], v[228:231], v[212:215], v[64:67]
	v_mfma_f32_16x16x32_bf16 v[92:95], v[224:227], v[192:195], v[92:95]
	v_mfma_f32_16x16x32_bf16 v[88:91], v[232:235], v[192:195], v[88:91]
	v_mfma_f32_16x16x32_bf16 v[84:87], v[224:227], v[200:203], v[84:87]
	v_mfma_f32_16x16x32_bf16 v[80:83], v[232:235], v[200:203], v[80:83]
	v_mfma_f32_16x16x32_bf16 v[76:79], v[224:227], v[208:211], v[76:79]
	v_mfma_f32_16x16x32_bf16 v[72:75], v[232:235], v[208:211], v[72:75]
	v_mfma_f32_16x16x32_bf16 v[68:71], v[224:227], v[216:219], v[68:71]
	v_mfma_f32_16x16x32_bf16 v[64:67], v[232:235], v[216:219], v[64:67]
	v_readfirstlane_b32 s53, v157
	v_lshl_add_u64 v[236:237], v[236:237], 0, s[42:43]
	s_mov_b32 m0, s53
	v_readfirstlane_b32 s53, v158
	s_barrier
; #define STAGE(P, BASE, LD, br, kt) do { const char* _g = (const char*)((BASE) + (size_t)(br) * (LD) + (size_t)(kt) * 64); \
;     for (int _i = 0; _i < 2; ++_i) { int _b = tidx * 16 + _i * 8192; int _r, _c; stage_rc(_b, _r, _c); \
;       __builtin_amdgcn_global_load_lds((const unsigned*)(_g + (unsigned)((_r * (LD) + _c) * 2)), (unsigned*)((char*)(P) + _b), 16, 0, 0); } } while (0)
; #define LDA(dst, b, h) for (int m = 0; m < 4; ++m) for (int k = 0; k < 2; ++k) \
;     dst[m][k] = *reinterpret_cast<const bf16x8*>((char*)SA(b, h) + lds_byte(wr * 64 + m * 16 + fr, k * 32 + fq * 8))
; #define LDB(dst, b, h) for (int n = 0; n < 2; ++n) for (int k = 0; k < 2; ++k) \
;     dst[n][k] = *reinterpret_cast<const bf16x8*>((char*)SB(b, h) + lds_byte(wc * 32 + n * 16 + fr, k * 32 + fq * 8))
; #define MMA(ai, bj, At_, Bt_) do { __builtin_amdgcn_s_setprio(1); \
;     for (int k = 0; k < 2; ++k) for (int m = 0; m < 4; ++m) for (int n = 0; n < 2; ++n) \
;       acc[ai][bj][m][n] = __builtin_amdgcn_mfma_f32_16x16x32_bf16(At_[m][k], Bt_[n][k], acc[ai][bj][m][n], 0, 0, 0); \
;     __builtin_amdgcn_s_setprio(0); } while (0)
; #define WAIT_V(n) asm volatile("s_waitcnt vmcnt(" #n ")" ::: "memory")
; #define WAIT_L(n) asm volatile("s_waitcnt lgkmcnt(" #n ")" ::: "memory")
; #define BAR __builtin_amdgcn_s_barrier()
; #define SCHED __builtin_amdgcn_sched_barrier(0)
; template <int EPI, int lda, int ldb, int N, int K>
; __device__ __forceinline__ void gemm_phase(const u16* __restrict__ A, const u16* __restrict__ Bt, const GemmEpi ep, int wv) {
;     ...
;       LDA(At, 1, 1); STAGE(SA(1, 0), Ab, lda, brow, t + 3);
;       BAR; WAIT_L(0); MMA(1, 0, At, B0); BAR; SCHED;
;       STAGE(SB(1, 1), Bt, ldb, bcol + HALF, t + 3);
;       WAIT_V(6); BAR; MMA(1, 1, At, B1); BAR;
;     }
;     { LDB(B0, 0, 0); LDA(At, 0, 0); STAGE(SA(1, 1), Ab, lda, brow + HALF, nt - 1);
;       BAR; WAIT_L(0); MMA(0, 0, At, B0); BAR;
	ds_read_b128 v[188:191], v152 offset:49152
	ds_read_b128 v[192:195], v152 offset:50176
	ds_read_b128 v[196:199], v151 offset:49152
	ds_read_b128 v[200:203], v151 offset:50176
	ds_read_b128 v[204:207], v150 offset:49152
	ds_read_b128 v[208:211], v150 offset:50176
	ds_read_b128 v[212:215], v149 offset:49152
	ds_read_b128 v[216:219], v149 offset:50176
	global_load_lds_dwordx4 v[236:237], off
	v_lshl_add_u64 v[236:237], v[238:239], 0, s[42:43]
	s_mov_b32 m0, s53
	s_nop 0
	global_load_lds_dwordx4 v[236:237], off
	s_barrier
	s_waitcnt lgkmcnt(0)
	s_waitcnt lgkmcnt(0)
	v_mfma_f32_16x16x32_bf16 v[60:63], v[172:175], v[188:191], v[60:63]
	v_mfma_f32_16x16x32_bf16 v[56:59], v[180:183], v[188:191], v[56:59]
	v_mfma_f32_16x16x32_bf16 v[52:55], v[172:175], v[196:199], v[52:55]
	v_mfma_f32_16x16x32_bf16 v[48:51], v[180:183], v[196:199], v[48:51]
	v_mfma_f32_16x16x32_bf16 v[44:47], v[172:175], v[204:207], v[44:47]
	v_mfma_f32_16x16x32_bf16 v[40:43], v[180:183], v[204:207], v[40:43]
	v_mfma_f32_16x16x32_bf16 v[36:39], v[172:175], v[212:215], v[36:39]
	v_mfma_f32_16x16x32_bf16 v[32:35], v[180:183], v[212:215], v[32:35]
	v_mfma_f32_16x16x32_bf16 v[60:63], v[176:179], v[192:195], v[60:63]
	v_mfma_f32_16x16x32_bf16 v[56:59], v[184:187], v[192:195], v[56:59]
	v_mfma_f32_16x16x32_bf16 v[52:55], v[176:179], v[200:203], v[52:55]
	v_mfma_f32_16x16x32_bf16 v[48:51], v[184:187], v[200:203], v[48:51]
	v_mfma_f32_16x16x32_bf16 v[44:47], v[176:179], v[208:211], v[44:47]
	v_mfma_f32_16x16x32_bf16 v[40:43], v[184:187], v[208:211], v[40:43]
	v_mfma_f32_16x16x32_bf16 v[36:39], v[176:179], v[216:219], v[36:39]
	v_mfma_f32_16x16x32_bf16 v[32:35], v[184:187], v[216:219], v[32:35]
	s_barrier
	v_readfirstlane_b32 s53, v159
	v_add_u32_e32 v171, 0x2000, v159
	v_lshl_add_u64 v[172:173], v[240:241], 0, s[44:45]
	s_mov_b32 m0, s53
	v_readfirstlane_b32 s53, v171
	global_load_lds_dwordx4 v[172:173], off
	v_lshl_add_u64 v[172:173], v[242:243], 0, s[44:45]
	s_mov_b32 m0, s53
	s_nop 0
	global_load_lds_dwordx4 v[172:173], off
	s_waitcnt vmcnt(6)
	s_barrier
	v_mfma_f32_16x16x32_bf16 v[28:31], v[220:223], v[188:191], v[28:31]
	v_mfma_f32_16x16x32_bf16 v[24:27], v[228:231], v[188:191], v[24:27]
	v_mfma_f32_16x16x32_bf16 v[20:23], v[220:223], v[196:199], v[20:23]
	v_mfma_f32_16x16x32_bf16 v[16:19], v[228:231], v[196:199], v[16:19]
	v_mfma_f32_16x16x32_bf16 v[12:15], v[220:223], v[204:207], v[12:15]
	v_mfma_f32_16x16x32_bf16 v[8:11], v[228:231], v[204:207], v[8:11]
	v_mfma_f32_16x16x32_bf16 v[4:7], v[220:223], v[212:215], v[4:7]
	v_mfma_f32_16x16x32_bf16 v[0:3], v[228:231], v[212:215], v[0:3]
	v_mfma_f32_16x16x32_bf16 v[28:31], v[224:227], v[192:195], v[28:31]
	v_mfma_f32_16x16x32_bf16 v[24:27], v[232:235], v[192:195], v[24:27]
	v_mfma_f32_16x16x32_bf16 v[20:23], v[224:227], v[200:203], v[20:23]
	v_mfma_f32_16x16x32_bf16 v[16:19], v[232:235], v[200:203], v[16:19]
	v_mfma_f32_16x16x32_bf16 v[12:15], v[224:227], v[208:211], v[12:15]
	v_mfma_f32_16x16x32_bf16 v[8:11], v[232:235], v[208:211], v[8:11]
	v_mfma_f32_16x16x32_bf16 v[4:7], v[224:227], v[216:219], v[4:7]
	v_mfma_f32_16x16x32_bf16 v[0:3], v[232:235], v[216:219], v[0:3]
	s_add_i32 s52, s52, 2
	s_add_u32 s50, s50, 0x100
	s_addc_u32 s51, s51, 0
	s_cmp_gt_u32 s52, 27
	s_barrier
	s_cbranch_scc0 .LBB0_770
	s_add_i32 s50, s48, 0x80
	s_mul_hi_i32 s51, s50, 0x1080
	s_mulk_i32 s50, 0x1080
	s_add_u32 s50, s61, s50
	s_addc_u32 s51, s62, s51
	v_lshl_add_u64 v[158:159], s[50:51], 0, v[128:129]
	v_readfirstlane_b32 s52, v169
	v_lshl_add_u64 v[158:159], v[158:159], 0, s[46:47]
	s_mov_b32 m0, s52
	ds_read_b128 v[134:137], v161
	ds_read_b128 v[138:141], v161 offset:1024
	ds_read_b128 v[172:175], v161 offset:2048
	ds_read_b128 v[176:179], v161 offset:3072
	ds_read_b128 v[180:183], v152
	ds_read_b128 v[184:187], v152 offset:1024
	ds_read_b128 v[188:191], v151
	ds_read_b128 v[192:195], v151 offset:1024
	ds_read_b128 v[196:199], v150
	ds_read_b128 v[200:203], v150 offset:1024
	ds_read_b128 v[204:207], v149
	ds_read_b128 v[208:211], v149 offset:1024
	global_load_lds_dwordx4 v[158:159], off
	v_lshl_add_u64 v[158:159], s[50:51], 0, v[132:133]
	v_readfirstlane_b32 s50, v170
	v_lshl_add_u64 v[158:159], v[158:159], 0, s[46:47]
	s_mov_b32 m0, s50
	s_nop 0
	global_load_lds_dwordx4 v[158:159], off
	s_barrier
	s_waitcnt lgkmcnt(0)
	s_waitcnt lgkmcnt(0)
	v_mfma_f32_16x16x32_bf16 v[124:127], v[134:137], v[180:183], v[124:127]
	v_mfma_f32_16x16x32_bf16 v[120:123], v[172:175], v[180:183], v[120:123]
	v_mfma_f32_16x16x32_bf16 v[116:119], v[134:137], v[188:191], v[116:119]
	v_mfma_f32_16x16x32_bf16 v[112:115], v[172:175], v[188:191], v[112:115]
	v_mfma_f32_16x16x32_bf16 v[108:111], v[134:137], v[196:199], v[108:111]
	v_mfma_f32_16x16x32_bf16 v[104:107], v[172:175], v[196:199], v[104:107]
	v_mfma_f32_16x16x32_bf16 v[100:103], v[134:137], v[204:207], v[100:103]
	v_mfma_f32_16x16x32_bf16 v[96:99], v[172:175], v[204:207], v[96:99]
	v_mfma_f32_16x16x32_bf16 v[124:127], v[138:141], v[184:187], v[124:127]
	v_mfma_f32_16x16x32_bf16 v[120:123], v[176:179], v[184:187], v[120:123]
	v_mfma_f32_16x16x32_bf16 v[116:119], v[138:141], v[192:195], v[116:119]
	v_mfma_f32_16x16x32_bf16 v[112:115], v[176:179], v[192:195], v[112:115]
	v_mfma_f32_16x16x32_bf16 v[108:111], v[138:141], v[200:203], v[108:111]
	v_mfma_f32_16x16x32_bf16 v[104:107], v[176:179], v[200:203], v[104:107]
	v_mfma_f32_16x16x32_bf16 v[100:103], v[138:141], v[208:211], v[100:103]
	v_mfma_f32_16x16x32_bf16 v[96:99], v[176:179], v[208:211], v[96:99]
	s_barrier
	ds_read_b128 v[212:215], v160
	ds_read_b128 v[216:219], v160 offset:1024
	ds_read_b128 v[220:223], v160 offset:2048
	ds_read_b128 v[158:161], v160 offset:3072
	s_barrier
; #define LDA(dst, b, h) for (int m = 0; m < 4; ++m) for (int k = 0; k < 2; ++k) \
;     dst[m][k] = *reinterpret_cast<const bf16x8*>((char*)SA(b, h) + lds_byte(wr * 64 + m * 16 + fr, k * 32 + fq * 8))
; #define LDB(dst, b, h) for (int n = 0; n < 2; ++n) for (int k = 0; k < 2; ++k) \
;     dst[n][k] = *reinterpret_cast<const bf16x8*>((char*)SB(b, h) + lds_byte(wc * 32 + n * 16 + fr, k * 32 + fq * 8))
; #define MMA(ai, bj, At_, Bt_) do { __builtin_amdgcn_s_setprio(1); \
;     for (int k = 0; k < 2; ++k) for (int m = 0; m < 4; ++m) for (int n = 0; n < 2; ++n) \
;       acc[ai][bj][m][n] = __builtin_amdgcn_mfma_f32_16x16x32_bf16(At_[m][k], Bt_[n][k], acc[ai][bj][m][n], 0, 0, 0); \
;     __builtin_amdgcn_s_setprio(0); } while (0)
; #define WAIT_V(n) asm volatile("s_waitcnt vmcnt(" #n ")" ::: "memory")
; #define WAIT_L(n) asm volatile("s_waitcnt lgkmcnt(" #n ")" ::: "memory")
; #define BAR __builtin_amdgcn_s_barrier()
; template <int EPI, int lda, int ldb, int N, int K>
; __device__ __forceinline__ void gemm_phase(const u16* __restrict__ A, const u16* __restrict__ Bt, const GemmEpi ep, int wv) {
;     ...
;       LDB(B1, 0, 1); BAR; WAIT_L(0); MMA(0, 1, At, B1); BAR;
;       LDA(At, 0, 1); WAIT_V(4); BAR; WAIT_L(0); MMA(1, 0, At, B0); MMA(1, 1, At, B1); BAR; }
;     { LDB(B0, 1, 0); LDA(At, 1, 0); WAIT_V(2); BAR; WAIT_L(0); MMA(0, 0, At, B0); BAR;
	s_waitcnt lgkmcnt(0)
	s_waitcnt lgkmcnt(0)
	v_mfma_f32_16x16x32_bf16 v[92:95], v[212:215], v[180:183], v[92:95]
	v_mfma_f32_16x16x32_bf16 v[88:91], v[220:223], v[180:183], v[88:91]
	v_mfma_f32_16x16x32_bf16 v[76:79], v[212:215], v[196:199], v[76:79]
	v_mfma_f32_16x16x32_bf16 v[72:75], v[220:223], v[196:199], v[72:75]
	v_mfma_f32_16x16x32_bf16 v[84:87], v[212:215], v[188:191], v[84:87]
	v_mfma_f32_16x16x32_bf16 v[80:83], v[220:223], v[188:191], v[80:83]
	v_mfma_f32_16x16x32_bf16 v[68:71], v[212:215], v[204:207], v[68:71]
	v_mfma_f32_16x16x32_bf16 v[64:67], v[220:223], v[204:207], v[64:67]
	v_mfma_f32_16x16x32_bf16 v[92:95], v[216:219], v[184:187], v[92:95]
	v_mfma_f32_16x16x32_bf16 v[88:91], v[158:161], v[184:187], v[88:91]
	v_mfma_f32_16x16x32_bf16 v[76:79], v[216:219], v[200:203], v[76:79]
	v_mfma_f32_16x16x32_bf16 v[72:75], v[158:161], v[200:203], v[72:75]
	v_mfma_f32_16x16x32_bf16 v[180:183], v[216:219], v[192:195], v[84:87]
	v_mfma_f32_16x16x32_bf16 v[184:187], v[158:161], v[192:195], v[80:83]
	v_mfma_f32_16x16x32_bf16 v[188:191], v[216:219], v[208:211], v[68:71]
	v_mfma_f32_16x16x32_bf16 v[192:195], v[158:161], v[208:211], v[64:67]
	s_barrier
	s_nop 0
	ds_read_b128 v[64:67], v152 offset:16384
	ds_read_b128 v[68:71], v152 offset:17408
	ds_read_b128 v[80:83], v151 offset:16384
	ds_read_b128 v[84:87], v151 offset:17408
	ds_read_b128 v[196:199], v150 offset:16384
	ds_read_b128 v[200:203], v150 offset:17408
	ds_read_b128 v[204:207], v149 offset:16384
	ds_read_b128 v[208:211], v149 offset:17408
	s_waitcnt vmcnt(4)
	s_barrier
	s_waitcnt lgkmcnt(0)
	s_waitcnt lgkmcnt(0)
	v_mfma_f32_16x16x32_bf16 v[60:63], v[134:137], v[64:67], v[60:63]
	v_mfma_f32_16x16x32_bf16 v[56:59], v[172:175], v[64:67], v[56:59]
	v_mfma_f32_16x16x32_bf16 v[52:55], v[134:137], v[80:83], v[52:55]
	v_mfma_f32_16x16x32_bf16 v[48:51], v[172:175], v[80:83], v[48:51]
	v_mfma_f32_16x16x32_bf16 v[44:47], v[134:137], v[196:199], v[44:47]
	v_mfma_f32_16x16x32_bf16 v[40:43], v[172:175], v[196:199], v[40:43]
	v_mfma_f32_16x16x32_bf16 v[36:39], v[134:137], v[204:207], v[36:39]
	v_mfma_f32_16x16x32_bf16 v[32:35], v[172:175], v[204:207], v[32:35]
	v_mfma_f32_16x16x32_bf16 v[60:63], v[138:141], v[68:71], v[60:63]
	v_mfma_f32_16x16x32_bf16 v[56:59], v[176:179], v[68:71], v[56:59]
	v_mfma_f32_16x16x32_bf16 v[52:55], v[138:141], v[84:87], v[52:55]
	v_mfma_f32_16x16x32_bf16 v[48:51], v[176:179], v[84:87], v[48:51]
	v_mfma_f32_16x16x32_bf16 v[44:47], v[138:141], v[200:203], v[44:47]
	v_mfma_f32_16x16x32_bf16 v[40:43], v[176:179], v[200:203], v[40:43]
	v_mfma_f32_16x16x32_bf16 v[36:39], v[138:141], v[208:211], v[36:39]
	v_mfma_f32_16x16x32_bf16 v[32:35], v[176:179], v[208:211], v[32:35]
	v_mfma_f32_16x16x32_bf16 v[28:31], v[212:215], v[64:67], v[28:31]
	v_mfma_f32_16x16x32_bf16 v[24:27], v[220:223], v[64:67], v[24:27]
	v_mfma_f32_16x16x32_bf16 v[12:15], v[212:215], v[196:199], v[12:15]
	v_mfma_f32_16x16x32_bf16 v[8:11], v[220:223], v[196:199], v[8:11]
	v_mfma_f32_16x16x32_bf16 v[20:23], v[212:215], v[80:83], v[20:23]
	v_mfma_f32_16x16x32_bf16 v[16:19], v[220:223], v[80:83], v[16:19]
	v_mfma_f32_16x16x32_bf16 v[4:7], v[212:215], v[204:207], v[4:7]
	v_mfma_f32_16x16x32_bf16 v[0:3], v[220:223], v[204:207], v[0:3]
	v_mfma_f32_16x16x32_bf16 v[28:31], v[216:219], v[68:71], v[28:31]
	v_mfma_f32_16x16x32_bf16 v[24:27], v[158:161], v[68:71], v[24:27]
	v_mfma_f32_16x16x32_bf16 v[12:15], v[216:219], v[200:203], v[12:15]
	v_mfma_f32_16x16x32_bf16 v[8:11], v[158:161], v[200:203], v[8:11]
	v_mfma_f32_16x16x32_bf16 v[134:137], v[216:219], v[84:87], v[20:23]
	v_mfma_f32_16x16x32_bf16 v[138:141], v[158:161], v[84:87], v[16:19]
	v_mfma_f32_16x16x32_bf16 v[170:173], v[216:219], v[208:211], v[4:7]
	v_mfma_f32_16x16x32_bf16 v[158:161], v[158:161], v[208:211], v[0:3]
	s_barrier
	s_nop 0
	ds_read_b128 v[0:3], v156
	ds_read_b128 v[4:7], v156 offset:1024
	ds_read_b128 v[16:19], v156 offset:2048
	ds_read_b128 v[174:177], v156 offset:3072
	ds_read_b128 v[20:23], v152 offset:32768
	ds_read_b128 v[196:199], v152 offset:33792
	ds_read_b128 v[200:203], v151 offset:32768
	ds_read_b128 v[204:207], v151 offset:33792
	ds_read_b128 v[208:211], v150 offset:32768
	ds_read_b128 v[212:215], v150 offset:33792
	ds_read_b128 v[216:219], v149 offset:32768
	ds_read_b128 v[220:223], v149 offset:33792
	s_waitcnt vmcnt(2)
	s_barrier
; #define LDA(dst, b, h) for (int m = 0; m < 4; ++m) for (int k = 0; k < 2; ++k) \
;     dst[m][k] = *reinterpret_cast<const bf16x8*>((char*)SA(b, h) + lds_byte(wr * 64 + m * 16 + fr, k * 32 + fq * 8))
; #define LDB(dst, b, h) for (int n = 0; n < 2; ++n) for (int k = 0; k < 2; ++k) \
;     dst[n][k] = *reinterpret_cast<const bf16x8*>((char*)SB(b, h) + lds_byte(wc * 32 + n * 16 + fr, k * 32 + fq * 8))
; #define MMA(ai, bj, At_, Bt_) do { __builtin_amdgcn_s_setprio(1); \
;     for (int k = 0; k < 2; ++k) for (int m = 0; m < 4; ++m) for (int n = 0; n < 2; ++n) \
;       acc[ai][bj][m][n] = __builtin_amdgcn_mfma_f32_16x16x32_bf16(At_[m][k], Bt_[n][k], acc[ai][bj][m][n], 0, 0, 0); \
;     __builtin_amdgcn_s_setprio(0); } while (0)
; #define WAIT_V(n) asm volatile("s_waitcnt vmcnt(" #n ")" ::: "memory")
; #define WAIT_L(n) asm volatile("s_waitcnt lgkmcnt(" #n ")" ::: "memory")
; #define BAR __builtin_amdgcn_s_barrier()
; template <int EPI, int lda, int ldb, int N, int K>
; __device__ __forceinline__ void gemm_phase(const u16* __restrict__ A, const u16* __restrict__ Bt, const GemmEpi ep, int wv) {
;     ...
;     { LDB(B0, 1, 0); LDA(At, 1, 0); WAIT_V(2); BAR; WAIT_L(0); MMA(0, 0, At, B0); BAR;
;       LDB(B1, 1, 1); WAIT_V(0); BAR; WAIT_L(0); MMA(0, 1, At, B1); BAR;
;       LDA(At, 1, 1); BAR; WAIT_L(0); MMA(1, 0, At, B0); MMA(1, 1, At, B1); BAR; }
;     if (wr == 0) BAR;
	s_waitcnt lgkmcnt(0)
	s_waitcnt lgkmcnt(0)
	v_mfma_f32_16x16x32_bf16 v[64:67], v[0:3], v[20:23], v[124:127]
	v_mfma_f32_16x16x32_bf16 v[68:71], v[16:19], v[20:23], v[120:123]
	v_mfma_f32_16x16x32_bf16 v[80:83], v[0:3], v[200:203], v[116:119]
	v_mfma_f32_16x16x32_bf16 v[84:87], v[16:19], v[200:203], v[112:115]
	v_mfma_f32_16x16x32_bf16 v[108:111], v[0:3], v[208:211], v[108:111]
	v_mfma_f32_16x16x32_bf16 v[104:107], v[16:19], v[208:211], v[104:107]
	v_mfma_f32_16x16x32_bf16 v[120:123], v[0:3], v[216:219], v[100:103]
	v_mfma_f32_16x16x32_bf16 v[124:127], v[16:19], v[216:219], v[96:99]
	v_mfma_f32_16x16x32_bf16 v[116:119], v[4:7], v[196:199], v[64:67]
	v_mfma_f32_16x16x32_bf16 v[112:115], v[174:177], v[196:199], v[68:71]
	v_mfma_f32_16x16x32_bf16 v[100:103], v[4:7], v[204:207], v[80:83]
	v_mfma_f32_16x16x32_bf16 v[96:99], v[174:177], v[204:207], v[84:87]
	v_mfma_f32_16x16x32_bf16 v[84:87], v[4:7], v[212:215], v[108:111]
	v_mfma_f32_16x16x32_bf16 v[80:83], v[174:177], v[212:215], v[104:107]
	v_mfma_f32_16x16x32_bf16 v[68:71], v[4:7], v[220:223], v[120:123]
	v_mfma_f32_16x16x32_bf16 v[64:67], v[174:177], v[220:223], v[124:127]
	s_barrier
	ds_read_b128 v[224:227], v154
	ds_read_b128 v[228:231], v154 offset:1024
	ds_read_b128 v[232:235], v154 offset:2048
	ds_read_b128 v[154:157], v154 offset:3072
	s_waitcnt vmcnt(0)
	s_barrier
	s_waitcnt lgkmcnt(0)
	s_waitcnt lgkmcnt(0)
	v_mfma_f32_16x16x32_bf16 v[92:95], v[224:227], v[20:23], v[92:95]
	v_mfma_f32_16x16x32_bf16 v[20:23], v[232:235], v[20:23], v[88:91]
	v_mfma_f32_16x16x32_bf16 v[88:91], v[224:227], v[200:203], v[180:183]
	v_mfma_f32_16x16x32_bf16 v[104:107], v[232:235], v[200:203], v[184:187]
	v_mfma_f32_16x16x32_bf16 v[76:79], v[224:227], v[208:211], v[76:79]
	v_mfma_f32_16x16x32_bf16 v[72:75], v[232:235], v[208:211], v[72:75]
	v_mfma_f32_16x16x32_bf16 v[178:181], v[224:227], v[216:219], v[188:191]
	v_mfma_f32_16x16x32_bf16 v[182:185], v[232:235], v[216:219], v[192:195]
	v_mfma_f32_16x16x32_bf16 v[124:127], v[228:231], v[196:199], v[92:95]
	v_mfma_f32_16x16x32_bf16 v[120:123], v[154:157], v[196:199], v[20:23]
	v_mfma_f32_16x16x32_bf16 v[108:111], v[228:231], v[204:207], v[88:91]
	v_mfma_f32_16x16x32_bf16 v[104:107], v[154:157], v[204:207], v[104:107]
	v_mfma_f32_16x16x32_bf16 v[92:95], v[228:231], v[212:215], v[76:79]
	v_mfma_f32_16x16x32_bf16 v[88:91], v[154:157], v[212:215], v[72:75]
	v_mfma_f32_16x16x32_bf16 v[76:79], v[228:231], v[220:223], v[178:181]
	v_mfma_f32_16x16x32_bf16 v[72:75], v[154:157], v[220:223], v[182:185]
	s_barrier
	ds_read_b128 v[178:181], v152 offset:49152
	ds_read_b128 v[182:185], v152 offset:50176
	ds_read_b128 v[186:189], v151 offset:49152
	ds_read_b128 v[190:193], v151 offset:50176
	ds_read_b128 v[194:197], v150 offset:49152
	ds_read_b128 v[150:153], v150 offset:50176
	ds_read_b128 v[198:201], v149 offset:49152
	ds_read_b128 v[202:205], v149 offset:50176
	s_barrier
	s_waitcnt lgkmcnt(0)
	s_waitcnt lgkmcnt(0)
	v_mfma_f32_16x16x32_bf16 v[20:23], v[0:3], v[178:181], v[60:63]
	v_mfma_f32_16x16x32_bf16 v[56:59], v[16:19], v[178:181], v[56:59]
	v_mfma_f32_16x16x32_bf16 v[60:63], v[0:3], v[186:189], v[52:55]
	v_mfma_f32_16x16x32_bf16 v[206:209], v[16:19], v[186:189], v[48:51]
	v_mfma_f32_16x16x32_bf16 v[44:47], v[0:3], v[194:197], v[44:47]
	v_mfma_f32_16x16x32_bf16 v[40:43], v[16:19], v[194:197], v[40:43]
	v_mfma_f32_16x16x32_bf16 v[0:3], v[0:3], v[198:201], v[36:39]
	v_mfma_f32_16x16x32_bf16 v[210:213], v[16:19], v[198:201], v[32:35]
	v_mfma_f32_16x16x32_bf16 v[52:55], v[4:7], v[182:185], v[20:23]
	v_mfma_f32_16x16x32_bf16 v[48:51], v[174:177], v[182:185], v[56:59]
	v_mfma_f32_16x16x32_bf16 v[36:39], v[4:7], v[190:193], v[60:63]
	v_mfma_f32_16x16x32_bf16 v[32:35], v[174:177], v[190:193], v[206:209]
	v_mfma_f32_16x16x32_bf16 v[20:23], v[4:7], v[150:153], v[44:47]
	v_mfma_f32_16x16x32_bf16 v[16:19], v[174:177], v[150:153], v[40:43]
	v_mfma_f32_16x16x32_bf16 v[4:7], v[4:7], v[202:205], v[0:3]
	v_mfma_f32_16x16x32_bf16 v[0:3], v[174:177], v[202:205], v[210:213]
	v_mfma_f32_16x16x32_bf16 v[28:31], v[224:227], v[178:181], v[28:31]
	v_mfma_f32_16x16x32_bf16 v[24:27], v[232:235], v[178:181], v[24:27]
	v_mfma_f32_16x16x32_bf16 v[40:43], v[224:227], v[186:189], v[134:137]
	v_mfma_f32_16x16x32_bf16 v[134:137], v[232:235], v[186:189], v[138:141]
	v_mfma_f32_16x16x32_bf16 v[12:15], v[224:227], v[194:197], v[12:15]
	v_mfma_f32_16x16x32_bf16 v[8:11], v[232:235], v[194:197], v[8:11]
	v_mfma_f32_16x16x32_bf16 v[138:141], v[224:227], v[198:201], v[170:173]
	v_mfma_f32_16x16x32_bf16 v[158:161], v[232:235], v[198:201], v[158:161]
	v_mfma_f32_16x16x32_bf16 v[60:63], v[228:231], v[182:185], v[28:31]
	v_mfma_f32_16x16x32_bf16 v[56:59], v[154:157], v[182:185], v[24:27]
	v_mfma_f32_16x16x32_bf16 v[44:47], v[228:231], v[190:193], v[40:43]
	v_mfma_f32_16x16x32_bf16 v[40:43], v[154:157], v[190:193], v[134:137]
	v_mfma_f32_16x16x32_bf16 v[28:31], v[228:231], v[150:153], v[12:15]
	v_mfma_f32_16x16x32_bf16 v[24:27], v[154:157], v[150:153], v[8:11]
	v_mfma_f32_16x16x32_bf16 v[12:15], v[228:231], v[202:205], v[138:141]
	v_mfma_f32_16x16x32_bf16 v[8:11], v[154:157], v[202:205], v[158:161]
	v_cmp_gt_u32_e32 vcc, s66, v130
	s_barrier
	s_and_saveexec_b64 s[50:51], vcc
	s_cbranch_execz .LBB0_773
	s_barrier

; #define STAGE(P, BASE, LD, br, kt) do { const char* _g = (const char*)((BASE) + (size_t)(br) * (LD) + (size_t)(kt) * 64); \
;     for (int _i = 0; _i < 2; ++_i) { int _b = tidx * 16 + _i * 8192; int _r, _c; stage_rc(_b, _r, _c); \
;       __builtin_amdgcn_global_load_lds((const unsigned*)(_g + (unsigned)((_r * (LD) + _c) * 2)), (unsigned*)((char*)(P) + _b), 16, 0, 0); } } while (0)
; #define LDA(dst, b, h) for (int m = 0; m < 4; ++m) for (int k = 0; k < 2; ++k) \
;     dst[m][k] = *reinterpret_cast<const bf16x8*>((char*)SA(b, h) + lds_byte(wr * 64 + m * 16 + fr, k * 32 + fq * 8))
; #define LDB(dst, b, h) for (int n = 0; n < 2; ++n) for (int k = 0; k < 2; ++k) \
;     dst[n][k] = *reinterpret_cast<const bf16x8*>((char*)SB(b, h) + lds_byte(wc * 32 + n * 16 + fr, k * 32 + fq * 8))
; #define MMA(ai, bj, At_, Bt_) do { __builtin_amdgcn_s_setprio(1); \
;     for (int k = 0; k < 2; ++k) for (int m = 0; m < 4; ++m) for (int n = 0; n < 2; ++n) \
;       acc[ai][bj][m][n] = __builtin_amdgcn_mfma_f32_16x16x32_bf16(At_[m][k], Bt_[n][k], acc[ai][bj][m][n], 0, 0, 0); \
;     __builtin_amdgcn_s_setprio(0); } while (0)
; #define WAIT_V(n) asm volatile("s_waitcnt vmcnt(" #n ")" ::: "memory")
; #define WAIT_L(n) asm volatile("s_waitcnt lgkmcnt(" #n ")" ::: "memory")
; #define BAR __builtin_amdgcn_s_barrier()
; #define SCHED __builtin_amdgcn_sched_barrier(0)
; template <int EPI, int lda, int ldb, int N, int K>
; __device__ __forceinline__ void gemm_phase(const u16* __restrict__ A, const u16* __restrict__ Bt, const GemmEpi ep, int wv) {
;     ...
;     for (int t = 0; t < nt - 2; t += 2) {
;       LDB(B0, 0, 0); SCHED; LDA(At, 0, 0); STAGE(SA(1, 1), Ab, lda, brow + HALF, t + 1);
;       WAIT_L(8); BAR; WAIT_L(0); MMA(0, 0, At, B0); BAR; SCHED;
;       LDB(B1, 0, 1); STAGE(SB(0, 0), Bt, ldb, bcol, t + 2);
;       BAR; WAIT_L(0); MMA(0, 1, At, B1); BAR;
;       LDA(At, 0, 1); STAGE(SA(0, 0), Ab, lda, brow, t + 2);
;       BAR; WAIT_L(0); MMA(1, 0, At, B0); BAR; SCHED;
;       STAGE(SB(0, 1), Bt, ldb, bcol + HALF, t + 2);
;       WAIT_V(6); BAR; MMA(1, 1, At, B1); BAR;
.LBB0_838:
	ds_read_b128 v[168:171], v164
	ds_read_b128 v[174:177], v164 offset:1024
	ds_read_b128 v[178:181], v164 offset:2048
	ds_read_b128 v[182:185], v164 offset:3072
	v_add_u32_e32 v172, 0xc000, v147
	v_lshl_add_u64 v[238:239], v[136:137], 0, s[50:51]
	v_readfirstlane_b32 s73, v172
	v_add_u32_e32 v173, 0xe000, v147
	v_lshl_add_u64 v[166:167], v[238:239], 0, s[22:23]
	s_mov_b32 m0, s73
	v_lshl_add_u64 v[240:241], v[134:135], 0, s[50:51]
	v_readfirstlane_b32 s73, v173
	ds_read_b128 v[186:189], v155
	ds_read_b128 v[190:193], v155 offset:1024
	ds_read_b128 v[194:197], v154
	ds_read_b128 v[198:201], v154 offset:1024
	ds_read_b128 v[202:205], v153
	ds_read_b128 v[206:209], v153 offset:1024
	ds_read_b128 v[210:213], v152
	ds_read_b128 v[214:217], v152 offset:1024
	global_load_lds_dwordx4 v[166:167], off
	v_lshl_add_u64 v[166:167], v[240:241], 0, s[22:23]
	s_mov_b32 m0, s73
	s_nop 0
	global_load_lds_dwordx4 v[166:167], off
	s_waitcnt lgkmcnt(8)
	s_barrier
	s_waitcnt lgkmcnt(0)
	s_waitcnt lgkmcnt(0)
	v_mfma_f32_16x16x32_bf16 v[124:127], v[168:171], v[186:189], v[124:127]
	ds_read_b128 v[218:221], v163
	v_mfma_f32_16x16x32_bf16 v[120:123], v[178:181], v[186:189], v[120:123]
	v_mfma_f32_16x16x32_bf16 v[116:119], v[168:171], v[194:197], v[116:119]
	ds_read_b128 v[222:225], v163 offset:1024
	v_mfma_f32_16x16x32_bf16 v[112:115], v[178:181], v[194:197], v[112:115]
	v_mfma_f32_16x16x32_bf16 v[108:111], v[168:171], v[202:205], v[108:111]
	ds_read_b128 v[226:229], v163 offset:2048
	v_mfma_f32_16x16x32_bf16 v[104:107], v[178:181], v[202:205], v[104:107]
	v_mfma_f32_16x16x32_bf16 v[100:103], v[168:171], v[210:213], v[100:103]
	ds_read_b128 v[230:233], v163 offset:3072
	v_mfma_f32_16x16x32_bf16 v[96:99], v[178:181], v[210:213], v[96:99]
	v_mfma_f32_16x16x32_bf16 v[124:127], v[174:177], v[190:193], v[124:127]
	v_mfma_f32_16x16x32_bf16 v[120:123], v[182:185], v[190:193], v[120:123]
	v_mfma_f32_16x16x32_bf16 v[116:119], v[174:177], v[198:201], v[116:119]
	v_mfma_f32_16x16x32_bf16 v[112:115], v[182:185], v[198:201], v[112:115]
	v_mfma_f32_16x16x32_bf16 v[108:111], v[174:177], v[206:209], v[108:111]
	v_mfma_f32_16x16x32_bf16 v[104:107], v[182:185], v[206:209], v[104:107]
	v_mfma_f32_16x16x32_bf16 v[100:103], v[174:177], v[214:217], v[100:103]
	v_mfma_f32_16x16x32_bf16 v[96:99], v[182:185], v[214:217], v[96:99]
	s_barrier
	v_add_u32_e32 v165, s63, v156
	v_lshl_add_u64 v[242:243], v[144:145], 0, s[50:51]
	v_readfirstlane_b32 s73, v165
	v_lshl_add_u64 v[166:167], v[242:243], 0, s[24:25]
	s_mov_b32 m0, s73
	global_load_lds_dwordx4 v[166:167], off
	v_add_u32_e32 v166, 0x2000, v165
	v_lshl_add_u64 v[244:245], v[142:143], 0, s[50:51]
	v_readfirstlane_b32 s73, v166
	v_lshl_add_u64 v[234:235], v[244:245], 0, s[24:25]
	s_mov_b32 m0, s73
	s_nop 0
	global_load_lds_dwordx4 v[234:235], off
	s_barrier
	s_waitcnt lgkmcnt(0)
	s_waitcnt lgkmcnt(0)
	v_mfma_f32_16x16x32_bf16 v[92:95], v[218:221], v[186:189], v[92:95]
	v_mfma_f32_16x16x32_bf16 v[88:91], v[226:229], v[186:189], v[88:91]
	v_mfma_f32_16x16x32_bf16 v[84:87], v[218:221], v[194:197], v[84:87]
	v_mfma_f32_16x16x32_bf16 v[80:83], v[226:229], v[194:197], v[80:83]
	v_mfma_f32_16x16x32_bf16 v[76:79], v[218:221], v[202:205], v[76:79]
	v_mfma_f32_16x16x32_bf16 v[72:75], v[226:229], v[202:205], v[72:75]
	v_mfma_f32_16x16x32_bf16 v[68:71], v[218:221], v[210:213], v[68:71]
	v_mfma_f32_16x16x32_bf16 v[64:67], v[226:229], v[210:213], v[64:67]
	v_mfma_f32_16x16x32_bf16 v[92:95], v[222:225], v[190:193], v[92:95]
	v_mfma_f32_16x16x32_bf16 v[88:91], v[230:233], v[190:193], v[88:91]
	v_mfma_f32_16x16x32_bf16 v[84:87], v[222:225], v[198:201], v[84:87]
	v_mfma_f32_16x16x32_bf16 v[80:83], v[230:233], v[198:201], v[80:83]
	v_mfma_f32_16x16x32_bf16 v[76:79], v[222:225], v[206:209], v[76:79]
	v_mfma_f32_16x16x32_bf16 v[72:75], v[230:233], v[206:209], v[72:75]
	v_mfma_f32_16x16x32_bf16 v[68:71], v[222:225], v[214:217], v[68:71]
	v_mfma_f32_16x16x32_bf16 v[64:67], v[230:233], v[214:217], v[64:67]
	v_readfirstlane_b32 s73, v147
	v_add_u32_e32 v167, 0x2000, v147
	v_lshl_add_u64 v[234:235], v[238:239], 0, s[26:27]
	s_mov_b32 m0, s73
	v_readfirstlane_b32 s73, v167
	s_barrier
	ds_read_b128 v[186:189], v155 offset:16384
	ds_read_b128 v[190:193], v155 offset:17408
	ds_read_b128 v[194:197], v154 offset:16384
	ds_read_b128 v[198:201], v154 offset:17408
	ds_read_b128 v[202:205], v153 offset:16384
	ds_read_b128 v[206:209], v153 offset:17408
	ds_read_b128 v[210:213], v152 offset:16384
	ds_read_b128 v[214:217], v152 offset:17408
	global_load_lds_dwordx4 v[234:235], off
	v_lshl_add_u64 v[234:235], v[240:241], 0, s[26:27]
	s_mov_b32 m0, s73
	s_nop 0
	global_load_lds_dwordx4 v[234:235], off
	s_barrier
	s_waitcnt lgkmcnt(0)
	s_waitcnt lgkmcnt(0)
	v_mfma_f32_16x16x32_bf16 v[60:63], v[168:171], v[186:189], v[60:63]
	v_mfma_f32_16x16x32_bf16 v[56:59], v[178:181], v[186:189], v[56:59]
	v_mfma_f32_16x16x32_bf16 v[52:55], v[168:171], v[194:197], v[52:55]
	v_mfma_f32_16x16x32_bf16 v[48:51], v[178:181], v[194:197], v[48:51]
	v_mfma_f32_16x16x32_bf16 v[44:47], v[168:171], v[202:205], v[44:47]
	v_mfma_f32_16x16x32_bf16 v[40:43], v[178:181], v[202:205], v[40:43]
	v_mfma_f32_16x16x32_bf16 v[36:39], v[168:171], v[210:213], v[36:39]
	v_mfma_f32_16x16x32_bf16 v[32:35], v[178:181], v[210:213], v[32:35]
	v_mfma_f32_16x16x32_bf16 v[60:63], v[174:177], v[190:193], v[60:63]
	v_mfma_f32_16x16x32_bf16 v[56:59], v[182:185], v[190:193], v[56:59]
	v_mfma_f32_16x16x32_bf16 v[52:55], v[174:177], v[198:201], v[52:55]
	v_mfma_f32_16x16x32_bf16 v[48:51], v[182:185], v[198:201], v[48:51]
	v_mfma_f32_16x16x32_bf16 v[44:47], v[174:177], v[206:209], v[44:47]
	v_mfma_f32_16x16x32_bf16 v[40:43], v[182:185], v[206:209], v[40:43]
	v_mfma_f32_16x16x32_bf16 v[36:39], v[174:177], v[214:217], v[36:39]
	v_mfma_f32_16x16x32_bf16 v[32:35], v[182:185], v[214:217], v[32:35]
	s_barrier
; #define STAGE(P, BASE, LD, br, kt) do { const char* _g = (const char*)((BASE) + (size_t)(br) * (LD) + (size_t)(kt) * 64); \
;     for (int _i = 0; _i < 2; ++_i) { int _b = tidx * 16 + _i * 8192; int _r, _c; stage_rc(_b, _r, _c); \
;       __builtin_amdgcn_global_load_lds((const unsigned*)(_g + (unsigned)((_r * (LD) + _c) * 2)), (unsigned*)((char*)(P) + _b), 16, 0, 0); } } while (0)
; #define LDA(dst, b, h) for (int m = 0; m < 4; ++m) for (int k = 0; k < 2; ++k) \
;     dst[m][k] = *reinterpret_cast<const bf16x8*>((char*)SA(b, h) + lds_byte(wr * 64 + m * 16 + fr, k * 32 + fq * 8))
; #define LDB(dst, b, h) for (int n = 0; n < 2; ++n) for (int k = 0; k < 2; ++k) \
;     dst[n][k] = *reinterpret_cast<const bf16x8*>((char*)SB(b, h) + lds_byte(wc * 32 + n * 16 + fr, k * 32 + fq * 8))
; #define MMA(ai, bj, At_, Bt_) do { __builtin_amdgcn_s_setprio(1); \
;     for (int k = 0; k < 2; ++k) for (int m = 0; m < 4; ++m) for (int n = 0; n < 2; ++n) \
;       acc[ai][bj][m][n] = __builtin_amdgcn_mfma_f32_16x16x32_bf16(At_[m][k], Bt_[n][k], acc[ai][bj][m][n], 0, 0, 0); \
;     __builtin_amdgcn_s_setprio(0); } while (0)
; #define WAIT_V(n) asm volatile("s_waitcnt vmcnt(" #n ")" ::: "memory")
; #define WAIT_L(n) asm volatile("s_waitcnt lgkmcnt(" #n ")" ::: "memory")
; #define BAR __builtin_amdgcn_s_barrier()
; #define SCHED __builtin_amdgcn_sched_barrier(0)
; template <int EPI, int lda, int ldb, int N, int K>
; __device__ __forceinline__ void gemm_phase(const u16* __restrict__ A, const u16* __restrict__ Bt, const GemmEpi ep, int wv) {
;     ...
;       WAIT_V(6); BAR; MMA(1, 1, At, B1); BAR;
;       LDB(B0, 1, 0); SCHED; LDA(At, 1, 0); STAGE(SA(0, 1), Ab, lda, brow + HALF, t + 2);
;       WAIT_L(8); BAR; WAIT_L(0); MMA(0, 0, At, B0); BAR; SCHED;
;       LDB(B1, 1, 1); STAGE(SB(1, 0), Bt, ldb, bcol, t + 3);
;       BAR; WAIT_L(0); MMA(0, 1, At, B1); BAR;
;       LDA(At, 1, 1); STAGE(SA(1, 0), Ab, lda, brow, t + 3);
;       BAR; WAIT_L(0); MMA(1, 0, At, B0); BAR; SCHED;
	v_add_u32_e32 v168, s64, v156
	v_lshl_add_u64 v[246:247], v[140:141], 0, s[50:51]
	v_readfirstlane_b32 s73, v168
	v_add_u32_e32 v169, 0x2000, v168
	v_lshl_add_u64 v[170:171], v[246:247], 0, s[40:41]
	s_mov_b32 m0, s73
	v_lshl_add_u64 v[248:249], v[138:139], 0, s[50:51]
	v_readfirstlane_b32 s73, v169
	global_load_lds_dwordx4 v[170:171], off
	v_lshl_add_u64 v[170:171], v[248:249], 0, s[40:41]
	s_mov_b32 m0, s73
	s_nop 0
	global_load_lds_dwordx4 v[170:171], off
	s_waitcnt vmcnt(6)
	s_barrier
	v_mfma_f32_16x16x32_bf16 v[28:31], v[218:221], v[186:189], v[28:31]
	v_mfma_f32_16x16x32_bf16 v[24:27], v[226:229], v[186:189], v[24:27]
	ds_read_b128 v[174:177], v159
	v_mfma_f32_16x16x32_bf16 v[20:23], v[218:221], v[194:197], v[20:23]
	v_mfma_f32_16x16x32_bf16 v[16:19], v[226:229], v[194:197], v[16:19]
	ds_read_b128 v[178:181], v159 offset:1024
	v_mfma_f32_16x16x32_bf16 v[12:15], v[218:221], v[202:205], v[12:15]
	v_mfma_f32_16x16x32_bf16 v[8:11], v[226:229], v[202:205], v[8:11]
	ds_read_b128 v[182:185], v159 offset:2048
	v_mfma_f32_16x16x32_bf16 v[4:7], v[218:221], v[210:213], v[4:7]
	v_mfma_f32_16x16x32_bf16 v[0:3], v[226:229], v[210:213], v[0:3]
	ds_read_b128 v[186:189], v159 offset:3072
	v_mfma_f32_16x16x32_bf16 v[28:31], v[222:225], v[190:193], v[28:31]
	v_mfma_f32_16x16x32_bf16 v[24:27], v[230:233], v[190:193], v[24:27]
	v_mfma_f32_16x16x32_bf16 v[20:23], v[222:225], v[198:201], v[20:23]
	v_mfma_f32_16x16x32_bf16 v[16:19], v[230:233], v[198:201], v[16:19]
	v_mfma_f32_16x16x32_bf16 v[12:15], v[222:225], v[206:209], v[12:15]
	v_mfma_f32_16x16x32_bf16 v[8:11], v[230:233], v[206:209], v[8:11]
	v_mfma_f32_16x16x32_bf16 v[4:7], v[222:225], v[214:217], v[4:7]
	v_mfma_f32_16x16x32_bf16 v[0:3], v[230:233], v[214:217], v[0:3]
	s_barrier
	v_add_u32_e32 v170, 0x4000, v147
	v_add_u32_e32 v171, 0x6000, v147
	v_readfirstlane_b32 s73, v170
	v_lshl_add_u64 v[222:223], v[238:239], 0, s[42:43]
	s_mov_b32 m0, s73
	v_readfirstlane_b32 s73, v171
	ds_read_b128 v[190:193], v155 offset:32768
	ds_read_b128 v[194:197], v155 offset:33792
	ds_read_b128 v[198:201], v154 offset:32768
	ds_read_b128 v[202:205], v154 offset:33792
	ds_read_b128 v[206:209], v153 offset:32768
	ds_read_b128 v[210:213], v153 offset:33792
	ds_read_b128 v[214:217], v152 offset:32768
	ds_read_b128 v[218:221], v152 offset:33792
	global_load_lds_dwordx4 v[222:223], off
	v_lshl_add_u64 v[222:223], v[240:241], 0, s[42:43]
	s_mov_b32 m0, s73
	s_nop 0
	global_load_lds_dwordx4 v[222:223], off
	s_waitcnt lgkmcnt(8)
	s_barrier
	s_waitcnt lgkmcnt(0)
	s_waitcnt lgkmcnt(0)
	v_mfma_f32_16x16x32_bf16 v[124:127], v[174:177], v[190:193], v[124:127]
	ds_read_b128 v[222:225], v157
	v_mfma_f32_16x16x32_bf16 v[120:123], v[182:185], v[190:193], v[120:123]
	v_mfma_f32_16x16x32_bf16 v[116:119], v[174:177], v[198:201], v[116:119]
	ds_read_b128 v[226:229], v157 offset:1024
	v_mfma_f32_16x16x32_bf16 v[112:115], v[182:185], v[198:201], v[112:115]
	v_mfma_f32_16x16x32_bf16 v[108:111], v[174:177], v[206:209], v[108:111]
	ds_read_b128 v[230:233], v157 offset:2048
	v_mfma_f32_16x16x32_bf16 v[104:107], v[182:185], v[206:209], v[104:107]
	v_mfma_f32_16x16x32_bf16 v[100:103], v[174:177], v[214:217], v[100:103]
	ds_read_b128 v[234:237], v157 offset:3072
	v_mfma_f32_16x16x32_bf16 v[96:99], v[182:185], v[214:217], v[96:99]
	v_mfma_f32_16x16x32_bf16 v[124:127], v[178:181], v[194:197], v[124:127]
	v_mfma_f32_16x16x32_bf16 v[120:123], v[186:189], v[194:197], v[120:123]
	v_mfma_f32_16x16x32_bf16 v[116:119], v[178:181], v[202:205], v[116:119]
	v_mfma_f32_16x16x32_bf16 v[112:115], v[186:189], v[202:205], v[112:115]
	v_mfma_f32_16x16x32_bf16 v[108:111], v[178:181], v[210:213], v[108:111]
	v_mfma_f32_16x16x32_bf16 v[104:107], v[186:189], v[210:213], v[104:107]
	v_mfma_f32_16x16x32_bf16 v[100:103], v[178:181], v[218:221], v[100:103]
	v_mfma_f32_16x16x32_bf16 v[96:99], v[186:189], v[218:221], v[96:99]
	s_barrier
	v_readfirstlane_b32 s73, v158
	v_lshl_add_u64 v[242:243], v[242:243], 0, s[44:45]
	s_mov_b32 m0, s73
	global_load_lds_dwordx4 v[242:243], off
	v_lshl_add_u64 v[242:243], v[244:245], 0, s[44:45]
	v_add_u32_e32 v244, 0x2000, v158
	s_nop 0
	v_readfirstlane_b32 s73, v244
	s_mov_b32 m0, s73
	s_nop 0
	global_load_lds_dwordx4 v[242:243], off
	s_barrier
	s_waitcnt lgkmcnt(0)
	s_waitcnt lgkmcnt(0)
	v_mfma_f32_16x16x32_bf16 v[92:95], v[222:225], v[190:193], v[92:95]
	v_mfma_f32_16x16x32_bf16 v[88:91], v[230:233], v[190:193], v[88:91]
	v_mfma_f32_16x16x32_bf16 v[84:87], v[222:225], v[198:201], v[84:87]
	v_mfma_f32_16x16x32_bf16 v[80:83], v[230:233], v[198:201], v[80:83]
	v_mfma_f32_16x16x32_bf16 v[76:79], v[222:225], v[206:209], v[76:79]
	v_mfma_f32_16x16x32_bf16 v[72:75], v[230:233], v[206:209], v[72:75]
	v_mfma_f32_16x16x32_bf16 v[68:71], v[222:225], v[214:217], v[68:71]
	v_mfma_f32_16x16x32_bf16 v[64:67], v[230:233], v[214:217], v[64:67]
	v_mfma_f32_16x16x32_bf16 v[92:95], v[226:229], v[194:197], v[92:95]
	v_mfma_f32_16x16x32_bf16 v[88:91], v[234:237], v[194:197], v[88:91]
	v_mfma_f32_16x16x32_bf16 v[84:87], v[226:229], v[202:205], v[84:87]
	v_mfma_f32_16x16x32_bf16 v[80:83], v[234:237], v[202:205], v[80:83]
	v_mfma_f32_16x16x32_bf16 v[76:79], v[226:229], v[210:213], v[76:79]
	v_mfma_f32_16x16x32_bf16 v[72:75], v[234:237], v[210:213], v[72:75]
	v_mfma_f32_16x16x32_bf16 v[68:71], v[226:229], v[218:221], v[68:71]
	v_mfma_f32_16x16x32_bf16 v[64:67], v[234:237], v[218:221], v[64:67]
	v_readfirstlane_b32 s73, v160
	v_lshl_add_u64 v[238:239], v[238:239], 0, s[46:47]
	s_mov_b32 m0, s73
	v_readfirstlane_b32 s73, v161
	s_barrier
; #define STAGE(P, BASE, LD, br, kt) do { const char* _g = (const char*)((BASE) + (size_t)(br) * (LD) + (size_t)(kt) * 64); \
;     for (int _i = 0; _i < 2; ++_i) { int _b = tidx * 16 + _i * 8192; int _r, _c; stage_rc(_b, _r, _c); \
;       __builtin_amdgcn_global_load_lds((const unsigned*)(_g + (unsigned)((_r * (LD) + _c) * 2)), (unsigned*)((char*)(P) + _b), 16, 0, 0); } } while (0)
; #define LDA(dst, b, h) for (int m = 0; m < 4; ++m) for (int k = 0; k < 2; ++k) \
;     dst[m][k] = *reinterpret_cast<const bf16x8*>((char*)SA(b, h) + lds_byte(wr * 64 + m * 16 + fr, k * 32 + fq * 8))
; #define LDB(dst, b, h) for (int n = 0; n < 2; ++n) for (int k = 0; k < 2; ++k) \
;     dst[n][k] = *reinterpret_cast<const bf16x8*>((char*)SB(b, h) + lds_byte(wc * 32 + n * 16 + fr, k * 32 + fq * 8))
; #define MMA(ai, bj, At_, Bt_) do { __builtin_amdgcn_s_setprio(1); \
;     for (int k = 0; k < 2; ++k) for (int m = 0; m < 4; ++m) for (int n = 0; n < 2; ++n) \
;       acc[ai][bj][m][n] = __builtin_amdgcn_mfma_f32_16x16x32_bf16(At_[m][k], Bt_[n][k], acc[ai][bj][m][n], 0, 0, 0); \
;     __builtin_amdgcn_s_setprio(0); } while (0)
; #define WAIT_V(n) asm volatile("s_waitcnt vmcnt(" #n ")" ::: "memory")
; #define WAIT_L(n) asm volatile("s_waitcnt lgkmcnt(" #n ")" ::: "memory")
; #define BAR __builtin_amdgcn_s_barrier()
; #define SCHED __builtin_amdgcn_sched_barrier(0)
; template <int EPI, int lda, int ldb, int N, int K>
; __device__ __forceinline__ void gemm_phase(const u16* __restrict__ A, const u16* __restrict__ Bt, const GemmEpi ep, int wv) {
;     ...
;       LDA(At, 1, 1); STAGE(SA(1, 0), Ab, lda, brow, t + 3);
;       BAR; WAIT_L(0); MMA(1, 0, At, B0); BAR; SCHED;
;       STAGE(SB(1, 1), Bt, ldb, bcol + HALF, t + 3);
;       WAIT_V(6); BAR; MMA(1, 1, At, B1); BAR;
;     }
;     { LDB(B0, 0, 0); LDA(At, 0, 0); STAGE(SA(1, 1), Ab, lda, brow + HALF, nt - 1);
;       BAR; WAIT_L(0); MMA(0, 0, At, B0); BAR;
	ds_read_b128 v[190:193], v155 offset:49152
	ds_read_b128 v[194:197], v155 offset:50176
	ds_read_b128 v[198:201], v154 offset:49152
	ds_read_b128 v[202:205], v154 offset:50176
	ds_read_b128 v[206:209], v153 offset:49152
	ds_read_b128 v[210:213], v153 offset:50176
	ds_read_b128 v[214:217], v152 offset:49152
	ds_read_b128 v[218:221], v152 offset:50176
	global_load_lds_dwordx4 v[238:239], off
	v_lshl_add_u64 v[238:239], v[240:241], 0, s[46:47]
	s_mov_b32 m0, s73
	s_nop 0
	global_load_lds_dwordx4 v[238:239], off
	s_barrier
	s_waitcnt lgkmcnt(0)
	s_waitcnt lgkmcnt(0)
	v_mfma_f32_16x16x32_bf16 v[60:63], v[174:177], v[190:193], v[60:63]
	v_mfma_f32_16x16x32_bf16 v[56:59], v[182:185], v[190:193], v[56:59]
	v_mfma_f32_16x16x32_bf16 v[52:55], v[174:177], v[198:201], v[52:55]
	v_mfma_f32_16x16x32_bf16 v[48:51], v[182:185], v[198:201], v[48:51]
	v_mfma_f32_16x16x32_bf16 v[44:47], v[174:177], v[206:209], v[44:47]
	v_mfma_f32_16x16x32_bf16 v[40:43], v[182:185], v[206:209], v[40:43]
	v_mfma_f32_16x16x32_bf16 v[36:39], v[174:177], v[214:217], v[36:39]
	v_mfma_f32_16x16x32_bf16 v[32:35], v[182:185], v[214:217], v[32:35]
	v_mfma_f32_16x16x32_bf16 v[60:63], v[178:181], v[194:197], v[60:63]
	v_mfma_f32_16x16x32_bf16 v[56:59], v[186:189], v[194:197], v[56:59]
	v_mfma_f32_16x16x32_bf16 v[52:55], v[178:181], v[202:205], v[52:55]
	v_mfma_f32_16x16x32_bf16 v[48:51], v[186:189], v[202:205], v[48:51]
	v_mfma_f32_16x16x32_bf16 v[44:47], v[178:181], v[210:213], v[44:47]
	v_mfma_f32_16x16x32_bf16 v[40:43], v[186:189], v[210:213], v[40:43]
	v_mfma_f32_16x16x32_bf16 v[36:39], v[178:181], v[218:221], v[36:39]
	v_mfma_f32_16x16x32_bf16 v[32:35], v[186:189], v[218:221], v[32:35]
	s_barrier
	v_readfirstlane_b32 s73, v162
	v_add_u32_e32 v176, 0x2000, v162
	v_lshl_add_u64 v[174:175], v[246:247], 0, s[48:49]
	s_mov_b32 m0, s73
	v_readfirstlane_b32 s73, v176
	global_load_lds_dwordx4 v[174:175], off
	v_lshl_add_u64 v[174:175], v[248:249], 0, s[48:49]
	s_mov_b32 m0, s73
	s_nop 0
	global_load_lds_dwordx4 v[174:175], off
	s_waitcnt vmcnt(6)
	s_barrier
	v_mfma_f32_16x16x32_bf16 v[28:31], v[222:225], v[190:193], v[28:31]
	v_mfma_f32_16x16x32_bf16 v[24:27], v[230:233], v[190:193], v[24:27]
	v_mfma_f32_16x16x32_bf16 v[20:23], v[222:225], v[198:201], v[20:23]
	v_mfma_f32_16x16x32_bf16 v[16:19], v[230:233], v[198:201], v[16:19]
	v_mfma_f32_16x16x32_bf16 v[12:15], v[222:225], v[206:209], v[12:15]
	v_mfma_f32_16x16x32_bf16 v[8:11], v[230:233], v[206:209], v[8:11]
	v_mfma_f32_16x16x32_bf16 v[4:7], v[222:225], v[214:217], v[4:7]
	v_mfma_f32_16x16x32_bf16 v[0:3], v[230:233], v[214:217], v[0:3]
	v_mfma_f32_16x16x32_bf16 v[28:31], v[226:229], v[194:197], v[28:31]
	v_mfma_f32_16x16x32_bf16 v[24:27], v[234:237], v[194:197], v[24:27]
	v_mfma_f32_16x16x32_bf16 v[20:23], v[226:229], v[202:205], v[20:23]
	v_mfma_f32_16x16x32_bf16 v[16:19], v[234:237], v[202:205], v[16:19]
	v_mfma_f32_16x16x32_bf16 v[12:15], v[226:229], v[210:213], v[12:15]
	v_mfma_f32_16x16x32_bf16 v[8:11], v[234:237], v[210:213], v[8:11]
	v_mfma_f32_16x16x32_bf16 v[4:7], v[226:229], v[218:221], v[4:7]
	v_mfma_f32_16x16x32_bf16 v[0:3], v[234:237], v[218:221], v[0:3]
	s_add_i32 s72, s72, 2
	s_add_u32 s50, s50, 0x100
	s_addc_u32 s51, s51, 0
	s_cmpk_gt_u32 s72, 0x51
	s_barrier
	s_cbranch_scc0 .LBB0_838
	s_add_i32 s50, s18, 0x80
	s_mul_hi_i32 s51, s50, 0x2b00
	s_mulk_i32 s50, 0x2b00
	s_add_u32 s50, s56, s50
	s_addc_u32 s51, s57, s51
	s_add_u32 s50, s50, 0x2a80
	s_addc_u32 s51, s51, 0
	v_readfirstlane_b32 s72, v172
	v_lshl_add_u64 v[160:161], s[50:51], 0, v[128:129]
	s_mov_b32 m0, s72
	ds_read_b128 v[134:137], v164
	ds_read_b128 v[138:141], v164 offset:1024
	ds_read_b128 v[142:145], v164 offset:2048
	ds_read_b128 v[174:177], v164 offset:3072
	ds_read_b128 v[178:181], v155
	ds_read_b128 v[182:185], v155 offset:1024
	ds_read_b128 v[186:189], v154
	ds_read_b128 v[190:193], v154 offset:1024
	ds_read_b128 v[194:197], v153
	ds_read_b128 v[198:201], v153 offset:1024
	ds_read_b128 v[202:205], v152
	ds_read_b128 v[206:209], v152 offset:1024
	global_load_lds_dwordx4 v[160:161], off
	v_lshl_add_u64 v[160:161], s[50:51], 0, v[132:133]
	v_readfirstlane_b32 s50, v173
	s_mov_b32 m0, s50
	s_nop 0
	global_load_lds_dwordx4 v[160:161], off
	s_barrier
	s_waitcnt lgkmcnt(0)
	s_waitcnt lgkmcnt(0)
	v_mfma_f32_16x16x32_bf16 v[124:127], v[134:137], v[178:181], v[124:127]
	v_mfma_f32_16x16x32_bf16 v[120:123], v[142:145], v[178:181], v[120:123]
	v_mfma_f32_16x16x32_bf16 v[116:119], v[134:137], v[186:189], v[116:119]
	v_mfma_f32_16x16x32_bf16 v[112:115], v[142:145], v[186:189], v[112:115]
	v_mfma_f32_16x16x32_bf16 v[108:111], v[134:137], v[194:197], v[108:111]
	v_mfma_f32_16x16x32_bf16 v[104:107], v[142:145], v[194:197], v[104:107]
	v_mfma_f32_16x16x32_bf16 v[100:103], v[134:137], v[202:205], v[100:103]
	v_mfma_f32_16x16x32_bf16 v[96:99], v[142:145], v[202:205], v[96:99]
	v_mfma_f32_16x16x32_bf16 v[124:127], v[138:141], v[182:185], v[124:127]
	v_mfma_f32_16x16x32_bf16 v[120:123], v[174:177], v[182:185], v[120:123]
	v_mfma_f32_16x16x32_bf16 v[116:119], v[138:141], v[190:193], v[116:119]
	v_mfma_f32_16x16x32_bf16 v[112:115], v[174:177], v[190:193], v[112:115]
	v_mfma_f32_16x16x32_bf16 v[108:111], v[138:141], v[198:201], v[108:111]
	v_mfma_f32_16x16x32_bf16 v[104:107], v[174:177], v[198:201], v[104:107]
	v_mfma_f32_16x16x32_bf16 v[100:103], v[138:141], v[206:209], v[100:103]
	v_mfma_f32_16x16x32_bf16 v[96:99], v[174:177], v[206:209], v[96:99]
	s_barrier
	ds_read_b128 v[210:213], v163
	ds_read_b128 v[214:217], v163 offset:1024
	ds_read_b128 v[218:221], v163 offset:2048
	ds_read_b128 v[160:163], v163 offset:3072
	s_barrier
; #define LDA(dst, b, h) for (int m = 0; m < 4; ++m) for (int k = 0; k < 2; ++k) \
;     dst[m][k] = *reinterpret_cast<const bf16x8*>((char*)SA(b, h) + lds_byte(wr * 64 + m * 16 + fr, k * 32 + fq * 8))
; #define LDB(dst, b, h) for (int n = 0; n < 2; ++n) for (int k = 0; k < 2; ++k) \
;     dst[n][k] = *reinterpret_cast<const bf16x8*>((char*)SB(b, h) + lds_byte(wc * 32 + n * 16 + fr, k * 32 + fq * 8))
; #define MMA(ai, bj, At_, Bt_) do { __builtin_amdgcn_s_setprio(1); \
;     for (int k = 0; k < 2; ++k) for (int m = 0; m < 4; ++m) for (int n = 0; n < 2; ++n) \
;       acc[ai][bj][m][n] = __builtin_amdgcn_mfma_f32_16x16x32_bf16(At_[m][k], Bt_[n][k], acc[ai][bj][m][n], 0, 0, 0); \
;     __builtin_amdgcn_s_setprio(0); } while (0)
; #define WAIT_V(n) asm volatile("s_waitcnt vmcnt(" #n ")" ::: "memory")
; #define WAIT_L(n) asm volatile("s_waitcnt lgkmcnt(" #n ")" ::: "memory")
; #define BAR __builtin_amdgcn_s_barrier()
; template <int EPI, int lda, int ldb, int N, int K>
; __device__ __forceinline__ void gemm_phase(const u16* __restrict__ A, const u16* __restrict__ Bt, const GemmEpi ep, int wv) {
;     ...
;       LDB(B1, 0, 1); BAR; WAIT_L(0); MMA(0, 1, At, B1); BAR;
;       LDA(At, 0, 1); WAIT_V(4); BAR; WAIT_L(0); MMA(1, 0, At, B0); MMA(1, 1, At, B1); BAR; }
;     { LDB(B0, 1, 0); LDA(At, 1, 0); WAIT_V(2); BAR; WAIT_L(0); MMA(0, 0, At, B0); BAR;
	s_waitcnt lgkmcnt(0)
	s_waitcnt lgkmcnt(0)
	v_mfma_f32_16x16x32_bf16 v[92:95], v[210:213], v[178:181], v[92:95]
	v_mfma_f32_16x16x32_bf16 v[88:91], v[218:221], v[178:181], v[88:91]
	v_mfma_f32_16x16x32_bf16 v[76:79], v[210:213], v[194:197], v[76:79]
	v_mfma_f32_16x16x32_bf16 v[72:75], v[218:221], v[194:197], v[72:75]
	v_mfma_f32_16x16x32_bf16 v[84:87], v[210:213], v[186:189], v[84:87]
	v_mfma_f32_16x16x32_bf16 v[80:83], v[218:221], v[186:189], v[80:83]
	v_mfma_f32_16x16x32_bf16 v[68:71], v[210:213], v[202:205], v[68:71]
	v_mfma_f32_16x16x32_bf16 v[64:67], v[218:221], v[202:205], v[64:67]
	v_mfma_f32_16x16x32_bf16 v[92:95], v[214:217], v[182:185], v[92:95]
	v_mfma_f32_16x16x32_bf16 v[88:91], v[160:163], v[182:185], v[88:91]
	v_mfma_f32_16x16x32_bf16 v[76:79], v[214:217], v[198:201], v[76:79]
	v_mfma_f32_16x16x32_bf16 v[72:75], v[160:163], v[198:201], v[72:75]
	v_mfma_f32_16x16x32_bf16 v[178:181], v[214:217], v[190:193], v[84:87]
	v_mfma_f32_16x16x32_bf16 v[182:185], v[160:163], v[190:193], v[80:83]
	v_mfma_f32_16x16x32_bf16 v[186:189], v[214:217], v[206:209], v[68:71]
	v_mfma_f32_16x16x32_bf16 v[190:193], v[160:163], v[206:209], v[64:67]
	s_barrier
	s_nop 0
	ds_read_b128 v[64:67], v155 offset:16384
	ds_read_b128 v[68:71], v155 offset:17408
	ds_read_b128 v[80:83], v154 offset:16384
	ds_read_b128 v[84:87], v154 offset:17408
	ds_read_b128 v[194:197], v153 offset:16384
	ds_read_b128 v[198:201], v153 offset:17408
	ds_read_b128 v[202:205], v152 offset:16384
	ds_read_b128 v[206:209], v152 offset:17408
	s_waitcnt vmcnt(4)
	s_barrier
	s_waitcnt lgkmcnt(0)
	s_waitcnt lgkmcnt(0)
	v_mfma_f32_16x16x32_bf16 v[60:63], v[134:137], v[64:67], v[60:63]
	v_mfma_f32_16x16x32_bf16 v[56:59], v[142:145], v[64:67], v[56:59]
	v_mfma_f32_16x16x32_bf16 v[52:55], v[134:137], v[80:83], v[52:55]
	v_mfma_f32_16x16x32_bf16 v[48:51], v[142:145], v[80:83], v[48:51]
	v_mfma_f32_16x16x32_bf16 v[44:47], v[134:137], v[194:197], v[44:47]
	v_mfma_f32_16x16x32_bf16 v[40:43], v[142:145], v[194:197], v[40:43]
	v_mfma_f32_16x16x32_bf16 v[36:39], v[134:137], v[202:205], v[36:39]
	v_mfma_f32_16x16x32_bf16 v[32:35], v[142:145], v[202:205], v[32:35]
	v_mfma_f32_16x16x32_bf16 v[60:63], v[138:141], v[68:71], v[60:63]
	v_mfma_f32_16x16x32_bf16 v[56:59], v[174:177], v[68:71], v[56:59]
	v_mfma_f32_16x16x32_bf16 v[52:55], v[138:141], v[84:87], v[52:55]
	v_mfma_f32_16x16x32_bf16 v[48:51], v[174:177], v[84:87], v[48:51]
	v_mfma_f32_16x16x32_bf16 v[44:47], v[138:141], v[198:201], v[44:47]
	v_mfma_f32_16x16x32_bf16 v[40:43], v[174:177], v[198:201], v[40:43]
	v_mfma_f32_16x16x32_bf16 v[36:39], v[138:141], v[206:209], v[36:39]
	v_mfma_f32_16x16x32_bf16 v[32:35], v[174:177], v[206:209], v[32:35]
	v_mfma_f32_16x16x32_bf16 v[28:31], v[210:213], v[64:67], v[28:31]
	v_mfma_f32_16x16x32_bf16 v[16:19], v[218:221], v[80:83], v[16:19]
	v_mfma_f32_16x16x32_bf16 v[12:15], v[210:213], v[194:197], v[12:15]
	v_mfma_f32_16x16x32_bf16 v[0:3], v[218:221], v[202:205], v[0:3]
	v_mfma_f32_16x16x32_bf16 v[24:27], v[218:221], v[64:67], v[24:27]
	v_mfma_f32_16x16x32_bf16 v[20:23], v[210:213], v[80:83], v[20:23]
	v_mfma_f32_16x16x32_bf16 v[8:11], v[218:221], v[194:197], v[8:11]
	v_mfma_f32_16x16x32_bf16 v[4:7], v[210:213], v[202:205], v[4:7]
	v_mfma_f32_16x16x32_bf16 v[28:31], v[214:217], v[68:71], v[28:31]
	v_mfma_f32_16x16x32_bf16 v[16:19], v[160:163], v[84:87], v[16:19]
	v_mfma_f32_16x16x32_bf16 v[12:15], v[214:217], v[198:201], v[12:15]
	v_mfma_f32_16x16x32_bf16 v[0:3], v[160:163], v[206:209], v[0:3]
	v_mfma_f32_16x16x32_bf16 v[134:137], v[160:163], v[68:71], v[24:27]
	v_mfma_f32_16x16x32_bf16 v[138:141], v[214:217], v[84:87], v[20:23]
	v_mfma_f32_16x16x32_bf16 v[142:145], v[160:163], v[198:201], v[8:11]
	v_mfma_f32_16x16x32_bf16 v[172:175], v[214:217], v[206:209], v[4:7]
	s_barrier
	s_nop 0
	ds_read_b128 v[4:7], v159
	ds_read_b128 v[8:11], v159 offset:1024
	ds_read_b128 v[20:23], v159 offset:2048
	ds_read_b128 v[158:161], v159 offset:3072
	ds_read_b128 v[24:27], v155 offset:32768
	ds_read_b128 v[194:197], v155 offset:33792
	ds_read_b128 v[198:201], v154 offset:32768
	ds_read_b128 v[202:205], v154 offset:33792
	ds_read_b128 v[206:209], v153 offset:32768
	ds_read_b128 v[210:213], v153 offset:33792
	ds_read_b128 v[214:217], v152 offset:32768
	ds_read_b128 v[218:221], v152 offset:33792
	s_waitcnt vmcnt(2)
	s_barrier
; #define LDA(dst, b, h) for (int m = 0; m < 4; ++m) for (int k = 0; k < 2; ++k) \
;     dst[m][k] = *reinterpret_cast<const bf16x8*>((char*)SA(b, h) + lds_byte(wr * 64 + m * 16 + fr, k * 32 + fq * 8))
; #define LDB(dst, b, h) for (int n = 0; n < 2; ++n) for (int k = 0; k < 2; ++k) \
;     dst[n][k] = *reinterpret_cast<const bf16x8*>((char*)SB(b, h) + lds_byte(wc * 32 + n * 16 + fr, k * 32 + fq * 8))
; #define MMA(ai, bj, At_, Bt_) do { __builtin_amdgcn_s_setprio(1); \
;     for (int k = 0; k < 2; ++k) for (int m = 0; m < 4; ++m) for (int n = 0; n < 2; ++n) \
;       acc[ai][bj][m][n] = __builtin_amdgcn_mfma_f32_16x16x32_bf16(At_[m][k], Bt_[n][k], acc[ai][bj][m][n], 0, 0, 0); \
;     __builtin_amdgcn_s_setprio(0); } while (0)
; #define WAIT_V(n) asm volatile("s_waitcnt vmcnt(" #n ")" ::: "memory")
; #define WAIT_L(n) asm volatile("s_waitcnt lgkmcnt(" #n ")" ::: "memory")
; #define BAR __builtin_amdgcn_s_barrier()
; template <int EPI, int lda, int ldb, int N, int K>
; __device__ __forceinline__ void gemm_phase(const u16* __restrict__ A, const u16* __restrict__ Bt, const GemmEpi ep, int wv) {
;     ...
;     { LDB(B0, 1, 0); LDA(At, 1, 0); WAIT_V(2); BAR; WAIT_L(0); MMA(0, 0, At, B0); BAR;
;       LDB(B1, 1, 1); WAIT_V(0); BAR; WAIT_L(0); MMA(0, 1, At, B1); BAR;
;       LDA(At, 1, 1); BAR; WAIT_L(0); MMA(1, 0, At, B0); MMA(1, 1, At, B1); BAR; }
;     if (wr == 0) BAR;
	s_waitcnt lgkmcnt(0)
	s_waitcnt lgkmcnt(0)
	v_mfma_f32_16x16x32_bf16 v[64:67], v[4:7], v[24:27], v[124:127]
	v_mfma_f32_16x16x32_bf16 v[68:71], v[20:23], v[24:27], v[120:123]
	v_mfma_f32_16x16x32_bf16 v[80:83], v[4:7], v[198:201], v[116:119]
	v_mfma_f32_16x16x32_bf16 v[84:87], v[20:23], v[198:201], v[112:115]
	v_mfma_f32_16x16x32_bf16 v[108:111], v[4:7], v[206:209], v[108:111]
	v_mfma_f32_16x16x32_bf16 v[104:107], v[20:23], v[206:209], v[104:107]
	v_mfma_f32_16x16x32_bf16 v[120:123], v[4:7], v[214:217], v[100:103]
	v_mfma_f32_16x16x32_bf16 v[124:127], v[20:23], v[214:217], v[96:99]
	v_mfma_f32_16x16x32_bf16 v[116:119], v[8:11], v[194:197], v[64:67]
	v_mfma_f32_16x16x32_bf16 v[112:115], v[158:161], v[194:197], v[68:71]
	v_mfma_f32_16x16x32_bf16 v[100:103], v[8:11], v[202:205], v[80:83]
	v_mfma_f32_16x16x32_bf16 v[96:99], v[158:161], v[202:205], v[84:87]
	v_mfma_f32_16x16x32_bf16 v[84:87], v[8:11], v[210:213], v[108:111]
	v_mfma_f32_16x16x32_bf16 v[80:83], v[158:161], v[210:213], v[104:107]
	v_mfma_f32_16x16x32_bf16 v[68:71], v[8:11], v[218:221], v[120:123]
	v_mfma_f32_16x16x32_bf16 v[64:67], v[158:161], v[218:221], v[124:127]
	s_barrier
	ds_read_b128 v[222:225], v157
	ds_read_b128 v[226:229], v157 offset:1024
	ds_read_b128 v[230:233], v157 offset:2048
	ds_read_b128 v[234:237], v157 offset:3072
	s_waitcnt vmcnt(0)
	s_barrier
	s_waitcnt lgkmcnt(0)
	s_waitcnt lgkmcnt(0)
	v_mfma_f32_16x16x32_bf16 v[92:95], v[222:225], v[24:27], v[92:95]
	v_mfma_f32_16x16x32_bf16 v[24:27], v[230:233], v[24:27], v[88:91]
	v_mfma_f32_16x16x32_bf16 v[88:91], v[222:225], v[198:201], v[178:181]
	v_mfma_f32_16x16x32_bf16 v[104:107], v[230:233], v[198:201], v[182:185]
	v_mfma_f32_16x16x32_bf16 v[76:79], v[222:225], v[206:209], v[76:79]
	v_mfma_f32_16x16x32_bf16 v[72:75], v[230:233], v[206:209], v[72:75]
	v_mfma_f32_16x16x32_bf16 v[176:179], v[222:225], v[214:217], v[186:189]
	v_mfma_f32_16x16x32_bf16 v[180:183], v[230:233], v[214:217], v[190:193]
	v_mfma_f32_16x16x32_bf16 v[124:127], v[226:229], v[194:197], v[92:95]
	v_mfma_f32_16x16x32_bf16 v[120:123], v[234:237], v[194:197], v[24:27]
	v_mfma_f32_16x16x32_bf16 v[108:111], v[226:229], v[202:205], v[88:91]
	v_mfma_f32_16x16x32_bf16 v[104:107], v[234:237], v[202:205], v[104:107]
	v_mfma_f32_16x16x32_bf16 v[92:95], v[226:229], v[210:213], v[76:79]
	v_mfma_f32_16x16x32_bf16 v[88:91], v[234:237], v[210:213], v[72:75]
	v_mfma_f32_16x16x32_bf16 v[76:79], v[226:229], v[218:221], v[176:179]
	v_mfma_f32_16x16x32_bf16 v[72:75], v[234:237], v[218:221], v[180:183]
	s_barrier
	ds_read_b128 v[176:179], v155 offset:49152
	ds_read_b128 v[180:183], v155 offset:50176
	ds_read_b128 v[184:187], v154 offset:49152
	ds_read_b128 v[154:157], v154 offset:50176
	ds_read_b128 v[188:191], v153 offset:49152
	ds_read_b128 v[192:195], v153 offset:50176
	ds_read_b128 v[196:199], v152 offset:49152
	ds_read_b128 v[200:203], v152 offset:50176
	s_barrier
	s_waitcnt lgkmcnt(0)
	s_waitcnt lgkmcnt(0)
	v_mfma_f32_16x16x32_bf16 v[24:27], v[4:7], v[176:179], v[60:63]
	v_mfma_f32_16x16x32_bf16 v[60:63], v[20:23], v[176:179], v[56:59]
	v_mfma_f32_16x16x32_bf16 v[204:207], v[4:7], v[184:187], v[52:55]
	v_mfma_f32_16x16x32_bf16 v[48:51], v[20:23], v[184:187], v[48:51]
	v_mfma_f32_16x16x32_bf16 v[44:47], v[4:7], v[188:191], v[44:47]
	v_mfma_f32_16x16x32_bf16 v[208:211], v[20:23], v[188:191], v[40:43]
	v_mfma_f32_16x16x32_bf16 v[4:7], v[4:7], v[196:199], v[36:39]
	v_mfma_f32_16x16x32_bf16 v[32:35], v[20:23], v[196:199], v[32:35]
	v_mfma_f32_16x16x32_bf16 v[56:59], v[8:11], v[180:183], v[24:27]
	v_mfma_f32_16x16x32_bf16 v[52:55], v[158:161], v[180:183], v[60:63]
	v_mfma_f32_16x16x32_bf16 v[40:43], v[8:11], v[154:157], v[204:207]
	v_mfma_f32_16x16x32_bf16 v[36:39], v[158:161], v[154:157], v[48:51]
	v_mfma_f32_16x16x32_bf16 v[24:27], v[8:11], v[192:195], v[44:47]
	v_mfma_f32_16x16x32_bf16 v[20:23], v[158:161], v[192:195], v[208:211]
	v_mfma_f32_16x16x32_bf16 v[8:11], v[8:11], v[200:203], v[4:7]
	v_mfma_f32_16x16x32_bf16 v[4:7], v[158:161], v[200:203], v[32:35]
	v_mfma_f32_16x16x32_bf16 v[28:31], v[222:225], v[176:179], v[28:31]
	v_mfma_f32_16x16x32_bf16 v[32:35], v[230:233], v[176:179], v[134:137]
	v_mfma_f32_16x16x32_bf16 v[44:47], v[222:225], v[184:187], v[138:141]
	v_mfma_f32_16x16x32_bf16 v[16:19], v[230:233], v[184:187], v[16:19]
	v_mfma_f32_16x16x32_bf16 v[12:15], v[222:225], v[188:191], v[12:15]
	v_mfma_f32_16x16x32_bf16 v[134:137], v[230:233], v[188:191], v[142:145]
	v_mfma_f32_16x16x32_bf16 v[138:141], v[222:225], v[196:199], v[172:175]
	v_mfma_f32_16x16x32_bf16 v[0:3], v[230:233], v[196:199], v[0:3]
	v_mfma_f32_16x16x32_bf16 v[60:63], v[226:229], v[180:183], v[28:31]
	v_mfma_f32_16x16x32_bf16 v[48:51], v[234:237], v[180:183], v[32:35]
	v_mfma_f32_16x16x32_bf16 v[44:47], v[226:229], v[154:157], v[44:47]
	v_mfma_f32_16x16x32_bf16 v[32:35], v[234:237], v[154:157], v[16:19]
	v_mfma_f32_16x16x32_bf16 v[28:31], v[226:229], v[192:195], v[12:15]
	v_mfma_f32_16x16x32_bf16 v[16:19], v[234:237], v[192:195], v[134:137]
	v_mfma_f32_16x16x32_bf16 v[12:15], v[226:229], v[200:203], v[138:141]
	v_mfma_f32_16x16x32_bf16 v[0:3], v[234:237], v[200:203], v[0:3]
	v_cmp_gt_u32_e32 vcc, s69, v130
	s_barrier
	s_and_saveexec_b64 s[50:51], vcc
	s_cbranch_execz .LBB0_841
	s_barrier

; #define STAGE(P, BASE, LD, br, kt) do { const char* _g = (const char*)((BASE) + (size_t)(br) * (LD) + (size_t)(kt) * 64); \
;     for (int _i = 0; _i < 2; ++_i) { int _b = tidx * 16 + _i * 8192; int _r, _c; stage_rc(_b, _r, _c); \
;       __builtin_amdgcn_global_load_lds((const unsigned*)(_g + (unsigned)((_r * (LD) + _c) * 2)), (unsigned*)((char*)(P) + _b), 16, 0, 0); } } while (0)
; #define LDA(dst, b, h) for (int m = 0; m < 4; ++m) for (int k = 0; k < 2; ++k) \
;     dst[m][k] = *reinterpret_cast<const bf16x8*>((char*)SA(b, h) + lds_byte(wr * 64 + m * 16 + fr, k * 32 + fq * 8))
; #define LDB(dst, b, h) for (int n = 0; n < 2; ++n) for (int k = 0; k < 2; ++k) \
;     dst[n][k] = *reinterpret_cast<const bf16x8*>((char*)SB(b, h) + lds_byte(wc * 32 + n * 16 + fr, k * 32 + fq * 8))
; #define MMA(ai, bj, At_, Bt_) do { __builtin_amdgcn_s_setprio(1); \
;     for (int k = 0; k < 2; ++k) for (int m = 0; m < 4; ++m) for (int n = 0; n < 2; ++n) \
;       acc[ai][bj][m][n] = __builtin_amdgcn_mfma_f32_16x16x32_bf16(At_[m][k], Bt_[n][k], acc[ai][bj][m][n], 0, 0, 0); \
;     __builtin_amdgcn_s_setprio(0); } while (0)
; #define WAIT_V(n) asm volatile("s_waitcnt vmcnt(" #n ")" ::: "memory")
; #define WAIT_L(n) asm volatile("s_waitcnt lgkmcnt(" #n ")" ::: "memory")
; #define BAR __builtin_amdgcn_s_barrier()
; #define SCHED __builtin_amdgcn_sched_barrier(0)
; template <int EPI, int lda, int ldb, int N, int K>
; __device__ __forceinline__ void gemm_phase(const u16* __restrict__ A, const u16* __restrict__ Bt, const GemmEpi ep, int wv) {
;     ...
;     for (int t = 0; t < nt - 2; t += 2) {
;       LDB(B0, 0, 0); SCHED; LDA(At, 0, 0); STAGE(SA(1, 1), Ab, lda, brow + HALF, t + 1);
;       WAIT_L(8); BAR; WAIT_L(0); MMA(0, 0, At, B0); BAR; SCHED;
;       LDB(B1, 0, 1); STAGE(SB(0, 0), Bt, ldb, bcol, t + 2);
;       BAR; WAIT_L(0); MMA(0, 1, At, B1); BAR;
;       LDA(At, 0, 1); STAGE(SA(0, 0), Ab, lda, brow, t + 2);
;       BAR; WAIT_L(0); MMA(1, 0, At, B0); BAR; SCHED;
;       STAGE(SB(0, 1), Bt, ldb, bcol + HALF, t + 2);
;       WAIT_V(6); BAR; MMA(1, 1, At, B1); BAR;
.LBB0_1147:
	ds_read_b128 v[172:175], v161
	ds_read_b128 v[176:179], v161 offset:1024
	ds_read_b128 v[180:183], v161 offset:2048
	ds_read_b128 v[184:187], v161 offset:3072
	v_add_u32_e32 v169, 0xc000, v148
	v_lshl_add_u64 v[236:237], v[138:139], 0, s[60:61]
	v_readfirstlane_b32 s63, v169
	v_add_u32_e32 v170, 0xe000, v148
	v_lshl_add_u64 v[162:163], v[236:237], 0, s[22:23]
	s_mov_b32 m0, s63
	v_lshl_add_u64 v[238:239], v[140:141], 0, s[60:61]
	v_readfirstlane_b32 s63, v170
	ds_read_b128 v[164:167], v152
	ds_read_b128 v[188:191], v152 offset:1024
	ds_read_b128 v[192:195], v151
	ds_read_b128 v[196:199], v151 offset:1024
	ds_read_b128 v[200:203], v150
	ds_read_b128 v[204:207], v150 offset:1024
	ds_read_b128 v[208:211], v149
	ds_read_b128 v[212:215], v149 offset:1024
	global_load_lds_dwordx4 v[162:163], off
	v_lshl_add_u64 v[162:163], v[238:239], 0, s[22:23]
	s_mov_b32 m0, s63
	s_nop 0
	global_load_lds_dwordx4 v[162:163], off
	s_waitcnt lgkmcnt(8)
	s_barrier
	s_waitcnt lgkmcnt(0)
	s_waitcnt lgkmcnt(0)
	v_mfma_f32_16x16x32_bf16 v[124:127], v[164:167], v[172:175], v[124:127]
	ds_read_b128 v[216:219], v160
	v_mfma_f32_16x16x32_bf16 v[120:123], v[164:167], v[180:183], v[120:123]
	v_mfma_f32_16x16x32_bf16 v[116:119], v[192:195], v[172:175], v[116:119]
	ds_read_b128 v[220:223], v160 offset:1024
	v_mfma_f32_16x16x32_bf16 v[112:115], v[192:195], v[180:183], v[112:115]
	v_mfma_f32_16x16x32_bf16 v[108:111], v[200:203], v[172:175], v[108:111]
	ds_read_b128 v[224:227], v160 offset:2048
	v_mfma_f32_16x16x32_bf16 v[104:107], v[200:203], v[180:183], v[104:107]
	v_mfma_f32_16x16x32_bf16 v[100:103], v[208:211], v[172:175], v[100:103]
	ds_read_b128 v[228:231], v160 offset:3072
	v_mfma_f32_16x16x32_bf16 v[96:99], v[208:211], v[180:183], v[96:99]
	v_mfma_f32_16x16x32_bf16 v[124:127], v[188:191], v[176:179], v[124:127]
	v_mfma_f32_16x16x32_bf16 v[120:123], v[188:191], v[184:187], v[120:123]
	v_mfma_f32_16x16x32_bf16 v[116:119], v[196:199], v[176:179], v[116:119]
	v_mfma_f32_16x16x32_bf16 v[112:115], v[196:199], v[184:187], v[112:115]
	v_mfma_f32_16x16x32_bf16 v[108:111], v[204:207], v[176:179], v[108:111]
	v_mfma_f32_16x16x32_bf16 v[104:107], v[204:207], v[184:187], v[104:107]
	v_mfma_f32_16x16x32_bf16 v[100:103], v[212:215], v[176:179], v[100:103]
	v_mfma_f32_16x16x32_bf16 v[96:99], v[212:215], v[184:187], v[96:99]
	s_barrier
	v_add_u32_e32 v162, s75, v154
	v_lshl_add_u64 v[240:241], v[134:135], 0, s[60:61]
	v_readfirstlane_b32 s63, v162
	v_add_u32_e32 v163, 0x2000, v162
	v_lshl_add_u64 v[232:233], v[240:241], 0, s[24:25]
	s_mov_b32 m0, s63
	v_lshl_add_u64 v[242:243], v[136:137], 0, s[60:61]
	v_readfirstlane_b32 s63, v163
	global_load_lds_dwordx4 v[232:233], off
	v_lshl_add_u64 v[232:233], v[242:243], 0, s[24:25]
	s_mov_b32 m0, s63
	s_nop 0
	global_load_lds_dwordx4 v[232:233], off
	s_barrier
	s_waitcnt lgkmcnt(0)
	s_waitcnt lgkmcnt(0)
	v_mfma_f32_16x16x32_bf16 v[92:95], v[164:167], v[216:219], v[92:95]
	v_mfma_f32_16x16x32_bf16 v[88:91], v[164:167], v[224:227], v[88:91]
	v_mfma_f32_16x16x32_bf16 v[84:87], v[192:195], v[216:219], v[84:87]
	v_mfma_f32_16x16x32_bf16 v[80:83], v[192:195], v[224:227], v[80:83]
	v_mfma_f32_16x16x32_bf16 v[76:79], v[200:203], v[216:219], v[76:79]
	v_mfma_f32_16x16x32_bf16 v[72:75], v[200:203], v[224:227], v[72:75]
	v_mfma_f32_16x16x32_bf16 v[68:71], v[208:211], v[216:219], v[68:71]
	v_mfma_f32_16x16x32_bf16 v[64:67], v[208:211], v[224:227], v[64:67]
	v_mfma_f32_16x16x32_bf16 v[92:95], v[188:191], v[220:223], v[92:95]
	v_mfma_f32_16x16x32_bf16 v[88:91], v[188:191], v[228:231], v[88:91]
	v_mfma_f32_16x16x32_bf16 v[84:87], v[196:199], v[220:223], v[84:87]
	v_mfma_f32_16x16x32_bf16 v[80:83], v[196:199], v[228:231], v[80:83]
	v_mfma_f32_16x16x32_bf16 v[76:79], v[204:207], v[220:223], v[76:79]
	v_mfma_f32_16x16x32_bf16 v[72:75], v[204:207], v[228:231], v[72:75]
	v_mfma_f32_16x16x32_bf16 v[68:71], v[212:215], v[220:223], v[68:71]
	v_mfma_f32_16x16x32_bf16 v[64:67], v[212:215], v[228:231], v[64:67]
	v_readfirstlane_b32 s63, v148
	v_lshl_add_u64 v[164:165], v[236:237], 0, s[26:27]
	s_mov_b32 m0, s63
	s_barrier
	ds_read_b128 v[188:191], v152 offset:16384
	ds_read_b128 v[192:195], v152 offset:17408
	ds_read_b128 v[196:199], v151 offset:16384
	ds_read_b128 v[200:203], v151 offset:17408
	ds_read_b128 v[204:207], v150 offset:16384
	ds_read_b128 v[208:211], v150 offset:17408
	ds_read_b128 v[212:215], v149 offset:16384
	ds_read_b128 v[232:235], v149 offset:17408
	global_load_lds_dwordx4 v[164:165], off
	v_add_u32_e32 v164, 0x2000, v148
	v_lshl_add_u64 v[166:167], v[238:239], 0, s[26:27]
	v_readfirstlane_b32 s63, v164
	s_mov_b32 m0, s63
	s_nop 0
	global_load_lds_dwordx4 v[166:167], off
	s_barrier
	s_waitcnt lgkmcnt(0)
	s_waitcnt lgkmcnt(0)
	v_mfma_f32_16x16x32_bf16 v[60:63], v[188:191], v[172:175], v[60:63]
	v_mfma_f32_16x16x32_bf16 v[56:59], v[188:191], v[180:183], v[56:59]
	v_mfma_f32_16x16x32_bf16 v[52:55], v[196:199], v[172:175], v[52:55]
	v_mfma_f32_16x16x32_bf16 v[48:51], v[196:199], v[180:183], v[48:51]
	v_mfma_f32_16x16x32_bf16 v[44:47], v[204:207], v[172:175], v[44:47]
	v_mfma_f32_16x16x32_bf16 v[40:43], v[204:207], v[180:183], v[40:43]
	v_mfma_f32_16x16x32_bf16 v[36:39], v[212:215], v[172:175], v[36:39]
	v_mfma_f32_16x16x32_bf16 v[32:35], v[212:215], v[180:183], v[32:35]
	v_mfma_f32_16x16x32_bf16 v[60:63], v[192:195], v[176:179], v[60:63]
	v_mfma_f32_16x16x32_bf16 v[56:59], v[192:195], v[184:187], v[56:59]
	v_mfma_f32_16x16x32_bf16 v[52:55], v[200:203], v[176:179], v[52:55]
	v_mfma_f32_16x16x32_bf16 v[48:51], v[200:203], v[184:187], v[48:51]
	v_mfma_f32_16x16x32_bf16 v[44:47], v[208:211], v[176:179], v[44:47]
	v_mfma_f32_16x16x32_bf16 v[40:43], v[208:211], v[184:187], v[40:43]
	v_mfma_f32_16x16x32_bf16 v[36:39], v[232:235], v[176:179], v[36:39]
	v_mfma_f32_16x16x32_bf16 v[32:35], v[232:235], v[184:187], v[32:35]
	s_barrier
; #define STAGE(P, BASE, LD, br, kt) do { const char* _g = (const char*)((BASE) + (size_t)(br) * (LD) + (size_t)(kt) * 64); \
;     for (int _i = 0; _i < 2; ++_i) { int _b = tidx * 16 + _i * 8192; int _r, _c; stage_rc(_b, _r, _c); \
;       __builtin_amdgcn_global_load_lds((const unsigned*)(_g + (unsigned)((_r * (LD) + _c) * 2)), (unsigned*)((char*)(P) + _b), 16, 0, 0); } } while (0)
; #define LDA(dst, b, h) for (int m = 0; m < 4; ++m) for (int k = 0; k < 2; ++k) \
;     dst[m][k] = *reinterpret_cast<const bf16x8*>((char*)SA(b, h) + lds_byte(wr * 64 + m * 16 + fr, k * 32 + fq * 8))
; #define LDB(dst, b, h) for (int n = 0; n < 2; ++n) for (int k = 0; k < 2; ++k) \
;     dst[n][k] = *reinterpret_cast<const bf16x8*>((char*)SB(b, h) + lds_byte(wc * 32 + n * 16 + fr, k * 32 + fq * 8))
; #define MMA(ai, bj, At_, Bt_) do { __builtin_amdgcn_s_setprio(1); \
;     for (int k = 0; k < 2; ++k) for (int m = 0; m < 4; ++m) for (int n = 0; n < 2; ++n) \
;       acc[ai][bj][m][n] = __builtin_amdgcn_mfma_f32_16x16x32_bf16(At_[m][k], Bt_[n][k], acc[ai][bj][m][n], 0, 0, 0); \
;     __builtin_amdgcn_s_setprio(0); } while (0)
; #define WAIT_V(n) asm volatile("s_waitcnt vmcnt(" #n ")" ::: "memory")
; #define WAIT_L(n) asm volatile("s_waitcnt lgkmcnt(" #n ")" ::: "memory")
; #define BAR __builtin_amdgcn_s_barrier()
; #define SCHED __builtin_amdgcn_sched_barrier(0)
; template <int EPI, int lda, int ldb, int N, int K>
; __device__ __forceinline__ void gemm_phase(const u16* __restrict__ A, const u16* __restrict__ Bt, const GemmEpi ep, int wv) {
;     ...
;       WAIT_V(6); BAR; MMA(1, 1, At, B1); BAR;
;       LDB(B0, 1, 0); SCHED; LDA(At, 1, 0); STAGE(SA(0, 1), Ab, lda, brow + HALF, t + 2);
;       WAIT_L(8); BAR; WAIT_L(0); MMA(0, 0, At, B0); BAR; SCHED;
;       LDB(B1, 1, 1); STAGE(SB(1, 0), Bt, ldb, bcol, t + 3);
;       BAR; WAIT_L(0); MMA(0, 1, At, B1); BAR;
;       LDA(At, 1, 1); STAGE(SA(1, 0), Ab, lda, brow, t + 3);
;       BAR; WAIT_L(0); MMA(1, 0, At, B0); BAR; SCHED;
	v_add_u32_e32 v165, s76, v154
	v_lshl_add_u64 v[166:167], v[240:241], 0, s[40:41]
	v_readfirstlane_b32 s63, v165
	s_mov_b32 m0, s63
	v_lshl_add_u64 v[172:173], v[242:243], 0, s[40:41]
	global_load_lds_dwordx4 v[166:167], off
	v_add_u32_e32 v166, 0x2000, v165
	s_nop 0
	v_readfirstlane_b32 s63, v166
	s_mov_b32 m0, s63
	s_nop 0
	global_load_lds_dwordx4 v[172:173], off
	s_waitcnt vmcnt(6)
	s_barrier
	v_mfma_f32_16x16x32_bf16 v[28:31], v[188:191], v[216:219], v[28:31]
	ds_read_b128 v[172:175], v155
	v_mfma_f32_16x16x32_bf16 v[24:27], v[188:191], v[224:227], v[24:27]
	v_mfma_f32_16x16x32_bf16 v[20:23], v[196:199], v[216:219], v[20:23]
	ds_read_b128 v[176:179], v155 offset:1024
	v_mfma_f32_16x16x32_bf16 v[16:19], v[196:199], v[224:227], v[16:19]
	v_mfma_f32_16x16x32_bf16 v[12:15], v[204:207], v[216:219], v[12:15]
	ds_read_b128 v[180:183], v155 offset:2048
	v_mfma_f32_16x16x32_bf16 v[8:11], v[204:207], v[224:227], v[8:11]
	v_mfma_f32_16x16x32_bf16 v[4:7], v[212:215], v[216:219], v[4:7]
	ds_read_b128 v[184:187], v155 offset:3072
	v_mfma_f32_16x16x32_bf16 v[0:3], v[212:215], v[224:227], v[0:3]
	v_mfma_f32_16x16x32_bf16 v[28:31], v[192:195], v[220:223], v[28:31]
	v_mfma_f32_16x16x32_bf16 v[24:27], v[192:195], v[228:231], v[24:27]
	v_mfma_f32_16x16x32_bf16 v[20:23], v[200:203], v[220:223], v[20:23]
	v_mfma_f32_16x16x32_bf16 v[16:19], v[200:203], v[228:231], v[16:19]
	v_mfma_f32_16x16x32_bf16 v[12:15], v[208:211], v[220:223], v[12:15]
	v_mfma_f32_16x16x32_bf16 v[8:11], v[208:211], v[228:231], v[8:11]
	v_mfma_f32_16x16x32_bf16 v[4:7], v[232:235], v[220:223], v[4:7]
	v_mfma_f32_16x16x32_bf16 v[0:3], v[232:235], v[228:231], v[0:3]
	s_barrier
	v_add_u32_e32 v167, 0x4000, v148
	v_add_u32_e32 v168, 0x6000, v148
	v_readfirstlane_b32 s63, v167
	v_lshl_add_u64 v[220:221], v[236:237], 0, s[42:43]
	s_mov_b32 m0, s63
	v_readfirstlane_b32 s63, v168
	ds_read_b128 v[188:191], v152 offset:32768
	ds_read_b128 v[192:195], v152 offset:33792
	ds_read_b128 v[196:199], v151 offset:32768
	ds_read_b128 v[200:203], v151 offset:33792
	ds_read_b128 v[204:207], v150 offset:32768
	ds_read_b128 v[208:211], v150 offset:33792
	ds_read_b128 v[212:215], v149 offset:32768
	ds_read_b128 v[216:219], v149 offset:33792
	global_load_lds_dwordx4 v[220:221], off
	v_lshl_add_u64 v[220:221], v[238:239], 0, s[42:43]
	s_mov_b32 m0, s63
	s_nop 0
	global_load_lds_dwordx4 v[220:221], off
	s_waitcnt lgkmcnt(8)
	s_barrier
	s_waitcnt lgkmcnt(0)
	s_waitcnt lgkmcnt(0)
	v_mfma_f32_16x16x32_bf16 v[124:127], v[188:191], v[172:175], v[124:127]
	ds_read_b128 v[220:223], v153
	v_mfma_f32_16x16x32_bf16 v[120:123], v[188:191], v[180:183], v[120:123]
	v_mfma_f32_16x16x32_bf16 v[116:119], v[196:199], v[172:175], v[116:119]
	ds_read_b128 v[224:227], v153 offset:1024
	v_mfma_f32_16x16x32_bf16 v[112:115], v[196:199], v[180:183], v[112:115]
	v_mfma_f32_16x16x32_bf16 v[108:111], v[204:207], v[172:175], v[108:111]
	ds_read_b128 v[228:231], v153 offset:2048
	v_mfma_f32_16x16x32_bf16 v[104:107], v[204:207], v[180:183], v[104:107]
	v_mfma_f32_16x16x32_bf16 v[100:103], v[212:215], v[172:175], v[100:103]
	ds_read_b128 v[232:235], v153 offset:3072
	v_mfma_f32_16x16x32_bf16 v[96:99], v[212:215], v[180:183], v[96:99]
	v_mfma_f32_16x16x32_bf16 v[124:127], v[192:195], v[176:179], v[124:127]
	v_mfma_f32_16x16x32_bf16 v[120:123], v[192:195], v[184:187], v[120:123]
	v_mfma_f32_16x16x32_bf16 v[116:119], v[200:203], v[176:179], v[116:119]
	v_mfma_f32_16x16x32_bf16 v[112:115], v[200:203], v[184:187], v[112:115]
	v_mfma_f32_16x16x32_bf16 v[108:111], v[208:211], v[176:179], v[108:111]
	v_mfma_f32_16x16x32_bf16 v[104:107], v[208:211], v[184:187], v[104:107]
	v_mfma_f32_16x16x32_bf16 v[100:103], v[216:219], v[176:179], v[100:103]
	v_mfma_f32_16x16x32_bf16 v[96:99], v[216:219], v[184:187], v[96:99]
	s_barrier
	v_readfirstlane_b32 s63, v156
	v_add_u32_e32 v171, 0x2000, v156
	v_lshl_add_u64 v[244:245], v[240:241], 0, s[44:45]
	s_mov_b32 m0, s63
	v_readfirstlane_b32 s63, v171
	global_load_lds_dwordx4 v[244:245], off
	v_lshl_add_u64 v[244:245], v[242:243], 0, s[44:45]
	s_mov_b32 m0, s63
	s_nop 0
	global_load_lds_dwordx4 v[244:245], off
	s_barrier
	s_waitcnt lgkmcnt(0)
	s_waitcnt lgkmcnt(0)
	v_mfma_f32_16x16x32_bf16 v[92:95], v[188:191], v[220:223], v[92:95]
	v_mfma_f32_16x16x32_bf16 v[88:91], v[188:191], v[228:231], v[88:91]
	v_mfma_f32_16x16x32_bf16 v[84:87], v[196:199], v[220:223], v[84:87]
	v_mfma_f32_16x16x32_bf16 v[80:83], v[196:199], v[228:231], v[80:83]
	v_mfma_f32_16x16x32_bf16 v[76:79], v[204:207], v[220:223], v[76:79]
	v_mfma_f32_16x16x32_bf16 v[72:75], v[204:207], v[228:231], v[72:75]
	v_mfma_f32_16x16x32_bf16 v[68:71], v[212:215], v[220:223], v[68:71]
	v_mfma_f32_16x16x32_bf16 v[64:67], v[212:215], v[228:231], v[64:67]
	v_mfma_f32_16x16x32_bf16 v[92:95], v[192:195], v[224:227], v[92:95]
	v_mfma_f32_16x16x32_bf16 v[88:91], v[192:195], v[232:235], v[88:91]
	v_mfma_f32_16x16x32_bf16 v[84:87], v[200:203], v[224:227], v[84:87]
	v_mfma_f32_16x16x32_bf16 v[80:83], v[200:203], v[232:235], v[80:83]
	v_mfma_f32_16x16x32_bf16 v[76:79], v[208:211], v[224:227], v[76:79]
	v_mfma_f32_16x16x32_bf16 v[72:75], v[208:211], v[232:235], v[72:75]
	v_mfma_f32_16x16x32_bf16 v[68:71], v[216:219], v[224:227], v[68:71]
	v_mfma_f32_16x16x32_bf16 v[64:67], v[216:219], v[232:235], v[64:67]
	v_readfirstlane_b32 s63, v157
	v_lshl_add_u64 v[236:237], v[236:237], 0, s[46:47]
	s_mov_b32 m0, s63
	v_readfirstlane_b32 s63, v158
	s_barrier
; #define STAGE(P, BASE, LD, br, kt) do { const char* _g = (const char*)((BASE) + (size_t)(br) * (LD) + (size_t)(kt) * 64); \
;     for (int _i = 0; _i < 2; ++_i) { int _b = tidx * 16 + _i * 8192; int _r, _c; stage_rc(_b, _r, _c); \
;       __builtin_amdgcn_global_load_lds((const unsigned*)(_g + (unsigned)((_r * (LD) + _c) * 2)), (unsigned*)((char*)(P) + _b), 16, 0, 0); } } while (0)
; #define LDA(dst, b, h) for (int m = 0; m < 4; ++m) for (int k = 0; k < 2; ++k) \
;     dst[m][k] = *reinterpret_cast<const bf16x8*>((char*)SA(b, h) + lds_byte(wr * 64 + m * 16 + fr, k * 32 + fq * 8))
; #define LDB(dst, b, h) for (int n = 0; n < 2; ++n) for (int k = 0; k < 2; ++k) \
;     dst[n][k] = *reinterpret_cast<const bf16x8*>((char*)SB(b, h) + lds_byte(wc * 32 + n * 16 + fr, k * 32 + fq * 8))
; #define MMA(ai, bj, At_, Bt_) do { __builtin_amdgcn_s_setprio(1); \
;     for (int k = 0; k < 2; ++k) for (int m = 0; m < 4; ++m) for (int n = 0; n < 2; ++n) \
;       acc[ai][bj][m][n] = __builtin_amdgcn_mfma_f32_16x16x32_bf16(At_[m][k], Bt_[n][k], acc[ai][bj][m][n], 0, 0, 0); \
;     __builtin_amdgcn_s_setprio(0); } while (0)
; #define WAIT_V(n) asm volatile("s_waitcnt vmcnt(" #n ")" ::: "memory")
; #define WAIT_L(n) asm volatile("s_waitcnt lgkmcnt(" #n ")" ::: "memory")
; #define BAR __builtin_amdgcn_s_barrier()
; #define SCHED __builtin_amdgcn_sched_barrier(0)
; template <int EPI, int lda, int ldb, int N, int K>
; __device__ __forceinline__ void gemm_phase(const u16* __restrict__ A, const u16* __restrict__ Bt, const GemmEpi ep, int wv) {
;     ...
;       LDA(At, 1, 1); STAGE(SA(1, 0), Ab, lda, brow, t + 3);
;       BAR; WAIT_L(0); MMA(1, 0, At, B0); BAR; SCHED;
;       STAGE(SB(1, 1), Bt, ldb, bcol + HALF, t + 3);
;       WAIT_V(6); BAR; MMA(1, 1, At, B1); BAR;
;     }
;     { LDB(B0, 0, 0); LDA(At, 0, 0); STAGE(SA(1, 1), Ab, lda, brow + HALF, nt - 1);
;       BAR; WAIT_L(0); MMA(0, 0, At, B0); BAR;
	ds_read_b128 v[188:191], v152 offset:49152
	ds_read_b128 v[192:195], v152 offset:50176
	ds_read_b128 v[196:199], v151 offset:49152
	ds_read_b128 v[200:203], v151 offset:50176
	ds_read_b128 v[204:207], v150 offset:49152
	ds_read_b128 v[208:211], v150 offset:50176
	ds_read_b128 v[212:215], v149 offset:49152
	ds_read_b128 v[216:219], v149 offset:50176
	global_load_lds_dwordx4 v[236:237], off
	v_lshl_add_u64 v[236:237], v[238:239], 0, s[46:47]
	s_mov_b32 m0, s63
	s_nop 0
	global_load_lds_dwordx4 v[236:237], off
	s_barrier
	s_waitcnt lgkmcnt(0)
	s_waitcnt lgkmcnt(0)
	v_mfma_f32_16x16x32_bf16 v[60:63], v[188:191], v[172:175], v[60:63]
	v_mfma_f32_16x16x32_bf16 v[56:59], v[188:191], v[180:183], v[56:59]
	v_mfma_f32_16x16x32_bf16 v[52:55], v[196:199], v[172:175], v[52:55]
	v_mfma_f32_16x16x32_bf16 v[48:51], v[196:199], v[180:183], v[48:51]
	v_mfma_f32_16x16x32_bf16 v[44:47], v[204:207], v[172:175], v[44:47]
	v_mfma_f32_16x16x32_bf16 v[40:43], v[204:207], v[180:183], v[40:43]
	v_mfma_f32_16x16x32_bf16 v[36:39], v[212:215], v[172:175], v[36:39]
	v_mfma_f32_16x16x32_bf16 v[32:35], v[212:215], v[180:183], v[32:35]
	v_mfma_f32_16x16x32_bf16 v[60:63], v[192:195], v[176:179], v[60:63]
	v_mfma_f32_16x16x32_bf16 v[56:59], v[192:195], v[184:187], v[56:59]
	v_mfma_f32_16x16x32_bf16 v[52:55], v[200:203], v[176:179], v[52:55]
	v_mfma_f32_16x16x32_bf16 v[48:51], v[200:203], v[184:187], v[48:51]
	v_mfma_f32_16x16x32_bf16 v[44:47], v[208:211], v[176:179], v[44:47]
	v_mfma_f32_16x16x32_bf16 v[40:43], v[208:211], v[184:187], v[40:43]
	v_mfma_f32_16x16x32_bf16 v[36:39], v[216:219], v[176:179], v[36:39]
	v_mfma_f32_16x16x32_bf16 v[32:35], v[216:219], v[184:187], v[32:35]
	s_barrier
	v_readfirstlane_b32 s63, v159
	v_add_u32_e32 v171, 0x2000, v159
	v_lshl_add_u64 v[172:173], v[240:241], 0, s[48:49]
	s_mov_b32 m0, s63
	v_readfirstlane_b32 s63, v171
	global_load_lds_dwordx4 v[172:173], off
	v_lshl_add_u64 v[172:173], v[242:243], 0, s[48:49]
	s_mov_b32 m0, s63
	s_nop 0
	global_load_lds_dwordx4 v[172:173], off
	s_waitcnt vmcnt(6)
	s_barrier
	v_mfma_f32_16x16x32_bf16 v[28:31], v[188:191], v[220:223], v[28:31]
	v_mfma_f32_16x16x32_bf16 v[24:27], v[188:191], v[228:231], v[24:27]
	v_mfma_f32_16x16x32_bf16 v[20:23], v[196:199], v[220:223], v[20:23]
	v_mfma_f32_16x16x32_bf16 v[16:19], v[196:199], v[228:231], v[16:19]
	v_mfma_f32_16x16x32_bf16 v[12:15], v[204:207], v[220:223], v[12:15]
	v_mfma_f32_16x16x32_bf16 v[8:11], v[204:207], v[228:231], v[8:11]
	v_mfma_f32_16x16x32_bf16 v[4:7], v[212:215], v[220:223], v[4:7]
	v_mfma_f32_16x16x32_bf16 v[0:3], v[212:215], v[228:231], v[0:3]
	v_mfma_f32_16x16x32_bf16 v[28:31], v[192:195], v[224:227], v[28:31]
	v_mfma_f32_16x16x32_bf16 v[24:27], v[192:195], v[232:235], v[24:27]
	v_mfma_f32_16x16x32_bf16 v[20:23], v[200:203], v[224:227], v[20:23]
	v_mfma_f32_16x16x32_bf16 v[16:19], v[200:203], v[232:235], v[16:19]
	v_mfma_f32_16x16x32_bf16 v[12:15], v[208:211], v[224:227], v[12:15]
	v_mfma_f32_16x16x32_bf16 v[8:11], v[208:211], v[232:235], v[8:11]
	v_mfma_f32_16x16x32_bf16 v[4:7], v[216:219], v[224:227], v[4:7]
	v_mfma_f32_16x16x32_bf16 v[0:3], v[216:219], v[232:235], v[0:3]
	s_add_i32 s62, s62, 2
	s_add_u32 s60, s60, 0x100
	s_addc_u32 s61, s61, 0
	s_cmp_gt_u32 s62, 27
	s_barrier
	s_cbranch_scc0 .LBB0_1147
	s_add_i32 s60, s58, 0x80
	s_mul_hi_i32 s61, s60, 0x1080
	s_mulk_i32 s60, 0x1080
	s_add_u32 s60, s69, s60
	s_addc_u32 s61, s70, s61
	v_lshl_add_u64 v[208:209], s[60:61], 0, v[128:129]
	v_readfirstlane_b32 s62, v169
	v_lshl_add_u64 v[208:209], v[208:209], 0, s[50:51]
	s_mov_b32 m0, s62
	ds_read_b128 v[134:137], v161
	ds_read_b128 v[138:141], v161 offset:1024
	ds_read_b128 v[156:159], v161 offset:2048
	ds_read_b128 v[172:175], v161 offset:3072
	ds_read_b128 v[176:179], v152
	ds_read_b128 v[180:183], v152 offset:1024
	ds_read_b128 v[184:187], v151
	ds_read_b128 v[188:191], v151 offset:1024
	ds_read_b128 v[192:195], v150
	ds_read_b128 v[196:199], v150 offset:1024
	ds_read_b128 v[200:203], v149
	ds_read_b128 v[204:207], v149 offset:1024
	global_load_lds_dwordx4 v[208:209], off
	v_lshl_add_u64 v[208:209], s[60:61], 0, v[132:133]
	v_readfirstlane_b32 s60, v170
	v_lshl_add_u64 v[208:209], v[208:209], 0, s[50:51]
	s_mov_b32 m0, s60
	s_nop 0
	global_load_lds_dwordx4 v[208:209], off
	s_barrier
	s_waitcnt lgkmcnt(0)
	s_waitcnt lgkmcnt(0)
	v_mfma_f32_16x16x32_bf16 v[124:127], v[176:179], v[134:137], v[124:127]
	v_mfma_f32_16x16x32_bf16 v[120:123], v[176:179], v[156:159], v[120:123]
	v_mfma_f32_16x16x32_bf16 v[116:119], v[184:187], v[134:137], v[116:119]
	v_mfma_f32_16x16x32_bf16 v[112:115], v[184:187], v[156:159], v[112:115]
	v_mfma_f32_16x16x32_bf16 v[108:111], v[192:195], v[134:137], v[108:111]
	v_mfma_f32_16x16x32_bf16 v[104:107], v[192:195], v[156:159], v[104:107]
	v_mfma_f32_16x16x32_bf16 v[100:103], v[200:203], v[134:137], v[100:103]
	v_mfma_f32_16x16x32_bf16 v[96:99], v[200:203], v[156:159], v[96:99]
	v_mfma_f32_16x16x32_bf16 v[124:127], v[180:183], v[138:141], v[124:127]
	v_mfma_f32_16x16x32_bf16 v[120:123], v[180:183], v[172:175], v[120:123]
	v_mfma_f32_16x16x32_bf16 v[116:119], v[188:191], v[138:141], v[116:119]
	v_mfma_f32_16x16x32_bf16 v[112:115], v[188:191], v[172:175], v[112:115]
	v_mfma_f32_16x16x32_bf16 v[108:111], v[196:199], v[138:141], v[108:111]
	v_mfma_f32_16x16x32_bf16 v[104:107], v[196:199], v[172:175], v[104:107]
	v_mfma_f32_16x16x32_bf16 v[100:103], v[204:207], v[138:141], v[100:103]
	v_mfma_f32_16x16x32_bf16 v[96:99], v[204:207], v[172:175], v[96:99]
	s_barrier
	ds_read_b128 v[208:211], v160
	ds_read_b128 v[212:215], v160 offset:1024
	ds_read_b128 v[216:219], v160 offset:2048
	ds_read_b128 v[220:223], v160 offset:3072
	s_barrier
; #define LDA(dst, b, h) for (int m = 0; m < 4; ++m) for (int k = 0; k < 2; ++k) \
;     dst[m][k] = *reinterpret_cast<const bf16x8*>((char*)SA(b, h) + lds_byte(wr * 64 + m * 16 + fr, k * 32 + fq * 8))
; #define LDB(dst, b, h) for (int n = 0; n < 2; ++n) for (int k = 0; k < 2; ++k) \
;     dst[n][k] = *reinterpret_cast<const bf16x8*>((char*)SB(b, h) + lds_byte(wc * 32 + n * 16 + fr, k * 32 + fq * 8))
; #define MMA(ai, bj, At_, Bt_) do { __builtin_amdgcn_s_setprio(1); \
;     for (int k = 0; k < 2; ++k) for (int m = 0; m < 4; ++m) for (int n = 0; n < 2; ++n) \
;       acc[ai][bj][m][n] = __builtin_amdgcn_mfma_f32_16x16x32_bf16(At_[m][k], Bt_[n][k], acc[ai][bj][m][n], 0, 0, 0); \
;     __builtin_amdgcn_s_setprio(0); } while (0)
; #define WAIT_V(n) asm volatile("s_waitcnt vmcnt(" #n ")" ::: "memory")
; #define WAIT_L(n) asm volatile("s_waitcnt lgkmcnt(" #n ")" ::: "memory")
; #define BAR __builtin_amdgcn_s_barrier()
; template <int EPI, int lda, int ldb, int N, int K>
; __device__ __forceinline__ void gemm_phase(const u16* __restrict__ A, const u16* __restrict__ Bt, const GemmEpi ep, int wv) {
;     ...
;       LDB(B1, 0, 1); BAR; WAIT_L(0); MMA(0, 1, At, B1); BAR;
;       LDA(At, 0, 1); WAIT_V(4); BAR; WAIT_L(0); MMA(1, 0, At, B0); MMA(1, 1, At, B1); BAR; }
;     { LDB(B0, 1, 0); LDA(At, 1, 0); WAIT_V(2); BAR; WAIT_L(0); MMA(0, 0, At, B0); BAR;
	s_waitcnt lgkmcnt(0)
	s_waitcnt lgkmcnt(0)
	v_mfma_f32_16x16x32_bf16 v[92:95], v[176:179], v[208:211], v[92:95]
	v_mfma_f32_16x16x32_bf16 v[88:91], v[176:179], v[216:219], v[88:91]
	v_mfma_f32_16x16x32_bf16 v[76:79], v[192:195], v[208:211], v[76:79]
	v_mfma_f32_16x16x32_bf16 v[72:75], v[192:195], v[216:219], v[72:75]
	v_mfma_f32_16x16x32_bf16 v[84:87], v[184:187], v[208:211], v[84:87]
	v_mfma_f32_16x16x32_bf16 v[80:83], v[184:187], v[216:219], v[80:83]
	v_mfma_f32_16x16x32_bf16 v[68:71], v[200:203], v[208:211], v[68:71]
	v_mfma_f32_16x16x32_bf16 v[64:67], v[200:203], v[216:219], v[64:67]
	v_mfma_f32_16x16x32_bf16 v[92:95], v[180:183], v[212:215], v[92:95]
	v_mfma_f32_16x16x32_bf16 v[88:91], v[180:183], v[220:223], v[88:91]
	v_mfma_f32_16x16x32_bf16 v[76:79], v[196:199], v[212:215], v[76:79]
	v_mfma_f32_16x16x32_bf16 v[72:75], v[196:199], v[220:223], v[72:75]
	v_mfma_f32_16x16x32_bf16 v[176:179], v[188:191], v[212:215], v[84:87]
	v_mfma_f32_16x16x32_bf16 v[180:183], v[188:191], v[220:223], v[80:83]
	v_mfma_f32_16x16x32_bf16 v[184:187], v[204:207], v[212:215], v[68:71]
	v_mfma_f32_16x16x32_bf16 v[188:191], v[204:207], v[220:223], v[64:67]
	s_barrier
	s_nop 0
	ds_read_b128 v[64:67], v152 offset:16384
	ds_read_b128 v[68:71], v152 offset:17408
	ds_read_b128 v[80:83], v151 offset:16384
	ds_read_b128 v[84:87], v151 offset:17408
	ds_read_b128 v[192:195], v150 offset:16384
	ds_read_b128 v[196:199], v150 offset:17408
	ds_read_b128 v[200:203], v149 offset:16384
	ds_read_b128 v[204:207], v149 offset:17408
	s_waitcnt vmcnt(4)
	s_barrier
	s_waitcnt lgkmcnt(0)
	s_waitcnt lgkmcnt(0)
	v_mfma_f32_16x16x32_bf16 v[60:63], v[64:67], v[134:137], v[60:63]
	v_mfma_f32_16x16x32_bf16 v[56:59], v[64:67], v[156:159], v[56:59]
	v_mfma_f32_16x16x32_bf16 v[52:55], v[80:83], v[134:137], v[52:55]
	v_mfma_f32_16x16x32_bf16 v[48:51], v[80:83], v[156:159], v[48:51]
	v_mfma_f32_16x16x32_bf16 v[44:47], v[192:195], v[134:137], v[44:47]
	v_mfma_f32_16x16x32_bf16 v[40:43], v[192:195], v[156:159], v[40:43]
	v_mfma_f32_16x16x32_bf16 v[36:39], v[200:203], v[134:137], v[36:39]
	v_mfma_f32_16x16x32_bf16 v[32:35], v[200:203], v[156:159], v[32:35]
	v_mfma_f32_16x16x32_bf16 v[60:63], v[68:71], v[138:141], v[60:63]
	v_mfma_f32_16x16x32_bf16 v[56:59], v[68:71], v[172:175], v[56:59]
	v_mfma_f32_16x16x32_bf16 v[52:55], v[84:87], v[138:141], v[52:55]
	v_mfma_f32_16x16x32_bf16 v[48:51], v[84:87], v[172:175], v[48:51]
	v_mfma_f32_16x16x32_bf16 v[44:47], v[196:199], v[138:141], v[44:47]
	v_mfma_f32_16x16x32_bf16 v[40:43], v[196:199], v[172:175], v[40:43]
	v_mfma_f32_16x16x32_bf16 v[36:39], v[204:207], v[138:141], v[36:39]
	v_mfma_f32_16x16x32_bf16 v[32:35], v[204:207], v[172:175], v[32:35]
	v_mfma_f32_16x16x32_bf16 v[28:31], v[64:67], v[208:211], v[28:31]
	v_mfma_f32_16x16x32_bf16 v[24:27], v[64:67], v[216:219], v[24:27]
	v_mfma_f32_16x16x32_bf16 v[12:15], v[192:195], v[208:211], v[12:15]
	v_mfma_f32_16x16x32_bf16 v[8:11], v[192:195], v[216:219], v[8:11]
	v_mfma_f32_16x16x32_bf16 v[20:23], v[80:83], v[208:211], v[20:23]
	v_mfma_f32_16x16x32_bf16 v[16:19], v[80:83], v[216:219], v[16:19]
	v_mfma_f32_16x16x32_bf16 v[4:7], v[200:203], v[208:211], v[4:7]
	v_mfma_f32_16x16x32_bf16 v[0:3], v[200:203], v[216:219], v[0:3]
	v_mfma_f32_16x16x32_bf16 v[28:31], v[68:71], v[212:215], v[28:31]
	v_mfma_f32_16x16x32_bf16 v[24:27], v[68:71], v[220:223], v[24:27]
	v_mfma_f32_16x16x32_bf16 v[12:15], v[196:199], v[212:215], v[12:15]
	v_mfma_f32_16x16x32_bf16 v[8:11], v[196:199], v[220:223], v[8:11]
	v_mfma_f32_16x16x32_bf16 v[134:137], v[84:87], v[212:215], v[20:23]
	v_mfma_f32_16x16x32_bf16 v[138:141], v[84:87], v[220:223], v[16:19]
	v_mfma_f32_16x16x32_bf16 v[156:159], v[204:207], v[212:215], v[4:7]
	v_mfma_f32_16x16x32_bf16 v[170:173], v[204:207], v[220:223], v[0:3]
	s_barrier
	s_nop 0
	ds_read_b128 v[0:3], v155
	ds_read_b128 v[4:7], v155 offset:1024
	ds_read_b128 v[16:19], v155 offset:2048
	ds_read_b128 v[192:195], v155 offset:3072
	ds_read_b128 v[20:23], v152 offset:32768
	ds_read_b128 v[196:199], v152 offset:33792
	ds_read_b128 v[200:203], v151 offset:32768
	ds_read_b128 v[204:207], v151 offset:33792
	ds_read_b128 v[208:211], v150 offset:32768
	ds_read_b128 v[212:215], v150 offset:33792
	ds_read_b128 v[216:219], v149 offset:32768
	ds_read_b128 v[220:223], v149 offset:33792
	s_waitcnt vmcnt(2)
	s_barrier
; #define LDA(dst, b, h) for (int m = 0; m < 4; ++m) for (int k = 0; k < 2; ++k) \
;     dst[m][k] = *reinterpret_cast<const bf16x8*>((char*)SA(b, h) + lds_byte(wr * 64 + m * 16 + fr, k * 32 + fq * 8))
; #define LDB(dst, b, h) for (int n = 0; n < 2; ++n) for (int k = 0; k < 2; ++k) \
;     dst[n][k] = *reinterpret_cast<const bf16x8*>((char*)SB(b, h) + lds_byte(wc * 32 + n * 16 + fr, k * 32 + fq * 8))
; #define MMA(ai, bj, At_, Bt_) do { __builtin_amdgcn_s_setprio(1); \
;     for (int k = 0; k < 2; ++k) for (int m = 0; m < 4; ++m) for (int n = 0; n < 2; ++n) \
;       acc[ai][bj][m][n] = __builtin_amdgcn_mfma_f32_16x16x32_bf16(At_[m][k], Bt_[n][k], acc[ai][bj][m][n], 0, 0, 0); \
;     __builtin_amdgcn_s_setprio(0); } while (0)
; #define WAIT_V(n) asm volatile("s_waitcnt vmcnt(" #n ")" ::: "memory")
; #define WAIT_L(n) asm volatile("s_waitcnt lgkmcnt(" #n ")" ::: "memory")
; #define BAR __builtin_amdgcn_s_barrier()
; template <int EPI, int lda, int ldb, int N, int K>
; __device__ __forceinline__ void gemm_phase(const u16* __restrict__ A, const u16* __restrict__ Bt, const GemmEpi ep, int wv) {
;     ...
;     { LDB(B0, 1, 0); LDA(At, 1, 0); WAIT_V(2); BAR; WAIT_L(0); MMA(0, 0, At, B0); BAR;
;       LDB(B1, 1, 1); WAIT_V(0); BAR; WAIT_L(0); MMA(0, 1, At, B1); BAR;
;       LDA(At, 1, 1); BAR; WAIT_L(0); MMA(1, 0, At, B0); MMA(1, 1, At, B1); BAR; }
;     if (wr == 0) BAR;
	s_waitcnt lgkmcnt(0)
	s_waitcnt lgkmcnt(0)
	v_mfma_f32_16x16x32_bf16 v[64:67], v[20:23], v[0:3], v[124:127]
	v_mfma_f32_16x16x32_bf16 v[68:71], v[20:23], v[16:19], v[120:123]
	v_mfma_f32_16x16x32_bf16 v[80:83], v[200:203], v[0:3], v[116:119]
	v_mfma_f32_16x16x32_bf16 v[84:87], v[200:203], v[16:19], v[112:115]
	v_mfma_f32_16x16x32_bf16 v[108:111], v[208:211], v[0:3], v[108:111]
	v_mfma_f32_16x16x32_bf16 v[104:107], v[208:211], v[16:19], v[104:107]
	v_mfma_f32_16x16x32_bf16 v[120:123], v[216:219], v[0:3], v[100:103]
	v_mfma_f32_16x16x32_bf16 v[124:127], v[216:219], v[16:19], v[96:99]
	v_mfma_f32_16x16x32_bf16 v[116:119], v[196:199], v[4:7], v[64:67]
	v_mfma_f32_16x16x32_bf16 v[112:115], v[196:199], v[192:195], v[68:71]
	v_mfma_f32_16x16x32_bf16 v[100:103], v[204:207], v[4:7], v[80:83]
	v_mfma_f32_16x16x32_bf16 v[96:99], v[204:207], v[192:195], v[84:87]
	v_mfma_f32_16x16x32_bf16 v[84:87], v[212:215], v[4:7], v[108:111]
	v_mfma_f32_16x16x32_bf16 v[80:83], v[212:215], v[192:195], v[104:107]
	v_mfma_f32_16x16x32_bf16 v[68:71], v[220:223], v[4:7], v[120:123]
	v_mfma_f32_16x16x32_bf16 v[64:67], v[220:223], v[192:195], v[124:127]
	s_barrier
	ds_read_b128 v[224:227], v153
	ds_read_b128 v[228:231], v153 offset:1024
	ds_read_b128 v[232:235], v153 offset:2048
	ds_read_b128 v[236:239], v153 offset:3072
	s_waitcnt vmcnt(0)
	s_barrier
	s_waitcnt lgkmcnt(0)
	s_waitcnt lgkmcnt(0)
	v_mfma_f32_16x16x32_bf16 v[92:95], v[20:23], v[224:227], v[92:95]
	v_mfma_f32_16x16x32_bf16 v[20:23], v[20:23], v[232:235], v[88:91]
	v_mfma_f32_16x16x32_bf16 v[88:91], v[200:203], v[224:227], v[176:179]
	v_mfma_f32_16x16x32_bf16 v[104:107], v[200:203], v[232:235], v[180:183]
	v_mfma_f32_16x16x32_bf16 v[76:79], v[208:211], v[224:227], v[76:79]
	v_mfma_f32_16x16x32_bf16 v[72:75], v[208:211], v[232:235], v[72:75]
	v_mfma_f32_16x16x32_bf16 v[174:177], v[216:219], v[224:227], v[184:187]
	v_mfma_f32_16x16x32_bf16 v[178:181], v[216:219], v[232:235], v[188:191]
	v_mfma_f32_16x16x32_bf16 v[124:127], v[196:199], v[228:231], v[92:95]
	v_mfma_f32_16x16x32_bf16 v[120:123], v[196:199], v[236:239], v[20:23]
	v_mfma_f32_16x16x32_bf16 v[108:111], v[204:207], v[228:231], v[88:91]
	v_mfma_f32_16x16x32_bf16 v[104:107], v[204:207], v[236:239], v[104:107]
	v_mfma_f32_16x16x32_bf16 v[92:95], v[212:215], v[228:231], v[76:79]
	v_mfma_f32_16x16x32_bf16 v[88:91], v[212:215], v[236:239], v[72:75]
	v_mfma_f32_16x16x32_bf16 v[76:79], v[220:223], v[228:231], v[174:177]
	v_mfma_f32_16x16x32_bf16 v[72:75], v[220:223], v[236:239], v[178:181]
	s_barrier
	ds_read_b128 v[174:177], v152 offset:49152
	ds_read_b128 v[152:155], v152 offset:50176
	ds_read_b128 v[178:181], v151 offset:49152
	ds_read_b128 v[182:185], v151 offset:50176
	ds_read_b128 v[186:189], v150 offset:49152
	ds_read_b128 v[196:199], v150 offset:50176
	ds_read_b128 v[200:203], v149 offset:49152
	ds_read_b128 v[204:207], v149 offset:50176
	s_barrier
	s_waitcnt lgkmcnt(0)
	s_waitcnt lgkmcnt(0)
	v_mfma_f32_16x16x32_bf16 v[20:23], v[174:177], v[0:3], v[60:63]
	v_mfma_f32_16x16x32_bf16 v[56:59], v[174:177], v[16:19], v[56:59]
	v_mfma_f32_16x16x32_bf16 v[60:63], v[178:181], v[0:3], v[52:55]
	v_mfma_f32_16x16x32_bf16 v[208:211], v[178:181], v[16:19], v[48:51]
	v_mfma_f32_16x16x32_bf16 v[44:47], v[186:189], v[0:3], v[44:47]
	v_mfma_f32_16x16x32_bf16 v[40:43], v[186:189], v[16:19], v[40:43]
	v_mfma_f32_16x16x32_bf16 v[0:3], v[200:203], v[0:3], v[36:39]
	v_mfma_f32_16x16x32_bf16 v[212:215], v[200:203], v[16:19], v[32:35]
	v_mfma_f32_16x16x32_bf16 v[52:55], v[152:155], v[4:7], v[20:23]
	v_mfma_f32_16x16x32_bf16 v[48:51], v[152:155], v[192:195], v[56:59]
	v_mfma_f32_16x16x32_bf16 v[36:39], v[182:185], v[4:7], v[60:63]
	v_mfma_f32_16x16x32_bf16 v[32:35], v[182:185], v[192:195], v[208:211]
	v_mfma_f32_16x16x32_bf16 v[20:23], v[196:199], v[4:7], v[44:47]
	v_mfma_f32_16x16x32_bf16 v[16:19], v[196:199], v[192:195], v[40:43]
	v_mfma_f32_16x16x32_bf16 v[4:7], v[204:207], v[4:7], v[0:3]
	v_mfma_f32_16x16x32_bf16 v[0:3], v[204:207], v[192:195], v[212:215]
	v_mfma_f32_16x16x32_bf16 v[28:31], v[174:177], v[224:227], v[28:31]
	v_mfma_f32_16x16x32_bf16 v[24:27], v[174:177], v[232:235], v[24:27]
	v_mfma_f32_16x16x32_bf16 v[40:43], v[178:181], v[224:227], v[134:137]
	v_mfma_f32_16x16x32_bf16 v[134:137], v[178:181], v[232:235], v[138:141]
	v_mfma_f32_16x16x32_bf16 v[12:15], v[186:189], v[224:227], v[12:15]
	v_mfma_f32_16x16x32_bf16 v[8:11], v[186:189], v[232:235], v[8:11]
	v_mfma_f32_16x16x32_bf16 v[138:141], v[200:203], v[224:227], v[156:159]
	v_mfma_f32_16x16x32_bf16 v[156:159], v[200:203], v[232:235], v[170:173]
	v_mfma_f32_16x16x32_bf16 v[60:63], v[152:155], v[228:231], v[28:31]
	v_mfma_f32_16x16x32_bf16 v[56:59], v[152:155], v[236:239], v[24:27]
	v_mfma_f32_16x16x32_bf16 v[44:47], v[182:185], v[228:231], v[40:43]
	v_mfma_f32_16x16x32_bf16 v[40:43], v[182:185], v[236:239], v[134:137]
	v_mfma_f32_16x16x32_bf16 v[28:31], v[196:199], v[228:231], v[12:15]
	v_mfma_f32_16x16x32_bf16 v[24:27], v[196:199], v[236:239], v[8:11]
	v_mfma_f32_16x16x32_bf16 v[12:15], v[204:207], v[228:231], v[138:141]
	v_mfma_f32_16x16x32_bf16 v[8:11], v[204:207], v[236:239], v[156:159]
	v_cmp_gt_u32_e32 vcc, s80, v130
	s_barrier
	s_and_saveexec_b64 s[60:61], vcc
	s_cbranch_execz .LBB0_1150
	s_barrier

; #define STAGE(P, BASE, LD, br, kt) do { const char* _g = (const char*)((BASE) + (size_t)(br) * (LD) + (size_t)(kt) * 64); \
;     for (int _i = 0; _i < 2; ++_i) { int _b = tidx * 16 + _i * 8192; int _r, _c; stage_rc(_b, _r, _c); \
;       __builtin_amdgcn_global_load_lds((const unsigned*)(_g + (unsigned)((_r * (LD) + _c) * 2)), (unsigned*)((char*)(P) + _b), 16, 0, 0); } } while (0)
; #define LDA(dst, b, h) for (int m = 0; m < 4; ++m) for (int k = 0; k < 2; ++k) \
;     dst[m][k] = *reinterpret_cast<const bf16x8*>((char*)SA(b, h) + lds_byte(wr * 64 + m * 16 + fr, k * 32 + fq * 8))
; #define LDB(dst, b, h) for (int n = 0; n < 2; ++n) for (int k = 0; k < 2; ++k) \
;     dst[n][k] = *reinterpret_cast<const bf16x8*>((char*)SB(b, h) + lds_byte(wc * 32 + n * 16 + fr, k * 32 + fq * 8))
; #define MMA(ai, bj, At_, Bt_) do { __builtin_amdgcn_s_setprio(1); \
;     for (int k = 0; k < 2; ++k) for (int m = 0; m < 4; ++m) for (int n = 0; n < 2; ++n) \
;       acc[ai][bj][m][n] = __builtin_amdgcn_mfma_f32_16x16x32_bf16(At_[m][k], Bt_[n][k], acc[ai][bj][m][n], 0, 0, 0); \
;     __builtin_amdgcn_s_setprio(0); } while (0)
; #define WAIT_V(n) asm volatile("s_waitcnt vmcnt(" #n ")" ::: "memory")
; #define WAIT_L(n) asm volatile("s_waitcnt lgkmcnt(" #n ")" ::: "memory")
; #define BAR __builtin_amdgcn_s_barrier()
; #define SCHED __builtin_amdgcn_sched_barrier(0)
; template <int EPI, int lda, int ldb, int N, int K>
; __device__ __forceinline__ void gemm_phase(const u16* __restrict__ A, const u16* __restrict__ Bt, const GemmEpi ep, int wv) {
;     ...
;     for (int t = 0; t < nt - 2; t += 2) {
;       LDB(B0, 0, 0); SCHED; LDA(At, 0, 0); STAGE(SA(1, 1), Ab, lda, brow + HALF, t + 1);
;       WAIT_L(8); BAR; WAIT_L(0); MMA(0, 0, At, B0); BAR; SCHED;
;       LDB(B1, 0, 1); STAGE(SB(0, 0), Bt, ldb, bcol, t + 2);
;       BAR; WAIT_L(0); MMA(0, 1, At, B1); BAR;
;       LDA(At, 0, 1); STAGE(SA(0, 0), Ab, lda, brow, t + 2);
;       BAR; WAIT_L(0); MMA(1, 0, At, B0); BAR; SCHED;
;       STAGE(SB(0, 1), Bt, ldb, bcol + HALF, t + 2);
;       WAIT_V(6); BAR; MMA(1, 1, At, B1); BAR;
.LBB0_1448:
	ds_read_b128 v[164:167], v160
	ds_read_b128 v[170:173], v160 offset:1024
	ds_read_b128 v[174:177], v160 offset:2048
	ds_read_b128 v[178:181], v160 offset:3072
	v_add_u32_e32 v168, 0xc000, v143
	v_lshl_add_u64 v[234:235], v[138:139], 0, s[44:45]
	v_readfirstlane_b32 s47, v168
	v_add_u32_e32 v169, 0xe000, v143
	v_lshl_add_u64 v[162:163], v[234:235], 0, s[20:21]
	s_mov_b32 m0, s47
	v_lshl_add_u64 v[236:237], v[140:141], 0, s[44:45]
	v_readfirstlane_b32 s47, v169
	ds_read_b128 v[182:185], v151
	ds_read_b128 v[186:189], v151 offset:1024
	ds_read_b128 v[190:193], v150
	ds_read_b128 v[194:197], v150 offset:1024
	ds_read_b128 v[198:201], v149
	ds_read_b128 v[202:205], v149 offset:1024
	ds_read_b128 v[206:209], v148
	ds_read_b128 v[210:213], v148 offset:1024
	global_load_lds_dwordx4 v[162:163], off
	v_lshl_add_u64 v[162:163], v[236:237], 0, s[20:21]
	s_mov_b32 m0, s47
	s_nop 0
	global_load_lds_dwordx4 v[162:163], off
	s_waitcnt lgkmcnt(8)
	s_barrier
	s_waitcnt lgkmcnt(0)
	s_waitcnt lgkmcnt(0)
	v_mfma_f32_16x16x32_bf16 v[124:127], v[164:167], v[182:185], v[124:127]
	ds_read_b128 v[214:217], v159
	v_mfma_f32_16x16x32_bf16 v[120:123], v[174:177], v[182:185], v[120:123]
	v_mfma_f32_16x16x32_bf16 v[116:119], v[164:167], v[190:193], v[116:119]
	ds_read_b128 v[218:221], v159 offset:1024
	v_mfma_f32_16x16x32_bf16 v[112:115], v[174:177], v[190:193], v[112:115]
	v_mfma_f32_16x16x32_bf16 v[108:111], v[164:167], v[198:201], v[108:111]
	ds_read_b128 v[222:225], v159 offset:2048
	v_mfma_f32_16x16x32_bf16 v[104:107], v[174:177], v[198:201], v[104:107]
	v_mfma_f32_16x16x32_bf16 v[100:103], v[164:167], v[206:209], v[100:103]
	ds_read_b128 v[226:229], v159 offset:3072
	v_mfma_f32_16x16x32_bf16 v[96:99], v[174:177], v[206:209], v[96:99]
	v_mfma_f32_16x16x32_bf16 v[124:127], v[170:173], v[186:189], v[124:127]
	v_mfma_f32_16x16x32_bf16 v[120:123], v[178:181], v[186:189], v[120:123]
	v_mfma_f32_16x16x32_bf16 v[116:119], v[170:173], v[194:197], v[116:119]
	v_mfma_f32_16x16x32_bf16 v[112:115], v[178:181], v[194:197], v[112:115]
	v_mfma_f32_16x16x32_bf16 v[108:111], v[170:173], v[202:205], v[108:111]
	v_mfma_f32_16x16x32_bf16 v[104:107], v[178:181], v[202:205], v[104:107]
	v_mfma_f32_16x16x32_bf16 v[100:103], v[170:173], v[210:213], v[100:103]
	v_mfma_f32_16x16x32_bf16 v[96:99], v[178:181], v[210:213], v[96:99]
	s_barrier
	v_add_u32_e32 v161, s55, v153
	v_lshl_add_u64 v[238:239], v[134:135], 0, s[44:45]
	v_readfirstlane_b32 s47, v161
	v_lshl_add_u64 v[162:163], v[238:239], 0, s[22:23]
	s_mov_b32 m0, s47
	global_load_lds_dwordx4 v[162:163], off
	v_add_u32_e32 v162, 0x2000, v161
	v_lshl_add_u64 v[240:241], v[136:137], 0, s[44:45]
	v_readfirstlane_b32 s47, v162
	v_lshl_add_u64 v[230:231], v[240:241], 0, s[22:23]
	s_mov_b32 m0, s47
	s_nop 0
	global_load_lds_dwordx4 v[230:231], off
	s_barrier
	s_waitcnt lgkmcnt(0)
	s_waitcnt lgkmcnt(0)
	v_mfma_f32_16x16x32_bf16 v[92:95], v[214:217], v[182:185], v[92:95]
	v_mfma_f32_16x16x32_bf16 v[88:91], v[222:225], v[182:185], v[88:91]
	v_mfma_f32_16x16x32_bf16 v[84:87], v[214:217], v[190:193], v[84:87]
	v_mfma_f32_16x16x32_bf16 v[80:83], v[222:225], v[190:193], v[80:83]
	v_mfma_f32_16x16x32_bf16 v[76:79], v[214:217], v[198:201], v[76:79]
	v_mfma_f32_16x16x32_bf16 v[72:75], v[222:225], v[198:201], v[72:75]
	v_mfma_f32_16x16x32_bf16 v[68:71], v[214:217], v[206:209], v[68:71]
	v_mfma_f32_16x16x32_bf16 v[64:67], v[222:225], v[206:209], v[64:67]
	v_mfma_f32_16x16x32_bf16 v[92:95], v[218:221], v[186:189], v[92:95]
	v_mfma_f32_16x16x32_bf16 v[88:91], v[226:229], v[186:189], v[88:91]
	v_mfma_f32_16x16x32_bf16 v[84:87], v[218:221], v[194:197], v[84:87]
	v_mfma_f32_16x16x32_bf16 v[80:83], v[226:229], v[194:197], v[80:83]
	v_mfma_f32_16x16x32_bf16 v[76:79], v[218:221], v[202:205], v[76:79]
	v_mfma_f32_16x16x32_bf16 v[72:75], v[226:229], v[202:205], v[72:75]
	v_mfma_f32_16x16x32_bf16 v[68:71], v[218:221], v[210:213], v[68:71]
	v_mfma_f32_16x16x32_bf16 v[64:67], v[226:229], v[210:213], v[64:67]
	v_readfirstlane_b32 s47, v143
	v_add_u32_e32 v163, 0x2000, v143
	v_lshl_add_u64 v[230:231], v[234:235], 0, s[24:25]
	s_mov_b32 m0, s47
	v_readfirstlane_b32 s47, v163
	s_barrier
	ds_read_b128 v[182:185], v151 offset:16384
	ds_read_b128 v[186:189], v151 offset:17408
	ds_read_b128 v[190:193], v150 offset:16384
	ds_read_b128 v[194:197], v150 offset:17408
	ds_read_b128 v[198:201], v149 offset:16384
	ds_read_b128 v[202:205], v149 offset:17408
	ds_read_b128 v[206:209], v148 offset:16384
	ds_read_b128 v[210:213], v148 offset:17408
	global_load_lds_dwordx4 v[230:231], off
	v_lshl_add_u64 v[230:231], v[236:237], 0, s[24:25]
	s_mov_b32 m0, s47
	s_nop 0
	global_load_lds_dwordx4 v[230:231], off
	s_barrier
	s_waitcnt lgkmcnt(0)
	s_waitcnt lgkmcnt(0)
	v_mfma_f32_16x16x32_bf16 v[60:63], v[164:167], v[182:185], v[60:63]
	v_mfma_f32_16x16x32_bf16 v[56:59], v[174:177], v[182:185], v[56:59]
	v_mfma_f32_16x16x32_bf16 v[52:55], v[164:167], v[190:193], v[52:55]
	v_mfma_f32_16x16x32_bf16 v[48:51], v[174:177], v[190:193], v[48:51]
	v_mfma_f32_16x16x32_bf16 v[44:47], v[164:167], v[198:201], v[44:47]
	v_mfma_f32_16x16x32_bf16 v[40:43], v[174:177], v[198:201], v[40:43]
	v_mfma_f32_16x16x32_bf16 v[36:39], v[164:167], v[206:209], v[36:39]
	v_mfma_f32_16x16x32_bf16 v[32:35], v[174:177], v[206:209], v[32:35]
	v_mfma_f32_16x16x32_bf16 v[60:63], v[170:173], v[186:189], v[60:63]
	v_mfma_f32_16x16x32_bf16 v[56:59], v[178:181], v[186:189], v[56:59]
	v_mfma_f32_16x16x32_bf16 v[52:55], v[170:173], v[194:197], v[52:55]
	v_mfma_f32_16x16x32_bf16 v[48:51], v[178:181], v[194:197], v[48:51]
	v_mfma_f32_16x16x32_bf16 v[44:47], v[170:173], v[202:205], v[44:47]
	v_mfma_f32_16x16x32_bf16 v[40:43], v[178:181], v[202:205], v[40:43]
	v_mfma_f32_16x16x32_bf16 v[36:39], v[170:173], v[210:213], v[36:39]
	v_mfma_f32_16x16x32_bf16 v[32:35], v[178:181], v[210:213], v[32:35]
	s_barrier
; #define STAGE(P, BASE, LD, br, kt) do { const char* _g = (const char*)((BASE) + (size_t)(br) * (LD) + (size_t)(kt) * 64); \
;     for (int _i = 0; _i < 2; ++_i) { int _b = tidx * 16 + _i * 8192; int _r, _c; stage_rc(_b, _r, _c); \
;       __builtin_amdgcn_global_load_lds((const unsigned*)(_g + (unsigned)((_r * (LD) + _c) * 2)), (unsigned*)((char*)(P) + _b), 16, 0, 0); } } while (0)
; #define LDA(dst, b, h) for (int m = 0; m < 4; ++m) for (int k = 0; k < 2; ++k) \
;     dst[m][k] = *reinterpret_cast<const bf16x8*>((char*)SA(b, h) + lds_byte(wr * 64 + m * 16 + fr, k * 32 + fq * 8))
; #define LDB(dst, b, h) for (int n = 0; n < 2; ++n) for (int k = 0; k < 2; ++k) \
;     dst[n][k] = *reinterpret_cast<const bf16x8*>((char*)SB(b, h) + lds_byte(wc * 32 + n * 16 + fr, k * 32 + fq * 8))
; #define MMA(ai, bj, At_, Bt_) do { __builtin_amdgcn_s_setprio(1); \
;     for (int k = 0; k < 2; ++k) for (int m = 0; m < 4; ++m) for (int n = 0; n < 2; ++n) \
;       acc[ai][bj][m][n] = __builtin_amdgcn_mfma_f32_16x16x32_bf16(At_[m][k], Bt_[n][k], acc[ai][bj][m][n], 0, 0, 0); \
;     __builtin_amdgcn_s_setprio(0); } while (0)
; #define WAIT_V(n) asm volatile("s_waitcnt vmcnt(" #n ")" ::: "memory")
; #define WAIT_L(n) asm volatile("s_waitcnt lgkmcnt(" #n ")" ::: "memory")
; #define BAR __builtin_amdgcn_s_barrier()
; #define SCHED __builtin_amdgcn_sched_barrier(0)
; template <int EPI, int lda, int ldb, int N, int K>
; __device__ __forceinline__ void gemm_phase(const u16* __restrict__ A, const u16* __restrict__ Bt, const GemmEpi ep, int wv) {
;     ...
;       STAGE(SB(0, 1), Bt, ldb, bcol + HALF, t + 2);
;       WAIT_V(6); BAR; MMA(1, 1, At, B1); BAR;
;       LDB(B0, 1, 0); SCHED; LDA(At, 1, 0); STAGE(SA(0, 1), Ab, lda, brow + HALF, t + 2);
;       WAIT_L(8); BAR; WAIT_L(0); MMA(0, 0, At, B0); BAR; SCHED;
;       LDB(B1, 1, 1); STAGE(SB(1, 0), Bt, ldb, bcol, t + 3);
;       BAR; WAIT_L(0); MMA(0, 1, At, B1); BAR;
;       LDA(At, 1, 1); STAGE(SA(1, 0), Ab, lda, brow, t + 3);
	v_add_u32_e32 v164, s56, v153
	v_add_u32_e32 v165, 0x2000, v164
	v_readfirstlane_b32 s47, v164
	v_lshl_add_u64 v[166:167], v[238:239], 0, s[26:27]
	s_mov_b32 m0, s47
	v_readfirstlane_b32 s47, v165
	global_load_lds_dwordx4 v[166:167], off
	v_lshl_add_u64 v[166:167], v[240:241], 0, s[26:27]
	s_mov_b32 m0, s47
	s_nop 0
	global_load_lds_dwordx4 v[166:167], off
	s_waitcnt vmcnt(6)
	s_barrier
	v_mfma_f32_16x16x32_bf16 v[28:31], v[214:217], v[182:185], v[28:31]
	v_mfma_f32_16x16x32_bf16 v[24:27], v[222:225], v[182:185], v[24:27]
	ds_read_b128 v[170:173], v154
	v_mfma_f32_16x16x32_bf16 v[20:23], v[214:217], v[190:193], v[20:23]
	v_mfma_f32_16x16x32_bf16 v[16:19], v[222:225], v[190:193], v[16:19]
	ds_read_b128 v[174:177], v154 offset:1024
	v_mfma_f32_16x16x32_bf16 v[12:15], v[214:217], v[198:201], v[12:15]
	v_mfma_f32_16x16x32_bf16 v[8:11], v[222:225], v[198:201], v[8:11]
	ds_read_b128 v[178:181], v154 offset:2048
	v_mfma_f32_16x16x32_bf16 v[4:7], v[214:217], v[206:209], v[4:7]
	v_mfma_f32_16x16x32_bf16 v[0:3], v[222:225], v[206:209], v[0:3]
	ds_read_b128 v[182:185], v154 offset:3072
	v_mfma_f32_16x16x32_bf16 v[28:31], v[218:221], v[186:189], v[28:31]
	v_mfma_f32_16x16x32_bf16 v[24:27], v[226:229], v[186:189], v[24:27]
	v_mfma_f32_16x16x32_bf16 v[20:23], v[218:221], v[194:197], v[20:23]
	v_mfma_f32_16x16x32_bf16 v[16:19], v[226:229], v[194:197], v[16:19]
	v_mfma_f32_16x16x32_bf16 v[12:15], v[218:221], v[202:205], v[12:15]
	v_mfma_f32_16x16x32_bf16 v[8:11], v[226:229], v[202:205], v[8:11]
	v_mfma_f32_16x16x32_bf16 v[4:7], v[218:221], v[210:213], v[4:7]
	v_mfma_f32_16x16x32_bf16 v[0:3], v[226:229], v[210:213], v[0:3]
	s_barrier
	v_add_u32_e32 v166, 0x4000, v143
	v_add_u32_e32 v167, 0x6000, v143
	v_readfirstlane_b32 s47, v166
	v_lshl_add_u64 v[218:219], v[234:235], 0, s[34:35]
	s_mov_b32 m0, s47
	v_readfirstlane_b32 s47, v167
	ds_read_b128 v[186:189], v151 offset:32768
	ds_read_b128 v[190:193], v151 offset:33792
	ds_read_b128 v[194:197], v150 offset:32768
	ds_read_b128 v[198:201], v150 offset:33792
	ds_read_b128 v[202:205], v149 offset:32768
	ds_read_b128 v[206:209], v149 offset:33792
	ds_read_b128 v[210:213], v148 offset:32768
	ds_read_b128 v[214:217], v148 offset:33792
	global_load_lds_dwordx4 v[218:219], off
	v_lshl_add_u64 v[218:219], v[236:237], 0, s[34:35]
	s_mov_b32 m0, s47
	s_nop 0
	global_load_lds_dwordx4 v[218:219], off
	s_waitcnt lgkmcnt(8)
	s_barrier
	s_waitcnt lgkmcnt(0)
	s_waitcnt lgkmcnt(0)
	v_mfma_f32_16x16x32_bf16 v[124:127], v[170:173], v[186:189], v[124:127]
	ds_read_b128 v[218:221], v152
	v_mfma_f32_16x16x32_bf16 v[120:123], v[178:181], v[186:189], v[120:123]
	v_mfma_f32_16x16x32_bf16 v[116:119], v[170:173], v[194:197], v[116:119]
	ds_read_b128 v[222:225], v152 offset:1024
	v_mfma_f32_16x16x32_bf16 v[112:115], v[178:181], v[194:197], v[112:115]
	v_mfma_f32_16x16x32_bf16 v[108:111], v[170:173], v[202:205], v[108:111]
	ds_read_b128 v[226:229], v152 offset:2048
	v_mfma_f32_16x16x32_bf16 v[104:107], v[178:181], v[202:205], v[104:107]
	v_mfma_f32_16x16x32_bf16 v[100:103], v[170:173], v[210:213], v[100:103]
	ds_read_b128 v[230:233], v152 offset:3072
	v_mfma_f32_16x16x32_bf16 v[96:99], v[178:181], v[210:213], v[96:99]
	v_mfma_f32_16x16x32_bf16 v[124:127], v[174:177], v[190:193], v[124:127]
	v_mfma_f32_16x16x32_bf16 v[120:123], v[182:185], v[190:193], v[120:123]
	v_mfma_f32_16x16x32_bf16 v[116:119], v[174:177], v[198:201], v[116:119]
	v_mfma_f32_16x16x32_bf16 v[112:115], v[182:185], v[198:201], v[112:115]
	v_mfma_f32_16x16x32_bf16 v[108:111], v[174:177], v[206:209], v[108:111]
	v_mfma_f32_16x16x32_bf16 v[104:107], v[182:185], v[206:209], v[104:107]
	v_mfma_f32_16x16x32_bf16 v[100:103], v[174:177], v[214:217], v[100:103]
	v_mfma_f32_16x16x32_bf16 v[96:99], v[182:185], v[214:217], v[96:99]
	s_barrier
	v_readfirstlane_b32 s47, v155
	v_add_u32_e32 v244, 0x2000, v155
	v_lshl_add_u64 v[242:243], v[238:239], 0, s[36:37]
	s_mov_b32 m0, s47
	v_readfirstlane_b32 s47, v244
	global_load_lds_dwordx4 v[242:243], off
	v_lshl_add_u64 v[242:243], v[240:241], 0, s[36:37]
	s_mov_b32 m0, s47
	s_nop 0
	global_load_lds_dwordx4 v[242:243], off
	s_barrier
	s_waitcnt lgkmcnt(0)
	s_waitcnt lgkmcnt(0)
	v_mfma_f32_16x16x32_bf16 v[92:95], v[218:221], v[186:189], v[92:95]
	v_mfma_f32_16x16x32_bf16 v[88:91], v[226:229], v[186:189], v[88:91]
	v_mfma_f32_16x16x32_bf16 v[84:87], v[218:221], v[194:197], v[84:87]
	v_mfma_f32_16x16x32_bf16 v[80:83], v[226:229], v[194:197], v[80:83]
	v_mfma_f32_16x16x32_bf16 v[76:79], v[218:221], v[202:205], v[76:79]
	v_mfma_f32_16x16x32_bf16 v[72:75], v[226:229], v[202:205], v[72:75]
	v_mfma_f32_16x16x32_bf16 v[68:71], v[218:221], v[210:213], v[68:71]
	v_mfma_f32_16x16x32_bf16 v[64:67], v[226:229], v[210:213], v[64:67]
	v_mfma_f32_16x16x32_bf16 v[92:95], v[222:225], v[190:193], v[92:95]
	v_mfma_f32_16x16x32_bf16 v[88:91], v[230:233], v[190:193], v[88:91]
	v_mfma_f32_16x16x32_bf16 v[84:87], v[222:225], v[198:201], v[84:87]
	v_mfma_f32_16x16x32_bf16 v[80:83], v[230:233], v[198:201], v[80:83]
	v_mfma_f32_16x16x32_bf16 v[76:79], v[222:225], v[206:209], v[76:79]
	v_mfma_f32_16x16x32_bf16 v[72:75], v[230:233], v[206:209], v[72:75]
	v_mfma_f32_16x16x32_bf16 v[68:71], v[222:225], v[214:217], v[68:71]
	v_mfma_f32_16x16x32_bf16 v[64:67], v[230:233], v[214:217], v[64:67]
	v_readfirstlane_b32 s47, v156
	v_lshl_add_u64 v[234:235], v[234:235], 0, s[38:39]
	s_mov_b32 m0, s47
	v_readfirstlane_b32 s47, v157
	s_barrier
; #define STAGE(P, BASE, LD, br, kt) do { const char* _g = (const char*)((BASE) + (size_t)(br) * (LD) + (size_t)(kt) * 64); \
;     for (int _i = 0; _i < 2; ++_i) { int _b = tidx * 16 + _i * 8192; int _r, _c; stage_rc(_b, _r, _c); \
;       __builtin_amdgcn_global_load_lds((const unsigned*)(_g + (unsigned)((_r * (LD) + _c) * 2)), (unsigned*)((char*)(P) + _b), 16, 0, 0); } } while (0)
; #define LDA(dst, b, h) for (int m = 0; m < 4; ++m) for (int k = 0; k < 2; ++k) \
;     dst[m][k] = *reinterpret_cast<const bf16x8*>((char*)SA(b, h) + lds_byte(wr * 64 + m * 16 + fr, k * 32 + fq * 8))
; #define LDB(dst, b, h) for (int n = 0; n < 2; ++n) for (int k = 0; k < 2; ++k) \
;     dst[n][k] = *reinterpret_cast<const bf16x8*>((char*)SB(b, h) + lds_byte(wc * 32 + n * 16 + fr, k * 32 + fq * 8))
; #define MMA(ai, bj, At_, Bt_) do { __builtin_amdgcn_s_setprio(1); \
;     for (int k = 0; k < 2; ++k) for (int m = 0; m < 4; ++m) for (int n = 0; n < 2; ++n) \
;       acc[ai][bj][m][n] = __builtin_amdgcn_mfma_f32_16x16x32_bf16(At_[m][k], Bt_[n][k], acc[ai][bj][m][n], 0, 0, 0); \
;     __builtin_amdgcn_s_setprio(0); } while (0)
; #define WAIT_V(n) asm volatile("s_waitcnt vmcnt(" #n ")" ::: "memory")
; #define WAIT_L(n) asm volatile("s_waitcnt lgkmcnt(" #n ")" ::: "memory")
; #define BAR __builtin_amdgcn_s_barrier()
; #define SCHED __builtin_amdgcn_sched_barrier(0)
; template <int EPI, int lda, int ldb, int N, int K>
; __device__ __forceinline__ void gemm_phase(const u16* __restrict__ A, const u16* __restrict__ Bt, const GemmEpi ep, int wv) {
;     ...
;       LDA(At, 1, 1); STAGE(SA(1, 0), Ab, lda, brow, t + 3);
;       BAR; WAIT_L(0); MMA(1, 0, At, B0); BAR; SCHED;
;       STAGE(SB(1, 1), Bt, ldb, bcol + HALF, t + 3);
;       WAIT_V(6); BAR; MMA(1, 1, At, B1); BAR;
;     }
;     { LDB(B0, 0, 0); LDA(At, 0, 0); STAGE(SA(1, 1), Ab, lda, brow + HALF, nt - 1);
;       BAR; WAIT_L(0); MMA(0, 0, At, B0); BAR;
	ds_read_b128 v[186:189], v151 offset:49152
	ds_read_b128 v[190:193], v151 offset:50176
	ds_read_b128 v[194:197], v150 offset:49152
	ds_read_b128 v[198:201], v150 offset:50176
	ds_read_b128 v[202:205], v149 offset:49152
	ds_read_b128 v[206:209], v149 offset:50176
	ds_read_b128 v[210:213], v148 offset:49152
	ds_read_b128 v[214:217], v148 offset:50176
	global_load_lds_dwordx4 v[234:235], off
	v_lshl_add_u64 v[234:235], v[236:237], 0, s[38:39]
	s_mov_b32 m0, s47
	s_nop 0
	global_load_lds_dwordx4 v[234:235], off
	s_barrier
	s_waitcnt lgkmcnt(0)
	s_waitcnt lgkmcnt(0)
	v_mfma_f32_16x16x32_bf16 v[60:63], v[170:173], v[186:189], v[60:63]
	v_mfma_f32_16x16x32_bf16 v[56:59], v[178:181], v[186:189], v[56:59]
	v_mfma_f32_16x16x32_bf16 v[52:55], v[170:173], v[194:197], v[52:55]
	v_mfma_f32_16x16x32_bf16 v[48:51], v[178:181], v[194:197], v[48:51]
	v_mfma_f32_16x16x32_bf16 v[44:47], v[170:173], v[202:205], v[44:47]
	v_mfma_f32_16x16x32_bf16 v[40:43], v[178:181], v[202:205], v[40:43]
	v_mfma_f32_16x16x32_bf16 v[36:39], v[170:173], v[210:213], v[36:39]
	v_mfma_f32_16x16x32_bf16 v[32:35], v[178:181], v[210:213], v[32:35]
	v_mfma_f32_16x16x32_bf16 v[60:63], v[174:177], v[190:193], v[60:63]
	v_mfma_f32_16x16x32_bf16 v[56:59], v[182:185], v[190:193], v[56:59]
	v_mfma_f32_16x16x32_bf16 v[52:55], v[174:177], v[198:201], v[52:55]
	v_mfma_f32_16x16x32_bf16 v[48:51], v[182:185], v[198:201], v[48:51]
	v_mfma_f32_16x16x32_bf16 v[44:47], v[174:177], v[206:209], v[44:47]
	v_mfma_f32_16x16x32_bf16 v[40:43], v[182:185], v[206:209], v[40:43]
	v_mfma_f32_16x16x32_bf16 v[36:39], v[174:177], v[214:217], v[36:39]
	v_mfma_f32_16x16x32_bf16 v[32:35], v[182:185], v[214:217], v[32:35]
	s_barrier
	v_readfirstlane_b32 s47, v158
	v_add_u32_e32 v172, 0x2000, v158
	v_lshl_add_u64 v[170:171], v[238:239], 0, s[40:41]
	s_mov_b32 m0, s47
	v_readfirstlane_b32 s47, v172
	global_load_lds_dwordx4 v[170:171], off
	v_lshl_add_u64 v[170:171], v[240:241], 0, s[40:41]
	s_mov_b32 m0, s47
	s_nop 0
	global_load_lds_dwordx4 v[170:171], off
	s_waitcnt vmcnt(6)
	s_barrier
	v_mfma_f32_16x16x32_bf16 v[28:31], v[218:221], v[186:189], v[28:31]
	v_mfma_f32_16x16x32_bf16 v[24:27], v[226:229], v[186:189], v[24:27]
	v_mfma_f32_16x16x32_bf16 v[20:23], v[218:221], v[194:197], v[20:23]
	v_mfma_f32_16x16x32_bf16 v[16:19], v[226:229], v[194:197], v[16:19]
	v_mfma_f32_16x16x32_bf16 v[12:15], v[218:221], v[202:205], v[12:15]
	v_mfma_f32_16x16x32_bf16 v[8:11], v[226:229], v[202:205], v[8:11]
	v_mfma_f32_16x16x32_bf16 v[4:7], v[218:221], v[210:213], v[4:7]
	v_mfma_f32_16x16x32_bf16 v[0:3], v[226:229], v[210:213], v[0:3]
	v_mfma_f32_16x16x32_bf16 v[28:31], v[222:225], v[190:193], v[28:31]
	v_mfma_f32_16x16x32_bf16 v[24:27], v[230:233], v[190:193], v[24:27]
	v_mfma_f32_16x16x32_bf16 v[20:23], v[222:225], v[198:201], v[20:23]
	v_mfma_f32_16x16x32_bf16 v[16:19], v[230:233], v[198:201], v[16:19]
	v_mfma_f32_16x16x32_bf16 v[12:15], v[222:225], v[206:209], v[12:15]
	v_mfma_f32_16x16x32_bf16 v[8:11], v[230:233], v[206:209], v[8:11]
	v_mfma_f32_16x16x32_bf16 v[4:7], v[222:225], v[214:217], v[4:7]
	v_mfma_f32_16x16x32_bf16 v[0:3], v[230:233], v[214:217], v[0:3]
	s_add_i32 s46, s46, 2
	s_add_u32 s44, s44, 0x100
	s_addc_u32 s45, s45, 0
	s_cmp_gt_u32 s46, 27
	s_barrier
	s_cbranch_scc0 .LBB0_1448
	s_lshl_b64 s[44:45], s[16:17], 12
	s_add_u32 s44, s14, s44
	s_addc_u32 s45, s15, s45
	s_add_u32 s44, s44, 0x80000
	s_addc_u32 s45, s45, 0
	v_lshl_add_u64 v[156:157], s[44:45], 0, v[128:129]
	v_readfirstlane_b32 s46, v168
	v_lshl_add_u64 v[156:157], v[156:157], 0, s[42:43]
	s_mov_b32 m0, s46
	ds_read_b128 v[134:137], v160
	ds_read_b128 v[138:141], v160 offset:1024
	ds_read_b128 v[170:173], v160 offset:2048
	ds_read_b128 v[174:177], v160 offset:3072
	ds_read_b128 v[178:181], v151
	ds_read_b128 v[182:185], v151 offset:1024
	ds_read_b128 v[186:189], v150
	ds_read_b128 v[190:193], v150 offset:1024
	ds_read_b128 v[194:197], v149
	ds_read_b128 v[198:201], v149 offset:1024
	ds_read_b128 v[202:205], v148
	ds_read_b128 v[206:209], v148 offset:1024
	global_load_lds_dwordx4 v[156:157], off
	v_lshl_add_u64 v[156:157], s[44:45], 0, v[132:133]
	v_readfirstlane_b32 s44, v169
	v_lshl_add_u64 v[156:157], v[156:157], 0, s[42:43]
	s_mov_b32 m0, s44
	s_nop 0
	global_load_lds_dwordx4 v[156:157], off
	s_barrier
	s_waitcnt lgkmcnt(0)
	s_waitcnt lgkmcnt(0)
	v_mfma_f32_16x16x32_bf16 v[124:127], v[134:137], v[178:181], v[124:127]
	v_mfma_f32_16x16x32_bf16 v[120:123], v[170:173], v[178:181], v[120:123]
	v_mfma_f32_16x16x32_bf16 v[116:119], v[134:137], v[186:189], v[116:119]
	v_mfma_f32_16x16x32_bf16 v[112:115], v[170:173], v[186:189], v[112:115]
	v_mfma_f32_16x16x32_bf16 v[108:111], v[134:137], v[194:197], v[108:111]
	v_mfma_f32_16x16x32_bf16 v[104:107], v[170:173], v[194:197], v[104:107]
	v_mfma_f32_16x16x32_bf16 v[100:103], v[134:137], v[202:205], v[100:103]
	v_mfma_f32_16x16x32_bf16 v[96:99], v[170:173], v[202:205], v[96:99]
	v_mfma_f32_16x16x32_bf16 v[124:127], v[138:141], v[182:185], v[124:127]
	v_mfma_f32_16x16x32_bf16 v[120:123], v[174:177], v[182:185], v[120:123]
	v_mfma_f32_16x16x32_bf16 v[116:119], v[138:141], v[190:193], v[116:119]
	v_mfma_f32_16x16x32_bf16 v[112:115], v[174:177], v[190:193], v[112:115]
	v_mfma_f32_16x16x32_bf16 v[108:111], v[138:141], v[198:201], v[108:111]
	v_mfma_f32_16x16x32_bf16 v[104:107], v[174:177], v[198:201], v[104:107]
	v_mfma_f32_16x16x32_bf16 v[100:103], v[138:141], v[206:209], v[100:103]
	v_mfma_f32_16x16x32_bf16 v[96:99], v[174:177], v[206:209], v[96:99]
	s_barrier
	ds_read_b128 v[210:213], v159
	ds_read_b128 v[214:217], v159 offset:1024
	ds_read_b128 v[218:221], v159 offset:2048
	ds_read_b128 v[156:159], v159 offset:3072
	s_barrier
; #define LDA(dst, b, h) for (int m = 0; m < 4; ++m) for (int k = 0; k < 2; ++k) \
;     dst[m][k] = *reinterpret_cast<const bf16x8*>((char*)SA(b, h) + lds_byte(wr * 64 + m * 16 + fr, k * 32 + fq * 8))
; #define LDB(dst, b, h) for (int n = 0; n < 2; ++n) for (int k = 0; k < 2; ++k) \
;     dst[n][k] = *reinterpret_cast<const bf16x8*>((char*)SB(b, h) + lds_byte(wc * 32 + n * 16 + fr, k * 32 + fq * 8))
; #define MMA(ai, bj, At_, Bt_) do { __builtin_amdgcn_s_setprio(1); \
;     for (int k = 0; k < 2; ++k) for (int m = 0; m < 4; ++m) for (int n = 0; n < 2; ++n) \
;       acc[ai][bj][m][n] = __builtin_amdgcn_mfma_f32_16x16x32_bf16(At_[m][k], Bt_[n][k], acc[ai][bj][m][n], 0, 0, 0); \
;     __builtin_amdgcn_s_setprio(0); } while (0)
; #define WAIT_V(n) asm volatile("s_waitcnt vmcnt(" #n ")" ::: "memory")
; #define WAIT_L(n) asm volatile("s_waitcnt lgkmcnt(" #n ")" ::: "memory")
; #define BAR __builtin_amdgcn_s_barrier()
; template <int EPI, int lda, int ldb, int N, int K>
; __device__ __forceinline__ void gemm_phase(const u16* __restrict__ A, const u16* __restrict__ Bt, const GemmEpi ep, int wv) {
;     ...
;       LDB(B1, 0, 1); BAR; WAIT_L(0); MMA(0, 1, At, B1); BAR;
;       LDA(At, 0, 1); WAIT_V(4); BAR; WAIT_L(0); MMA(1, 0, At, B0); MMA(1, 1, At, B1); BAR; }
;     { LDB(B0, 1, 0); LDA(At, 1, 0); WAIT_V(2); BAR; WAIT_L(0); MMA(0, 0, At, B0); BAR;
	s_waitcnt lgkmcnt(0)
	s_waitcnt lgkmcnt(0)
	v_mfma_f32_16x16x32_bf16 v[92:95], v[210:213], v[178:181], v[92:95]
	v_mfma_f32_16x16x32_bf16 v[88:91], v[218:221], v[178:181], v[88:91]
	v_mfma_f32_16x16x32_bf16 v[76:79], v[210:213], v[194:197], v[76:79]
	v_mfma_f32_16x16x32_bf16 v[72:75], v[218:221], v[194:197], v[72:75]
	v_mfma_f32_16x16x32_bf16 v[84:87], v[210:213], v[186:189], v[84:87]
	v_mfma_f32_16x16x32_bf16 v[80:83], v[218:221], v[186:189], v[80:83]
	v_mfma_f32_16x16x32_bf16 v[68:71], v[210:213], v[202:205], v[68:71]
	v_mfma_f32_16x16x32_bf16 v[64:67], v[218:221], v[202:205], v[64:67]
	v_mfma_f32_16x16x32_bf16 v[92:95], v[214:217], v[182:185], v[92:95]
	v_mfma_f32_16x16x32_bf16 v[88:91], v[156:159], v[182:185], v[88:91]
	v_mfma_f32_16x16x32_bf16 v[76:79], v[214:217], v[198:201], v[76:79]
	v_mfma_f32_16x16x32_bf16 v[72:75], v[156:159], v[198:201], v[72:75]
	v_mfma_f32_16x16x32_bf16 v[178:181], v[214:217], v[190:193], v[84:87]
	v_mfma_f32_16x16x32_bf16 v[182:185], v[156:159], v[190:193], v[80:83]
	v_mfma_f32_16x16x32_bf16 v[186:189], v[214:217], v[206:209], v[68:71]
	v_mfma_f32_16x16x32_bf16 v[190:193], v[156:159], v[206:209], v[64:67]
	s_barrier
	s_nop 0
	ds_read_b128 v[64:67], v151 offset:16384
	ds_read_b128 v[68:71], v151 offset:17408
	ds_read_b128 v[80:83], v150 offset:16384
	ds_read_b128 v[84:87], v150 offset:17408
	ds_read_b128 v[194:197], v149 offset:16384
	ds_read_b128 v[198:201], v149 offset:17408
	ds_read_b128 v[202:205], v148 offset:16384
	ds_read_b128 v[206:209], v148 offset:17408
	s_waitcnt vmcnt(4)
	s_barrier
	s_waitcnt lgkmcnt(0)
	s_waitcnt lgkmcnt(0)
	v_mfma_f32_16x16x32_bf16 v[60:63], v[134:137], v[64:67], v[60:63]
	v_mfma_f32_16x16x32_bf16 v[56:59], v[170:173], v[64:67], v[56:59]
	v_mfma_f32_16x16x32_bf16 v[52:55], v[134:137], v[80:83], v[52:55]
	v_mfma_f32_16x16x32_bf16 v[48:51], v[170:173], v[80:83], v[48:51]
	v_mfma_f32_16x16x32_bf16 v[44:47], v[134:137], v[194:197], v[44:47]
	v_mfma_f32_16x16x32_bf16 v[40:43], v[170:173], v[194:197], v[40:43]
	v_mfma_f32_16x16x32_bf16 v[36:39], v[134:137], v[202:205], v[36:39]
	v_mfma_f32_16x16x32_bf16 v[32:35], v[170:173], v[202:205], v[32:35]
	v_mfma_f32_16x16x32_bf16 v[60:63], v[138:141], v[68:71], v[60:63]
	v_mfma_f32_16x16x32_bf16 v[56:59], v[174:177], v[68:71], v[56:59]
	v_mfma_f32_16x16x32_bf16 v[52:55], v[138:141], v[84:87], v[52:55]
	v_mfma_f32_16x16x32_bf16 v[48:51], v[174:177], v[84:87], v[48:51]
	v_mfma_f32_16x16x32_bf16 v[44:47], v[138:141], v[198:201], v[44:47]
	v_mfma_f32_16x16x32_bf16 v[40:43], v[174:177], v[198:201], v[40:43]
	v_mfma_f32_16x16x32_bf16 v[36:39], v[138:141], v[206:209], v[36:39]
	v_mfma_f32_16x16x32_bf16 v[32:35], v[174:177], v[206:209], v[32:35]
	v_mfma_f32_16x16x32_bf16 v[28:31], v[210:213], v[64:67], v[28:31]
	v_mfma_f32_16x16x32_bf16 v[20:23], v[210:213], v[80:83], v[20:23]
	v_mfma_f32_16x16x32_bf16 v[12:15], v[210:213], v[194:197], v[12:15]
	v_mfma_f32_16x16x32_bf16 v[4:7], v[210:213], v[202:205], v[4:7]
	v_mfma_f32_16x16x32_bf16 v[24:27], v[218:221], v[64:67], v[24:27]
	v_mfma_f32_16x16x32_bf16 v[16:19], v[218:221], v[80:83], v[16:19]
	v_mfma_f32_16x16x32_bf16 v[8:11], v[218:221], v[194:197], v[8:11]
	v_mfma_f32_16x16x32_bf16 v[0:3], v[218:221], v[202:205], v[0:3]
	v_mfma_f32_16x16x32_bf16 v[28:31], v[214:217], v[68:71], v[28:31]
	v_mfma_f32_16x16x32_bf16 v[20:23], v[214:217], v[84:87], v[20:23]
	v_mfma_f32_16x16x32_bf16 v[12:15], v[214:217], v[198:201], v[12:15]
	v_mfma_f32_16x16x32_bf16 v[4:7], v[214:217], v[206:209], v[4:7]
	v_mfma_f32_16x16x32_bf16 v[134:137], v[156:159], v[68:71], v[24:27]
	v_mfma_f32_16x16x32_bf16 v[138:141], v[156:159], v[84:87], v[16:19]
	v_mfma_f32_16x16x32_bf16 v[168:171], v[156:159], v[198:201], v[8:11]
	v_mfma_f32_16x16x32_bf16 v[156:159], v[156:159], v[206:209], v[0:3]
	s_barrier
	s_nop 0
	ds_read_b128 v[0:3], v154
	ds_read_b128 v[8:11], v154 offset:1024
	ds_read_b128 v[16:19], v154 offset:2048
	ds_read_b128 v[172:175], v154 offset:3072
	ds_read_b128 v[24:27], v151 offset:32768
	ds_read_b128 v[194:197], v151 offset:33792
	ds_read_b128 v[198:201], v150 offset:32768
	ds_read_b128 v[202:205], v150 offset:33792
	ds_read_b128 v[206:209], v149 offset:32768
	ds_read_b128 v[210:213], v149 offset:33792
	ds_read_b128 v[214:217], v148 offset:32768
	ds_read_b128 v[218:221], v148 offset:33792
	s_waitcnt vmcnt(2)
	s_barrier
; #define LDA(dst, b, h) for (int m = 0; m < 4; ++m) for (int k = 0; k < 2; ++k) \
;     dst[m][k] = *reinterpret_cast<const bf16x8*>((char*)SA(b, h) + lds_byte(wr * 64 + m * 16 + fr, k * 32 + fq * 8))
; #define LDB(dst, b, h) for (int n = 0; n < 2; ++n) for (int k = 0; k < 2; ++k) \
;     dst[n][k] = *reinterpret_cast<const bf16x8*>((char*)SB(b, h) + lds_byte(wc * 32 + n * 16 + fr, k * 32 + fq * 8))
; #define MMA(ai, bj, At_, Bt_) do { __builtin_amdgcn_s_setprio(1); \
;     for (int k = 0; k < 2; ++k) for (int m = 0; m < 4; ++m) for (int n = 0; n < 2; ++n) \
;       acc[ai][bj][m][n] = __builtin_amdgcn_mfma_f32_16x16x32_bf16(At_[m][k], Bt_[n][k], acc[ai][bj][m][n], 0, 0, 0); \
;     __builtin_amdgcn_s_setprio(0); } while (0)
; #define WAIT_V(n) asm volatile("s_waitcnt vmcnt(" #n ")" ::: "memory")
; #define WAIT_L(n) asm volatile("s_waitcnt lgkmcnt(" #n ")" ::: "memory")
; #define BAR __builtin_amdgcn_s_barrier()
; template <int EPI, int lda, int ldb, int N, int K>
; __device__ __forceinline__ void gemm_phase(const u16* __restrict__ A, const u16* __restrict__ Bt, const GemmEpi ep, int wv) {
;     ...
;     { LDB(B0, 1, 0); LDA(At, 1, 0); WAIT_V(2); BAR; WAIT_L(0); MMA(0, 0, At, B0); BAR;
;       LDB(B1, 1, 1); WAIT_V(0); BAR; WAIT_L(0); MMA(0, 1, At, B1); BAR;
;       LDA(At, 1, 1); BAR; WAIT_L(0); MMA(1, 0, At, B0); MMA(1, 1, At, B1); BAR; }
;     if (wr == 0) BAR;
	s_waitcnt lgkmcnt(0)
	s_waitcnt lgkmcnt(0)
	v_mfma_f32_16x16x32_bf16 v[64:67], v[0:3], v[24:27], v[124:127]
	v_mfma_f32_16x16x32_bf16 v[68:71], v[16:19], v[24:27], v[120:123]
	v_mfma_f32_16x16x32_bf16 v[80:83], v[0:3], v[198:201], v[116:119]
	v_mfma_f32_16x16x32_bf16 v[84:87], v[16:19], v[198:201], v[112:115]
	v_mfma_f32_16x16x32_bf16 v[108:111], v[0:3], v[206:209], v[108:111]
	v_mfma_f32_16x16x32_bf16 v[104:107], v[16:19], v[206:209], v[104:107]
	v_mfma_f32_16x16x32_bf16 v[120:123], v[0:3], v[214:217], v[100:103]
	v_mfma_f32_16x16x32_bf16 v[124:127], v[16:19], v[214:217], v[96:99]
	v_mfma_f32_16x16x32_bf16 v[116:119], v[8:11], v[194:197], v[64:67]
	v_mfma_f32_16x16x32_bf16 v[112:115], v[172:175], v[194:197], v[68:71]
	v_mfma_f32_16x16x32_bf16 v[100:103], v[8:11], v[202:205], v[80:83]
	v_mfma_f32_16x16x32_bf16 v[96:99], v[172:175], v[202:205], v[84:87]
	v_mfma_f32_16x16x32_bf16 v[84:87], v[8:11], v[210:213], v[108:111]
	v_mfma_f32_16x16x32_bf16 v[80:83], v[172:175], v[210:213], v[104:107]
	v_mfma_f32_16x16x32_bf16 v[68:71], v[8:11], v[218:221], v[120:123]
	v_mfma_f32_16x16x32_bf16 v[64:67], v[172:175], v[218:221], v[124:127]
	s_barrier
	ds_read_b128 v[222:225], v152
	ds_read_b128 v[226:229], v152 offset:1024
	ds_read_b128 v[230:233], v152 offset:2048
	ds_read_b128 v[152:155], v152 offset:3072
	s_waitcnt vmcnt(0)
	s_barrier
	s_waitcnt lgkmcnt(0)
	s_waitcnt lgkmcnt(0)
	v_mfma_f32_16x16x32_bf16 v[92:95], v[222:225], v[24:27], v[92:95]
	v_mfma_f32_16x16x32_bf16 v[24:27], v[230:233], v[24:27], v[88:91]
	v_mfma_f32_16x16x32_bf16 v[88:91], v[222:225], v[198:201], v[178:181]
	v_mfma_f32_16x16x32_bf16 v[104:107], v[230:233], v[198:201], v[182:185]
	v_mfma_f32_16x16x32_bf16 v[76:79], v[222:225], v[206:209], v[76:79]
	v_mfma_f32_16x16x32_bf16 v[72:75], v[230:233], v[206:209], v[72:75]
	v_mfma_f32_16x16x32_bf16 v[176:179], v[222:225], v[214:217], v[186:189]
	v_mfma_f32_16x16x32_bf16 v[180:183], v[230:233], v[214:217], v[190:193]
	v_mfma_f32_16x16x32_bf16 v[124:127], v[226:229], v[194:197], v[92:95]
	v_mfma_f32_16x16x32_bf16 v[120:123], v[152:155], v[194:197], v[24:27]
	v_mfma_f32_16x16x32_bf16 v[108:111], v[226:229], v[202:205], v[88:91]
	v_mfma_f32_16x16x32_bf16 v[104:107], v[152:155], v[202:205], v[104:107]
	v_mfma_f32_16x16x32_bf16 v[92:95], v[226:229], v[210:213], v[76:79]
	v_mfma_f32_16x16x32_bf16 v[88:91], v[152:155], v[210:213], v[72:75]
	v_mfma_f32_16x16x32_bf16 v[76:79], v[226:229], v[218:221], v[176:179]
	v_mfma_f32_16x16x32_bf16 v[72:75], v[152:155], v[218:221], v[180:183]
	s_barrier
	ds_read_b128 v[176:179], v151 offset:49152
	ds_read_b128 v[180:183], v151 offset:50176
	ds_read_b128 v[184:187], v150 offset:49152
	ds_read_b128 v[188:191], v150 offset:50176
	ds_read_b128 v[192:195], v149 offset:49152
	ds_read_b128 v[196:199], v149 offset:50176
	ds_read_b128 v[200:203], v148 offset:49152
	ds_read_b128 v[148:151], v148 offset:50176
	s_barrier
	s_waitcnt lgkmcnt(0)
	s_waitcnt lgkmcnt(0)
	v_mfma_f32_16x16x32_bf16 v[24:27], v[0:3], v[176:179], v[60:63]
	v_mfma_f32_16x16x32_bf16 v[60:63], v[16:19], v[176:179], v[56:59]
	v_mfma_f32_16x16x32_bf16 v[52:55], v[0:3], v[184:187], v[52:55]
	v_mfma_f32_16x16x32_bf16 v[204:207], v[16:19], v[184:187], v[48:51]
	v_mfma_f32_16x16x32_bf16 v[44:47], v[0:3], v[192:195], v[44:47]
	v_mfma_f32_16x16x32_bf16 v[208:211], v[16:19], v[192:195], v[40:43]
	v_mfma_f32_16x16x32_bf16 v[0:3], v[0:3], v[200:203], v[36:39]
	v_mfma_f32_16x16x32_bf16 v[36:39], v[16:19], v[200:203], v[32:35]
	v_mfma_f32_16x16x32_bf16 v[56:59], v[8:11], v[180:183], v[24:27]
	v_mfma_f32_16x16x32_bf16 v[48:51], v[172:175], v[180:183], v[60:63]
	v_mfma_f32_16x16x32_bf16 v[40:43], v[8:11], v[188:191], v[52:55]
	v_mfma_f32_16x16x32_bf16 v[32:35], v[172:175], v[188:191], v[204:207]
	v_mfma_f32_16x16x32_bf16 v[24:27], v[8:11], v[196:199], v[44:47]
	v_mfma_f32_16x16x32_bf16 v[16:19], v[172:175], v[196:199], v[208:211]
	v_mfma_f32_16x16x32_bf16 v[8:11], v[8:11], v[148:151], v[0:3]
	v_mfma_f32_16x16x32_bf16 v[0:3], v[172:175], v[148:151], v[36:39]
	v_mfma_f32_16x16x32_bf16 v[28:31], v[222:225], v[176:179], v[28:31]
	v_mfma_f32_16x16x32_bf16 v[36:39], v[230:233], v[176:179], v[134:137]
	v_mfma_f32_16x16x32_bf16 v[20:23], v[222:225], v[184:187], v[20:23]
	v_mfma_f32_16x16x32_bf16 v[134:137], v[230:233], v[184:187], v[138:141]
	v_mfma_f32_16x16x32_bf16 v[12:15], v[222:225], v[192:195], v[12:15]
	v_mfma_f32_16x16x32_bf16 v[138:141], v[230:233], v[192:195], v[168:171]
	v_mfma_f32_16x16x32_bf16 v[4:7], v[222:225], v[200:203], v[4:7]
	v_mfma_f32_16x16x32_bf16 v[156:159], v[230:233], v[200:203], v[156:159]
	v_mfma_f32_16x16x32_bf16 v[60:63], v[226:229], v[180:183], v[28:31]
	v_mfma_f32_16x16x32_bf16 v[52:55], v[152:155], v[180:183], v[36:39]
	v_mfma_f32_16x16x32_bf16 v[44:47], v[226:229], v[188:191], v[20:23]
	v_mfma_f32_16x16x32_bf16 v[36:39], v[152:155], v[188:191], v[134:137]
	v_mfma_f32_16x16x32_bf16 v[28:31], v[226:229], v[196:199], v[12:15]
	v_mfma_f32_16x16x32_bf16 v[20:23], v[152:155], v[196:199], v[138:141]
	v_mfma_f32_16x16x32_bf16 v[12:15], v[226:229], v[148:151], v[4:7]
	v_mfma_f32_16x16x32_bf16 v[4:7], v[152:155], v[148:151], v[156:159]
	v_cmp_gt_u32_e32 vcc, s60, v130
	s_barrier
	s_and_saveexec_b64 s[44:45], vcc
	s_cbranch_execz .LBB0_1451
	s_barrier

; #define STAGE(P, BASE, LD, br, kt) do { const char* _g = (const char*)((BASE) + (size_t)(br) * (LD) + (size_t)(kt) * 64); \
;     for (int _i = 0; _i < 2; ++_i) { int _b = tidx * 16 + _i * 8192; int _r, _c; stage_rc(_b, _r, _c); \
;       __builtin_amdgcn_global_load_lds((const unsigned*)(_g + (unsigned)((_r * (LD) + _c) * 2)), (unsigned*)((char*)(P) + _b), 16, 0, 0); } } while (0)
; #define LDA(dst, b, h) for (int m = 0; m < 4; ++m) for (int k = 0; k < 2; ++k) \
;     dst[m][k] = *reinterpret_cast<const bf16x8*>((char*)SA(b, h) + lds_byte(wr * 64 + m * 16 + fr, k * 32 + fq * 8))
; #define LDB(dst, b, h) for (int n = 0; n < 2; ++n) for (int k = 0; k < 2; ++k) \
;     dst[n][k] = *reinterpret_cast<const bf16x8*>((char*)SB(b, h) + lds_byte(wc * 32 + n * 16 + fr, k * 32 + fq * 8))
; #define MMA(ai, bj, At_, Bt_) do { __builtin_amdgcn_s_setprio(1); \
;     for (int k = 0; k < 2; ++k) for (int m = 0; m < 4; ++m) for (int n = 0; n < 2; ++n) \
;       acc[ai][bj][m][n] = __builtin_amdgcn_mfma_f32_16x16x32_bf16(At_[m][k], Bt_[n][k], acc[ai][bj][m][n], 0, 0, 0); \
;     __builtin_amdgcn_s_setprio(0); } while (0)
; #define WAIT_L(n) asm volatile("s_waitcnt lgkmcnt(" #n ")" ::: "memory")
; #define BAR __builtin_amdgcn_s_barrier()
; #define SCHED __builtin_amdgcn_sched_barrier(0)
; template <int EPI, int lda, int ldb, int N, int K>
; __device__ __forceinline__ void gemm_phase(const u16* __restrict__ A, const u16* __restrict__ Bt, const GemmEpi ep, int wv) {
;     ...
;       LDB(B0, 0, 0); SCHED; LDA(At, 0, 0); STAGE(SA(1, 1), Ab, lda, brow + HALF, t + 1);
;       WAIT_L(8); BAR; WAIT_L(0); MMA(0, 0, At, B0); BAR; SCHED;
;       LDB(B1, 0, 1); STAGE(SB(0, 0), Bt, ldb, bcol, t + 2);
;       BAR; WAIT_L(0); MMA(0, 1, At, B1); BAR;
;       LDA(At, 0, 1); STAGE(SA(0, 0), Ab, lda, brow, t + 2);
;       BAR; WAIT_L(0); MMA(1, 0, At, B0); BAR; SCHED;
.LBB0_1564:
	ds_read_b128 v[172:175], v161
	ds_read_b128 v[176:179], v161 offset:1024
	ds_read_b128 v[180:183], v161 offset:2048
	ds_read_b128 v[184:187], v161 offset:3072
	v_add_u32_e32 v169, 0xc000, v148
	v_lshl_add_u64 v[236:237], v[136:137], 0, s[40:41]
	v_readfirstlane_b32 s43, v169
	v_add_u32_e32 v170, 0xe000, v148
	v_lshl_add_u64 v[162:163], v[236:237], 0, s[14:15]
	s_mov_b32 m0, s43
	v_lshl_add_u64 v[238:239], v[134:135], 0, s[40:41]
	v_readfirstlane_b32 s43, v170
	ds_read_b128 v[164:167], v152
	ds_read_b128 v[188:191], v152 offset:1024
	ds_read_b128 v[192:195], v151
	ds_read_b128 v[196:199], v151 offset:1024
	ds_read_b128 v[200:203], v150
	ds_read_b128 v[204:207], v150 offset:1024
	ds_read_b128 v[208:211], v149
	ds_read_b128 v[212:215], v149 offset:1024
	global_load_lds_dwordx4 v[162:163], off
	v_lshl_add_u64 v[162:163], v[238:239], 0, s[14:15]
	s_mov_b32 m0, s43
	s_nop 0
	global_load_lds_dwordx4 v[162:163], off
	s_waitcnt lgkmcnt(8)
	s_barrier
	s_waitcnt lgkmcnt(0)
	s_waitcnt lgkmcnt(0)
	v_mfma_f32_16x16x32_bf16 v[124:127], v[172:175], v[164:167], v[124:127]
	ds_read_b128 v[216:219], v160
	v_mfma_f32_16x16x32_bf16 v[120:123], v[180:183], v[164:167], v[120:123]
	v_mfma_f32_16x16x32_bf16 v[116:119], v[172:175], v[192:195], v[116:119]
	ds_read_b128 v[220:223], v160 offset:1024
	v_mfma_f32_16x16x32_bf16 v[112:115], v[180:183], v[192:195], v[112:115]
	v_mfma_f32_16x16x32_bf16 v[108:111], v[172:175], v[200:203], v[108:111]
	ds_read_b128 v[224:227], v160 offset:2048
	v_mfma_f32_16x16x32_bf16 v[104:107], v[180:183], v[200:203], v[104:107]
	v_mfma_f32_16x16x32_bf16 v[100:103], v[172:175], v[208:211], v[100:103]
	ds_read_b128 v[228:231], v160 offset:3072
	v_mfma_f32_16x16x32_bf16 v[96:99], v[180:183], v[208:211], v[96:99]
	v_mfma_f32_16x16x32_bf16 v[124:127], v[176:179], v[188:191], v[124:127]
	v_mfma_f32_16x16x32_bf16 v[120:123], v[184:187], v[188:191], v[120:123]
	v_mfma_f32_16x16x32_bf16 v[116:119], v[176:179], v[196:199], v[116:119]
	v_mfma_f32_16x16x32_bf16 v[112:115], v[184:187], v[196:199], v[112:115]
	v_mfma_f32_16x16x32_bf16 v[108:111], v[176:179], v[204:207], v[108:111]
	v_mfma_f32_16x16x32_bf16 v[104:107], v[184:187], v[204:207], v[104:107]
	v_mfma_f32_16x16x32_bf16 v[100:103], v[176:179], v[212:215], v[100:103]
	v_mfma_f32_16x16x32_bf16 v[96:99], v[184:187], v[212:215], v[96:99]
	s_barrier
	v_add_u32_e32 v162, s52, v153
	v_lshl_add_u64 v[240:241], v[140:141], 0, s[40:41]
	v_readfirstlane_b32 s43, v162
	v_add_u32_e32 v163, 0x2000, v162
	v_lshl_add_u64 v[232:233], v[240:241], 0, s[16:17]
	s_mov_b32 m0, s43
	v_lshl_add_u64 v[242:243], v[138:139], 0, s[40:41]
	v_readfirstlane_b32 s43, v163
	global_load_lds_dwordx4 v[232:233], off
	v_lshl_add_u64 v[232:233], v[242:243], 0, s[16:17]
	s_mov_b32 m0, s43
	s_nop 0
	global_load_lds_dwordx4 v[232:233], off
	s_barrier
	s_waitcnt lgkmcnt(0)
	s_waitcnt lgkmcnt(0)
	v_mfma_f32_16x16x32_bf16 v[92:95], v[216:219], v[164:167], v[92:95]
	v_mfma_f32_16x16x32_bf16 v[88:91], v[224:227], v[164:167], v[88:91]
	v_mfma_f32_16x16x32_bf16 v[84:87], v[216:219], v[192:195], v[84:87]
	v_mfma_f32_16x16x32_bf16 v[80:83], v[224:227], v[192:195], v[80:83]
	v_mfma_f32_16x16x32_bf16 v[76:79], v[216:219], v[200:203], v[76:79]
	v_mfma_f32_16x16x32_bf16 v[72:75], v[224:227], v[200:203], v[72:75]
	v_mfma_f32_16x16x32_bf16 v[68:71], v[216:219], v[208:211], v[68:71]
	v_mfma_f32_16x16x32_bf16 v[64:67], v[224:227], v[208:211], v[64:67]
	v_mfma_f32_16x16x32_bf16 v[92:95], v[220:223], v[188:191], v[92:95]
	v_mfma_f32_16x16x32_bf16 v[88:91], v[228:231], v[188:191], v[88:91]
	v_mfma_f32_16x16x32_bf16 v[84:87], v[220:223], v[196:199], v[84:87]
	v_mfma_f32_16x16x32_bf16 v[80:83], v[228:231], v[196:199], v[80:83]
	v_mfma_f32_16x16x32_bf16 v[76:79], v[220:223], v[204:207], v[76:79]
	v_mfma_f32_16x16x32_bf16 v[72:75], v[228:231], v[204:207], v[72:75]
	v_mfma_f32_16x16x32_bf16 v[68:71], v[220:223], v[212:215], v[68:71]
	v_mfma_f32_16x16x32_bf16 v[64:67], v[228:231], v[212:215], v[64:67]
	v_readfirstlane_b32 s43, v148
	v_lshl_add_u64 v[164:165], v[236:237], 0, s[18:19]
	s_mov_b32 m0, s43
	s_barrier
	ds_read_b128 v[188:191], v152 offset:16384
	ds_read_b128 v[192:195], v152 offset:17408
	ds_read_b128 v[196:199], v151 offset:16384
	ds_read_b128 v[200:203], v151 offset:17408
	ds_read_b128 v[204:207], v150 offset:16384
	ds_read_b128 v[208:211], v150 offset:17408
	ds_read_b128 v[212:215], v149 offset:16384
	ds_read_b128 v[232:235], v149 offset:17408
	global_load_lds_dwordx4 v[164:165], off
	v_add_u32_e32 v164, 0x2000, v148
	v_lshl_add_u64 v[166:167], v[238:239], 0, s[18:19]
	v_readfirstlane_b32 s43, v164
	s_mov_b32 m0, s43
	s_nop 0
	global_load_lds_dwordx4 v[166:167], off
	s_barrier
	s_waitcnt lgkmcnt(0)
	s_waitcnt lgkmcnt(0)
	v_mfma_f32_16x16x32_bf16 v[60:63], v[172:175], v[188:191], v[60:63]
	v_mfma_f32_16x16x32_bf16 v[56:59], v[180:183], v[188:191], v[56:59]
	v_mfma_f32_16x16x32_bf16 v[52:55], v[172:175], v[196:199], v[52:55]
	v_mfma_f32_16x16x32_bf16 v[48:51], v[180:183], v[196:199], v[48:51]
	v_mfma_f32_16x16x32_bf16 v[44:47], v[172:175], v[204:207], v[44:47]
	v_mfma_f32_16x16x32_bf16 v[40:43], v[180:183], v[204:207], v[40:43]
	v_mfma_f32_16x16x32_bf16 v[36:39], v[172:175], v[212:215], v[36:39]
	v_mfma_f32_16x16x32_bf16 v[32:35], v[180:183], v[212:215], v[32:35]
	v_mfma_f32_16x16x32_bf16 v[60:63], v[176:179], v[192:195], v[60:63]
	v_mfma_f32_16x16x32_bf16 v[56:59], v[184:187], v[192:195], v[56:59]
	v_mfma_f32_16x16x32_bf16 v[52:55], v[176:179], v[200:203], v[52:55]
	v_mfma_f32_16x16x32_bf16 v[48:51], v[184:187], v[200:203], v[48:51]
	v_mfma_f32_16x16x32_bf16 v[44:47], v[176:179], v[208:211], v[44:47]
	v_mfma_f32_16x16x32_bf16 v[40:43], v[184:187], v[208:211], v[40:43]
	v_mfma_f32_16x16x32_bf16 v[36:39], v[176:179], v[232:235], v[36:39]
	v_mfma_f32_16x16x32_bf16 v[32:35], v[184:187], v[232:235], v[32:35]
	s_barrier
; #define STAGE(P, BASE, LD, br, kt) do { const char* _g = (const char*)((BASE) + (size_t)(br) * (LD) + (size_t)(kt) * 64); \
;     for (int _i = 0; _i < 2; ++_i) { int _b = tidx * 16 + _i * 8192; int _r, _c; stage_rc(_b, _r, _c); \
;       __builtin_amdgcn_global_load_lds((const unsigned*)(_g + (unsigned)((_r * (LD) + _c) * 2)), (unsigned*)((char*)(P) + _b), 16, 0, 0); } } while (0)
; #define LDA(dst, b, h) for (int m = 0; m < 4; ++m) for (int k = 0; k < 2; ++k) \
;     dst[m][k] = *reinterpret_cast<const bf16x8*>((char*)SA(b, h) + lds_byte(wr * 64 + m * 16 + fr, k * 32 + fq * 8))
; #define LDB(dst, b, h) for (int n = 0; n < 2; ++n) for (int k = 0; k < 2; ++k) \
;     dst[n][k] = *reinterpret_cast<const bf16x8*>((char*)SB(b, h) + lds_byte(wc * 32 + n * 16 + fr, k * 32 + fq * 8))
; #define MMA(ai, bj, At_, Bt_) do { __builtin_amdgcn_s_setprio(1); \
;     for (int k = 0; k < 2; ++k) for (int m = 0; m < 4; ++m) for (int n = 0; n < 2; ++n) \
;       acc[ai][bj][m][n] = __builtin_amdgcn_mfma_f32_16x16x32_bf16(At_[m][k], Bt_[n][k], acc[ai][bj][m][n], 0, 0, 0); \
;     __builtin_amdgcn_s_setprio(0); } while (0)
; #define WAIT_V(n) asm volatile("s_waitcnt vmcnt(" #n ")" ::: "memory")
; #define WAIT_L(n) asm volatile("s_waitcnt lgkmcnt(" #n ")" ::: "memory")
; #define BAR __builtin_amdgcn_s_barrier()
; #define SCHED __builtin_amdgcn_sched_barrier(0)
; template <int EPI, int lda, int ldb, int N, int K>
; __device__ __forceinline__ void gemm_phase(const u16* __restrict__ A, const u16* __restrict__ Bt, const GemmEpi ep, int wv) {
;     ...
;       STAGE(SB(0, 1), Bt, ldb, bcol + HALF, t + 2);
;       WAIT_V(6); BAR; MMA(1, 1, At, B1); BAR;
;       LDB(B0, 1, 0); SCHED; LDA(At, 1, 0); STAGE(SA(0, 1), Ab, lda, brow + HALF, t + 2);
;       WAIT_L(8); BAR; WAIT_L(0); MMA(0, 0, At, B0); BAR; SCHED;
;       LDB(B1, 1, 1); STAGE(SB(1, 0), Bt, ldb, bcol, t + 3);
;       BAR; WAIT_L(0); MMA(0, 1, At, B1); BAR;
;       LDA(At, 1, 1); STAGE(SA(1, 0), Ab, lda, brow, t + 3);
;       BAR; WAIT_L(0); MMA(1, 0, At, B0); BAR; SCHED;
	v_add_u32_e32 v165, s53, v153
	v_lshl_add_u64 v[166:167], v[240:241], 0, s[20:21]
	v_readfirstlane_b32 s43, v165
	s_mov_b32 m0, s43
	v_lshl_add_u64 v[172:173], v[242:243], 0, s[20:21]
	global_load_lds_dwordx4 v[166:167], off
	v_add_u32_e32 v166, 0x2000, v165
	s_nop 0
	v_readfirstlane_b32 s43, v166
	s_mov_b32 m0, s43
	s_nop 0
	global_load_lds_dwordx4 v[172:173], off
	s_waitcnt vmcnt(6)
	s_barrier
	v_mfma_f32_16x16x32_bf16 v[28:31], v[216:219], v[188:191], v[28:31]
	ds_read_b128 v[172:175], v156
	v_mfma_f32_16x16x32_bf16 v[24:27], v[224:227], v[188:191], v[24:27]
	v_mfma_f32_16x16x32_bf16 v[20:23], v[216:219], v[196:199], v[20:23]
	ds_read_b128 v[176:179], v156 offset:1024
	v_mfma_f32_16x16x32_bf16 v[16:19], v[224:227], v[196:199], v[16:19]
	v_mfma_f32_16x16x32_bf16 v[12:15], v[216:219], v[204:207], v[12:15]
	ds_read_b128 v[180:183], v156 offset:2048
	v_mfma_f32_16x16x32_bf16 v[8:11], v[224:227], v[204:207], v[8:11]
	v_mfma_f32_16x16x32_bf16 v[4:7], v[216:219], v[212:215], v[4:7]
	ds_read_b128 v[184:187], v156 offset:3072
	v_mfma_f32_16x16x32_bf16 v[0:3], v[224:227], v[212:215], v[0:3]
	v_mfma_f32_16x16x32_bf16 v[28:31], v[220:223], v[192:195], v[28:31]
	v_mfma_f32_16x16x32_bf16 v[24:27], v[228:231], v[192:195], v[24:27]
	v_mfma_f32_16x16x32_bf16 v[20:23], v[220:223], v[200:203], v[20:23]
	v_mfma_f32_16x16x32_bf16 v[16:19], v[228:231], v[200:203], v[16:19]
	v_mfma_f32_16x16x32_bf16 v[12:15], v[220:223], v[208:211], v[12:15]
	v_mfma_f32_16x16x32_bf16 v[8:11], v[228:231], v[208:211], v[8:11]
	v_mfma_f32_16x16x32_bf16 v[4:7], v[220:223], v[232:235], v[4:7]
	v_mfma_f32_16x16x32_bf16 v[0:3], v[228:231], v[232:235], v[0:3]
	s_barrier
	v_add_u32_e32 v167, 0x4000, v148
	v_add_u32_e32 v168, 0x6000, v148
	v_readfirstlane_b32 s43, v167
	v_lshl_add_u64 v[220:221], v[236:237], 0, s[22:23]
	s_mov_b32 m0, s43
	v_readfirstlane_b32 s43, v168
	ds_read_b128 v[188:191], v152 offset:32768
	ds_read_b128 v[192:195], v152 offset:33792
	ds_read_b128 v[196:199], v151 offset:32768
	ds_read_b128 v[200:203], v151 offset:33792
	ds_read_b128 v[204:207], v150 offset:32768
	ds_read_b128 v[208:211], v150 offset:33792
	ds_read_b128 v[212:215], v149 offset:32768
	ds_read_b128 v[216:219], v149 offset:33792
	global_load_lds_dwordx4 v[220:221], off
	v_lshl_add_u64 v[220:221], v[238:239], 0, s[22:23]
	s_mov_b32 m0, s43
	s_nop 0
	global_load_lds_dwordx4 v[220:221], off
	s_waitcnt lgkmcnt(8)
	s_barrier
	s_waitcnt lgkmcnt(0)
	s_waitcnt lgkmcnt(0)
	v_mfma_f32_16x16x32_bf16 v[124:127], v[172:175], v[188:191], v[124:127]
	ds_read_b128 v[220:223], v154
	v_mfma_f32_16x16x32_bf16 v[120:123], v[180:183], v[188:191], v[120:123]
	v_mfma_f32_16x16x32_bf16 v[116:119], v[172:175], v[196:199], v[116:119]
	ds_read_b128 v[224:227], v154 offset:1024
	v_mfma_f32_16x16x32_bf16 v[112:115], v[180:183], v[196:199], v[112:115]
	v_mfma_f32_16x16x32_bf16 v[108:111], v[172:175], v[204:207], v[108:111]
	ds_read_b128 v[228:231], v154 offset:2048
	v_mfma_f32_16x16x32_bf16 v[104:107], v[180:183], v[204:207], v[104:107]
	v_mfma_f32_16x16x32_bf16 v[100:103], v[172:175], v[212:215], v[100:103]
	ds_read_b128 v[232:235], v154 offset:3072
	v_mfma_f32_16x16x32_bf16 v[96:99], v[180:183], v[212:215], v[96:99]
	v_mfma_f32_16x16x32_bf16 v[124:127], v[176:179], v[192:195], v[124:127]
	v_mfma_f32_16x16x32_bf16 v[120:123], v[184:187], v[192:195], v[120:123]
	v_mfma_f32_16x16x32_bf16 v[116:119], v[176:179], v[200:203], v[116:119]
	v_mfma_f32_16x16x32_bf16 v[112:115], v[184:187], v[200:203], v[112:115]
	v_mfma_f32_16x16x32_bf16 v[108:111], v[176:179], v[208:211], v[108:111]
	v_mfma_f32_16x16x32_bf16 v[104:107], v[184:187], v[208:211], v[104:107]
	v_mfma_f32_16x16x32_bf16 v[100:103], v[176:179], v[216:219], v[100:103]
	v_mfma_f32_16x16x32_bf16 v[96:99], v[184:187], v[216:219], v[96:99]
	s_barrier
	v_readfirstlane_b32 s43, v155
	v_add_u32_e32 v171, 0x2000, v155
	v_lshl_add_u64 v[244:245], v[240:241], 0, s[24:25]
	s_mov_b32 m0, s43
	v_readfirstlane_b32 s43, v171
	global_load_lds_dwordx4 v[244:245], off
	v_lshl_add_u64 v[244:245], v[242:243], 0, s[24:25]
	s_mov_b32 m0, s43
	s_nop 0
	global_load_lds_dwordx4 v[244:245], off
	s_barrier
	s_waitcnt lgkmcnt(0)
	s_waitcnt lgkmcnt(0)
	v_mfma_f32_16x16x32_bf16 v[92:95], v[220:223], v[188:191], v[92:95]
	v_mfma_f32_16x16x32_bf16 v[88:91], v[228:231], v[188:191], v[88:91]
	v_mfma_f32_16x16x32_bf16 v[84:87], v[220:223], v[196:199], v[84:87]
	v_mfma_f32_16x16x32_bf16 v[80:83], v[228:231], v[196:199], v[80:83]
	v_mfma_f32_16x16x32_bf16 v[76:79], v[220:223], v[204:207], v[76:79]
	v_mfma_f32_16x16x32_bf16 v[72:75], v[228:231], v[204:207], v[72:75]
	v_mfma_f32_16x16x32_bf16 v[68:71], v[220:223], v[212:215], v[68:71]
	v_mfma_f32_16x16x32_bf16 v[64:67], v[228:231], v[212:215], v[64:67]
	v_mfma_f32_16x16x32_bf16 v[92:95], v[224:227], v[192:195], v[92:95]
	v_mfma_f32_16x16x32_bf16 v[88:91], v[232:235], v[192:195], v[88:91]
	v_mfma_f32_16x16x32_bf16 v[84:87], v[224:227], v[200:203], v[84:87]
	v_mfma_f32_16x16x32_bf16 v[80:83], v[232:235], v[200:203], v[80:83]
	v_mfma_f32_16x16x32_bf16 v[76:79], v[224:227], v[208:211], v[76:79]
	v_mfma_f32_16x16x32_bf16 v[72:75], v[232:235], v[208:211], v[72:75]
	v_mfma_f32_16x16x32_bf16 v[68:71], v[224:227], v[216:219], v[68:71]
	v_mfma_f32_16x16x32_bf16 v[64:67], v[232:235], v[216:219], v[64:67]
	v_readfirstlane_b32 s43, v157
	v_lshl_add_u64 v[236:237], v[236:237], 0, s[26:27]
	s_mov_b32 m0, s43
	v_readfirstlane_b32 s43, v158
	s_barrier
; #define STAGE(P, BASE, LD, br, kt) do { const char* _g = (const char*)((BASE) + (size_t)(br) * (LD) + (size_t)(kt) * 64); \
;     for (int _i = 0; _i < 2; ++_i) { int _b = tidx * 16 + _i * 8192; int _r, _c; stage_rc(_b, _r, _c); \
;       __builtin_amdgcn_global_load_lds((const unsigned*)(_g + (unsigned)((_r * (LD) + _c) * 2)), (unsigned*)((char*)(P) + _b), 16, 0, 0); } } while (0)
; #define LDA(dst, b, h) for (int m = 0; m < 4; ++m) for (int k = 0; k < 2; ++k) \
;     dst[m][k] = *reinterpret_cast<const bf16x8*>((char*)SA(b, h) + lds_byte(wr * 64 + m * 16 + fr, k * 32 + fq * 8))
; #define LDB(dst, b, h) for (int n = 0; n < 2; ++n) for (int k = 0; k < 2; ++k) \
;     dst[n][k] = *reinterpret_cast<const bf16x8*>((char*)SB(b, h) + lds_byte(wc * 32 + n * 16 + fr, k * 32 + fq * 8))
; #define MMA(ai, bj, At_, Bt_) do { __builtin_amdgcn_s_setprio(1); \
;     for (int k = 0; k < 2; ++k) for (int m = 0; m < 4; ++m) for (int n = 0; n < 2; ++n) \
;       acc[ai][bj][m][n] = __builtin_amdgcn_mfma_f32_16x16x32_bf16(At_[m][k], Bt_[n][k], acc[ai][bj][m][n], 0, 0, 0); \
;     __builtin_amdgcn_s_setprio(0); } while (0)
; #define WAIT_V(n) asm volatile("s_waitcnt vmcnt(" #n ")" ::: "memory")
; #define WAIT_L(n) asm volatile("s_waitcnt lgkmcnt(" #n ")" ::: "memory")
; #define BAR __builtin_amdgcn_s_barrier()
; #define SCHED __builtin_amdgcn_sched_barrier(0)
; template <int EPI, int lda, int ldb, int N, int K>
; __device__ __forceinline__ void gemm_phase(const u16* __restrict__ A, const u16* __restrict__ Bt, const GemmEpi ep, int wv) {
;     ...
;       LDA(At, 1, 1); STAGE(SA(1, 0), Ab, lda, brow, t + 3);
;       BAR; WAIT_L(0); MMA(1, 0, At, B0); BAR; SCHED;
;       STAGE(SB(1, 1), Bt, ldb, bcol + HALF, t + 3);
;       WAIT_V(6); BAR; MMA(1, 1, At, B1); BAR;
;     }
;     { LDB(B0, 0, 0); LDA(At, 0, 0); STAGE(SA(1, 1), Ab, lda, brow + HALF, nt - 1);
;       BAR; WAIT_L(0); MMA(0, 0, At, B0); BAR;
	ds_read_b128 v[188:191], v152 offset:49152
	ds_read_b128 v[192:195], v152 offset:50176
	ds_read_b128 v[196:199], v151 offset:49152
	ds_read_b128 v[200:203], v151 offset:50176
	ds_read_b128 v[204:207], v150 offset:49152
	ds_read_b128 v[208:211], v150 offset:50176
	ds_read_b128 v[212:215], v149 offset:49152
	ds_read_b128 v[216:219], v149 offset:50176
	global_load_lds_dwordx4 v[236:237], off
	v_lshl_add_u64 v[236:237], v[238:239], 0, s[26:27]
	s_mov_b32 m0, s43
	s_nop 0
	global_load_lds_dwordx4 v[236:237], off
	s_barrier
	s_waitcnt lgkmcnt(0)
	s_waitcnt lgkmcnt(0)
	v_mfma_f32_16x16x32_bf16 v[60:63], v[172:175], v[188:191], v[60:63]
	v_mfma_f32_16x16x32_bf16 v[56:59], v[180:183], v[188:191], v[56:59]
	v_mfma_f32_16x16x32_bf16 v[52:55], v[172:175], v[196:199], v[52:55]
	v_mfma_f32_16x16x32_bf16 v[48:51], v[180:183], v[196:199], v[48:51]
	v_mfma_f32_16x16x32_bf16 v[44:47], v[172:175], v[204:207], v[44:47]
	v_mfma_f32_16x16x32_bf16 v[40:43], v[180:183], v[204:207], v[40:43]
	v_mfma_f32_16x16x32_bf16 v[36:39], v[172:175], v[212:215], v[36:39]
	v_mfma_f32_16x16x32_bf16 v[32:35], v[180:183], v[212:215], v[32:35]
	v_mfma_f32_16x16x32_bf16 v[60:63], v[176:179], v[192:195], v[60:63]
	v_mfma_f32_16x16x32_bf16 v[56:59], v[184:187], v[192:195], v[56:59]
	v_mfma_f32_16x16x32_bf16 v[52:55], v[176:179], v[200:203], v[52:55]
	v_mfma_f32_16x16x32_bf16 v[48:51], v[184:187], v[200:203], v[48:51]
	v_mfma_f32_16x16x32_bf16 v[44:47], v[176:179], v[208:211], v[44:47]
	v_mfma_f32_16x16x32_bf16 v[40:43], v[184:187], v[208:211], v[40:43]
	v_mfma_f32_16x16x32_bf16 v[36:39], v[176:179], v[216:219], v[36:39]
	v_mfma_f32_16x16x32_bf16 v[32:35], v[184:187], v[216:219], v[32:35]
	s_barrier
	v_readfirstlane_b32 s43, v159
	v_add_u32_e32 v171, 0x2000, v159
	v_lshl_add_u64 v[172:173], v[240:241], 0, s[34:35]
	s_mov_b32 m0, s43
	v_readfirstlane_b32 s43, v171
	global_load_lds_dwordx4 v[172:173], off
	v_lshl_add_u64 v[172:173], v[242:243], 0, s[34:35]
	s_mov_b32 m0, s43
	s_nop 0
	global_load_lds_dwordx4 v[172:173], off
	s_waitcnt vmcnt(6)
	s_barrier
	v_mfma_f32_16x16x32_bf16 v[28:31], v[220:223], v[188:191], v[28:31]
	v_mfma_f32_16x16x32_bf16 v[24:27], v[228:231], v[188:191], v[24:27]
	v_mfma_f32_16x16x32_bf16 v[20:23], v[220:223], v[196:199], v[20:23]
	v_mfma_f32_16x16x32_bf16 v[16:19], v[228:231], v[196:199], v[16:19]
	v_mfma_f32_16x16x32_bf16 v[12:15], v[220:223], v[204:207], v[12:15]
	v_mfma_f32_16x16x32_bf16 v[8:11], v[228:231], v[204:207], v[8:11]
	v_mfma_f32_16x16x32_bf16 v[4:7], v[220:223], v[212:215], v[4:7]
	v_mfma_f32_16x16x32_bf16 v[0:3], v[228:231], v[212:215], v[0:3]
	v_mfma_f32_16x16x32_bf16 v[28:31], v[224:227], v[192:195], v[28:31]
	v_mfma_f32_16x16x32_bf16 v[24:27], v[232:235], v[192:195], v[24:27]
	v_mfma_f32_16x16x32_bf16 v[20:23], v[224:227], v[200:203], v[20:23]
	v_mfma_f32_16x16x32_bf16 v[16:19], v[232:235], v[200:203], v[16:19]
	v_mfma_f32_16x16x32_bf16 v[12:15], v[224:227], v[208:211], v[12:15]
	v_mfma_f32_16x16x32_bf16 v[8:11], v[232:235], v[208:211], v[8:11]
	v_mfma_f32_16x16x32_bf16 v[4:7], v[224:227], v[216:219], v[4:7]
	v_mfma_f32_16x16x32_bf16 v[0:3], v[232:235], v[216:219], v[0:3]
	s_add_i32 s42, s42, 2
	s_add_u32 s40, s40, 0x100
	s_addc_u32 s41, s41, 0
	s_cmp_gt_u32 s42, 27
	s_barrier
	s_cbranch_scc0 .LBB0_1564
	s_add_i32 s40, s38, 0x80
	s_mul_hi_i32 s41, s40, 0x1080
	s_mulk_i32 s40, 0x1080
	s_add_u32 s40, s49, s40
	s_addc_u32 s41, s50, s41
	v_lshl_add_u64 v[158:159], s[40:41], 0, v[128:129]
	v_readfirstlane_b32 s42, v169
	v_lshl_add_u64 v[158:159], v[158:159], 0, s[36:37]
	s_mov_b32 m0, s42
	ds_read_b128 v[134:137], v161
	ds_read_b128 v[138:141], v161 offset:1024
	ds_read_b128 v[172:175], v161 offset:2048
	ds_read_b128 v[176:179], v161 offset:3072
	ds_read_b128 v[180:183], v152
	ds_read_b128 v[184:187], v152 offset:1024
	ds_read_b128 v[188:191], v151
	ds_read_b128 v[192:195], v151 offset:1024
	ds_read_b128 v[196:199], v150
	ds_read_b128 v[200:203], v150 offset:1024
	ds_read_b128 v[204:207], v149
	ds_read_b128 v[208:211], v149 offset:1024
	global_load_lds_dwordx4 v[158:159], off
	v_lshl_add_u64 v[158:159], s[40:41], 0, v[132:133]
	v_readfirstlane_b32 s40, v170
	v_lshl_add_u64 v[158:159], v[158:159], 0, s[36:37]
	s_mov_b32 m0, s40
	s_nop 0
	global_load_lds_dwordx4 v[158:159], off
	s_barrier
	s_waitcnt lgkmcnt(0)
	s_waitcnt lgkmcnt(0)
	v_mfma_f32_16x16x32_bf16 v[124:127], v[134:137], v[180:183], v[124:127]
	v_mfma_f32_16x16x32_bf16 v[120:123], v[172:175], v[180:183], v[120:123]
	v_mfma_f32_16x16x32_bf16 v[116:119], v[134:137], v[188:191], v[116:119]
	v_mfma_f32_16x16x32_bf16 v[112:115], v[172:175], v[188:191], v[112:115]
	v_mfma_f32_16x16x32_bf16 v[108:111], v[134:137], v[196:199], v[108:111]
	v_mfma_f32_16x16x32_bf16 v[104:107], v[172:175], v[196:199], v[104:107]
	v_mfma_f32_16x16x32_bf16 v[100:103], v[134:137], v[204:207], v[100:103]
	v_mfma_f32_16x16x32_bf16 v[96:99], v[172:175], v[204:207], v[96:99]
	v_mfma_f32_16x16x32_bf16 v[124:127], v[138:141], v[184:187], v[124:127]
	v_mfma_f32_16x16x32_bf16 v[120:123], v[176:179], v[184:187], v[120:123]
	v_mfma_f32_16x16x32_bf16 v[116:119], v[138:141], v[192:195], v[116:119]
	v_mfma_f32_16x16x32_bf16 v[112:115], v[176:179], v[192:195], v[112:115]
	v_mfma_f32_16x16x32_bf16 v[108:111], v[138:141], v[200:203], v[108:111]
	v_mfma_f32_16x16x32_bf16 v[104:107], v[176:179], v[200:203], v[104:107]
	v_mfma_f32_16x16x32_bf16 v[100:103], v[138:141], v[208:211], v[100:103]
	v_mfma_f32_16x16x32_bf16 v[96:99], v[176:179], v[208:211], v[96:99]
	s_barrier
	ds_read_b128 v[212:215], v160
	ds_read_b128 v[216:219], v160 offset:1024
	ds_read_b128 v[220:223], v160 offset:2048
	ds_read_b128 v[158:161], v160 offset:3072
	s_barrier
; #define LDA(dst, b, h) for (int m = 0; m < 4; ++m) for (int k = 0; k < 2; ++k) \
;     dst[m][k] = *reinterpret_cast<const bf16x8*>((char*)SA(b, h) + lds_byte(wr * 64 + m * 16 + fr, k * 32 + fq * 8))
; #define LDB(dst, b, h) for (int n = 0; n < 2; ++n) for (int k = 0; k < 2; ++k) \
;     dst[n][k] = *reinterpret_cast<const bf16x8*>((char*)SB(b, h) + lds_byte(wc * 32 + n * 16 + fr, k * 32 + fq * 8))
; #define MMA(ai, bj, At_, Bt_) do { __builtin_amdgcn_s_setprio(1); \
;     for (int k = 0; k < 2; ++k) for (int m = 0; m < 4; ++m) for (int n = 0; n < 2; ++n) \
;       acc[ai][bj][m][n] = __builtin_amdgcn_mfma_f32_16x16x32_bf16(At_[m][k], Bt_[n][k], acc[ai][bj][m][n], 0, 0, 0); \
;     __builtin_amdgcn_s_setprio(0); } while (0)
; #define WAIT_V(n) asm volatile("s_waitcnt vmcnt(" #n ")" ::: "memory")
; #define WAIT_L(n) asm volatile("s_waitcnt lgkmcnt(" #n ")" ::: "memory")
; #define BAR __builtin_amdgcn_s_barrier()
; template <int EPI, int lda, int ldb, int N, int K>
; __device__ __forceinline__ void gemm_phase(const u16* __restrict__ A, const u16* __restrict__ Bt, const GemmEpi ep, int wv) {
;     ...
;       LDB(B1, 0, 1); BAR; WAIT_L(0); MMA(0, 1, At, B1); BAR;
;       LDA(At, 0, 1); WAIT_V(4); BAR; WAIT_L(0); MMA(1, 0, At, B0); MMA(1, 1, At, B1); BAR; }
;     { LDB(B0, 1, 0); LDA(At, 1, 0); WAIT_V(2); BAR; WAIT_L(0); MMA(0, 0, At, B0); BAR;
	s_waitcnt lgkmcnt(0)
	s_waitcnt lgkmcnt(0)
	v_mfma_f32_16x16x32_bf16 v[92:95], v[212:215], v[180:183], v[92:95]
	v_mfma_f32_16x16x32_bf16 v[88:91], v[220:223], v[180:183], v[88:91]
	v_mfma_f32_16x16x32_bf16 v[76:79], v[212:215], v[196:199], v[76:79]
	v_mfma_f32_16x16x32_bf16 v[72:75], v[220:223], v[196:199], v[72:75]
	v_mfma_f32_16x16x32_bf16 v[84:87], v[212:215], v[188:191], v[84:87]
	v_mfma_f32_16x16x32_bf16 v[80:83], v[220:223], v[188:191], v[80:83]
	v_mfma_f32_16x16x32_bf16 v[68:71], v[212:215], v[204:207], v[68:71]
	v_mfma_f32_16x16x32_bf16 v[64:67], v[220:223], v[204:207], v[64:67]
	v_mfma_f32_16x16x32_bf16 v[92:95], v[216:219], v[184:187], v[92:95]
	v_mfma_f32_16x16x32_bf16 v[88:91], v[158:161], v[184:187], v[88:91]
	v_mfma_f32_16x16x32_bf16 v[76:79], v[216:219], v[200:203], v[76:79]
	v_mfma_f32_16x16x32_bf16 v[72:75], v[158:161], v[200:203], v[72:75]
	v_mfma_f32_16x16x32_bf16 v[180:183], v[216:219], v[192:195], v[84:87]
	v_mfma_f32_16x16x32_bf16 v[184:187], v[158:161], v[192:195], v[80:83]
	v_mfma_f32_16x16x32_bf16 v[188:191], v[216:219], v[208:211], v[68:71]
	v_mfma_f32_16x16x32_bf16 v[192:195], v[158:161], v[208:211], v[64:67]
	s_barrier
	s_nop 0
	ds_read_b128 v[64:67], v152 offset:16384
	ds_read_b128 v[68:71], v152 offset:17408
	ds_read_b128 v[80:83], v151 offset:16384
	ds_read_b128 v[84:87], v151 offset:17408
	ds_read_b128 v[196:199], v150 offset:16384
	ds_read_b128 v[200:203], v150 offset:17408
	ds_read_b128 v[204:207], v149 offset:16384
	ds_read_b128 v[208:211], v149 offset:17408
	s_waitcnt vmcnt(4)
	s_barrier
	s_waitcnt lgkmcnt(0)
	s_waitcnt lgkmcnt(0)
	v_mfma_f32_16x16x32_bf16 v[60:63], v[134:137], v[64:67], v[60:63]
	v_mfma_f32_16x16x32_bf16 v[56:59], v[172:175], v[64:67], v[56:59]
	v_mfma_f32_16x16x32_bf16 v[52:55], v[134:137], v[80:83], v[52:55]
	v_mfma_f32_16x16x32_bf16 v[48:51], v[172:175], v[80:83], v[48:51]
	v_mfma_f32_16x16x32_bf16 v[44:47], v[134:137], v[196:199], v[44:47]
	v_mfma_f32_16x16x32_bf16 v[40:43], v[172:175], v[196:199], v[40:43]
	v_mfma_f32_16x16x32_bf16 v[36:39], v[134:137], v[204:207], v[36:39]
	v_mfma_f32_16x16x32_bf16 v[32:35], v[172:175], v[204:207], v[32:35]
	v_mfma_f32_16x16x32_bf16 v[60:63], v[138:141], v[68:71], v[60:63]
	v_mfma_f32_16x16x32_bf16 v[56:59], v[176:179], v[68:71], v[56:59]
	v_mfma_f32_16x16x32_bf16 v[52:55], v[138:141], v[84:87], v[52:55]
	v_mfma_f32_16x16x32_bf16 v[48:51], v[176:179], v[84:87], v[48:51]
	v_mfma_f32_16x16x32_bf16 v[44:47], v[138:141], v[200:203], v[44:47]
	v_mfma_f32_16x16x32_bf16 v[40:43], v[176:179], v[200:203], v[40:43]
	v_mfma_f32_16x16x32_bf16 v[36:39], v[138:141], v[208:211], v[36:39]
	v_mfma_f32_16x16x32_bf16 v[32:35], v[176:179], v[208:211], v[32:35]
	v_mfma_f32_16x16x32_bf16 v[28:31], v[212:215], v[64:67], v[28:31]
	v_mfma_f32_16x16x32_bf16 v[24:27], v[220:223], v[64:67], v[24:27]
	v_mfma_f32_16x16x32_bf16 v[12:15], v[212:215], v[196:199], v[12:15]
	v_mfma_f32_16x16x32_bf16 v[8:11], v[220:223], v[196:199], v[8:11]
	v_mfma_f32_16x16x32_bf16 v[20:23], v[212:215], v[80:83], v[20:23]
	v_mfma_f32_16x16x32_bf16 v[16:19], v[220:223], v[80:83], v[16:19]
	v_mfma_f32_16x16x32_bf16 v[4:7], v[212:215], v[204:207], v[4:7]
	v_mfma_f32_16x16x32_bf16 v[0:3], v[220:223], v[204:207], v[0:3]
	v_mfma_f32_16x16x32_bf16 v[28:31], v[216:219], v[68:71], v[28:31]
	v_mfma_f32_16x16x32_bf16 v[24:27], v[158:161], v[68:71], v[24:27]
	v_mfma_f32_16x16x32_bf16 v[12:15], v[216:219], v[200:203], v[12:15]
	v_mfma_f32_16x16x32_bf16 v[8:11], v[158:161], v[200:203], v[8:11]
	v_mfma_f32_16x16x32_bf16 v[134:137], v[216:219], v[84:87], v[20:23]
	v_mfma_f32_16x16x32_bf16 v[138:141], v[158:161], v[84:87], v[16:19]
	v_mfma_f32_16x16x32_bf16 v[170:173], v[216:219], v[208:211], v[4:7]
	v_mfma_f32_16x16x32_bf16 v[158:161], v[158:161], v[208:211], v[0:3]
	s_barrier
	s_nop 0
	ds_read_b128 v[0:3], v156
	ds_read_b128 v[4:7], v156 offset:1024
	ds_read_b128 v[16:19], v156 offset:2048
	ds_read_b128 v[174:177], v156 offset:3072
	ds_read_b128 v[20:23], v152 offset:32768
	ds_read_b128 v[196:199], v152 offset:33792
	ds_read_b128 v[200:203], v151 offset:32768
	ds_read_b128 v[204:207], v151 offset:33792
	ds_read_b128 v[208:211], v150 offset:32768
	ds_read_b128 v[212:215], v150 offset:33792
	ds_read_b128 v[216:219], v149 offset:32768
	ds_read_b128 v[220:223], v149 offset:33792
	s_waitcnt vmcnt(2)
	s_barrier
; #define LDA(dst, b, h) for (int m = 0; m < 4; ++m) for (int k = 0; k < 2; ++k) \
;     dst[m][k] = *reinterpret_cast<const bf16x8*>((char*)SA(b, h) + lds_byte(wr * 64 + m * 16 + fr, k * 32 + fq * 8))
; #define LDB(dst, b, h) for (int n = 0; n < 2; ++n) for (int k = 0; k < 2; ++k) \
;     dst[n][k] = *reinterpret_cast<const bf16x8*>((char*)SB(b, h) + lds_byte(wc * 32 + n * 16 + fr, k * 32 + fq * 8))
; #define MMA(ai, bj, At_, Bt_) do { __builtin_amdgcn_s_setprio(1); \
;     for (int k = 0; k < 2; ++k) for (int m = 0; m < 4; ++m) for (int n = 0; n < 2; ++n) \
;       acc[ai][bj][m][n] = __builtin_amdgcn_mfma_f32_16x16x32_bf16(At_[m][k], Bt_[n][k], acc[ai][bj][m][n], 0, 0, 0); \
;     __builtin_amdgcn_s_setprio(0); } while (0)
; #define WAIT_V(n) asm volatile("s_waitcnt vmcnt(" #n ")" ::: "memory")
; #define WAIT_L(n) asm volatile("s_waitcnt lgkmcnt(" #n ")" ::: "memory")
; #define BAR __builtin_amdgcn_s_barrier()
; template <int EPI, int lda, int ldb, int N, int K>
; __device__ __forceinline__ void gemm_phase(const u16* __restrict__ A, const u16* __restrict__ Bt, const GemmEpi ep, int wv) {
;     ...
;     { LDB(B0, 1, 0); LDA(At, 1, 0); WAIT_V(2); BAR; WAIT_L(0); MMA(0, 0, At, B0); BAR;
;       LDB(B1, 1, 1); WAIT_V(0); BAR; WAIT_L(0); MMA(0, 1, At, B1); BAR;
;       LDA(At, 1, 1); BAR; WAIT_L(0); MMA(1, 0, At, B0); MMA(1, 1, At, B1); BAR; }
;     if (wr == 0) BAR;
	s_waitcnt lgkmcnt(0)
	s_waitcnt lgkmcnt(0)
	v_mfma_f32_16x16x32_bf16 v[64:67], v[0:3], v[20:23], v[124:127]
	v_mfma_f32_16x16x32_bf16 v[68:71], v[16:19], v[20:23], v[120:123]
	v_mfma_f32_16x16x32_bf16 v[80:83], v[0:3], v[200:203], v[116:119]
	v_mfma_f32_16x16x32_bf16 v[84:87], v[16:19], v[200:203], v[112:115]
	v_mfma_f32_16x16x32_bf16 v[108:111], v[0:3], v[208:211], v[108:111]
	v_mfma_f32_16x16x32_bf16 v[104:107], v[16:19], v[208:211], v[104:107]
	v_mfma_f32_16x16x32_bf16 v[120:123], v[0:3], v[216:219], v[100:103]
	v_mfma_f32_16x16x32_bf16 v[124:127], v[16:19], v[216:219], v[96:99]
	v_mfma_f32_16x16x32_bf16 v[116:119], v[4:7], v[196:199], v[64:67]
	v_mfma_f32_16x16x32_bf16 v[112:115], v[174:177], v[196:199], v[68:71]
	v_mfma_f32_16x16x32_bf16 v[100:103], v[4:7], v[204:207], v[80:83]
	v_mfma_f32_16x16x32_bf16 v[96:99], v[174:177], v[204:207], v[84:87]
	v_mfma_f32_16x16x32_bf16 v[84:87], v[4:7], v[212:215], v[108:111]
	v_mfma_f32_16x16x32_bf16 v[80:83], v[174:177], v[212:215], v[104:107]
	v_mfma_f32_16x16x32_bf16 v[68:71], v[4:7], v[220:223], v[120:123]
	v_mfma_f32_16x16x32_bf16 v[64:67], v[174:177], v[220:223], v[124:127]
	s_barrier
	ds_read_b128 v[224:227], v154
	ds_read_b128 v[228:231], v154 offset:1024
	ds_read_b128 v[232:235], v154 offset:2048
	ds_read_b128 v[154:157], v154 offset:3072
	s_waitcnt vmcnt(0)
	s_barrier
	s_waitcnt lgkmcnt(0)
	s_waitcnt lgkmcnt(0)
	v_mfma_f32_16x16x32_bf16 v[92:95], v[224:227], v[20:23], v[92:95]
	v_mfma_f32_16x16x32_bf16 v[20:23], v[232:235], v[20:23], v[88:91]
	v_mfma_f32_16x16x32_bf16 v[88:91], v[224:227], v[200:203], v[180:183]
	v_mfma_f32_16x16x32_bf16 v[104:107], v[232:235], v[200:203], v[184:187]
	v_mfma_f32_16x16x32_bf16 v[76:79], v[224:227], v[208:211], v[76:79]
	v_mfma_f32_16x16x32_bf16 v[72:75], v[232:235], v[208:211], v[72:75]
	v_mfma_f32_16x16x32_bf16 v[178:181], v[224:227], v[216:219], v[188:191]
	v_mfma_f32_16x16x32_bf16 v[182:185], v[232:235], v[216:219], v[192:195]
	v_mfma_f32_16x16x32_bf16 v[124:127], v[228:231], v[196:199], v[92:95]
	v_mfma_f32_16x16x32_bf16 v[120:123], v[154:157], v[196:199], v[20:23]
	v_mfma_f32_16x16x32_bf16 v[108:111], v[228:231], v[204:207], v[88:91]
	v_mfma_f32_16x16x32_bf16 v[104:107], v[154:157], v[204:207], v[104:107]
	v_mfma_f32_16x16x32_bf16 v[92:95], v[228:231], v[212:215], v[76:79]
	v_mfma_f32_16x16x32_bf16 v[88:91], v[154:157], v[212:215], v[72:75]
	v_mfma_f32_16x16x32_bf16 v[76:79], v[228:231], v[220:223], v[178:181]
	v_mfma_f32_16x16x32_bf16 v[72:75], v[154:157], v[220:223], v[182:185]
	s_barrier
	ds_read_b128 v[178:181], v152 offset:49152
	ds_read_b128 v[182:185], v152 offset:50176
	ds_read_b128 v[186:189], v151 offset:49152
	ds_read_b128 v[190:193], v151 offset:50176
	ds_read_b128 v[194:197], v150 offset:49152
	ds_read_b128 v[150:153], v150 offset:50176
	ds_read_b128 v[198:201], v149 offset:49152
	ds_read_b128 v[202:205], v149 offset:50176
	s_barrier
	s_waitcnt lgkmcnt(0)
	s_waitcnt lgkmcnt(0)
	v_mfma_f32_16x16x32_bf16 v[20:23], v[0:3], v[178:181], v[60:63]
	v_mfma_f32_16x16x32_bf16 v[56:59], v[16:19], v[178:181], v[56:59]
	v_mfma_f32_16x16x32_bf16 v[60:63], v[0:3], v[186:189], v[52:55]
	v_mfma_f32_16x16x32_bf16 v[206:209], v[16:19], v[186:189], v[48:51]
	v_mfma_f32_16x16x32_bf16 v[44:47], v[0:3], v[194:197], v[44:47]
	v_mfma_f32_16x16x32_bf16 v[40:43], v[16:19], v[194:197], v[40:43]
	v_mfma_f32_16x16x32_bf16 v[0:3], v[0:3], v[198:201], v[36:39]
	v_mfma_f32_16x16x32_bf16 v[210:213], v[16:19], v[198:201], v[32:35]
	v_mfma_f32_16x16x32_bf16 v[52:55], v[4:7], v[182:185], v[20:23]
	v_mfma_f32_16x16x32_bf16 v[48:51], v[174:177], v[182:185], v[56:59]
	v_mfma_f32_16x16x32_bf16 v[36:39], v[4:7], v[190:193], v[60:63]
	v_mfma_f32_16x16x32_bf16 v[32:35], v[174:177], v[190:193], v[206:209]
	v_mfma_f32_16x16x32_bf16 v[20:23], v[4:7], v[150:153], v[44:47]
	v_mfma_f32_16x16x32_bf16 v[16:19], v[174:177], v[150:153], v[40:43]
	v_mfma_f32_16x16x32_bf16 v[4:7], v[4:7], v[202:205], v[0:3]
	v_mfma_f32_16x16x32_bf16 v[0:3], v[174:177], v[202:205], v[210:213]
	v_mfma_f32_16x16x32_bf16 v[28:31], v[224:227], v[178:181], v[28:31]
	v_mfma_f32_16x16x32_bf16 v[24:27], v[232:235], v[178:181], v[24:27]
	v_mfma_f32_16x16x32_bf16 v[40:43], v[224:227], v[186:189], v[134:137]
	v_mfma_f32_16x16x32_bf16 v[134:137], v[232:235], v[186:189], v[138:141]
	v_mfma_f32_16x16x32_bf16 v[12:15], v[224:227], v[194:197], v[12:15]
	v_mfma_f32_16x16x32_bf16 v[8:11], v[232:235], v[194:197], v[8:11]
	v_mfma_f32_16x16x32_bf16 v[138:141], v[224:227], v[198:201], v[170:173]
	v_mfma_f32_16x16x32_bf16 v[158:161], v[232:235], v[198:201], v[158:161]
	v_mfma_f32_16x16x32_bf16 v[60:63], v[228:231], v[182:185], v[28:31]
	v_mfma_f32_16x16x32_bf16 v[56:59], v[154:157], v[182:185], v[24:27]
	v_mfma_f32_16x16x32_bf16 v[44:47], v[228:231], v[190:193], v[40:43]
	v_mfma_f32_16x16x32_bf16 v[40:43], v[154:157], v[190:193], v[134:137]
	v_mfma_f32_16x16x32_bf16 v[28:31], v[228:231], v[150:153], v[12:15]
	v_mfma_f32_16x16x32_bf16 v[24:27], v[154:157], v[150:153], v[8:11]
	v_mfma_f32_16x16x32_bf16 v[12:15], v[228:231], v[202:205], v[138:141]
	v_mfma_f32_16x16x32_bf16 v[8:11], v[154:157], v[202:205], v[158:161]
	v_cmp_gt_u32_e32 vcc, s54, v130
	s_barrier
	s_and_saveexec_b64 s[40:41], vcc
	s_cbranch_execz .LBB0_1567
	s_barrier

; #define STAGE(P, BASE, LD, br, kt) do { const char* _g = (const char*)((BASE) + (size_t)(br) * (LD) + (size_t)(kt) * 64); \
;     for (int _i = 0; _i < 2; ++_i) { int _b = tidx * 16 + _i * 8192; int _r, _c; stage_rc(_b, _r, _c); \
;       __builtin_amdgcn_global_load_lds((const unsigned*)(_g + (unsigned)((_r * (LD) + _c) * 2)), (unsigned*)((char*)(P) + _b), 16, 0, 0); } } while (0)
; #define LDA(dst, b, h) for (int m = 0; m < 4; ++m) for (int k = 0; k < 2; ++k) \
;     dst[m][k] = *reinterpret_cast<const bf16x8*>((char*)SA(b, h) + lds_byte(wr * 64 + m * 16 + fr, k * 32 + fq * 8))
; #define LDB(dst, b, h) for (int n = 0; n < 2; ++n) for (int k = 0; k < 2; ++k) \
;     dst[n][k] = *reinterpret_cast<const bf16x8*>((char*)SB(b, h) + lds_byte(wc * 32 + n * 16 + fr, k * 32 + fq * 8))
; #define MMA(ai, bj, At_, Bt_) do { __builtin_amdgcn_s_setprio(1); \
;     for (int k = 0; k < 2; ++k) for (int m = 0; m < 4; ++m) for (int n = 0; n < 2; ++n) \
;       acc[ai][bj][m][n] = __builtin_amdgcn_mfma_f32_16x16x32_bf16(At_[m][k], Bt_[n][k], acc[ai][bj][m][n], 0, 0, 0); \
;     __builtin_amdgcn_s_setprio(0); } while (0)
; #define WAIT_L(n) asm volatile("s_waitcnt lgkmcnt(" #n ")" ::: "memory")
; #define BAR __builtin_amdgcn_s_barrier()
; #define SCHED __builtin_amdgcn_sched_barrier(0)
; template <int EPI, int lda, int ldb, int N, int K>
; __device__ __forceinline__ void gemm_phase(const u16* __restrict__ A, const u16* __restrict__ Bt, const GemmEpi ep, int wv) {
;     ...
;       LDB(B0, 0, 0); SCHED; LDA(At, 0, 0); STAGE(SA(1, 1), Ab, lda, brow + HALF, t + 1);
;       WAIT_L(8); BAR; WAIT_L(0); MMA(0, 0, At, B0); BAR; SCHED;
;       LDB(B1, 0, 1); STAGE(SB(0, 0), Bt, ldb, bcol, t + 2);
;       BAR; WAIT_L(0); MMA(0, 1, At, B1); BAR;
;       LDA(At, 0, 1); STAGE(SA(0, 0), Ab, lda, brow, t + 2);
;       BAR; WAIT_L(0); MMA(1, 0, At, B0); BAR; SCHED;
.LBB0_1624:
	ds_read_b128 v[174:177], v163
	ds_read_b128 v[178:181], v163 offset:1024
	ds_read_b128 v[182:185], v163 offset:2048
	ds_read_b128 v[186:189], v163 offset:3072
	v_add_u32_e32 v171, 0xc000, v149
	v_lshl_add_u64 v[238:239], v[134:135], 0, s[28:29]
	v_readfirstlane_b32 s50, v171
	v_add_u32_e32 v172, 0xe000, v149
	v_lshl_add_u64 v[164:165], v[238:239], 0, s[10:11]
	s_mov_b32 m0, s50
	v_lshl_add_u64 v[240:241], v[132:133], 0, s[28:29]
	v_readfirstlane_b32 s50, v172
	ds_read_b128 v[166:169], v154
	ds_read_b128 v[190:193], v154 offset:1024
	ds_read_b128 v[194:197], v153
	ds_read_b128 v[198:201], v153 offset:1024
	ds_read_b128 v[202:205], v151
	ds_read_b128 v[206:209], v151 offset:1024
	ds_read_b128 v[210:213], v150
	ds_read_b128 v[214:217], v150 offset:1024
	global_load_lds_dwordx4 v[164:165], off
	v_lshl_add_u64 v[164:165], v[240:241], 0, s[10:11]
	s_mov_b32 m0, s50
	s_nop 0
	global_load_lds_dwordx4 v[164:165], off
	s_waitcnt lgkmcnt(8)
	s_barrier
	s_waitcnt lgkmcnt(0)
	s_waitcnt lgkmcnt(0)
	v_mfma_f32_16x16x32_bf16 v[124:127], v[166:169], v[174:177], v[124:127]
	ds_read_b128 v[218:221], v162
	v_mfma_f32_16x16x32_bf16 v[120:123], v[166:169], v[182:185], v[120:123]
	v_mfma_f32_16x16x32_bf16 v[116:119], v[194:197], v[174:177], v[116:119]
	ds_read_b128 v[222:225], v162 offset:1024
	v_mfma_f32_16x16x32_bf16 v[112:115], v[194:197], v[182:185], v[112:115]
	v_mfma_f32_16x16x32_bf16 v[108:111], v[202:205], v[174:177], v[108:111]
	ds_read_b128 v[226:229], v162 offset:2048
	v_mfma_f32_16x16x32_bf16 v[104:107], v[202:205], v[182:185], v[104:107]
	v_mfma_f32_16x16x32_bf16 v[100:103], v[210:213], v[174:177], v[100:103]
	ds_read_b128 v[230:233], v162 offset:3072
	v_mfma_f32_16x16x32_bf16 v[96:99], v[210:213], v[182:185], v[96:99]
	v_mfma_f32_16x16x32_bf16 v[124:127], v[190:193], v[178:181], v[124:127]
	v_mfma_f32_16x16x32_bf16 v[120:123], v[190:193], v[186:189], v[120:123]
	v_mfma_f32_16x16x32_bf16 v[116:119], v[198:201], v[178:181], v[116:119]
	v_mfma_f32_16x16x32_bf16 v[112:115], v[198:201], v[186:189], v[112:115]
	v_mfma_f32_16x16x32_bf16 v[108:111], v[206:209], v[178:181], v[108:111]
	v_mfma_f32_16x16x32_bf16 v[104:107], v[206:209], v[186:189], v[104:107]
	v_mfma_f32_16x16x32_bf16 v[100:103], v[214:217], v[178:181], v[100:103]
	v_mfma_f32_16x16x32_bf16 v[96:99], v[214:217], v[186:189], v[96:99]
	s_barrier
	v_add_u32_e32 v164, s40, v155
	v_lshl_add_u64 v[242:243], v[142:143], 0, s[28:29]
	v_readfirstlane_b32 s50, v164
	v_add_u32_e32 v165, 0x2000, v164
	v_lshl_add_u64 v[234:235], v[242:243], 0, s[12:13]
	s_mov_b32 m0, s50
	v_lshl_add_u64 v[244:245], v[140:141], 0, s[28:29]
	v_readfirstlane_b32 s50, v165
	global_load_lds_dwordx4 v[234:235], off
	v_lshl_add_u64 v[234:235], v[244:245], 0, s[12:13]
	s_mov_b32 m0, s50
	s_nop 0
	global_load_lds_dwordx4 v[234:235], off
	s_barrier
	s_waitcnt lgkmcnt(0)
	s_waitcnt lgkmcnt(0)
	v_mfma_f32_16x16x32_bf16 v[92:95], v[166:169], v[218:221], v[92:95]
	v_mfma_f32_16x16x32_bf16 v[88:91], v[166:169], v[226:229], v[88:91]
	v_mfma_f32_16x16x32_bf16 v[84:87], v[194:197], v[218:221], v[84:87]
	v_mfma_f32_16x16x32_bf16 v[80:83], v[194:197], v[226:229], v[80:83]
	v_mfma_f32_16x16x32_bf16 v[76:79], v[202:205], v[218:221], v[76:79]
	v_mfma_f32_16x16x32_bf16 v[72:75], v[202:205], v[226:229], v[72:75]
	v_mfma_f32_16x16x32_bf16 v[68:71], v[210:213], v[218:221], v[68:71]
	v_mfma_f32_16x16x32_bf16 v[64:67], v[210:213], v[226:229], v[64:67]
	v_mfma_f32_16x16x32_bf16 v[92:95], v[190:193], v[222:225], v[92:95]
	v_mfma_f32_16x16x32_bf16 v[88:91], v[190:193], v[230:233], v[88:91]
	v_mfma_f32_16x16x32_bf16 v[84:87], v[198:201], v[222:225], v[84:87]
	v_mfma_f32_16x16x32_bf16 v[80:83], v[198:201], v[230:233], v[80:83]
	v_mfma_f32_16x16x32_bf16 v[76:79], v[206:209], v[222:225], v[76:79]
	v_mfma_f32_16x16x32_bf16 v[72:75], v[206:209], v[230:233], v[72:75]
	v_mfma_f32_16x16x32_bf16 v[68:71], v[214:217], v[222:225], v[68:71]
	v_mfma_f32_16x16x32_bf16 v[64:67], v[214:217], v[230:233], v[64:67]
	v_readfirstlane_b32 s50, v149
	v_lshl_add_u64 v[166:167], v[238:239], 0, s[14:15]
	s_mov_b32 m0, s50
	s_barrier
	ds_read_b128 v[190:193], v154 offset:16384
	ds_read_b128 v[194:197], v154 offset:17408
	ds_read_b128 v[198:201], v153 offset:16384
	ds_read_b128 v[202:205], v153 offset:17408
	ds_read_b128 v[206:209], v151 offset:16384
	ds_read_b128 v[210:213], v151 offset:17408
	ds_read_b128 v[214:217], v150 offset:16384
	ds_read_b128 v[234:237], v150 offset:17408
	global_load_lds_dwordx4 v[166:167], off
	v_add_u32_e32 v166, 0x2000, v149
	v_lshl_add_u64 v[168:169], v[240:241], 0, s[14:15]
	v_readfirstlane_b32 s50, v166
	s_mov_b32 m0, s50
	s_nop 0
	global_load_lds_dwordx4 v[168:169], off
	s_barrier
	s_waitcnt lgkmcnt(0)
	s_waitcnt lgkmcnt(0)
	v_mfma_f32_16x16x32_bf16 v[60:63], v[190:193], v[174:177], v[60:63]
	v_mfma_f32_16x16x32_bf16 v[56:59], v[190:193], v[182:185], v[56:59]
	v_mfma_f32_16x16x32_bf16 v[52:55], v[198:201], v[174:177], v[52:55]
	v_mfma_f32_16x16x32_bf16 v[48:51], v[198:201], v[182:185], v[48:51]
	v_mfma_f32_16x16x32_bf16 v[44:47], v[206:209], v[174:177], v[44:47]
	v_mfma_f32_16x16x32_bf16 v[40:43], v[206:209], v[182:185], v[40:43]
	v_mfma_f32_16x16x32_bf16 v[36:39], v[214:217], v[174:177], v[36:39]
	v_mfma_f32_16x16x32_bf16 v[32:35], v[214:217], v[182:185], v[32:35]
	v_mfma_f32_16x16x32_bf16 v[60:63], v[194:197], v[178:181], v[60:63]
	v_mfma_f32_16x16x32_bf16 v[56:59], v[194:197], v[186:189], v[56:59]
	v_mfma_f32_16x16x32_bf16 v[52:55], v[202:205], v[178:181], v[52:55]
	v_mfma_f32_16x16x32_bf16 v[48:51], v[202:205], v[186:189], v[48:51]
	v_mfma_f32_16x16x32_bf16 v[44:47], v[210:213], v[178:181], v[44:47]
	v_mfma_f32_16x16x32_bf16 v[40:43], v[210:213], v[186:189], v[40:43]
	v_mfma_f32_16x16x32_bf16 v[36:39], v[234:237], v[178:181], v[36:39]
	v_mfma_f32_16x16x32_bf16 v[32:35], v[234:237], v[186:189], v[32:35]
	s_barrier
; #define STAGE(P, BASE, LD, br, kt) do { const char* _g = (const char*)((BASE) + (size_t)(br) * (LD) + (size_t)(kt) * 64); \
;     for (int _i = 0; _i < 2; ++_i) { int _b = tidx * 16 + _i * 8192; int _r, _c; stage_rc(_b, _r, _c); \
;       __builtin_amdgcn_global_load_lds((const unsigned*)(_g + (unsigned)((_r * (LD) + _c) * 2)), (unsigned*)((char*)(P) + _b), 16, 0, 0); } } while (0)
; #define LDA(dst, b, h) for (int m = 0; m < 4; ++m) for (int k = 0; k < 2; ++k) \
;     dst[m][k] = *reinterpret_cast<const bf16x8*>((char*)SA(b, h) + lds_byte(wr * 64 + m * 16 + fr, k * 32 + fq * 8))
; #define LDB(dst, b, h) for (int n = 0; n < 2; ++n) for (int k = 0; k < 2; ++k) \
;     dst[n][k] = *reinterpret_cast<const bf16x8*>((char*)SB(b, h) + lds_byte(wc * 32 + n * 16 + fr, k * 32 + fq * 8))
; #define MMA(ai, bj, At_, Bt_) do { __builtin_amdgcn_s_setprio(1); \
;     for (int k = 0; k < 2; ++k) for (int m = 0; m < 4; ++m) for (int n = 0; n < 2; ++n) \
;       acc[ai][bj][m][n] = __builtin_amdgcn_mfma_f32_16x16x32_bf16(At_[m][k], Bt_[n][k], acc[ai][bj][m][n], 0, 0, 0); \
;     __builtin_amdgcn_s_setprio(0); } while (0)
; #define WAIT_V(n) asm volatile("s_waitcnt vmcnt(" #n ")" ::: "memory")
; #define WAIT_L(n) asm volatile("s_waitcnt lgkmcnt(" #n ")" ::: "memory")
; #define BAR __builtin_amdgcn_s_barrier()
; #define SCHED __builtin_amdgcn_sched_barrier(0)
; template <int EPI, int lda, int ldb, int N, int K>
; __device__ __forceinline__ void gemm_phase(const u16* __restrict__ A, const u16* __restrict__ Bt, const GemmEpi ep, int wv) {
;     ...
;       STAGE(SB(0, 1), Bt, ldb, bcol + HALF, t + 2);
;       WAIT_V(6); BAR; MMA(1, 1, At, B1); BAR;
;       LDB(B0, 1, 0); SCHED; LDA(At, 1, 0); STAGE(SA(0, 1), Ab, lda, brow + HALF, t + 2);
;       WAIT_L(8); BAR; WAIT_L(0); MMA(0, 0, At, B0); BAR; SCHED;
;       LDB(B1, 1, 1); STAGE(SB(1, 0), Bt, ldb, bcol, t + 3);
;       BAR; WAIT_L(0); MMA(0, 1, At, B1); BAR;
;       LDA(At, 1, 1); STAGE(SA(1, 0), Ab, lda, brow, t + 3);
;       BAR; WAIT_L(0); MMA(1, 0, At, B0); BAR; SCHED;
	v_add_u32_e32 v167, s41, v155
	v_lshl_add_u64 v[246:247], v[138:139], 0, s[28:29]
	v_readfirstlane_b32 s50, v167
	v_lshl_add_u64 v[168:169], v[246:247], 0, s[16:17]
	s_mov_b32 m0, s50
	v_lshl_add_u64 v[248:249], v[136:137], 0, s[28:29]
	global_load_lds_dwordx4 v[168:169], off
	v_add_u32_e32 v168, 0x2000, v167
	v_lshl_add_u64 v[174:175], v[248:249], 0, s[16:17]
	v_readfirstlane_b32 s50, v168
	s_mov_b32 m0, s50
	s_nop 0
	global_load_lds_dwordx4 v[174:175], off
	s_waitcnt vmcnt(6)
	s_barrier
	v_mfma_f32_16x16x32_bf16 v[28:31], v[190:193], v[218:221], v[28:31]
	ds_read_b128 v[174:177], v158
	v_mfma_f32_16x16x32_bf16 v[24:27], v[190:193], v[226:229], v[24:27]
	v_mfma_f32_16x16x32_bf16 v[20:23], v[198:201], v[218:221], v[20:23]
	ds_read_b128 v[178:181], v158 offset:1024
	v_mfma_f32_16x16x32_bf16 v[16:19], v[198:201], v[226:229], v[16:19]
	v_mfma_f32_16x16x32_bf16 v[12:15], v[206:209], v[218:221], v[12:15]
	ds_read_b128 v[182:185], v158 offset:2048
	v_mfma_f32_16x16x32_bf16 v[8:11], v[206:209], v[226:229], v[8:11]
	v_mfma_f32_16x16x32_bf16 v[4:7], v[214:217], v[218:221], v[4:7]
	ds_read_b128 v[186:189], v158 offset:3072
	v_mfma_f32_16x16x32_bf16 v[0:3], v[214:217], v[226:229], v[0:3]
	v_mfma_f32_16x16x32_bf16 v[28:31], v[194:197], v[222:225], v[28:31]
	v_mfma_f32_16x16x32_bf16 v[24:27], v[194:197], v[230:233], v[24:27]
	v_mfma_f32_16x16x32_bf16 v[20:23], v[202:205], v[222:225], v[20:23]
	v_mfma_f32_16x16x32_bf16 v[16:19], v[202:205], v[230:233], v[16:19]
	v_mfma_f32_16x16x32_bf16 v[12:15], v[210:213], v[222:225], v[12:15]
	v_mfma_f32_16x16x32_bf16 v[8:11], v[210:213], v[230:233], v[8:11]
	v_mfma_f32_16x16x32_bf16 v[4:7], v[234:237], v[222:225], v[4:7]
	v_mfma_f32_16x16x32_bf16 v[0:3], v[234:237], v[230:233], v[0:3]
	s_barrier
	v_add_u32_e32 v169, 0x4000, v149
	v_add_u32_e32 v170, 0x6000, v149
	v_readfirstlane_b32 s50, v169
	v_lshl_add_u64 v[222:223], v[238:239], 0, s[18:19]
	s_mov_b32 m0, s50
	v_readfirstlane_b32 s50, v170
	ds_read_b128 v[190:193], v154 offset:32768
	ds_read_b128 v[194:197], v154 offset:33792
	ds_read_b128 v[198:201], v153 offset:32768
	ds_read_b128 v[202:205], v153 offset:33792
	ds_read_b128 v[206:209], v151 offset:32768
	ds_read_b128 v[210:213], v151 offset:33792
	ds_read_b128 v[214:217], v150 offset:32768
	ds_read_b128 v[218:221], v150 offset:33792
	global_load_lds_dwordx4 v[222:223], off
	v_lshl_add_u64 v[222:223], v[240:241], 0, s[18:19]
	s_mov_b32 m0, s50
	s_nop 0
	global_load_lds_dwordx4 v[222:223], off
	s_waitcnt lgkmcnt(8)
	s_barrier
	s_waitcnt lgkmcnt(0)
	s_waitcnt lgkmcnt(0)
	v_mfma_f32_16x16x32_bf16 v[124:127], v[190:193], v[174:177], v[124:127]
	ds_read_b128 v[222:225], v156
	v_mfma_f32_16x16x32_bf16 v[120:123], v[190:193], v[182:185], v[120:123]
	v_mfma_f32_16x16x32_bf16 v[116:119], v[198:201], v[174:177], v[116:119]
	ds_read_b128 v[226:229], v156 offset:1024
	v_mfma_f32_16x16x32_bf16 v[112:115], v[198:201], v[182:185], v[112:115]
	v_mfma_f32_16x16x32_bf16 v[108:111], v[206:209], v[174:177], v[108:111]
	ds_read_b128 v[230:233], v156 offset:2048
	v_mfma_f32_16x16x32_bf16 v[104:107], v[206:209], v[182:185], v[104:107]
	v_mfma_f32_16x16x32_bf16 v[100:103], v[214:217], v[174:177], v[100:103]
	ds_read_b128 v[234:237], v156 offset:3072
	v_mfma_f32_16x16x32_bf16 v[96:99], v[214:217], v[182:185], v[96:99]
	v_mfma_f32_16x16x32_bf16 v[124:127], v[194:197], v[178:181], v[124:127]
	v_mfma_f32_16x16x32_bf16 v[120:123], v[194:197], v[186:189], v[120:123]
	v_mfma_f32_16x16x32_bf16 v[116:119], v[202:205], v[178:181], v[116:119]
	v_mfma_f32_16x16x32_bf16 v[112:115], v[202:205], v[186:189], v[112:115]
	v_mfma_f32_16x16x32_bf16 v[108:111], v[210:213], v[178:181], v[108:111]
	v_mfma_f32_16x16x32_bf16 v[104:107], v[210:213], v[186:189], v[104:107]
	v_mfma_f32_16x16x32_bf16 v[100:103], v[218:221], v[178:181], v[100:103]
	v_mfma_f32_16x16x32_bf16 v[96:99], v[218:221], v[186:189], v[96:99]
	s_barrier
	v_readfirstlane_b32 s50, v157
	v_add_u32_e32 v173, 0x2000, v157
	v_lshl_add_u64 v[242:243], v[242:243], 0, s[20:21]
	s_mov_b32 m0, s50
	v_readfirstlane_b32 s50, v173
	global_load_lds_dwordx4 v[242:243], off
	v_lshl_add_u64 v[242:243], v[244:245], 0, s[20:21]
	s_mov_b32 m0, s50
	s_nop 0
	global_load_lds_dwordx4 v[242:243], off
	s_barrier
	s_waitcnt lgkmcnt(0)
	s_waitcnt lgkmcnt(0)
	v_mfma_f32_16x16x32_bf16 v[92:95], v[190:193], v[222:225], v[92:95]
	v_mfma_f32_16x16x32_bf16 v[88:91], v[190:193], v[230:233], v[88:91]
	v_mfma_f32_16x16x32_bf16 v[84:87], v[198:201], v[222:225], v[84:87]
	v_mfma_f32_16x16x32_bf16 v[80:83], v[198:201], v[230:233], v[80:83]
	v_mfma_f32_16x16x32_bf16 v[76:79], v[206:209], v[222:225], v[76:79]
	v_mfma_f32_16x16x32_bf16 v[72:75], v[206:209], v[230:233], v[72:75]
	v_mfma_f32_16x16x32_bf16 v[68:71], v[214:217], v[222:225], v[68:71]
	v_mfma_f32_16x16x32_bf16 v[64:67], v[214:217], v[230:233], v[64:67]
	v_mfma_f32_16x16x32_bf16 v[92:95], v[194:197], v[226:229], v[92:95]
	v_mfma_f32_16x16x32_bf16 v[88:91], v[194:197], v[234:237], v[88:91]
	v_mfma_f32_16x16x32_bf16 v[84:87], v[202:205], v[226:229], v[84:87]
	v_mfma_f32_16x16x32_bf16 v[80:83], v[202:205], v[234:237], v[80:83]
	v_mfma_f32_16x16x32_bf16 v[76:79], v[210:213], v[226:229], v[76:79]
	v_mfma_f32_16x16x32_bf16 v[72:75], v[210:213], v[234:237], v[72:75]
	v_mfma_f32_16x16x32_bf16 v[68:71], v[218:221], v[226:229], v[68:71]
	v_mfma_f32_16x16x32_bf16 v[64:67], v[218:221], v[234:237], v[64:67]
	v_readfirstlane_b32 s50, v159
	v_lshl_add_u64 v[238:239], v[238:239], 0, s[22:23]
	s_mov_b32 m0, s50
	v_readfirstlane_b32 s50, v160
	s_barrier
; #define STAGE(P, BASE, LD, br, kt) do { const char* _g = (const char*)((BASE) + (size_t)(br) * (LD) + (size_t)(kt) * 64); \
;     for (int _i = 0; _i < 2; ++_i) { int _b = tidx * 16 + _i * 8192; int _r, _c; stage_rc(_b, _r, _c); \
;       __builtin_amdgcn_global_load_lds((const unsigned*)(_g + (unsigned)((_r * (LD) + _c) * 2)), (unsigned*)((char*)(P) + _b), 16, 0, 0); } } while (0)
; #define LDA(dst, b, h) for (int m = 0; m < 4; ++m) for (int k = 0; k < 2; ++k) \
;     dst[m][k] = *reinterpret_cast<const bf16x8*>((char*)SA(b, h) + lds_byte(wr * 64 + m * 16 + fr, k * 32 + fq * 8))
; #define LDB(dst, b, h) for (int n = 0; n < 2; ++n) for (int k = 0; k < 2; ++k) \
;     dst[n][k] = *reinterpret_cast<const bf16x8*>((char*)SB(b, h) + lds_byte(wc * 32 + n * 16 + fr, k * 32 + fq * 8))
; #define MMA(ai, bj, At_, Bt_) do { __builtin_amdgcn_s_setprio(1); \
;     for (int k = 0; k < 2; ++k) for (int m = 0; m < 4; ++m) for (int n = 0; n < 2; ++n) \
;       acc[ai][bj][m][n] = __builtin_amdgcn_mfma_f32_16x16x32_bf16(At_[m][k], Bt_[n][k], acc[ai][bj][m][n], 0, 0, 0); \
;     __builtin_amdgcn_s_setprio(0); } while (0)
; #define WAIT_V(n) asm volatile("s_waitcnt vmcnt(" #n ")" ::: "memory")
; #define WAIT_L(n) asm volatile("s_waitcnt lgkmcnt(" #n ")" ::: "memory")
; #define BAR __builtin_amdgcn_s_barrier()
; #define SCHED __builtin_amdgcn_sched_barrier(0)
; template <int EPI, int lda, int ldb, int N, int K>
; __device__ __forceinline__ void gemm_phase(const u16* __restrict__ A, const u16* __restrict__ Bt, const GemmEpi ep, int wv) {
;     ...
;       LDA(At, 1, 1); STAGE(SA(1, 0), Ab, lda, brow, t + 3);
;       BAR; WAIT_L(0); MMA(1, 0, At, B0); BAR; SCHED;
;       STAGE(SB(1, 1), Bt, ldb, bcol + HALF, t + 3);
;       WAIT_V(6); BAR; MMA(1, 1, At, B1); BAR;
;     }
;     { LDB(B0, 0, 0); LDA(At, 0, 0); STAGE(SA(1, 1), Ab, lda, brow + HALF, nt - 1);
;       BAR; WAIT_L(0); MMA(0, 0, At, B0); BAR;
	ds_read_b128 v[190:193], v154 offset:49152
	ds_read_b128 v[194:197], v154 offset:50176
	ds_read_b128 v[198:201], v153 offset:49152
	ds_read_b128 v[202:205], v153 offset:50176
	ds_read_b128 v[206:209], v151 offset:49152
	ds_read_b128 v[210:213], v151 offset:50176
	ds_read_b128 v[214:217], v150 offset:49152
	ds_read_b128 v[218:221], v150 offset:50176
	global_load_lds_dwordx4 v[238:239], off
	v_lshl_add_u64 v[238:239], v[240:241], 0, s[22:23]
	s_mov_b32 m0, s50
	s_nop 0
	global_load_lds_dwordx4 v[238:239], off
	s_barrier
	s_waitcnt lgkmcnt(0)
	s_waitcnt lgkmcnt(0)
	v_mfma_f32_16x16x32_bf16 v[60:63], v[190:193], v[174:177], v[60:63]
	v_mfma_f32_16x16x32_bf16 v[56:59], v[190:193], v[182:185], v[56:59]
	v_mfma_f32_16x16x32_bf16 v[52:55], v[198:201], v[174:177], v[52:55]
	v_mfma_f32_16x16x32_bf16 v[48:51], v[198:201], v[182:185], v[48:51]
	v_mfma_f32_16x16x32_bf16 v[44:47], v[206:209], v[174:177], v[44:47]
	v_mfma_f32_16x16x32_bf16 v[40:43], v[206:209], v[182:185], v[40:43]
	v_mfma_f32_16x16x32_bf16 v[36:39], v[214:217], v[174:177], v[36:39]
	v_mfma_f32_16x16x32_bf16 v[32:35], v[214:217], v[182:185], v[32:35]
	v_mfma_f32_16x16x32_bf16 v[60:63], v[194:197], v[178:181], v[60:63]
	v_mfma_f32_16x16x32_bf16 v[56:59], v[194:197], v[186:189], v[56:59]
	v_mfma_f32_16x16x32_bf16 v[52:55], v[202:205], v[178:181], v[52:55]
	v_mfma_f32_16x16x32_bf16 v[48:51], v[202:205], v[186:189], v[48:51]
	v_mfma_f32_16x16x32_bf16 v[44:47], v[210:213], v[178:181], v[44:47]
	v_mfma_f32_16x16x32_bf16 v[40:43], v[210:213], v[186:189], v[40:43]
	v_mfma_f32_16x16x32_bf16 v[36:39], v[218:221], v[178:181], v[36:39]
	v_mfma_f32_16x16x32_bf16 v[32:35], v[218:221], v[186:189], v[32:35]
	s_barrier
	v_readfirstlane_b32 s50, v161
	v_add_u32_e32 v173, 0x2000, v161
	v_lshl_add_u64 v[174:175], v[246:247], 0, s[24:25]
	s_mov_b32 m0, s50
	v_readfirstlane_b32 s50, v173
	global_load_lds_dwordx4 v[174:175], off
	v_lshl_add_u64 v[174:175], v[248:249], 0, s[24:25]
	s_mov_b32 m0, s50
	s_nop 0
	global_load_lds_dwordx4 v[174:175], off
	s_waitcnt vmcnt(6)
	s_barrier
	v_mfma_f32_16x16x32_bf16 v[28:31], v[190:193], v[222:225], v[28:31]
	v_mfma_f32_16x16x32_bf16 v[24:27], v[190:193], v[230:233], v[24:27]
	v_mfma_f32_16x16x32_bf16 v[20:23], v[198:201], v[222:225], v[20:23]
	v_mfma_f32_16x16x32_bf16 v[16:19], v[198:201], v[230:233], v[16:19]
	v_mfma_f32_16x16x32_bf16 v[12:15], v[206:209], v[222:225], v[12:15]
	v_mfma_f32_16x16x32_bf16 v[8:11], v[206:209], v[230:233], v[8:11]
	v_mfma_f32_16x16x32_bf16 v[4:7], v[214:217], v[222:225], v[4:7]
	v_mfma_f32_16x16x32_bf16 v[0:3], v[214:217], v[230:233], v[0:3]
	v_mfma_f32_16x16x32_bf16 v[28:31], v[194:197], v[226:229], v[28:31]
	v_mfma_f32_16x16x32_bf16 v[24:27], v[194:197], v[234:237], v[24:27]
	v_mfma_f32_16x16x32_bf16 v[20:23], v[202:205], v[226:229], v[20:23]
	v_mfma_f32_16x16x32_bf16 v[16:19], v[202:205], v[234:237], v[16:19]
	v_mfma_f32_16x16x32_bf16 v[12:15], v[210:213], v[226:229], v[12:15]
	v_mfma_f32_16x16x32_bf16 v[8:11], v[210:213], v[234:237], v[8:11]
	v_mfma_f32_16x16x32_bf16 v[4:7], v[218:221], v[226:229], v[4:7]
	v_mfma_f32_16x16x32_bf16 v[0:3], v[218:221], v[234:237], v[0:3]
	s_add_i32 s49, s49, 2
	s_add_u32 s28, s28, 0x100
	s_addc_u32 s29, s29, 0
	s_cmpk_gt_u32 s49, 0x51
	s_barrier
	s_cbranch_scc0 .LBB0_1624
	s_add_i32 s28, s48, 0x80
	s_mul_hi_i32 s29, s28, 0x2b00
	s_mulk_i32 s28, 0x2b00
	s_add_u32 s28, s34, s28
	s_addc_u32 s29, s35, s29
	s_add_u32 s28, s28, 0x2a80
	s_addc_u32 s29, s29, 0
	v_readfirstlane_b32 s49, v171
	v_lshl_add_u64 v[160:161], s[28:29], 0, v[128:129]
	s_mov_b32 m0, s49
	ds_read_b128 v[132:135], v163
	ds_read_b128 v[136:139], v163 offset:1024
	ds_read_b128 v[140:143], v163 offset:2048
	ds_read_b128 v[174:177], v163 offset:3072
	ds_read_b128 v[178:181], v154
	ds_read_b128 v[182:185], v154 offset:1024
	ds_read_b128 v[186:189], v153
	ds_read_b128 v[190:193], v153 offset:1024
	ds_read_b128 v[194:197], v151
	ds_read_b128 v[198:201], v151 offset:1024
	ds_read_b128 v[202:205], v150
	ds_read_b128 v[206:209], v150 offset:1024
	global_load_lds_dwordx4 v[160:161], off
	v_lshl_add_u64 v[160:161], s[28:29], 0, v[130:131]
	v_readfirstlane_b32 s28, v172
	s_mov_b32 m0, s28
	s_nop 0
	global_load_lds_dwordx4 v[160:161], off
	s_barrier
	s_waitcnt lgkmcnt(0)
	s_waitcnt lgkmcnt(0)
	v_mfma_f32_16x16x32_bf16 v[124:127], v[178:181], v[132:135], v[124:127]
	v_mfma_f32_16x16x32_bf16 v[120:123], v[178:181], v[140:143], v[120:123]
	v_mfma_f32_16x16x32_bf16 v[116:119], v[186:189], v[132:135], v[116:119]
	v_mfma_f32_16x16x32_bf16 v[112:115], v[186:189], v[140:143], v[112:115]
	v_mfma_f32_16x16x32_bf16 v[108:111], v[194:197], v[132:135], v[108:111]
	v_mfma_f32_16x16x32_bf16 v[104:107], v[194:197], v[140:143], v[104:107]
	v_mfma_f32_16x16x32_bf16 v[100:103], v[202:205], v[132:135], v[100:103]
	v_mfma_f32_16x16x32_bf16 v[96:99], v[202:205], v[140:143], v[96:99]
	v_mfma_f32_16x16x32_bf16 v[124:127], v[182:185], v[136:139], v[124:127]
	v_mfma_f32_16x16x32_bf16 v[120:123], v[182:185], v[174:177], v[120:123]
	v_mfma_f32_16x16x32_bf16 v[116:119], v[190:193], v[136:139], v[116:119]
	v_mfma_f32_16x16x32_bf16 v[112:115], v[190:193], v[174:177], v[112:115]
	v_mfma_f32_16x16x32_bf16 v[108:111], v[198:201], v[136:139], v[108:111]
	v_mfma_f32_16x16x32_bf16 v[104:107], v[198:201], v[174:177], v[104:107]
	v_mfma_f32_16x16x32_bf16 v[100:103], v[206:209], v[136:139], v[100:103]
	v_mfma_f32_16x16x32_bf16 v[96:99], v[206:209], v[174:177], v[96:99]
	s_barrier
	ds_read_b128 v[210:213], v162
	ds_read_b128 v[214:217], v162 offset:1024
	ds_read_b128 v[218:221], v162 offset:2048
	ds_read_b128 v[160:163], v162 offset:3072
	s_barrier
; #define LDA(dst, b, h) for (int m = 0; m < 4; ++m) for (int k = 0; k < 2; ++k) \
;     dst[m][k] = *reinterpret_cast<const bf16x8*>((char*)SA(b, h) + lds_byte(wr * 64 + m * 16 + fr, k * 32 + fq * 8))
; #define LDB(dst, b, h) for (int n = 0; n < 2; ++n) for (int k = 0; k < 2; ++k) \
;     dst[n][k] = *reinterpret_cast<const bf16x8*>((char*)SB(b, h) + lds_byte(wc * 32 + n * 16 + fr, k * 32 + fq * 8))
; #define MMA(ai, bj, At_, Bt_) do { __builtin_amdgcn_s_setprio(1); \
;     for (int k = 0; k < 2; ++k) for (int m = 0; m < 4; ++m) for (int n = 0; n < 2; ++n) \
;       acc[ai][bj][m][n] = __builtin_amdgcn_mfma_f32_16x16x32_bf16(At_[m][k], Bt_[n][k], acc[ai][bj][m][n], 0, 0, 0); \
;     __builtin_amdgcn_s_setprio(0); } while (0)
; #define WAIT_V(n) asm volatile("s_waitcnt vmcnt(" #n ")" ::: "memory")
; #define WAIT_L(n) asm volatile("s_waitcnt lgkmcnt(" #n ")" ::: "memory")
; #define BAR __builtin_amdgcn_s_barrier()
; template <int EPI, int lda, int ldb, int N, int K>
; __device__ __forceinline__ void gemm_phase(const u16* __restrict__ A, const u16* __restrict__ Bt, const GemmEpi ep, int wv) {
;     ...
;       LDB(B1, 0, 1); BAR; WAIT_L(0); MMA(0, 1, At, B1); BAR;
;       LDA(At, 0, 1); WAIT_V(4); BAR; WAIT_L(0); MMA(1, 0, At, B0); MMA(1, 1, At, B1); BAR; }
;     { LDB(B0, 1, 0); LDA(At, 1, 0); WAIT_V(2); BAR; WAIT_L(0); MMA(0, 0, At, B0); BAR;
	s_waitcnt lgkmcnt(0)
	s_waitcnt lgkmcnt(0)
	v_mfma_f32_16x16x32_bf16 v[92:95], v[178:181], v[210:213], v[92:95]
	v_mfma_f32_16x16x32_bf16 v[88:91], v[178:181], v[218:221], v[88:91]
	v_mfma_f32_16x16x32_bf16 v[72:75], v[194:197], v[218:221], v[72:75]
	v_mfma_f32_16x16x32_bf16 v[68:71], v[202:205], v[210:213], v[68:71]
	v_mfma_f32_16x16x32_bf16 v[84:87], v[186:189], v[210:213], v[84:87]
	v_mfma_f32_16x16x32_bf16 v[80:83], v[186:189], v[218:221], v[80:83]
	v_mfma_f32_16x16x32_bf16 v[76:79], v[194:197], v[210:213], v[76:79]
	v_mfma_f32_16x16x32_bf16 v[64:67], v[202:205], v[218:221], v[64:67]
	v_mfma_f32_16x16x32_bf16 v[92:95], v[182:185], v[214:217], v[92:95]
	v_mfma_f32_16x16x32_bf16 v[88:91], v[182:185], v[160:163], v[88:91]
	v_mfma_f32_16x16x32_bf16 v[72:75], v[198:201], v[160:163], v[72:75]
	v_mfma_f32_16x16x32_bf16 v[68:71], v[206:209], v[214:217], v[68:71]
	v_mfma_f32_16x16x32_bf16 v[178:181], v[190:193], v[214:217], v[84:87]
	v_mfma_f32_16x16x32_bf16 v[182:185], v[190:193], v[160:163], v[80:83]
	v_mfma_f32_16x16x32_bf16 v[186:189], v[198:201], v[214:217], v[76:79]
	v_mfma_f32_16x16x32_bf16 v[190:193], v[206:209], v[160:163], v[64:67]
	s_barrier
	s_nop 0
	ds_read_b128 v[64:67], v154 offset:16384
	ds_read_b128 v[76:79], v154 offset:17408
	ds_read_b128 v[80:83], v153 offset:16384
	ds_read_b128 v[84:87], v153 offset:17408
	ds_read_b128 v[194:197], v151 offset:16384
	ds_read_b128 v[198:201], v151 offset:17408
	ds_read_b128 v[202:205], v150 offset:16384
	ds_read_b128 v[206:209], v150 offset:17408
	s_waitcnt vmcnt(4)
	s_barrier
	s_waitcnt lgkmcnt(0)
	s_waitcnt lgkmcnt(0)
	v_mfma_f32_16x16x32_bf16 v[60:63], v[64:67], v[132:135], v[60:63]
	v_mfma_f32_16x16x32_bf16 v[56:59], v[64:67], v[140:143], v[56:59]
	v_mfma_f32_16x16x32_bf16 v[52:55], v[80:83], v[132:135], v[52:55]
	v_mfma_f32_16x16x32_bf16 v[48:51], v[80:83], v[140:143], v[48:51]
	v_mfma_f32_16x16x32_bf16 v[44:47], v[194:197], v[132:135], v[44:47]
	v_mfma_f32_16x16x32_bf16 v[40:43], v[194:197], v[140:143], v[40:43]
	v_mfma_f32_16x16x32_bf16 v[36:39], v[202:205], v[132:135], v[36:39]
	v_mfma_f32_16x16x32_bf16 v[32:35], v[202:205], v[140:143], v[32:35]
	v_mfma_f32_16x16x32_bf16 v[60:63], v[76:79], v[136:139], v[60:63]
	v_mfma_f32_16x16x32_bf16 v[56:59], v[76:79], v[174:177], v[56:59]
	v_mfma_f32_16x16x32_bf16 v[52:55], v[84:87], v[136:139], v[52:55]
	v_mfma_f32_16x16x32_bf16 v[48:51], v[84:87], v[174:177], v[48:51]
	v_mfma_f32_16x16x32_bf16 v[44:47], v[198:201], v[136:139], v[44:47]
	v_mfma_f32_16x16x32_bf16 v[40:43], v[198:201], v[174:177], v[40:43]
	v_mfma_f32_16x16x32_bf16 v[36:39], v[206:209], v[136:139], v[36:39]
	v_mfma_f32_16x16x32_bf16 v[32:35], v[206:209], v[174:177], v[32:35]
	v_mfma_f32_16x16x32_bf16 v[28:31], v[64:67], v[210:213], v[28:31]
	v_mfma_f32_16x16x32_bf16 v[24:27], v[64:67], v[218:221], v[24:27]
	v_mfma_f32_16x16x32_bf16 v[12:15], v[194:197], v[210:213], v[12:15]
	v_mfma_f32_16x16x32_bf16 v[8:11], v[194:197], v[218:221], v[8:11]
	v_mfma_f32_16x16x32_bf16 v[20:23], v[80:83], v[210:213], v[20:23]
	v_mfma_f32_16x16x32_bf16 v[16:19], v[80:83], v[218:221], v[16:19]
	v_mfma_f32_16x16x32_bf16 v[4:7], v[202:205], v[210:213], v[4:7]
	v_mfma_f32_16x16x32_bf16 v[0:3], v[202:205], v[218:221], v[0:3]
	v_mfma_f32_16x16x32_bf16 v[28:31], v[76:79], v[214:217], v[28:31]
	v_mfma_f32_16x16x32_bf16 v[24:27], v[76:79], v[160:163], v[24:27]
	v_mfma_f32_16x16x32_bf16 v[12:15], v[198:201], v[214:217], v[12:15]
	v_mfma_f32_16x16x32_bf16 v[8:11], v[198:201], v[160:163], v[8:11]
	v_mfma_f32_16x16x32_bf16 v[132:135], v[84:87], v[214:217], v[20:23]
	v_mfma_f32_16x16x32_bf16 v[136:139], v[84:87], v[160:163], v[16:19]
	v_mfma_f32_16x16x32_bf16 v[140:143], v[206:209], v[214:217], v[4:7]
	v_mfma_f32_16x16x32_bf16 v[160:163], v[206:209], v[160:163], v[0:3]
	s_barrier
	s_nop 0
	ds_read_b128 v[0:3], v158
	ds_read_b128 v[4:7], v158 offset:1024
	ds_read_b128 v[16:19], v158 offset:2048
	ds_read_b128 v[172:175], v158 offset:3072
	ds_read_b128 v[20:23], v154 offset:32768
	ds_read_b128 v[194:197], v154 offset:33792
	ds_read_b128 v[198:201], v153 offset:32768
	ds_read_b128 v[202:205], v153 offset:33792
	ds_read_b128 v[206:209], v151 offset:32768
	ds_read_b128 v[210:213], v151 offset:33792
	ds_read_b128 v[214:217], v150 offset:32768
	ds_read_b128 v[218:221], v150 offset:33792
	s_waitcnt vmcnt(2)
	s_barrier
; #define LDA(dst, b, h) for (int m = 0; m < 4; ++m) for (int k = 0; k < 2; ++k) \
;     dst[m][k] = *reinterpret_cast<const bf16x8*>((char*)SA(b, h) + lds_byte(wr * 64 + m * 16 + fr, k * 32 + fq * 8))
; #define LDB(dst, b, h) for (int n = 0; n < 2; ++n) for (int k = 0; k < 2; ++k) \
;     dst[n][k] = *reinterpret_cast<const bf16x8*>((char*)SB(b, h) + lds_byte(wc * 32 + n * 16 + fr, k * 32 + fq * 8))
; #define MMA(ai, bj, At_, Bt_) do { __builtin_amdgcn_s_setprio(1); \
;     for (int k = 0; k < 2; ++k) for (int m = 0; m < 4; ++m) for (int n = 0; n < 2; ++n) \
;       acc[ai][bj][m][n] = __builtin_amdgcn_mfma_f32_16x16x32_bf16(At_[m][k], Bt_[n][k], acc[ai][bj][m][n], 0, 0, 0); \
;     __builtin_amdgcn_s_setprio(0); } while (0)
; #define WAIT_V(n) asm volatile("s_waitcnt vmcnt(" #n ")" ::: "memory")
; #define WAIT_L(n) asm volatile("s_waitcnt lgkmcnt(" #n ")" ::: "memory")
; #define BAR __builtin_amdgcn_s_barrier()
; template <int EPI, int lda, int ldb, int N, int K>
; __device__ __forceinline__ void gemm_phase(const u16* __restrict__ A, const u16* __restrict__ Bt, const GemmEpi ep, int wv) {
;     ...
;     { LDB(B0, 1, 0); LDA(At, 1, 0); WAIT_V(2); BAR; WAIT_L(0); MMA(0, 0, At, B0); BAR;
;       LDB(B1, 1, 1); WAIT_V(0); BAR; WAIT_L(0); MMA(0, 1, At, B1); BAR;
;       LDA(At, 1, 1); BAR; WAIT_L(0); MMA(1, 0, At, B0); MMA(1, 1, At, B1); BAR; }
;     if (wr == 0) BAR;
	s_waitcnt lgkmcnt(0)
	s_waitcnt lgkmcnt(0)
	v_mfma_f32_16x16x32_bf16 v[64:67], v[20:23], v[0:3], v[124:127]
	v_mfma_f32_16x16x32_bf16 v[76:79], v[20:23], v[16:19], v[120:123]
	v_mfma_f32_16x16x32_bf16 v[80:83], v[198:201], v[0:3], v[116:119]
	v_mfma_f32_16x16x32_bf16 v[84:87], v[198:201], v[16:19], v[112:115]
	v_mfma_f32_16x16x32_bf16 v[108:111], v[206:209], v[0:3], v[108:111]
	v_mfma_f32_16x16x32_bf16 v[104:107], v[206:209], v[16:19], v[104:107]
	v_mfma_f32_16x16x32_bf16 v[120:123], v[214:217], v[0:3], v[100:103]
	v_mfma_f32_16x16x32_bf16 v[124:127], v[214:217], v[16:19], v[96:99]
	v_mfma_f32_16x16x32_bf16 v[116:119], v[194:197], v[4:7], v[64:67]
	v_mfma_f32_16x16x32_bf16 v[112:115], v[194:197], v[172:175], v[76:79]
	v_mfma_f32_16x16x32_bf16 v[100:103], v[202:205], v[4:7], v[80:83]
	v_mfma_f32_16x16x32_bf16 v[96:99], v[202:205], v[172:175], v[84:87]
	v_mfma_f32_16x16x32_bf16 v[84:87], v[210:213], v[4:7], v[108:111]
	v_mfma_f32_16x16x32_bf16 v[80:83], v[210:213], v[172:175], v[104:107]
	v_mfma_f32_16x16x32_bf16 v[76:79], v[218:221], v[4:7], v[120:123]
	v_mfma_f32_16x16x32_bf16 v[64:67], v[218:221], v[172:175], v[124:127]
	s_barrier
	ds_read_b128 v[222:225], v156
	ds_read_b128 v[226:229], v156 offset:1024
	ds_read_b128 v[230:233], v156 offset:2048
	ds_read_b128 v[156:159], v156 offset:3072
	s_waitcnt vmcnt(0)
	s_barrier
	s_waitcnt lgkmcnt(0)
	s_waitcnt lgkmcnt(0)
	v_mfma_f32_16x16x32_bf16 v[92:95], v[20:23], v[222:225], v[92:95]
	v_mfma_f32_16x16x32_bf16 v[20:23], v[20:23], v[230:233], v[88:91]
	v_mfma_f32_16x16x32_bf16 v[88:91], v[198:201], v[222:225], v[178:181]
	v_mfma_f32_16x16x32_bf16 v[104:107], v[198:201], v[230:233], v[182:185]
	v_mfma_f32_16x16x32_bf16 v[176:179], v[206:209], v[222:225], v[186:189]
	v_mfma_f32_16x16x32_bf16 v[72:75], v[206:209], v[230:233], v[72:75]
	v_mfma_f32_16x16x32_bf16 v[68:71], v[214:217], v[222:225], v[68:71]
	v_mfma_f32_16x16x32_bf16 v[180:183], v[214:217], v[230:233], v[190:193]
	v_mfma_f32_16x16x32_bf16 v[124:127], v[194:197], v[226:229], v[92:95]
	v_mfma_f32_16x16x32_bf16 v[120:123], v[194:197], v[156:159], v[20:23]
	v_mfma_f32_16x16x32_bf16 v[108:111], v[202:205], v[226:229], v[88:91]
	v_mfma_f32_16x16x32_bf16 v[104:107], v[202:205], v[156:159], v[104:107]
	v_mfma_f32_16x16x32_bf16 v[92:95], v[210:213], v[226:229], v[176:179]
	v_mfma_f32_16x16x32_bf16 v[88:91], v[210:213], v[156:159], v[72:75]
	v_mfma_f32_16x16x32_bf16 v[72:75], v[218:221], v[226:229], v[68:71]
	v_mfma_f32_16x16x32_bf16 v[68:71], v[218:221], v[156:159], v[180:183]
	s_barrier
	ds_read_b128 v[176:179], v154 offset:49152
	ds_read_b128 v[180:183], v154 offset:50176
	ds_read_b128 v[184:187], v153 offset:49152
	ds_read_b128 v[188:191], v153 offset:50176
	ds_read_b128 v[192:195], v151 offset:49152
	ds_read_b128 v[196:199], v151 offset:50176
	ds_read_b128 v[200:203], v150 offset:49152
	ds_read_b128 v[204:207], v150 offset:50176
	s_barrier
	s_waitcnt lgkmcnt(0)
	s_waitcnt lgkmcnt(0)
	v_mfma_f32_16x16x32_bf16 v[20:23], v[176:179], v[0:3], v[60:63]
	v_mfma_f32_16x16x32_bf16 v[56:59], v[176:179], v[16:19], v[56:59]
	v_mfma_f32_16x16x32_bf16 v[60:63], v[184:187], v[0:3], v[52:55]
	v_mfma_f32_16x16x32_bf16 v[208:211], v[184:187], v[16:19], v[48:51]
	v_mfma_f32_16x16x32_bf16 v[44:47], v[192:195], v[0:3], v[44:47]
	v_mfma_f32_16x16x32_bf16 v[40:43], v[192:195], v[16:19], v[40:43]
	v_mfma_f32_16x16x32_bf16 v[0:3], v[200:203], v[0:3], v[36:39]
	v_mfma_f32_16x16x32_bf16 v[212:215], v[200:203], v[16:19], v[32:35]
	v_mfma_f32_16x16x32_bf16 v[52:55], v[180:183], v[4:7], v[20:23]
	v_mfma_f32_16x16x32_bf16 v[48:51], v[180:183], v[172:175], v[56:59]
	v_mfma_f32_16x16x32_bf16 v[36:39], v[188:191], v[4:7], v[60:63]
	v_mfma_f32_16x16x32_bf16 v[32:35], v[188:191], v[172:175], v[208:211]
	v_mfma_f32_16x16x32_bf16 v[20:23], v[196:199], v[4:7], v[44:47]
	v_mfma_f32_16x16x32_bf16 v[16:19], v[196:199], v[172:175], v[40:43]
	v_mfma_f32_16x16x32_bf16 v[4:7], v[204:207], v[4:7], v[0:3]
	v_mfma_f32_16x16x32_bf16 v[0:3], v[204:207], v[172:175], v[212:215]
	v_mfma_f32_16x16x32_bf16 v[28:31], v[176:179], v[222:225], v[28:31]
	v_mfma_f32_16x16x32_bf16 v[24:27], v[176:179], v[230:233], v[24:27]
	v_mfma_f32_16x16x32_bf16 v[40:43], v[184:187], v[222:225], v[132:135]
	v_mfma_f32_16x16x32_bf16 v[132:135], v[184:187], v[230:233], v[136:139]
	v_mfma_f32_16x16x32_bf16 v[12:15], v[192:195], v[222:225], v[12:15]
	v_mfma_f32_16x16x32_bf16 v[8:11], v[192:195], v[230:233], v[8:11]
	v_mfma_f32_16x16x32_bf16 v[136:139], v[200:203], v[222:225], v[140:143]
	v_mfma_f32_16x16x32_bf16 v[140:143], v[200:203], v[230:233], v[160:163]
	v_mfma_f32_16x16x32_bf16 v[60:63], v[180:183], v[226:229], v[28:31]
	v_mfma_f32_16x16x32_bf16 v[56:59], v[180:183], v[156:159], v[24:27]
	v_mfma_f32_16x16x32_bf16 v[44:47], v[188:191], v[226:229], v[40:43]
	v_mfma_f32_16x16x32_bf16 v[40:43], v[188:191], v[156:159], v[132:135]
	v_mfma_f32_16x16x32_bf16 v[28:31], v[196:199], v[226:229], v[12:15]
	v_mfma_f32_16x16x32_bf16 v[24:27], v[196:199], v[156:159], v[8:11]
	v_mfma_f32_16x16x32_bf16 v[12:15], v[204:207], v[226:229], v[136:139]
	v_mfma_f32_16x16x32_bf16 v[8:11], v[204:207], v[156:159], v[140:143]
	v_cmp_gt_u32_e32 vcc, s46, v147
	s_barrier
	s_and_saveexec_b64 s[28:29], vcc
	s_cbranch_execz .LBB0_1627
	s_barrier
